# XOR chunk swizzle of K=1024 GEMM operands (xb, merged, weights): rows no longer at one power-of-two stride per K slice
# baseline (speedup 1.0000x reference)
.LBB0_26:
	s_mov_b64 s[80:81], 0
	s_add_u32 s36, s20, s80
	s_addc_u32 s37, s21, s81
	s_lshl_b64 s[0:1], s[80:81], 2
	s_mov_b64 s[42:43], s[22:23]
	v_readlane_b32 s4, v253, 6
	s_mov_b64 s[40:41], s[20:21]
	v_readlane_b32 s5, v253, 7
	s_add_u32 s20, s4, s0
	s_addc_u32 s21, s5, s1
	s_add_u32 s0, s36, 0x58f0a00
	s_addc_u32 s1, s37, 0
	v_writelane_b32 v253, s0, 27
	s_mov_b32 s45, s27
	s_nop 0
	v_writelane_b32 v253, s1, 28
	s_mul_hi_i32 s0, s42, 0x66666667
	s_lshr_b32 s1, s0, 31
	s_ashr_i32 s0, s0, 3
	s_add_i32 s0, s0, s1
	s_mul_i32 s1, s0, 20
	s_sub_i32 s30, s42, s1
	s_mov_b32 s1, 0x6820a
	s_lshr_b32 s1, s1, s30
	s_and_b32 s1, s1, 1
	s_sub_u32 s1, 0, s1
	v_lshrrev_b32_e32 v197, 2, v195
	v_lshlrev_b32_e32 v197, 7, v197
	v_and_b32_e32 v197, s1, v197
	v_and_b32_e32 v196, 15, v195
	v_lshlrev_b32_e32 v196, 7, v196
	s_add_i32 s26, s30, -3
	s_cmp_lt_u32 s26, 12
	s_cselect_b64 s[4:5], -1, 0
	v_writelane_b32 v253, s4, 29
	s_cmp_eq_u32 s30, -1
	s_nop 0
	v_writelane_b32 v253, s5, 30
	s_cselect_b64 s[4:5], -1, 0
	s_cmp_eq_u32 s30, 1
	s_cselect_b32 s1, 0, 0x24d0000
	s_add_u32 s76, s36, s1
	s_addc_u32 s77, s37, 0
	s_add_u32 s34, s36, 0x3550000
	s_addc_u32 s35, s37, 0
	s_add_u32 s22, s36, 0x5550000
	s_addc_u32 s23, s37, 0
	s_add_u32 s18, s36, 0x58f4200
	v_writelane_b32 v253, s4, 31
	s_addc_u32 s19, s37, 0
	s_ashr_i32 s1, s0, 31
	v_writelane_b32 v253, s5, 32
	s_lshl_b32 s16, s0, 10
	s_lshl_b64 s[4:5], s[0:1], 22
	s_ashr_i32 s17, s16, 31
	v_writelane_b32 v253, s4, 33
	s_nop 1
	v_writelane_b32 v253, s5, 34
	s_add_u32 s4, s36, 0x24d0000
	s_addc_u32 s5, s37, 0
	v_writelane_b32 v253, s4, 35
	s_nop 1
	v_writelane_b32 v253, s5, 36
	s_add_u32 s4, s36, 0x58f0aa0
	s_addc_u32 s5, s37, 0
	v_writelane_b32 v253, s4, 37
	s_nop 1
	v_writelane_b32 v253, s5, 38
	s_add_u32 s4, s36, 0x58f0a98
	s_addc_u32 s5, s37, 0
	v_writelane_b32 v253, s4, 39
	s_nop 1
	v_writelane_b32 v253, s5, 40
	s_add_u32 s4, s36, 0x22d0000
	s_addc_u32 s5, s37, 0
	v_writelane_b32 v253, s4, 41
	s_nop 1
	v_writelane_b32 v253, s5, 42
	s_add_u32 s4, s36, 0x58f0a90
	s_addc_u32 s5, s37, 0
	s_add_u32 s78, s36, 0x1fd0000
	s_addc_u32 s79, s37, 0
	s_add_u32 s82, s36, 0x1880000
	v_writelane_b32 v253, s4, 43
	s_addc_u32 s83, s37, 0
	s_nop 0
	v_writelane_b32 v253, s5, 44
	s_add_u32 s4, s36, 0x58f0a20
	s_addc_u32 s5, s37, 0
	s_add_u32 s86, s36, 0x1080000
	v_writelane_b32 v253, s4, 45
	s_addc_u32 s87, s37, 0
	s_nop 0
	v_writelane_b32 v253, s5, 46
	s_add_u32 s4, s36, 0x58f0a18
	s_addc_u32 s5, s37, 0
	v_writelane_b32 v253, s4, 47
	s_nop 1
	v_writelane_b32 v253, s5, 48
	s_add_u32 s4, s36, 0xb00000
	s_addc_u32 s5, s37, 0
	v_writelane_b32 v253, s4, 49
	s_nop 1
	v_writelane_b32 v253, s5, 50
	s_add_u32 s4, s36, 0x58f0a08
	s_addc_u32 s5, s37, 0
	v_writelane_b32 v253, s4, 51
	s_nop 1
	v_writelane_b32 v253, s5, 52
	s_add_u32 s4, s36, 0x58f0ab0
	s_addc_u32 s5, s37, 0
	v_writelane_b32 v253, s4, 53
	s_nop 1
	v_writelane_b32 v253, s5, 54
	s_add_u32 s4, s36, 0x2fd0000
	s_addc_u32 s5, s37, 0
	v_writelane_b32 v253, s4, 55
	s_nop 1
	v_writelane_b32 v253, s5, 56
	s_lshl_b64 s[4:5], s[0:1], 19
	v_writelane_b32 v253, s4, 57
	s_nop 1
	v_writelane_b32 v253, s5, 58
	s_add_u32 s4, s36, 0x58f0a30
	s_addc_u32 s5, s37, 0
	v_writelane_b32 v253, s4, 59
	s_lshl_b32 s12, s0, 8
	s_ashr_i32 s13, s12, 31
	v_writelane_b32 v253, s5, 60
	s_lshl_b32 s4, s0, 7
	s_ashr_i32 s5, s4, 31
	s_add_u32 s90, s36, 0x1e80000
	s_addc_u32 s91, s37, 0
	s_add_i32 s1, s42, 19
	v_writelane_b32 v253, s4, 61
	s_cmp_lt_u32 s1, 39
	s_cselect_b64 s[14:15], -1, 0
	v_writelane_b32 v253, s5, 62
	s_add_u32 s4, s36, 0x5590000
	s_addc_u32 s5, s37, 0
	v_writelane_b32 v253, s4, 63
	s_mov_b32 s1, 0xe8f4800
	s_nop 0
	v_writelane_b32 v254, s5, 0
	s_add_u32 s4, s36, 0x5790000
	s_addc_u32 s5, s37, 0
	v_writelane_b32 v254, s4, 1
	s_nop 1
	v_writelane_b32 v254, s5, 2
	s_add_u32 s4, s36, 0x58f0800
	s_addc_u32 s5, s37, 0
	v_writelane_b32 v254, s4, 3
	s_cmp_eq_u32 s30, 17
	s_nop 0
	v_writelane_b32 v254, s5, 4
	s_cselect_b64 s[4:5], -1, 0
	s_cmp_eq_u32 s30, 2
	s_cselect_b64 s[6:7], -1, 0
	s_and_b64 s[8:9], s[4:5], exec
	s_cselect_b32 s1, s1, 0x58f4200
	s_add_u32 s94, s36, s1
	s_addc_u32 s95, s37, 0
	v_cndmask_b32_e64 v180, 0.5, 1.0, s[4:5]
	s_and_b64 s[4:5], s[4:5], exec
	s_movk_i32 s1, 0x400
	s_cselect_b32 s10, s1, 0xb00
	s_mov_b32 s1, 0x22d0000
	s_cselect_b32 s1, s1, 0x2fd0000
	s_and_b64 s[4:5], s[6:7], exec
	s_cselect_b32 s1, 0xb00000, s1
	s_add_u32 s96, s36, s1
	s_addc_u32 s97, s37, 0
	v_writelane_b32 v254, s14, 5
	s_lshr_b32 s1, s10, 6
	s_and_b64 s[4:5], s[6:7], s[14:15]
	v_writelane_b32 v254, s15, 6
	s_add_i32 s11, s1, -2
	s_add_i32 s1, s1, -1
	v_writelane_b32 v254, s4, 7
	s_cmp_lg_u32 s30, 15
	v_mov_b32_e32 v182, v180
	v_writelane_b32 v254, s5, 8
	s_cselect_b64 s[4:5], -1, 0
	s_add_u32 s70, s36, 0x88f4200
	s_addc_u32 s71, s37, 0
	s_add_u32 s72, s36, 0xe8f4200
	s_addc_u32 s73, s37, 0
	s_cmp_gt_u32 s26, 5
	v_writelane_b32 v254, s1, 9
	s_cselect_b64 s[14:15], -1, 0
	s_add_i32 s1, s30, -9
	v_writelane_b32 v254, s4, 10
	s_cmp_lt_u32 s26, 6
	s_cselect_b32 s1, s26, s1
	v_writelane_b32 v254, s5, 11
	s_lshl_b32 s8, s0, 2
	v_writelane_b32 v254, s30, 12
	s_and_b64 s[4:5], s[14:15], exec
	v_writelane_b32 v254, s1, 13
	s_cselect_b32 s1, 2, 0
	s_add_u32 s4, s36, 0xf0f4200
	v_writelane_b32 v254, s4, 14
	s_addc_u32 s4, s37, 0
	v_writelane_b32 v254, s4, 15
	s_add_u32 s4, s36, 0x100f4200
	s_addc_u32 s5, s37, 0
	v_writelane_b32 v254, s4, 16
	v_mov_b32_e32 v183, v180
	s_mov_b32 s9, s27
	v_writelane_b32 v254, s5, 17
	s_add_u32 s4, s36, 0x58f0000
	v_writelane_b32 v254, s4, 18
	s_addc_u32 s4, s37, 0
	v_writelane_b32 v254, s4, 19
	s_add_u32 s4, s36, 0xf8f4200
	v_writelane_b32 v254, s4, 20
	s_addc_u32 s4, s37, 0
	v_writelane_b32 v254, s4, 21
	s_add_u32 s4, s36, 0x108f4200
	s_addc_u32 s5, s37, 0
	v_writelane_b32 v254, s4, 22
	s_nop 1
	v_writelane_b32 v254, s5, 23
	s_add_u32 s4, s36, 0xf104200
	v_writelane_b32 v254, s4, 24
	s_addc_u32 s4, s37, 0
	v_writelane_b32 v254, s4, 25
	s_add_u32 s4, s36, 0xf904200
	v_writelane_b32 v254, s4, 26
	s_addc_u32 s4, s37, 0
	v_writelane_b32 v254, s4, 27
	s_and_b64 s[4:5], s[14:15], exec
	s_cselect_b32 s4, 0x1800000, 0
	s_cselect_b32 s44, 0x2000, 0
	s_add_u32 s4, s36, s4
	s_addc_u32 s5, s37, 0
	s_add_u32 s4, s4, 0x70c4600
	v_writelane_b32 v254, s4, 28
	s_addc_u32 s4, s5, 0
	v_writelane_b32 v254, s4, 29
	s_mov_b64 s[4:5], s[16:17]
	s_mov_b64 s[16:17], s[36:37]
	s_add_u32 s6, s16, 0x58b0000
	v_writelane_b32 v254, s6, 30
	s_addc_u32 s6, s17, 0
	v_writelane_b32 v254, s6, 31
	s_add_u32 s6, s16, 0xc8f4200
	s_addc_u32 s7, s17, 0
	v_writelane_b32 v254, s6, 32
	s_mul_i32 s36, s0, 0x60
	s_nop 0
	v_writelane_b32 v254, s7, 33
	s_add_u32 s6, s16, 0xe4f4200
	s_addc_u32 s7, s17, 0
	v_writelane_b32 v254, s6, 34
	s_nop 1
	v_writelane_b32 v254, s7, 35
	s_add_u32 s6, s16, 0x58f0a50
	s_addc_u32 s7, s17, 0
	v_writelane_b32 v254, s6, 36
	s_ashr_i32 s37, s36, 31
	s_nop 0
	v_writelane_b32 v254, s7, 37
	s_add_u32 s6, s16, 0x58a0000
	s_addc_u32 s7, s17, 0
	v_writelane_b32 v254, s6, 38
	s_nop 1
	v_writelane_b32 v254, s7, 39
	s_add_u32 s6, s16, 0x88f5950
	v_writelane_b32 v254, s6, 40
	s_addc_u32 s6, s17, 0
	v_writelane_b32 v254, s6, 41
	s_add_u32 s6, s16, 0x58f0a68
	s_addc_u32 s7, s17, 0
	v_writelane_b32 v254, s6, 42
	s_nop 1
	v_writelane_b32 v254, s7, 43
	s_add_u32 s6, s16, 0x58f0a60
	s_addc_u32 s7, s17, 0
	v_writelane_b32 v254, s6, 44
	s_nop 1
	v_writelane_b32 v254, s7, 45
	s_add_u32 s6, s16, 0x88f4540
	v_writelane_b32 v254, s6, 46
	s_addc_u32 s6, s17, 0
	v_writelane_b32 v254, s6, 47
	s_add_u32 s6, s16, 0x58f0a80
	s_addc_u32 s7, s17, 0
	v_writelane_b32 v254, s6, 48
	s_nop 1
	v_writelane_b32 v254, s7, 49
	s_add_u32 s6, s16, 0x5890000
	s_addc_u32 s7, s17, 0
	v_writelane_b32 v254, s6, 50
	s_nop 1
	v_writelane_b32 v254, s7, 51
	s_add_u32 s6, s16, 0x5898000
	s_addc_u32 s7, s17, 0
	s_lshl_b32 s38, s0, 6
	v_writelane_b32 v254, s6, 52
	s_ashr_i32 s39, s38, 31
	s_nop 0
	v_writelane_b32 v254, s7, 53
	s_and_b64 s[6:7], s[14:15], exec
	s_cselect_b32 s6, 0x1000000, 0
	s_add_u32 s6, s34, s6
	s_addc_u32 s7, s35, 0
	v_writelane_b32 v254, s6, 54
	s_and_b64 s[14:15], s[14:15], exec
	s_nop 0
	v_writelane_b32 v254, s7, 55
	s_mul_hi_i32 s7, s0, 0x1600000
	s_mul_i32 s6, s0, 0x1600000
	v_writelane_b32 v254, s6, 56
	s_nop 1
	v_writelane_b32 v254, s7, 57
	s_mul_hi_i32 s7, s0, 0x1ba8000
	s_mul_i32 s6, s0, 0x1ba8000
	v_writelane_b32 v254, s6, 58
	s_nop 1
	v_writelane_b32 v254, s7, 59
	s_mul_hi_i32 s7, s0, 0xb00000
	s_mul_i32 s6, s0, 0xb00000
	v_writelane_b32 v254, s6, 60
	s_nop 1
	v_writelane_b32 v254, s7, 61
	s_mul_hi_i32 s7, s0, 0xc0000
	s_mul_i32 s6, s0, 0xc0000
	v_writelane_b32 v254, s6, 62
	s_nop 1
	v_writelane_b32 v254, s7, 63
	s_mul_hi_i32 s7, s0, 0x6000
	s_mul_i32 s6, s0, 0x6000
	v_writelane_b32 v255, s6, 0
	s_mul_i32 s0, s0, 3
	s_nop 0
	v_writelane_b32 v255, s7, 1
	v_writelane_b32 v255, s0, 2
	s_cselect_b32 s0, 0x20000, 0
	s_add_u32 s14, s22, s0
	s_addc_u32 s15, s23, 0
	s_add_u32 s6, s16, 0x58f0a78
	s_addc_u32 s7, s17, 0
	v_writelane_b32 v255, s6, 3
	s_or_b32 s0, s1, s8
	v_readlane_b32 s1, v253, 12
	v_writelane_b32 v255, s7, 4
	v_writelane_b32 v255, s8, 5
	v_writelane_b32 v255, s0, 6
	v_writelane_b32 v255, s44, 7
	s_mul_i32 s0, s44, 0xc00
	s_add_u32 s6, s40, s0
	v_writelane_b32 v255, s45, 8
	v_writelane_b32 v255, s40, 9
	s_addc_u32 s7, s41, 0
	s_nop 0
	v_writelane_b32 v255, s41, 10
	v_writelane_b32 v255, s42, 11
	v_writelane_b32 v255, s43, 12
	v_writelane_b32 v255, s6, 13
	s_nop 1
	v_writelane_b32 v255, s7, 14
	s_add_u32 s6, s1, s0
	v_readlane_b32 s0, v253, 13
	s_addc_u32 s7, s0, 0
	v_writelane_b32 v255, s6, 15
	s_lshl_b64 s[0:1], s[36:37], 2
	s_nop 0
	v_writelane_b32 v255, s7, 16
	v_writelane_b32 v255, s0, 17
	s_nop 1
	v_writelane_b32 v255, s1, 18
	s_lshl_b64 s[0:1], s[38:39], 2
	v_writelane_b32 v255, s0, 19
	s_nop 1
	v_writelane_b32 v255, s1, 20
	s_lshl_b64 s[0:1], s[12:13], 2
	v_writelane_b32 v255, s0, 21
	s_nop 1
	v_writelane_b32 v255, s1, 22
	s_mov_b64 s[0:1], -1
	s_branch .LBB0_29

.LBB0_93:
	s_cmpk_gt_i32 s26, 0xff
	s_cbranch_scc1 .LBB0_118
	v_mov_b32 v1, v179
	s_ashr_i32 s12, s26, 31
	s_waitcnt lgkmcnt(0)
	v_bfe_i32 v5, v1, 27, 1
	v_lshlrev_b32_e32 v3, 4, v1
	v_lshrrev_b32_e32 v5, 22, v5
	v_add_u32_e32 v5, v3, v5
	v_and_b32_e32 v5, 0xfffffc00, v5
	v_ashrrev_i32_e32 v4, 31, v1
	v_sub_u32_e32 v3, v3, v5
	v_lshrrev_b32_e32 v4, 26, v4
	v_lshrrev_b32_e32 v5, 4, v3
	v_add_u32_e32 v4, v1, v4
	v_bitop3_b32 v5, v5, v3, 32 bitop3:0x6c
	v_ashrrev_i32_e32 v3, 31, v3
	v_ashrrev_i32_e32 v4, 6, v4
	v_lshrrev_b32_e32 v3, 26, v3
	s_lshr_b32 s12, s12, 26
	v_ashrrev_i32_e32 v2, 6, v1
	v_lshlrev_b32_e32 v6, 3, v4
	v_add_u32_e32 v3, v5, v3
	s_add_i32 s13, s26, s12
	v_readfirstlane_b32 s8, v2
	v_and_b32_e32 v6, 0x7ffffff0, v6
	v_ashrrev_i32_e32 v3, 6, v3
	s_ashr_i32 s12, s13, 6
	s_and_b32 s13, s13, 0xffffc0
	v_add_u32_e32 v6, v3, v6
	v_mul_i32_i24_e32 v3, 64, v3
	s_mov_b32 s30, s8
	s_mov_b32 s40, s27
	s_sub_i32 s13, s26, s13
	v_sub_u32_e32 v3, v5, v3
	s_ashr_i32 s41, s40, 31
	s_lshl_b32 s13, s13, 8
	s_lshl_b32 s36, s12, 8
	v_lshlrev_b32_e32 v4, 5, v4
	v_ashrrev_i16_sdwa v3, v194, sext(v3) dst_sel:DWORD dst_unused:UNUSED_PAD src0_sel:DWORD src1_sel:BYTE_0
	v_mul_lo_u32 v5, v6, s10
	s_lshl_b64 s[40:41], s[40:41], 7
	v_bfe_i32 v3, v3, 0, 16
	v_and_or_b32 v4, v4, 32, v5
	s_add_u32 s40, s96, s40
	v_add_lshl_u32 v144, v4, v3, 1
	s_addc_u32 s41, s97, s41
	s_lshl_b32 s30, s30, 10
	v_lshl_add_u64 v[4:5], s[40:41], 0, v[144:145]
	s_add_i32 s30, s30, 0
	s_mul_hi_i32 s41, s36, s10
	s_mul_i32 s40, s36, s10
	s_or_b32 s42, s36, 64
	s_add_i32 m0, s30, 0x10000
	v_lshl_add_u64 v[6:7], s[40:41], 1, v[4:5]
	s_mul_hi_i32 s43, s42, s10
	s_mul_i32 s42, s42, s10
	v_xor_b32_e32 v6, v197, v6
	global_load_lds_dwordx4 v[6:7], off
	v_lshl_add_u64 v[4:5], s[42:43], 1, v[4:5]
	s_add_i32 m0, s30, 0x12000
	s_mov_b32 s30, s8
	s_mov_b32 s44, s27
	v_xor_b32_e32 v4, v197, v4
	global_load_lds_dwordx4 v[4:5], off
	s_ashr_i32 s45, s44, 31
	s_ashr_i32 s37, s36, 31
	s_lshl_b64 s[44:45], s[44:45], 7
	s_add_u32 s44, s94, s44
	s_addc_u32 s45, s95, s45
	s_lshl_b32 s30, s30, 10
	v_lshl_add_u64 v[4:5], s[44:45], 0, v[144:145]
	s_add_i32 s30, s30, 0
	s_mul_hi_i32 s45, s13, s10
	s_mul_i32 s44, s13, s10
	s_or_b32 s46, s13, 64
	v_lshl_add_u64 v[6:7], s[44:45], 1, v[4:5]
	s_mov_b32 m0, s30
	s_mul_hi_i32 s47, s46, s10
	s_mul_i32 s46, s46, s10
	v_xor_b32_e32 v6, v197, v6
	global_load_lds_dwordx4 v[6:7], off
	v_lshl_add_u64 v[4:5], s[46:47], 1, v[4:5]
	s_add_i32 m0, s30, 0x2000
	s_mov_b32 s30, s8
	s_mov_b32 s48, s27
	v_xor_b32_e32 v4, v197, v4
	global_load_lds_dwordx4 v[4:5], off
	s_ashr_i32 s49, s48, 31
	s_or_b32 s50, s36, 0x80
	s_lshl_b64 s[48:49], s[48:49], 7
	s_add_u32 s48, s96, s48
	s_addc_u32 s49, s97, s49
	s_lshl_b32 s30, s30, 10
	v_lshl_add_u64 v[4:5], s[48:49], 0, v[144:145]
	s_add_i32 s30, s30, 0
	s_mul_hi_i32 s49, s50, s10
	s_mul_i32 s48, s50, s10
	s_or_b32 s50, s36, 0xc0
	s_add_i32 m0, s30, 0x14000
	v_lshl_add_u64 v[6:7], s[48:49], 1, v[4:5]
	s_mul_hi_i32 s55, s50, s10
	s_mul_i32 s54, s50, s10
	v_xor_b32_e32 v6, v197, v6
	global_load_lds_dwordx4 v[6:7], off
	v_lshl_add_u64 v[4:5], s[54:55], 1, v[4:5]
	s_add_i32 m0, s30, 0x16000
	s_mov_b32 s30, s8
	s_mov_b32 s50, s27
	v_xor_b32_e32 v4, v197, v4
	global_load_lds_dwordx4 v[4:5], off
	s_ashr_i32 s51, s50, 31
	s_or_b32 s52, s13, 0x80
	s_lshl_b64 s[50:51], s[50:51], 7
	s_add_u32 s50, s94, s50
	s_addc_u32 s51, s95, s51
	s_lshl_b32 s30, s30, 10
	v_lshl_add_u64 v[4:5], s[50:51], 0, v[144:145]
	s_add_i32 s30, s30, 0
	s_mul_hi_i32 s51, s52, s10
	s_mul_i32 s50, s52, s10
	s_or_b32 s52, s13, 0xc0
	s_add_i32 m0, s30, 0x4000
	v_lshl_add_u64 v[6:7], s[50:51], 1, v[4:5]
	s_mul_hi_i32 s53, s52, s10
	s_mul_i32 s52, s52, s10
	v_xor_b32_e32 v6, v197, v6
	global_load_lds_dwordx4 v[6:7], off
	v_lshl_add_u64 v[4:5], s[52:53], 1, v[4:5]
	s_add_i32 m0, s30, 0x6000
	v_ashrrev_i32_e32 v3, 8, v1
	v_xor_b32_e32 v4, v197, v4
	global_load_lds_dwordx4 v[4:5], off
	s_mov_b64 s[4:5], s[80:81]
	v_cmp_eq_u32_e32 vcc, 1, v3
	s_and_saveexec_b64 s[56:57], vcc
	s_cbranch_execz .LBB0_96
	s_barrier
.LBB0_96:
	s_or_b64 exec, exec, s[56:57]
	s_mov_b32 s56, 1
	s_mov_b32 s30, s8
	s_waitcnt vmcnt(4)
	s_barrier
	s_ashr_i32 s57, s56, 31
	s_lshl_b64 s[56:57], s[56:57], 7
	s_add_u32 s56, s96, s56
	s_addc_u32 s57, s97, s57
	s_lshl_b32 s30, s30, 10
	v_lshl_add_u64 v[4:5], s[56:57], 0, v[144:145]
	s_add_i32 s30, s31, s30
	v_lshl_add_u64 v[6:7], s[40:41], 1, v[4:5]
	s_mov_b32 m0, s30
	v_lshl_add_u64 v[4:5], s[42:43], 1, v[4:5]
	v_xor_b32_e32 v6, v197, v6
	global_load_lds_dwordx4 v[6:7], off
	s_add_i32 m0, s30, 0x2000
	s_mov_b32 s56, 1
	s_mov_b32 s30, s8
	v_xor_b32_e32 v4, v197, v4
	global_load_lds_dwordx4 v[4:5], off
	s_ashr_i32 s57, s56, 31
	s_lshl_b64 s[56:57], s[56:57], 7
	s_add_u32 s56, s94, s56
	s_addc_u32 s57, s95, s57
	s_lshl_b32 s30, s30, 10
	v_lshl_add_u64 v[4:5], s[56:57], 0, v[144:145]
	s_add_i32 s30, s30, 0
	s_add_i32 m0, s30, 0x8000
	v_lshl_add_u64 v[6:7], s[44:45], 1, v[4:5]
	v_xor_b32_e32 v6, v197, v6
	global_load_lds_dwordx4 v[6:7], off
	v_lshl_add_u64 v[4:5], s[46:47], 1, v[4:5]
	s_add_i32 m0, s30, 0xa000
	s_mov_b32 s56, 1
	s_mov_b32 s30, s8
	v_xor_b32_e32 v4, v197, v4
	global_load_lds_dwordx4 v[4:5], off
	s_ashr_i32 s57, s56, 31
	s_lshl_b64 s[56:57], s[56:57], 7
	s_add_u32 s56, s96, s56
	s_addc_u32 s57, s97, s57
	s_lshl_b32 s30, s30, 10
	v_lshl_add_u64 v[4:5], s[56:57], 0, v[144:145]
	s_add_i32 s30, s24, s30
	v_lshl_add_u64 v[6:7], s[48:49], 1, v[4:5]
	s_mov_b32 m0, s30
	v_lshl_add_u64 v[4:5], s[54:55], 1, v[4:5]
	v_xor_b32_e32 v6, v197, v6
	global_load_lds_dwordx4 v[6:7], off
	s_add_i32 m0, s30, 0x2000
	v_and_b32_e32 v8, 15, v1
	v_xor_b32_e32 v4, v197, v4
	global_load_lds_dwordx4 v[4:5], off
	v_lshlrev_b32_e32 v2, 12, v2
	v_lshlrev_b32_e32 v5, 2, v1
	v_and_b32_e32 v9, 48, v1
	v_and_b32_e32 v4, 0x3000, v2
	v_lshlrev_b32_e32 v2, 6, v8
	v_and_b32_e32 v5, 32, v5
	v_bitop3_b32 v2, v2, v5, v9 bitop3:0x36
	s_add_i32 s30, 0, 0x10000
	v_add_u32_e32 v6, s30, v2
	s_add_i32 s30, 0, 0x14000
	v_add_u32_e32 v7, s30, v2
	v_add_u32_e32 v8, s31, v2
	v_add_u32_e32 v10, s24, v2
	v_add_u32_e32 v11, 0, v2
	v_lshlrev_b32_e32 v2, 6, v1
	s_waitcnt vmcnt(6)
	v_lshlrev_b32_e32 v3, 13, v3
	v_and_or_b32 v2, v2, s25, v9
	v_xad_u32 v5, v2, v5, 0
	v_or_b32_e32 v9, 0x800, v3
	v_or_b32_e32 v12, 0x1000, v3
	v_or_b32_e32 v13, 0x1800, v3
	v_mov_b32_e32 v2, 0
	v_lshl_add_u64 v[130:131], s[94:95], 0, v[144:145]
	v_lshl_add_u64 v[132:133], s[96:97], 0, v[144:145]
	s_mov_b32 s92, 3
	v_add_u32_e32 v141, v6, v4
	v_add_u32_e32 v137, v11, v3
	v_add_u32_e32 v136, v5, v9
	v_add_u32_e32 v135, v5, v12
	v_add_u32_e32 v134, v5, v13
	v_add_u32_e32 v140, v7, v4
	v_add_u32_e32 v139, v8, v4
	v_add_u32_e32 v138, v10, v4
	v_mov_b32_e32 v3, v2
	v_mov_b32_e32 v4, v2
	v_mov_b32_e32 v5, v2
	v_mov_b32_e32 v6, v2
	v_mov_b32_e32 v7, v2
	v_mov_b32_e32 v8, v2
	v_mov_b32_e32 v9, v2
	v_mov_b32_e32 v10, v2
	v_mov_b32_e32 v11, v2
	v_mov_b32_e32 v12, v2
	v_mov_b32_e32 v13, v2
	v_mov_b32_e32 v14, v2
	v_mov_b32_e32 v15, v2
	v_mov_b32_e32 v16, v2
	v_mov_b32_e32 v17, v2
	v_mov_b32_e32 v18, v2
	v_mov_b32_e32 v19, v2
	v_mov_b32_e32 v20, v2
	v_mov_b32_e32 v21, v2
	v_mov_b32_e32 v22, v2
	v_mov_b32_e32 v23, v2
	v_mov_b32_e32 v24, v2
	v_mov_b32_e32 v25, v2
	v_mov_b32_e32 v26, v2
	v_mov_b32_e32 v27, v2
	v_mov_b32_e32 v28, v2
	v_mov_b32_e32 v29, v2
	v_mov_b32_e32 v30, v2
	v_mov_b32_e32 v31, v2
	v_mov_b32_e32 v32, v2
	v_mov_b32_e32 v33, v2
	v_mov_b32_e32 v34, v2
	v_mov_b32_e32 v35, v2
	v_mov_b32_e32 v36, v2
	v_mov_b32_e32 v37, v2
	v_mov_b32_e32 v38, v2
	v_mov_b32_e32 v39, v2
	v_mov_b32_e32 v40, v2
	v_mov_b32_e32 v41, v2
	v_mov_b32_e32 v42, v2
	v_mov_b32_e32 v43, v2
	v_mov_b32_e32 v44, v2
	v_mov_b32_e32 v45, v2
	v_mov_b32_e32 v46, v2
	v_mov_b32_e32 v47, v2
	v_mov_b32_e32 v48, v2
	v_mov_b32_e32 v49, v2
	v_mov_b32_e32 v50, v2
	v_mov_b32_e32 v51, v2
	v_mov_b32_e32 v52, v2
	v_mov_b32_e32 v53, v2
	v_mov_b32_e32 v54, v2
	v_mov_b32_e32 v55, v2
	v_mov_b32_e32 v56, v2
	v_mov_b32_e32 v57, v2
	v_mov_b32_e32 v58, v2
	v_mov_b32_e32 v59, v2
	v_mov_b32_e32 v60, v2
	v_mov_b32_e32 v61, v2
	v_mov_b32_e32 v62, v2
	v_mov_b32_e32 v63, v2
	v_mov_b32_e32 v64, v2
	v_mov_b32_e32 v65, v2
	v_mov_b32_e32 v66, v2
	v_mov_b32_e32 v67, v2
	v_mov_b32_e32 v68, v2
	v_mov_b32_e32 v69, v2
	v_mov_b32_e32 v70, v2
	v_mov_b32_e32 v71, v2
	v_mov_b32_e32 v72, v2
	v_mov_b32_e32 v73, v2
	v_mov_b32_e32 v74, v2
	v_mov_b32_e32 v75, v2
	v_mov_b32_e32 v76, v2
	v_mov_b32_e32 v77, v2
	v_mov_b32_e32 v78, v2
	v_mov_b32_e32 v79, v2
	v_mov_b32_e32 v80, v2
	v_mov_b32_e32 v81, v2
	v_mov_b32_e32 v82, v2
	v_mov_b32_e32 v83, v2
	v_mov_b32_e32 v84, v2
	v_mov_b32_e32 v85, v2
	v_mov_b32_e32 v86, v2
	v_mov_b32_e32 v87, v2
	v_mov_b32_e32 v88, v2
	v_mov_b32_e32 v89, v2
	v_mov_b32_e32 v90, v2
	v_mov_b32_e32 v91, v2
	v_mov_b32_e32 v92, v2
	v_mov_b32_e32 v93, v2
	v_mov_b32_e32 v94, v2
	v_mov_b32_e32 v95, v2
	v_mov_b32_e32 v96, v2
	v_mov_b32_e32 v97, v2
	v_mov_b32_e32 v98, v2
	v_mov_b32_e32 v99, v2
	v_mov_b32_e32 v100, v2
	v_mov_b32_e32 v101, v2
	v_mov_b32_e32 v102, v2
	v_mov_b32_e32 v103, v2
	v_mov_b32_e32 v104, v2
	v_mov_b32_e32 v105, v2
	v_mov_b32_e32 v106, v2
	v_mov_b32_e32 v107, v2
	v_mov_b32_e32 v108, v2
	v_mov_b32_e32 v109, v2
	v_mov_b32_e32 v110, v2
	v_mov_b32_e32 v111, v2
	v_mov_b32_e32 v112, v2
	v_mov_b32_e32 v113, v2
	v_mov_b32_e32 v114, v2
	v_mov_b32_e32 v115, v2
	v_mov_b32_e32 v116, v2
	v_mov_b32_e32 v117, v2
	v_mov_b32_e32 v118, v2
	v_mov_b32_e32 v119, v2
	v_mov_b32_e32 v120, v2
	v_mov_b32_e32 v121, v2
	v_mov_b32_e32 v122, v2
	v_mov_b32_e32 v123, v2
	v_mov_b32_e32 v124, v2
	v_mov_b32_e32 v125, v2
	v_mov_b32_e32 v126, v2
	v_mov_b32_e32 v127, v2
	v_mov_b32_e32 v128, v2
	v_mov_b32_e32 v129, v2
	s_barrier
.LBB0_97:
	ds_read_b128 v[146:149], v141
	ds_read_b128 v[150:153], v141 offset:1024
	ds_read_b128 v[154:157], v141 offset:2048
	ds_read_b128 v[158:161], v141 offset:3072
	s_add_i32 s56, s92, -2
	s_mov_b32 s30, s8
	ds_read_b128 v[162:165], v137
	ds_read_b128 v[166:169], v137 offset:1024
	ds_read_b128 v[170:173], v136
	ds_read_b128 v[174:177], v136 offset:1024
	ds_read_b128 v[184:187], v135
	ds_read_b128 v[188:191], v135 offset:1024
	ds_read_b128 v[204:207], v134
	ds_read_b128 v[208:211], v134 offset:1024
	s_ashr_i32 s57, s56, 31
	s_lshl_b64 s[56:57], s[56:57], 7
	s_lshl_b32 s30, s30, 10
	v_lshl_add_u64 v[192:193], v[130:131], 0, s[56:57]
	s_add_i32 s30, s30, 0
	s_lshl_b64 s[56:57], s[50:51], 1
	s_add_i32 m0, s30, 0xc000
	v_lshl_add_u64 v[200:201], v[192:193], 0, s[56:57]
	s_lshl_b64 s[58:59], s[52:53], 1
	v_xor_b32_e32 v200, v197, v200
	global_load_lds_dwordx4 v[200:201], off
	v_lshl_add_u64 v[192:193], v[192:193], 0, s[58:59]
	s_add_i32 m0, s30, 0xe000
	s_nop 0
	v_xor_b32_e32 v192, v197, v192
	global_load_lds_dwordx4 v[192:193], off
	s_waitcnt lgkmcnt(8)
	s_barrier
	s_waitcnt lgkmcnt(0)
	s_setprio 1
	s_waitcnt lgkmcnt(0)
	v_mfma_f32_16x16x32_bf16 v[126:129], v[146:149], v[162:165], v[126:129]
	v_mfma_f32_16x16x32_bf16 v[122:125], v[154:157], v[162:165], v[122:125]
	v_mfma_f32_16x16x32_bf16 v[118:121], v[146:149], v[170:173], v[118:121]
	v_mfma_f32_16x16x32_bf16 v[114:117], v[154:157], v[170:173], v[114:117]
	v_mfma_f32_16x16x32_bf16 v[110:113], v[146:149], v[184:187], v[110:113]
	v_mfma_f32_16x16x32_bf16 v[106:109], v[154:157], v[184:187], v[106:109]
	v_mfma_f32_16x16x32_bf16 v[102:105], v[146:149], v[204:207], v[102:105]
	v_mfma_f32_16x16x32_bf16 v[98:101], v[154:157], v[204:207], v[98:101]
	v_mfma_f32_16x16x32_bf16 v[126:129], v[150:153], v[166:169], v[126:129]
	v_mfma_f32_16x16x32_bf16 v[122:125], v[158:161], v[166:169], v[122:125]
	v_mfma_f32_16x16x32_bf16 v[118:121], v[150:153], v[174:177], v[118:121]
	v_mfma_f32_16x16x32_bf16 v[114:117], v[158:161], v[174:177], v[114:117]
	v_mfma_f32_16x16x32_bf16 v[110:113], v[150:153], v[188:191], v[110:113]
	v_mfma_f32_16x16x32_bf16 v[106:109], v[158:161], v[188:191], v[106:109]
	v_mfma_f32_16x16x32_bf16 v[102:105], v[150:153], v[208:211], v[102:105]
	v_mfma_f32_16x16x32_bf16 v[98:101], v[158:161], v[208:211], v[98:101]
	s_setprio 0
	s_barrier
	s_add_i32 s30, s92, -1
	s_mov_b32 s60, s30
	s_mov_b32 s62, s8
	ds_read_b128 v[212:215], v140
	ds_read_b128 v[216:219], v140 offset:1024
	ds_read_b128 v[220:223], v140 offset:2048
	ds_read_b128 v[224:227], v140 offset:3072
	s_ashr_i32 s61, s60, 31
	s_lshl_b64 s[60:61], s[60:61], 7
	v_lshl_add_u64 v[192:193], v[132:133], 0, s[60:61]
	s_lshl_b32 s60, s62, 10
	s_add_i32 s64, s60, 0
	s_lshl_b64 s[60:61], s[40:41], 1
	s_add_i32 m0, s64, 0x10000
	v_lshl_add_u64 v[200:201], v[192:193], 0, s[60:61]
	s_lshl_b64 s[62:63], s[42:43], 1
	v_xor_b32_e32 v200, v197, v200
	global_load_lds_dwordx4 v[200:201], off
	v_lshl_add_u64 v[192:193], v[192:193], 0, s[62:63]
	s_add_i32 m0, s64, 0x12000
	s_nop 0
	v_xor_b32_e32 v192, v197, v192
	global_load_lds_dwordx4 v[192:193], off
	s_barrier
	s_waitcnt lgkmcnt(0)
	s_setprio 1
	s_waitcnt lgkmcnt(0)
	v_mfma_f32_16x16x32_bf16 v[94:97], v[212:215], v[162:165], v[94:97]
	v_mfma_f32_16x16x32_bf16 v[90:93], v[220:223], v[162:165], v[90:93]
	v_mfma_f32_16x16x32_bf16 v[86:89], v[212:215], v[170:173], v[86:89]
	v_mfma_f32_16x16x32_bf16 v[82:85], v[220:223], v[170:173], v[82:85]
	v_mfma_f32_16x16x32_bf16 v[78:81], v[212:215], v[184:187], v[78:81]
	v_mfma_f32_16x16x32_bf16 v[74:77], v[220:223], v[184:187], v[74:77]
	v_mfma_f32_16x16x32_bf16 v[70:73], v[212:215], v[204:207], v[70:73]
	v_mfma_f32_16x16x32_bf16 v[66:69], v[220:223], v[204:207], v[66:69]
	v_mfma_f32_16x16x32_bf16 v[94:97], v[216:219], v[166:169], v[94:97]
	v_mfma_f32_16x16x32_bf16 v[90:93], v[224:227], v[166:169], v[90:93]
	v_mfma_f32_16x16x32_bf16 v[86:89], v[216:219], v[174:177], v[86:89]
	v_mfma_f32_16x16x32_bf16 v[82:85], v[224:227], v[174:177], v[82:85]
	v_mfma_f32_16x16x32_bf16 v[78:81], v[216:219], v[188:191], v[78:81]
	v_mfma_f32_16x16x32_bf16 v[74:77], v[224:227], v[188:191], v[74:77]
	v_mfma_f32_16x16x32_bf16 v[70:73], v[216:219], v[208:211], v[70:73]
	v_mfma_f32_16x16x32_bf16 v[66:69], v[224:227], v[208:211], v[66:69]
	s_setprio 0
	s_mov_b32 s64, s30
	s_mov_b32 s66, s8
	s_barrier
	ds_read_b128 v[162:165], v137 offset:16384
	ds_read_b128 v[166:169], v137 offset:17408
	ds_read_b128 v[170:173], v136 offset:16384
	ds_read_b128 v[174:177], v136 offset:17408
	ds_read_b128 v[184:187], v135 offset:16384
	ds_read_b128 v[188:191], v135 offset:17408
	ds_read_b128 v[204:207], v134 offset:16384
	ds_read_b128 v[208:211], v134 offset:17408
	s_ashr_i32 s65, s64, 31
	s_lshl_b64 s[64:65], s[64:65], 7
	v_lshl_add_u64 v[192:193], v[130:131], 0, s[64:65]
	s_lshl_b32 s64, s66, 10
	s_add_i32 s68, s64, 0
	s_lshl_b64 s[64:65], s[44:45], 1
	v_lshl_add_u64 v[200:201], v[192:193], 0, s[64:65]
	s_mov_b32 m0, s68
	s_lshl_b64 s[66:67], s[46:47], 1
	v_xor_b32_e32 v200, v197, v200
	global_load_lds_dwordx4 v[200:201], off
	v_lshl_add_u64 v[192:193], v[192:193], 0, s[66:67]
	s_add_i32 m0, s68, 0x2000
	s_nop 0
	v_xor_b32_e32 v192, v197, v192
	global_load_lds_dwordx4 v[192:193], off
	s_barrier
	s_waitcnt lgkmcnt(0)
	s_setprio 1
	s_waitcnt lgkmcnt(0)
	v_mfma_f32_16x16x32_bf16 v[62:65], v[146:149], v[162:165], v[62:65]
	v_mfma_f32_16x16x32_bf16 v[58:61], v[154:157], v[162:165], v[58:61]
	v_mfma_f32_16x16x32_bf16 v[54:57], v[146:149], v[170:173], v[54:57]
	v_mfma_f32_16x16x32_bf16 v[50:53], v[154:157], v[170:173], v[50:53]
	v_mfma_f32_16x16x32_bf16 v[46:49], v[146:149], v[184:187], v[46:49]
	v_mfma_f32_16x16x32_bf16 v[42:45], v[154:157], v[184:187], v[42:45]
	v_mfma_f32_16x16x32_bf16 v[38:41], v[146:149], v[204:207], v[38:41]
	v_mfma_f32_16x16x32_bf16 v[34:37], v[154:157], v[204:207], v[34:37]
	v_mfma_f32_16x16x32_bf16 v[62:65], v[150:153], v[166:169], v[62:65]
	v_mfma_f32_16x16x32_bf16 v[58:61], v[158:161], v[166:169], v[58:61]
	v_mfma_f32_16x16x32_bf16 v[54:57], v[150:153], v[174:177], v[54:57]
	v_mfma_f32_16x16x32_bf16 v[50:53], v[158:161], v[174:177], v[50:53]
	v_mfma_f32_16x16x32_bf16 v[46:49], v[150:153], v[188:191], v[46:49]
	v_mfma_f32_16x16x32_bf16 v[42:45], v[158:161], v[188:191], v[42:45]
	v_mfma_f32_16x16x32_bf16 v[38:41], v[150:153], v[208:211], v[38:41]
	v_mfma_f32_16x16x32_bf16 v[34:37], v[158:161], v[208:211], v[34:37]
	s_setprio 0
	s_barrier
	s_mov_b32 s68, s30
	s_mov_b32 s80, s8
	s_ashr_i32 s69, s68, 31
	s_lshl_b64 s[68:69], s[68:69], 7
	v_lshl_add_u64 v[146:147], v[132:133], 0, s[68:69]
	s_lshl_b32 s68, s80, 10
	s_add_i32 s80, s68, 0
	s_lshl_b64 s[68:69], s[48:49], 1
	s_add_i32 m0, s80, 0x14000
	v_lshl_add_u64 v[148:149], v[146:147], 0, s[68:69]
	s_lshl_b64 vcc, s[54:55], 1
	v_xor_b32_e32 v148, v197, v148
	global_load_lds_dwordx4 v[148:149], off
	v_lshl_add_u64 v[146:147], v[146:147], 0, vcc
	s_add_i32 m0, s80, 0x16000
	s_nop 0
	v_xor_b32_e32 v146, v197, v146
	global_load_lds_dwordx4 v[146:147], off
	s_waitcnt vmcnt(6)
	s_barrier
	s_setprio 1
	v_mfma_f32_16x16x32_bf16 v[30:33], v[212:215], v[162:165], v[30:33]
	v_mfma_f32_16x16x32_bf16 v[26:29], v[220:223], v[162:165], v[26:29]
	v_mfma_f32_16x16x32_bf16 v[22:25], v[212:215], v[170:173], v[22:25]
	v_mfma_f32_16x16x32_bf16 v[18:21], v[220:223], v[170:173], v[18:21]
	v_mfma_f32_16x16x32_bf16 v[14:17], v[212:215], v[184:187], v[14:17]
	v_mfma_f32_16x16x32_bf16 v[10:13], v[220:223], v[184:187], v[10:13]
	v_mfma_f32_16x16x32_bf16 v[6:9], v[212:215], v[204:207], v[6:9]
	v_mfma_f32_16x16x32_bf16 v[2:5], v[220:223], v[204:207], v[2:5]
	v_mfma_f32_16x16x32_bf16 v[30:33], v[216:219], v[166:169], v[30:33]
	v_mfma_f32_16x16x32_bf16 v[26:29], v[224:227], v[166:169], v[26:29]
	v_mfma_f32_16x16x32_bf16 v[22:25], v[216:219], v[174:177], v[22:25]
	v_mfma_f32_16x16x32_bf16 v[18:21], v[224:227], v[174:177], v[18:21]
	v_mfma_f32_16x16x32_bf16 v[14:17], v[216:219], v[188:191], v[14:17]
	v_mfma_f32_16x16x32_bf16 v[10:13], v[224:227], v[188:191], v[10:13]
	v_mfma_f32_16x16x32_bf16 v[6:9], v[216:219], v[208:211], v[6:9]
	v_mfma_f32_16x16x32_bf16 v[2:5], v[224:227], v[208:211], v[2:5]
	s_setprio 0
	s_barrier
	ds_read_b128 v[146:149], v139
	ds_read_b128 v[150:153], v139 offset:1024
	ds_read_b128 v[154:157], v139 offset:2048
	ds_read_b128 v[158:161], v139 offset:3072
	s_mov_b32 s80, s30
	s_mov_b32 s93, s8
	ds_read_b128 v[162:165], v137 offset:32768
	ds_read_b128 v[166:169], v137 offset:33792
	ds_read_b128 v[170:173], v136 offset:32768
	ds_read_b128 v[174:177], v136 offset:33792
	ds_read_b128 v[184:187], v135 offset:32768
	ds_read_b128 v[188:191], v135 offset:33792
	ds_read_b128 v[204:207], v134 offset:32768
	ds_read_b128 v[208:211], v134 offset:33792
	s_ashr_i32 s81, s80, 31
	s_lshl_b64 s[80:81], s[80:81], 7
	v_lshl_add_u64 v[192:193], v[130:131], 0, s[80:81]
	s_lshl_b32 s80, s93, 10
	s_add_i32 s80, s80, 0
	s_add_i32 m0, s80, 0x4000
	v_lshl_add_u64 v[200:201], v[192:193], 0, s[56:57]
	v_xor_b32_e32 v200, v197, v200
	global_load_lds_dwordx4 v[200:201], off
	v_lshl_add_u64 v[192:193], v[192:193], 0, s[58:59]
	s_add_i32 m0, s80, 0x6000
	s_nop 0
	v_xor_b32_e32 v192, v197, v192
	global_load_lds_dwordx4 v[192:193], off
	s_waitcnt lgkmcnt(8)
	s_barrier
	s_waitcnt lgkmcnt(0)
	s_setprio 1
	s_waitcnt lgkmcnt(0)
	v_mfma_f32_16x16x32_bf16 v[126:129], v[146:149], v[162:165], v[126:129]
	v_mfma_f32_16x16x32_bf16 v[122:125], v[154:157], v[162:165], v[122:125]
	v_mfma_f32_16x16x32_bf16 v[118:121], v[146:149], v[170:173], v[118:121]
	v_mfma_f32_16x16x32_bf16 v[114:117], v[154:157], v[170:173], v[114:117]
	v_mfma_f32_16x16x32_bf16 v[110:113], v[146:149], v[184:187], v[110:113]
	v_mfma_f32_16x16x32_bf16 v[106:109], v[154:157], v[184:187], v[106:109]
	v_mfma_f32_16x16x32_bf16 v[102:105], v[146:149], v[204:207], v[102:105]
	v_mfma_f32_16x16x32_bf16 v[98:101], v[154:157], v[204:207], v[98:101]
	v_mfma_f32_16x16x32_bf16 v[126:129], v[150:153], v[166:169], v[126:129]
	v_mfma_f32_16x16x32_bf16 v[122:125], v[158:161], v[166:169], v[122:125]
	v_mfma_f32_16x16x32_bf16 v[118:121], v[150:153], v[174:177], v[118:121]
	v_mfma_f32_16x16x32_bf16 v[114:117], v[158:161], v[174:177], v[114:117]
	v_mfma_f32_16x16x32_bf16 v[110:113], v[150:153], v[188:191], v[110:113]
	v_mfma_f32_16x16x32_bf16 v[106:109], v[158:161], v[188:191], v[106:109]
	v_mfma_f32_16x16x32_bf16 v[102:105], v[150:153], v[208:211], v[102:105]
	v_mfma_f32_16x16x32_bf16 v[98:101], v[158:161], v[208:211], v[98:101]
	s_setprio 0
	s_barrier
	s_mov_b32 s56, s92
	s_mov_b32 s58, s8
	ds_read_b128 v[212:215], v138
	ds_read_b128 v[216:219], v138 offset:1024
	ds_read_b128 v[220:223], v138 offset:2048
	ds_read_b128 v[224:227], v138 offset:3072
	s_ashr_i32 s57, s56, 31
	s_lshl_b64 s[56:57], s[56:57], 7
	v_lshl_add_u64 v[192:193], v[132:133], 0, s[56:57]
	s_lshl_b32 s56, s58, 10
	s_add_i32 s56, s56, 0
	s_add_i32 m0, s56, 0x18000
	v_lshl_add_u64 v[200:201], v[192:193], 0, s[60:61]
	v_xor_b32_e32 v200, v197, v200
	global_load_lds_dwordx4 v[200:201], off
	v_lshl_add_u64 v[192:193], v[192:193], 0, s[62:63]
	s_add_i32 m0, s56, 0x1a000
	s_nop 0
	v_xor_b32_e32 v192, v197, v192
	global_load_lds_dwordx4 v[192:193], off
	s_barrier
	s_waitcnt lgkmcnt(0)
	s_setprio 1
	s_waitcnt lgkmcnt(0)
	v_mfma_f32_16x16x32_bf16 v[94:97], v[212:215], v[162:165], v[94:97]
	v_mfma_f32_16x16x32_bf16 v[90:93], v[220:223], v[162:165], v[90:93]
	v_mfma_f32_16x16x32_bf16 v[86:89], v[212:215], v[170:173], v[86:89]
	v_mfma_f32_16x16x32_bf16 v[82:85], v[220:223], v[170:173], v[82:85]
	v_mfma_f32_16x16x32_bf16 v[78:81], v[212:215], v[184:187], v[78:81]
	v_mfma_f32_16x16x32_bf16 v[74:77], v[220:223], v[184:187], v[74:77]
	v_mfma_f32_16x16x32_bf16 v[70:73], v[212:215], v[204:207], v[70:73]
	v_mfma_f32_16x16x32_bf16 v[66:69], v[220:223], v[204:207], v[66:69]
	v_mfma_f32_16x16x32_bf16 v[94:97], v[216:219], v[166:169], v[94:97]
	v_mfma_f32_16x16x32_bf16 v[90:93], v[224:227], v[166:169], v[90:93]
	v_mfma_f32_16x16x32_bf16 v[86:89], v[216:219], v[174:177], v[86:89]
	v_mfma_f32_16x16x32_bf16 v[82:85], v[224:227], v[174:177], v[82:85]
	v_mfma_f32_16x16x32_bf16 v[78:81], v[216:219], v[188:191], v[78:81]
	v_mfma_f32_16x16x32_bf16 v[74:77], v[224:227], v[188:191], v[74:77]
	v_mfma_f32_16x16x32_bf16 v[70:73], v[216:219], v[208:211], v[70:73]
	v_mfma_f32_16x16x32_bf16 v[66:69], v[224:227], v[208:211], v[66:69]
	s_setprio 0
	s_mov_b32 s56, s92
	s_mov_b32 s58, s8
	s_barrier
	ds_read_b128 v[162:165], v137 offset:49152
	ds_read_b128 v[166:169], v137 offset:50176
	ds_read_b128 v[170:173], v136 offset:49152
	ds_read_b128 v[174:177], v136 offset:50176
	ds_read_b128 v[184:187], v135 offset:49152
	ds_read_b128 v[188:191], v135 offset:50176
	ds_read_b128 v[204:207], v134 offset:49152
	ds_read_b128 v[208:211], v134 offset:50176
	s_ashr_i32 s57, s56, 31
	s_lshl_b64 s[56:57], s[56:57], 7
	v_lshl_add_u64 v[192:193], v[130:131], 0, s[56:57]
	s_lshl_b32 s56, s58, 10
	s_add_i32 s56, s56, 0
	s_add_i32 m0, s56, 0x8000
	v_lshl_add_u64 v[200:201], v[192:193], 0, s[64:65]
	v_xor_b32_e32 v200, v197, v200
	global_load_lds_dwordx4 v[200:201], off
	v_lshl_add_u64 v[192:193], v[192:193], 0, s[66:67]
	s_add_i32 m0, s56, 0xa000
	s_nop 0
	v_xor_b32_e32 v192, v197, v192
	global_load_lds_dwordx4 v[192:193], off
	s_barrier
	s_waitcnt lgkmcnt(0)
	s_setprio 1
	s_waitcnt lgkmcnt(0)
	v_mfma_f32_16x16x32_bf16 v[62:65], v[146:149], v[162:165], v[62:65]
	v_mfma_f32_16x16x32_bf16 v[58:61], v[154:157], v[162:165], v[58:61]
	v_mfma_f32_16x16x32_bf16 v[54:57], v[146:149], v[170:173], v[54:57]
	v_mfma_f32_16x16x32_bf16 v[50:53], v[154:157], v[170:173], v[50:53]
	v_mfma_f32_16x16x32_bf16 v[46:49], v[146:149], v[184:187], v[46:49]
	v_mfma_f32_16x16x32_bf16 v[42:45], v[154:157], v[184:187], v[42:45]
	v_mfma_f32_16x16x32_bf16 v[38:41], v[146:149], v[204:207], v[38:41]
	v_mfma_f32_16x16x32_bf16 v[34:37], v[154:157], v[204:207], v[34:37]
	v_mfma_f32_16x16x32_bf16 v[62:65], v[150:153], v[166:169], v[62:65]
	v_mfma_f32_16x16x32_bf16 v[58:61], v[158:161], v[166:169], v[58:61]
	v_mfma_f32_16x16x32_bf16 v[54:57], v[150:153], v[174:177], v[54:57]
	v_mfma_f32_16x16x32_bf16 v[50:53], v[158:161], v[174:177], v[50:53]
	v_mfma_f32_16x16x32_bf16 v[46:49], v[150:153], v[188:191], v[46:49]
	v_mfma_f32_16x16x32_bf16 v[42:45], v[158:161], v[188:191], v[42:45]
	v_mfma_f32_16x16x32_bf16 v[38:41], v[150:153], v[208:211], v[38:41]
	v_mfma_f32_16x16x32_bf16 v[34:37], v[158:161], v[208:211], v[34:37]
	s_setprio 0
	s_barrier
	s_mov_b32 s56, s92
	s_mov_b32 s58, s8
	s_ashr_i32 s57, s56, 31
	s_lshl_b64 s[56:57], s[56:57], 7
	v_lshl_add_u64 v[146:147], v[132:133], 0, s[56:57]
	s_lshl_b32 s56, s58, 10
	s_add_i32 s56, s56, 0
	s_add_i32 m0, s56, 0x1c000
	v_lshl_add_u64 v[148:149], v[146:147], 0, s[68:69]
	v_xor_b32_e32 v148, v197, v148
	global_load_lds_dwordx4 v[148:149], off
	v_lshl_add_u64 v[146:147], v[146:147], 0, vcc
	s_add_i32 m0, s56, 0x1e000
	s_nop 0
	v_xor_b32_e32 v146, v197, v146
	global_load_lds_dwordx4 v[146:147], off
	s_waitcnt vmcnt(6)
	s_barrier
	s_setprio 1
	v_mfma_f32_16x16x32_bf16 v[30:33], v[212:215], v[162:165], v[30:33]
	v_mfma_f32_16x16x32_bf16 v[26:29], v[220:223], v[162:165], v[26:29]
	v_mfma_f32_16x16x32_bf16 v[22:25], v[212:215], v[170:173], v[22:25]
	v_mfma_f32_16x16x32_bf16 v[18:21], v[220:223], v[170:173], v[18:21]
	v_mfma_f32_16x16x32_bf16 v[14:17], v[212:215], v[184:187], v[14:17]
	v_mfma_f32_16x16x32_bf16 v[10:13], v[220:223], v[184:187], v[10:13]
	v_mfma_f32_16x16x32_bf16 v[6:9], v[212:215], v[204:207], v[6:9]
	v_mfma_f32_16x16x32_bf16 v[2:5], v[220:223], v[204:207], v[2:5]
	v_mfma_f32_16x16x32_bf16 v[30:33], v[216:219], v[166:169], v[30:33]
	v_mfma_f32_16x16x32_bf16 v[26:29], v[224:227], v[166:169], v[26:29]
	v_mfma_f32_16x16x32_bf16 v[22:25], v[216:219], v[174:177], v[22:25]
	v_mfma_f32_16x16x32_bf16 v[18:21], v[224:227], v[174:177], v[18:21]
	v_mfma_f32_16x16x32_bf16 v[14:17], v[216:219], v[188:191], v[14:17]
	v_mfma_f32_16x16x32_bf16 v[10:13], v[224:227], v[188:191], v[10:13]
	v_mfma_f32_16x16x32_bf16 v[6:9], v[216:219], v[208:211], v[6:9]
	v_mfma_f32_16x16x32_bf16 v[2:5], v[224:227], v[208:211], v[2:5]
	s_setprio 0
	s_add_i32 s92, s92, 2
	s_cmp_lt_u32 s30, s11
	s_barrier
	s_cbranch_scc1 .LBB0_97
	v_readlane_b32 s30, v254, 9
	s_mov_b32 s40, s30
	ds_read_b128 v[130:133], v141
	ds_read_b128 v[146:149], v141 offset:1024
	ds_read_b128 v[150:153], v141 offset:2048
	ds_read_b128 v[154:157], v141 offset:3072
	ds_read_b128 v[158:161], v137
	ds_read_b128 v[162:165], v137 offset:1024
	ds_read_b128 v[166:169], v136
	ds_read_b128 v[170:173], v136 offset:1024
	ds_read_b128 v[174:177], v135
	ds_read_b128 v[184:187], v135 offset:1024
	ds_read_b128 v[188:191], v134
	ds_read_b128 v[204:207], v134 offset:1024
	s_ashr_i32 s41, s40, 31
	s_lshl_b64 s[40:41], s[40:41], 7
	s_add_u32 s40, s94, s40
	s_addc_u32 s41, s95, s41
	s_lshl_b32 s8, s8, 10
	v_lshl_add_u64 v[192:193], s[40:41], 0, v[144:145]
	s_add_i32 s8, s8, 0
	s_add_i32 m0, s8, 0xc000
	v_lshl_add_u64 v[200:201], s[50:51], 1, v[192:193]
	v_xor_b32_e32 v200, v197, v200
	global_load_lds_dwordx4 v[200:201], off
	v_lshl_add_u64 v[192:193], s[52:53], 1, v[192:193]
	s_add_i32 m0, s8, 0xe000
	s_nop 0
	v_xor_b32_e32 v192, v197, v192
	global_load_lds_dwordx4 v[192:193], off
	s_barrier
	s_waitcnt lgkmcnt(0)
	s_setprio 1
	s_waitcnt lgkmcnt(0)
	v_mfma_f32_16x16x32_bf16 v[114:117], v[150:153], v[166:169], v[114:117]
	v_mfma_f32_16x16x32_bf16 v[102:105], v[130:133], v[188:191], v[102:105]
	v_mfma_f32_16x16x32_bf16 v[98:101], v[150:153], v[188:191], v[98:101]
	v_mfma_f32_16x16x32_bf16 v[126:129], v[130:133], v[158:161], v[126:129]
	v_mfma_f32_16x16x32_bf16 v[122:125], v[150:153], v[158:161], v[122:125]
	v_mfma_f32_16x16x32_bf16 v[118:121], v[130:133], v[166:169], v[118:121]
	v_mfma_f32_16x16x32_bf16 v[114:117], v[154:157], v[170:173], v[114:117]
	v_mfma_f32_16x16x32_bf16 v[110:113], v[130:133], v[174:177], v[110:113]
	v_mfma_f32_16x16x32_bf16 v[106:109], v[150:153], v[174:177], v[106:109]
	v_mfma_f32_16x16x32_bf16 v[102:105], v[146:149], v[204:207], v[102:105]
	v_mfma_f32_16x16x32_bf16 v[98:101], v[154:157], v[204:207], v[98:101]
	v_mfma_f32_16x16x32_bf16 v[126:129], v[146:149], v[162:165], v[126:129]
	v_mfma_f32_16x16x32_bf16 v[122:125], v[154:157], v[162:165], v[122:125]
	v_mfma_f32_16x16x32_bf16 v[118:121], v[146:149], v[170:173], v[118:121]
	v_mfma_f32_16x16x32_bf16 v[208:211], v[146:149], v[184:187], v[110:113]
	v_mfma_f32_16x16x32_bf16 v[212:215], v[154:157], v[184:187], v[106:109]
	s_setprio 0
	s_barrier
	s_nop 0
	ds_read_b128 v[106:109], v140
	ds_read_b128 v[110:113], v140 offset:1024
	ds_read_b128 v[216:219], v140 offset:2048
	ds_read_b128 v[220:223], v140 offset:3072
	s_barrier
	s_waitcnt lgkmcnt(0)
	s_setprio 1
	s_waitcnt lgkmcnt(0)
	v_mfma_f32_16x16x32_bf16 v[86:89], v[106:109], v[166:169], v[86:89]
	v_mfma_f32_16x16x32_bf16 v[82:85], v[216:219], v[166:169], v[82:85]
	v_mfma_f32_16x16x32_bf16 v[70:73], v[106:109], v[188:191], v[70:73]
	v_mfma_f32_16x16x32_bf16 v[66:69], v[216:219], v[188:191], v[66:69]
	v_mfma_f32_16x16x32_bf16 v[94:97], v[106:109], v[158:161], v[94:97]
	v_mfma_f32_16x16x32_bf16 v[90:93], v[216:219], v[158:161], v[90:93]
	v_mfma_f32_16x16x32_bf16 v[86:89], v[110:113], v[170:173], v[86:89]
	v_mfma_f32_16x16x32_bf16 v[82:85], v[220:223], v[170:173], v[82:85]
	v_mfma_f32_16x16x32_bf16 v[78:81], v[106:109], v[174:177], v[78:81]
	v_mfma_f32_16x16x32_bf16 v[74:77], v[216:219], v[174:177], v[74:77]
	v_mfma_f32_16x16x32_bf16 v[70:73], v[110:113], v[204:207], v[70:73]
	v_mfma_f32_16x16x32_bf16 v[66:69], v[220:223], v[204:207], v[66:69]
	v_mfma_f32_16x16x32_bf16 v[224:227], v[110:113], v[162:165], v[94:97]
	v_mfma_f32_16x16x32_bf16 v[158:161], v[220:223], v[162:165], v[90:93]
	v_mfma_f32_16x16x32_bf16 v[162:165], v[110:113], v[184:187], v[78:81]
	v_mfma_f32_16x16x32_bf16 v[166:169], v[220:223], v[184:187], v[74:77]
	s_setprio 0
	s_barrier
	s_nop 0
	ds_read_b128 v[74:77], v137 offset:16384
	ds_read_b128 v[78:81], v137 offset:17408
	ds_read_b128 v[90:93], v136 offset:16384
	ds_read_b128 v[94:97], v136 offset:17408
	ds_read_b128 v[170:173], v135 offset:16384
	ds_read_b128 v[174:177], v135 offset:17408
	ds_read_b128 v[184:187], v134 offset:16384
	ds_read_b128 v[188:191], v134 offset:17408
	s_waitcnt vmcnt(4)
	s_barrier
	s_waitcnt lgkmcnt(0)
	s_setprio 1
	s_waitcnt lgkmcnt(0)
	v_mfma_f32_16x16x32_bf16 v[62:65], v[130:133], v[74:77], v[62:65]
	v_mfma_f32_16x16x32_bf16 v[58:61], v[150:153], v[74:77], v[58:61]
	v_mfma_f32_16x16x32_bf16 v[54:57], v[130:133], v[90:93], v[54:57]
	v_mfma_f32_16x16x32_bf16 v[50:53], v[150:153], v[90:93], v[50:53]
	v_mfma_f32_16x16x32_bf16 v[38:41], v[130:133], v[184:187], v[38:41]
	v_mfma_f32_16x16x32_bf16 v[34:37], v[150:153], v[184:187], v[34:37]
	v_mfma_f32_16x16x32_bf16 v[62:65], v[146:149], v[78:81], v[62:65]
	v_mfma_f32_16x16x32_bf16 v[58:61], v[154:157], v[78:81], v[58:61]
	v_mfma_f32_16x16x32_bf16 v[54:57], v[146:149], v[94:97], v[54:57]
	v_mfma_f32_16x16x32_bf16 v[50:53], v[154:157], v[94:97], v[50:53]
	v_mfma_f32_16x16x32_bf16 v[46:49], v[130:133], v[170:173], v[46:49]
	v_mfma_f32_16x16x32_bf16 v[42:45], v[150:153], v[170:173], v[42:45]
	v_mfma_f32_16x16x32_bf16 v[38:41], v[146:149], v[188:191], v[38:41]
	v_mfma_f32_16x16x32_bf16 v[34:37], v[154:157], v[188:191], v[34:37]
	v_mfma_f32_16x16x32_bf16 v[204:207], v[146:149], v[174:177], v[46:49]
	v_mfma_f32_16x16x32_bf16 v[228:231], v[154:157], v[174:177], v[42:45]
	s_setprio 0
	s_setprio 1
	v_mfma_f32_16x16x32_bf16 v[22:25], v[106:109], v[90:93], v[22:25]
	v_mfma_f32_16x16x32_bf16 v[18:21], v[216:219], v[90:93], v[18:21]
	v_mfma_f32_16x16x32_bf16 v[6:9], v[106:109], v[184:187], v[6:9]
	v_mfma_f32_16x16x32_bf16 v[2:5], v[216:219], v[184:187], v[2:5]
	v_mfma_f32_16x16x32_bf16 v[30:33], v[106:109], v[74:77], v[30:33]
	v_mfma_f32_16x16x32_bf16 v[26:29], v[216:219], v[74:77], v[26:29]
	v_mfma_f32_16x16x32_bf16 v[22:25], v[110:113], v[94:97], v[22:25]
	v_mfma_f32_16x16x32_bf16 v[18:21], v[220:223], v[94:97], v[18:21]
	v_mfma_f32_16x16x32_bf16 v[14:17], v[106:109], v[170:173], v[14:17]
	v_mfma_f32_16x16x32_bf16 v[10:13], v[216:219], v[170:173], v[10:13]
	v_mfma_f32_16x16x32_bf16 v[6:9], v[110:113], v[188:191], v[6:9]
	v_mfma_f32_16x16x32_bf16 v[2:5], v[220:223], v[188:191], v[2:5]
	v_mfma_f32_16x16x32_bf16 v[130:133], v[110:113], v[78:81], v[30:33]
	v_mfma_f32_16x16x32_bf16 v[154:157], v[220:223], v[78:81], v[26:29]
	v_mfma_f32_16x16x32_bf16 v[232:235], v[110:113], v[174:177], v[14:17]
	v_mfma_f32_16x16x32_bf16 v[170:173], v[220:223], v[174:177], v[10:13]
	s_setprio 0
	s_barrier
	s_nop 0
	ds_read_b128 v[10:13], v139
	ds_read_b128 v[14:17], v139 offset:1024
	ds_read_b128 v[174:177], v139 offset:2048
	ds_read_b128 v[184:187], v139 offset:3072
	ds_read_b128 v[26:29], v137 offset:32768
	ds_read_b128 v[30:33], v137 offset:33792
	ds_read_b128 v[42:45], v136 offset:32768
	ds_read_b128 v[46:49], v136 offset:33792
	ds_read_b128 v[188:191], v135 offset:32768
	ds_read_b128 v[216:219], v135 offset:33792
	ds_read_b128 v[220:223], v134 offset:32768
	ds_read_b128 v[236:239], v134 offset:33792
	s_waitcnt vmcnt(2)
	s_barrier
	s_waitcnt lgkmcnt(0)
	s_setprio 1
	s_waitcnt lgkmcnt(0)
	v_mfma_f32_16x16x32_bf16 v[74:77], v[10:13], v[26:29], v[126:129]
	v_mfma_f32_16x16x32_bf16 v[150:153], v[14:17], v[30:33], v[74:77]
	v_mfma_f32_16x16x32_bf16 v[74:77], v[174:177], v[26:29], v[122:125]
	v_mfma_f32_16x16x32_bf16 v[146:149], v[184:187], v[30:33], v[74:77]
	v_mfma_f32_16x16x32_bf16 v[74:77], v[10:13], v[42:45], v[118:121]
	v_mfma_f32_16x16x32_bf16 v[110:113], v[14:17], v[46:49], v[74:77]
	v_mfma_f32_16x16x32_bf16 v[74:77], v[174:177], v[42:45], v[114:117]
	v_mfma_f32_16x16x32_bf16 v[106:109], v[184:187], v[46:49], v[74:77]
	v_mfma_f32_16x16x32_bf16 v[74:77], v[10:13], v[188:191], v[208:211]
	v_mfma_f32_16x16x32_bf16 v[94:97], v[14:17], v[216:219], v[74:77]
	v_mfma_f32_16x16x32_bf16 v[74:77], v[174:177], v[188:191], v[212:215]
	v_mfma_f32_16x16x32_bf16 v[90:93], v[184:187], v[216:219], v[74:77]
	v_mfma_f32_16x16x32_bf16 v[74:77], v[10:13], v[220:223], v[102:105]
	v_mfma_f32_16x16x32_bf16 v[78:81], v[14:17], v[236:239], v[74:77]
	v_mfma_f32_16x16x32_bf16 v[74:77], v[174:177], v[220:223], v[98:101]
	v_mfma_f32_16x16x32_bf16 v[74:77], v[184:187], v[236:239], v[74:77]
	s_setprio 0
	s_barrier
	ds_read_b128 v[118:121], v138
	ds_read_b128 v[122:125], v138 offset:1024
	ds_read_b128 v[126:129], v138 offset:2048
	ds_read_b128 v[208:211], v138 offset:3072
	s_waitcnt vmcnt(0)
	s_barrier
	s_waitcnt lgkmcnt(0)
	s_setprio 1
	s_waitcnt lgkmcnt(0)
	v_mfma_f32_16x16x32_bf16 v[98:101], v[118:121], v[26:29], v[224:227]
	v_mfma_f32_16x16x32_bf16 v[26:29], v[126:129], v[26:29], v[158:161]
	v_mfma_f32_16x16x32_bf16 v[114:117], v[208:211], v[30:33], v[26:29]
	v_mfma_f32_16x16x32_bf16 v[26:29], v[118:121], v[42:45], v[86:89]
	v_mfma_f32_16x16x32_bf16 v[102:105], v[122:125], v[46:49], v[26:29]
	v_mfma_f32_16x16x32_bf16 v[26:29], v[126:129], v[42:45], v[82:85]
	v_mfma_f32_16x16x32_bf16 v[138:141], v[122:125], v[30:33], v[98:101]
	v_mfma_f32_16x16x32_bf16 v[98:101], v[208:211], v[46:49], v[26:29]
	v_mfma_f32_16x16x32_bf16 v[26:29], v[118:121], v[188:191], v[162:165]
	v_mfma_f32_16x16x32_bf16 v[86:89], v[122:125], v[216:219], v[26:29]
	v_mfma_f32_16x16x32_bf16 v[26:29], v[126:129], v[188:191], v[166:169]
	v_mfma_f32_16x16x32_bf16 v[82:85], v[208:211], v[216:219], v[26:29]
	v_mfma_f32_16x16x32_bf16 v[26:29], v[118:121], v[220:223], v[70:73]
	v_mfma_f32_16x16x32_bf16 v[70:73], v[122:125], v[236:239], v[26:29]
	v_mfma_f32_16x16x32_bf16 v[26:29], v[126:129], v[220:223], v[66:69]
	v_mfma_f32_16x16x32_bf16 v[66:69], v[208:211], v[236:239], v[26:29]
	s_setprio 0
	s_barrier
	ds_read_b128 v[158:161], v137 offset:49152
	ds_read_b128 v[162:165], v137 offset:50176
	ds_read_b128 v[166:169], v136 offset:49152
	ds_read_b128 v[188:191], v136 offset:50176
	ds_read_b128 v[212:215], v135 offset:49152
	ds_read_b128 v[216:219], v135 offset:50176
	ds_read_b128 v[220:223], v134 offset:49152
	ds_read_b128 v[134:137], v134 offset:50176
	s_barrier
	s_waitcnt lgkmcnt(0)
	s_setprio 1
	s_waitcnt lgkmcnt(0)
	v_mfma_f32_16x16x32_bf16 v[26:29], v[10:13], v[158:161], v[62:65]
	v_mfma_f32_16x16x32_bf16 v[62:65], v[14:17], v[162:165], v[26:29]
	v_mfma_f32_16x16x32_bf16 v[26:29], v[174:177], v[158:161], v[58:61]
	v_mfma_f32_16x16x32_bf16 v[58:61], v[184:187], v[162:165], v[26:29]
	v_mfma_f32_16x16x32_bf16 v[26:29], v[10:13], v[166:169], v[54:57]
	v_mfma_f32_16x16x32_bf16 v[46:49], v[14:17], v[188:191], v[26:29]
	v_mfma_f32_16x16x32_bf16 v[26:29], v[174:177], v[166:169], v[50:53]
	v_mfma_f32_16x16x32_bf16 v[42:45], v[184:187], v[188:191], v[26:29]
	v_mfma_f32_16x16x32_bf16 v[26:29], v[10:13], v[212:215], v[204:207]
	v_mfma_f32_16x16x32_bf16 v[10:13], v[10:13], v[220:223], v[38:41]
	v_mfma_f32_16x16x32_bf16 v[30:33], v[14:17], v[216:219], v[26:29]
	v_mfma_f32_16x16x32_bf16 v[26:29], v[174:177], v[212:215], v[228:231]
	v_mfma_f32_16x16x32_bf16 v[14:17], v[14:17], v[134:137], v[10:13]
	v_mfma_f32_16x16x32_bf16 v[10:13], v[174:177], v[220:223], v[34:37]
	v_mfma_f32_16x16x32_bf16 v[26:29], v[184:187], v[216:219], v[26:29]
	v_mfma_f32_16x16x32_bf16 v[10:13], v[184:187], v[134:137], v[10:13]
	s_setprio 0
	s_setprio 1
	v_mfma_f32_16x16x32_bf16 v[34:37], v[118:121], v[158:161], v[130:133]
	v_mfma_f32_16x16x32_bf16 v[54:57], v[122:125], v[162:165], v[34:37]
	v_mfma_f32_16x16x32_bf16 v[34:37], v[126:129], v[158:161], v[154:157]
	v_mfma_f32_16x16x32_bf16 v[18:21], v[126:129], v[166:169], v[18:21]
	v_mfma_f32_16x16x32_bf16 v[50:53], v[208:211], v[162:165], v[34:37]
	v_mfma_f32_16x16x32_bf16 v[22:25], v[118:121], v[166:169], v[22:25]
	v_mfma_f32_16x16x32_bf16 v[34:37], v[208:211], v[188:191], v[18:21]
	v_mfma_f32_16x16x32_bf16 v[18:21], v[118:121], v[212:215], v[232:235]
	v_mfma_f32_16x16x32_bf16 v[38:41], v[122:125], v[188:191], v[22:25]
	v_mfma_f32_16x16x32_bf16 v[22:25], v[122:125], v[216:219], v[18:21]
	v_mfma_f32_16x16x32_bf16 v[18:21], v[126:129], v[212:215], v[170:173]
	v_mfma_f32_16x16x32_bf16 v[6:9], v[118:121], v[220:223], v[6:9]
	v_mfma_f32_16x16x32_bf16 v[2:5], v[126:129], v[220:223], v[2:5]
	v_mfma_f32_16x16x32_bf16 v[18:21], v[208:211], v[216:219], v[18:21]
	v_mfma_f32_16x16x32_bf16 v[6:9], v[122:125], v[134:137], v[6:9]
	v_mfma_f32_16x16x32_bf16 v[2:5], v[208:211], v[134:137], v[2:5]
	s_setprio 0
	v_cmp_gt_u32_e32 vcc, s85, v1
	s_barrier
	s_and_saveexec_b64 s[40:41], vcc
	s_cbranch_execz .LBB0_100
	s_barrier
.LBB0_100:
	s_or_b64 exec, exec, s[40:41]
	s_waitcnt vmcnt(0)
	s_barrier
	v_mov_b32 v1, v179
	s_lshl_b64 s[40:41], s[36:37], 2
	v_and_b32_e32 v121, 15, v1
	v_ashrrev_i32_e32 v118, 2, v1
	v_bfe_u32 v120, v1, 6, 2
	v_and_b32_e32 v123, 0xffffffc0, v118
	v_or_b32_e32 v118, s13, v121
	v_bfe_u32 v122, v1, 4, 2
	v_add_u32_e32 v156, v118, v123
	v_lshl_add_u64 v[118:119], v[142:143], 0, s[40:41]
	v_lshlrev_b32_e32 v144, 7, v120
	v_lshl_add_u64 v[118:119], v[118:119], 0, v[144:145]
	v_lshlrev_b32_e32 v144, 4, v122
	v_lshl_add_u64 v[158:159], v[118:119], 0, v[144:145]
	v_and_b32_e32 v119, 64, v195
	v_xor_b32_e32 v118, 16, v195
	v_add_u32_e32 v119, 64, v119
	v_cmp_lt_i32_e32 vcc, v118, v119
	v_ashrrev_i32_e32 v157, 31, v156
	v_lshlrev_b32_e32 v124, 5, v120
	v_cndmask_b32_e32 v118, v195, v118, vcc
	v_lshlrev_b32_e32 v162, 2, v118
	v_xor_b32_e32 v118, 32, v195
	v_cmp_lt_i32_e32 vcc, v118, v119
	v_lshlrev_b32_e32 v125, 2, v122
	v_or_b32_e32 v163, v123, v121
	v_cndmask_b32_e32 v118, v195, v118, vcc
	v_lshlrev_b32_e32 v144, 2, v118
	v_lshlrev_b64 v[118:119], 12, v[156:157]
	v_lshl_add_u64 v[118:119], v[158:159], 0, v[118:119]
	flat_load_dwordx4 v[166:169], v[118:119]
	flat_load_dwordx4 v[170:173], v[118:119] offset:64
	flat_load_dwordx4 v[174:177], v[118:119] offset:512
	flat_load_dwordx4 v[134:137], v[118:119] offset:576
	v_or_b32_e32 v118, 16, v156
	v_ashrrev_i32_e32 v119, 31, v118
	v_lshlrev_b64 v[118:119], 12, v[118:119]
	v_lshl_add_u64 v[118:119], v[158:159], 0, v[118:119]
	v_or3_b32 v154, s36, v124, v125
	v_mov_b32_e32 v155, s37
	v_cmp_eq_u32_e64 s[36:37], 0, v122
	v_lshl_add_u32 v164, v120, 10, 0
	flat_load_dwordx4 v[130:133], v[118:119]
	flat_load_dwordx4 v[126:129], v[118:119] offset:64
	flat_load_dwordx4 v[122:125], v[118:119] offset:512
	s_nop 0
	flat_load_dwordx4 v[118:121], v[118:119] offset:576
	v_add_u32_e32 v160, s13, v163
	v_ashrrev_i32_e32 v161, 31, v160
	v_lshlrev_b64 v[184:185], 10, v[160:161]
	v_lshl_add_u64 v[184:185], v[184:185], 0, v[154:155]
	v_mov_b32_e32 v181, v180
	s_waitcnt vmcnt(0) lgkmcnt(0)
	v_pk_fma_f32 v[168:169], v[180:181], v[152:153], v[168:169]
	v_pk_fma_f32 v[166:167], v[182:183], v[150:151], v[166:167]
	v_lshlrev_b64 v[152:153], 1, v[184:185]
	v_lshl_add_u64 v[150:151], v[184:185], 2, s[20:21]
	v_cvt_pk_bf16_f32 v186, v166, v167
	v_cvt_pk_bf16_f32 v187, v168, v169
	v_lshl_add_u64 v[184:185], s[34:35], 0, v[152:153]
	v_mul_f32_e32 v161, v167, v167
	v_pk_fma_f32 v[148:149], v[180:181], v[148:149], v[172:173]
	v_pk_fma_f32 v[146:147], v[182:183], v[146:147], v[170:171]
	global_store_dwordx4 v[150:151], v[166:169], off
	v_xor_b32_e32 v184, v196, v184
	global_store_dwordx2 v[184:185], v[186:187], off
	v_xor_b32_e32 v184, v196, v184
	v_fmac_f32_e32 v161, v166, v166
	global_store_dwordx4 v[150:151], v[146:149], off offset:64
	v_cvt_pk_bf16_f32 v166, v146, v147
	v_fmac_f32_e32 v161, v168, v168
	v_mul_f32_e32 v147, v147, v147
	v_fmac_f32_e32 v147, v146, v146
	v_fmac_f32_e32 v161, v169, v169
	v_or_b32_e32 v168, 32, v152
	v_mov_b32_e32 v169, v153
	v_fmac_f32_e32 v147, v148, v148
	v_cvt_pk_bf16_f32 v167, v148, v149
	v_lshl_add_u64 v[168:169], s[34:35], 0, v[168:169]
	v_fmac_f32_e32 v147, v149, v149
	v_pk_fma_f32 v[140:141], v[180:181], v[140:141], v[176:177]
	v_pk_fma_f32 v[138:139], v[182:183], v[138:139], v[174:175]
	v_or_b32_e32 v148, 0x100, v152
	v_mov_b32_e32 v149, v153
	v_xor_b32_e32 v168, v196, v168
	global_store_dwordx2 v[168:169], v[166:167], off
	v_xor_b32_e32 v168, v196, v168
	v_add_f32_e32 v161, v161, v147
	global_store_dwordx4 v[150:151], v[138:141], off offset:512
	v_cvt_pk_bf16_f32 v146, v138, v139
	v_cvt_pk_bf16_f32 v147, v140, v141
	v_lshl_add_u64 v[148:149], s[34:35], 0, v[148:149]
	v_mul_f32_e32 v139, v139, v139
	v_pk_fma_f32 v[116:117], v[180:181], v[116:117], v[136:137]
	v_pk_fma_f32 v[114:115], v[182:183], v[114:115], v[134:135]
	v_xor_b32_e32 v148, v196, v148
	global_store_dwordx2 v[148:149], v[146:147], off
	v_xor_b32_e32 v148, v196, v148
	v_fmac_f32_e32 v139, v138, v138
	global_store_dwordx4 v[150:151], v[114:117], off offset:576
	v_cvt_pk_bf16_f32 v134, v114, v115
	v_fmac_f32_e32 v139, v140, v140
	v_mul_f32_e32 v115, v115, v115
	v_fmac_f32_e32 v115, v114, v114
	v_fmac_f32_e32 v139, v141, v141
	v_fmac_f32_e32 v115, v116, v116
	v_add_f32_e32 v138, v161, v139
	v_fmac_f32_e32 v115, v117, v117
	v_add_f32_e32 v114, v138, v115
	ds_bpermute_b32 v115, v162, v114
	v_or_b32_e32 v152, 0x120, v152
	v_cvt_pk_bf16_f32 v135, v116, v117
	v_lshl_add_u64 v[136:137], s[34:35], 0, v[152:153]
	v_xor_b32_e32 v136, v196, v136
	global_store_dwordx2 v[136:137], v[134:135], off
	v_xor_b32_e32 v136, v196, v136
	s_waitcnt lgkmcnt(0)
	v_add_f32_e32 v114, v114, v115
	ds_bpermute_b32 v115, v144, v114
	v_lshl_add_u32 v134, v163, 2, v164
	s_and_saveexec_b64 s[40:41], s[36:37]
	s_cbranch_execz .LBB0_102
	s_waitcnt lgkmcnt(0)
	v_add_f32_e32 v114, v114, v115
	ds_write_b32 v134, v114
.LBB0_102:
	s_or_b64 exec, exec, s[40:41]
	v_add3_u32 v114, s13, v163, 16
	s_waitcnt lgkmcnt(0)
	v_ashrrev_i32_e32 v115, 31, v114
	v_lshlrev_b64 v[114:115], 10, v[114:115]
	v_lshl_add_u64 v[114:115], v[114:115], 0, v[154:155]
	v_pk_fma_f32 v[112:113], v[180:181], v[112:113], v[132:133]
	v_pk_fma_f32 v[110:111], v[182:183], v[110:111], v[130:131]
	v_lshl_add_u64 v[116:117], v[114:115], 2, s[20:21]
	v_lshlrev_b64 v[114:115], 1, v[114:115]
	v_cvt_pk_bf16_f32 v130, v110, v111
	v_cvt_pk_bf16_f32 v131, v112, v113
	v_lshl_add_u64 v[132:133], s[34:35], 0, v[114:115]
	global_store_dwordx4 v[116:117], v[110:113], off
	v_xor_b32_e32 v132, v196, v132
	global_store_dwordx2 v[132:133], v[130:131], off
	v_xor_b32_e32 v132, v196, v132
	v_mul_f32_e32 v130, v111, v111
	v_fmac_f32_e32 v130, v110, v110
	v_fmac_f32_e32 v130, v112, v112
	v_fmac_f32_e32 v130, v113, v113
	v_pk_fma_f32 v[108:109], v[180:181], v[108:109], v[128:129]
	v_pk_fma_f32 v[106:107], v[182:183], v[106:107], v[126:127]
	v_or_b32_e32 v112, 32, v114
	v_mov_b32_e32 v113, v115
	global_store_dwordx4 v[116:117], v[106:109], off offset:64
	v_cvt_pk_bf16_f32 v110, v106, v107
	v_cvt_pk_bf16_f32 v111, v108, v109
	v_lshl_add_u64 v[112:113], s[34:35], 0, v[112:113]
	v_mul_f32_e32 v107, v107, v107
	v_pk_fma_f32 v[104:105], v[180:181], v[104:105], v[124:125]
	v_pk_fma_f32 v[102:103], v[182:183], v[102:103], v[122:123]
	v_xor_b32_e32 v112, v196, v112
	global_store_dwordx2 v[112:113], v[110:111], off
	v_xor_b32_e32 v112, v196, v112
	v_fmac_f32_e32 v107, v106, v106
	global_store_dwordx4 v[116:117], v[102:105], off offset:512
	v_cvt_pk_bf16_f32 v106, v102, v103
	v_fmac_f32_e32 v107, v108, v108
	v_mul_f32_e32 v103, v103, v103
	v_fmac_f32_e32 v103, v102, v102
	v_fmac_f32_e32 v107, v109, v109
	v_fmac_f32_e32 v103, v104, v104
	v_add_f32_e32 v110, v130, v107
	v_fmac_f32_e32 v103, v105, v105
	v_pk_fma_f32 v[98:99], v[182:183], v[98:99], v[118:119]
	v_add_f32_e32 v102, v110, v103
	v_mul_f32_e32 v103, v99, v99
	v_pk_fma_f32 v[100:101], v[180:181], v[100:101], v[120:121]
	v_fmac_f32_e32 v103, v98, v98
	v_fmac_f32_e32 v103, v100, v100
	v_fmac_f32_e32 v103, v101, v101
	v_cvt_pk_bf16_f32 v107, v104, v105
	v_add_f32_e32 v104, v102, v103
	ds_bpermute_b32 v105, v162, v104
	v_or_b32_e32 v108, 0x100, v114
	v_mov_b32_e32 v109, v115
	v_lshl_add_u64 v[102:103], s[34:35], 0, v[108:109]
	v_xor_b32_e32 v102, v196, v102
	global_store_dwordx2 v[102:103], v[106:107], off
	v_xor_b32_e32 v102, v196, v102
	global_store_dwordx4 v[116:117], v[98:101], off offset:576
	v_cvt_pk_bf16_f32 v102, v98, v99
	v_or_b32_e32 v114, 0x120, v114
	s_waitcnt lgkmcnt(0)
	v_add_f32_e32 v98, v104, v105
	ds_bpermute_b32 v99, v144, v98
	v_cvt_pk_bf16_f32 v103, v100, v101
	v_lshl_add_u64 v[100:101], s[34:35], 0, v[114:115]
	v_xor_b32_e32 v100, v196, v100
	global_store_dwordx2 v[100:101], v[102:103], off
	v_xor_b32_e32 v100, v196, v100
	s_and_saveexec_b64 s[40:41], s[36:37]
	s_cbranch_execz .LBB0_104
	s_waitcnt lgkmcnt(0)
	v_add_f32_e32 v98, v98, v99
	ds_write_b32 v134, v98 offset:64
.LBB0_104:
	s_or_b64 exec, exec, s[40:41]
	v_or_b32_e32 v98, 32, v156
	s_waitcnt lgkmcnt(0)
	v_ashrrev_i32_e32 v99, 31, v98
	v_lshlrev_b64 v[98:99], 12, v[98:99]
	v_lshl_add_u64 v[98:99], v[158:159], 0, v[98:99]
	flat_load_dwordx4 v[118:121], v[98:99]
	flat_load_dwordx4 v[122:125], v[98:99] offset:64
	flat_load_dwordx4 v[126:129], v[98:99] offset:512
	flat_load_dwordx4 v[114:117], v[98:99] offset:576
	v_or_b32_e32 v98, 48, v156
	v_ashrrev_i32_e32 v99, 31, v98
	v_lshlrev_b64 v[98:99], 12, v[98:99]
	v_lshl_add_u64 v[98:99], v[158:159], 0, v[98:99]
	flat_load_dwordx4 v[110:113], v[98:99]
	flat_load_dwordx4 v[106:109], v[98:99] offset:64
	flat_load_dwordx4 v[102:105], v[98:99] offset:512
	s_nop 0
	flat_load_dwordx4 v[98:101], v[98:99] offset:576
	v_add3_u32 v130, s13, v163, 32
	v_ashrrev_i32_e32 v131, 31, v130
	v_lshlrev_b64 v[130:131], 10, v[130:131]
	v_lshl_add_u64 v[130:131], v[130:131], 0, v[154:155]
	v_mov_b32_e32 v181, v180
	s_waitcnt vmcnt(0) lgkmcnt(0)
	v_pk_fma_f32 v[96:97], v[180:181], v[96:97], v[120:121]
	v_pk_fma_f32 v[94:95], v[182:183], v[94:95], v[118:119]
	v_lshl_add_u64 v[118:119], v[130:131], 2, s[20:21]
	v_lshlrev_b64 v[130:131], 1, v[130:131]
	v_cvt_pk_bf16_f32 v120, v94, v95
	v_cvt_pk_bf16_f32 v121, v96, v97
	v_lshl_add_u64 v[132:133], s[34:35], 0, v[130:131]
	global_store_dwordx4 v[118:119], v[94:97], off
	v_xor_b32_e32 v132, v196, v132
	global_store_dwordx2 v[132:133], v[120:121], off
	v_xor_b32_e32 v132, v196, v132
	v_mul_f32_e32 v120, v95, v95
	v_pk_fma_f32 v[92:93], v[180:181], v[92:93], v[124:125]
	v_pk_fma_f32 v[90:91], v[182:183], v[90:91], v[122:123]
	v_fmac_f32_e32 v120, v94, v94
	global_store_dwordx4 v[118:119], v[90:93], off offset:64
	v_cvt_pk_bf16_f32 v94, v90, v91
	v_fmac_f32_e32 v120, v96, v96
	v_mul_f32_e32 v91, v91, v91
	v_fmac_f32_e32 v91, v90, v90
	v_fmac_f32_e32 v120, v97, v97
	v_or_b32_e32 v96, 32, v130
	v_mov_b32_e32 v97, v131
	v_fmac_f32_e32 v91, v92, v92
	v_cvt_pk_bf16_f32 v95, v92, v93
	v_lshl_add_u64 v[96:97], s[34:35], 0, v[96:97]
	v_fmac_f32_e32 v91, v93, v93
	v_pk_fma_f32 v[88:89], v[180:181], v[88:89], v[128:129]
	v_pk_fma_f32 v[86:87], v[182:183], v[86:87], v[126:127]
	v_or_b32_e32 v92, 0x100, v130
	v_mov_b32_e32 v93, v131
	v_xor_b32_e32 v96, v196, v96
	global_store_dwordx2 v[96:97], v[94:95], off
	v_xor_b32_e32 v96, v196, v96
	v_add_f32_e32 v94, v120, v91
	global_store_dwordx4 v[118:119], v[86:89], off offset:512
	v_cvt_pk_bf16_f32 v90, v86, v87
	v_cvt_pk_bf16_f32 v91, v88, v89
	v_lshl_add_u64 v[92:93], s[34:35], 0, v[92:93]
	v_mul_f32_e32 v87, v87, v87
	v_pk_fma_f32 v[84:85], v[180:181], v[84:85], v[116:117]
	v_pk_fma_f32 v[82:83], v[182:183], v[82:83], v[114:115]
	v_xor_b32_e32 v92, v196, v92
	global_store_dwordx2 v[92:93], v[90:91], off
	v_xor_b32_e32 v92, v196, v92
	v_fmac_f32_e32 v87, v86, v86
	global_store_dwordx4 v[118:119], v[82:85], off offset:576
	v_cvt_pk_bf16_f32 v86, v82, v83
	v_fmac_f32_e32 v87, v88, v88
	v_mul_f32_e32 v83, v83, v83
	v_fmac_f32_e32 v83, v82, v82
	v_fmac_f32_e32 v87, v89, v89
	v_fmac_f32_e32 v83, v84, v84
	v_add_f32_e32 v90, v94, v87
	v_fmac_f32_e32 v83, v85, v85
	v_add_f32_e32 v82, v90, v83
	ds_bpermute_b32 v83, v162, v82
	v_or_b32_e32 v130, 0x120, v130
	v_cvt_pk_bf16_f32 v87, v84, v85
	v_lshl_add_u64 v[88:89], s[34:35], 0, v[130:131]
	v_xor_b32_e32 v88, v196, v88
	global_store_dwordx2 v[88:89], v[86:87], off
	v_xor_b32_e32 v88, v196, v88
	s_waitcnt lgkmcnt(0)
	v_add_f32_e32 v82, v82, v83
	ds_bpermute_b32 v83, v144, v82
	s_and_saveexec_b64 s[40:41], s[36:37]
	s_mov_b64 s[80:81], s[4:5]
	s_cbranch_execz .LBB0_106
	s_waitcnt lgkmcnt(0)
	v_add_f32_e32 v82, v82, v83
	ds_write_b32 v134, v82 offset:128
.LBB0_106:
	s_or_b64 exec, exec, s[40:41]
	v_add3_u32 v82, s13, v163, 48
	s_waitcnt lgkmcnt(0)
	v_ashrrev_i32_e32 v83, 31, v82
	v_lshlrev_b64 v[82:83], 10, v[82:83]
	v_lshl_add_u64 v[82:83], v[82:83], 0, v[154:155]
	v_pk_fma_f32 v[80:81], v[180:181], v[80:81], v[112:113]
	v_pk_fma_f32 v[78:79], v[182:183], v[78:79], v[110:111]
	v_lshl_add_u64 v[84:85], v[82:83], 2, s[20:21]
	v_lshlrev_b64 v[82:83], 1, v[82:83]
	v_cvt_pk_bf16_f32 v86, v78, v79
	v_cvt_pk_bf16_f32 v87, v80, v81
	v_lshl_add_u64 v[88:89], s[34:35], 0, v[82:83]
	global_store_dwordx4 v[84:85], v[78:81], off
	v_xor_b32_e32 v88, v196, v88
	global_store_dwordx2 v[88:89], v[86:87], off
	v_xor_b32_e32 v88, v196, v88
	v_mul_f32_e32 v86, v79, v79
	v_fmac_f32_e32 v86, v78, v78
	v_fmac_f32_e32 v86, v80, v80
	v_fmac_f32_e32 v86, v81, v81
	v_pk_fma_f32 v[76:77], v[180:181], v[76:77], v[108:109]
	v_pk_fma_f32 v[74:75], v[182:183], v[74:75], v[106:107]
	v_or_b32_e32 v80, 32, v82
	v_mov_b32_e32 v81, v83
	global_store_dwordx4 v[84:85], v[74:77], off offset:64
	v_cvt_pk_bf16_f32 v78, v74, v75
	v_cvt_pk_bf16_f32 v79, v76, v77
	v_lshl_add_u64 v[80:81], s[34:35], 0, v[80:81]
	v_mul_f32_e32 v75, v75, v75
	v_pk_fma_f32 v[72:73], v[180:181], v[72:73], v[104:105]
	v_pk_fma_f32 v[70:71], v[182:183], v[70:71], v[102:103]
	v_xor_b32_e32 v80, v196, v80
	global_store_dwordx2 v[80:81], v[78:79], off
	v_xor_b32_e32 v80, v196, v80
	v_fmac_f32_e32 v75, v74, v74
	global_store_dwordx4 v[84:85], v[70:73], off offset:512
	v_cvt_pk_bf16_f32 v74, v70, v71
	v_fmac_f32_e32 v75, v76, v76
	v_mul_f32_e32 v71, v71, v71
	v_fmac_f32_e32 v71, v70, v70
	v_fmac_f32_e32 v75, v77, v77
	v_fmac_f32_e32 v71, v72, v72
	v_add_f32_e32 v78, v86, v75
	v_fmac_f32_e32 v71, v73, v73
	v_pk_fma_f32 v[66:67], v[182:183], v[66:67], v[98:99]
	v_add_f32_e32 v70, v78, v71
	v_mul_f32_e32 v71, v67, v67
	v_pk_fma_f32 v[68:69], v[180:181], v[68:69], v[100:101]
	v_fmac_f32_e32 v71, v66, v66
	v_fmac_f32_e32 v71, v68, v68
	v_fmac_f32_e32 v71, v69, v69
	v_cvt_pk_bf16_f32 v75, v72, v73
	v_add_f32_e32 v72, v70, v71
	ds_bpermute_b32 v73, v162, v72
	v_or_b32_e32 v76, 0x100, v82
	v_mov_b32_e32 v77, v83
	v_lshl_add_u64 v[70:71], s[34:35], 0, v[76:77]
	v_xor_b32_e32 v70, v196, v70
	global_store_dwordx2 v[70:71], v[74:75], off
	v_xor_b32_e32 v70, v196, v70
	global_store_dwordx4 v[84:85], v[66:69], off offset:576
	v_cvt_pk_bf16_f32 v70, v66, v67
	v_or_b32_e32 v82, 0x120, v82
	s_waitcnt lgkmcnt(0)
	v_add_f32_e32 v66, v72, v73
	ds_bpermute_b32 v67, v144, v66
	v_cvt_pk_bf16_f32 v71, v68, v69
	v_lshl_add_u64 v[68:69], s[34:35], 0, v[82:83]
	v_xor_b32_e32 v68, v196, v68
	global_store_dwordx2 v[68:69], v[70:71], off
	v_xor_b32_e32 v68, v196, v68
	s_and_saveexec_b64 s[40:41], s[36:37]
	s_cbranch_execz .LBB0_108
	s_waitcnt lgkmcnt(0)
	v_add_f32_e32 v66, v66, v67
	ds_write_b32 v134, v66 offset:192
; #define LAS __attribute__((address_space(3)))
; __device__ __forceinline__ unsigned cvt_pk(float lo, float hi) { f32x2_t v = {lo, hi}; bf16x2_t b = __builtin_convertvector(v, bf16x2_t); return __builtin_bit_cast(unsigned, b); }
; __device__ __forceinline__ void epi_resid(Acc& acc, int pm, int pn, const float* xsrc, float* xdst, bf16_t* xb, float* ssq, float alpha, LAS unsigned char* lds) {
;     TileIdx t = tile_idx();
;     LAS float* red = (LAS float*)lds;
; #pragma unroll
;     for (int ai = 0; ai < 2; ++ai)
; #pragma unroll
;         for (int mp = 0; mp < 2; ++mp) {
;             f32x4 xs[2][2][2];
; #pragma unroll
;             for (int mm = 0; mm < 2; ++mm)
; #pragma unroll
;                 for (int bj = 0; bj < 2; ++bj)
; #pragma unroll
;                     for (int n = 0; n < 2; ++n) {
;                         const int row = pm * 256 + ai * 128 + t.wr * 64 + (mp * 2 + mm) * 16 + t.fr;
;                         xs[mm][bj][n] = *(const f32x4*)(xsrc + (size_t)row * DM + pn * 256 + bj * 128 + t.wc * 32 + n * 16 + t.fq * 4);
;                     }
; #pragma unroll
;             for (int mm = 0; mm < 2; ++mm) {
;                 const int m = mp * 2 + mm;
;                 const int rl = ai * 128 + t.wr * 64 + m * 16 + t.fr;
;                 const int row = pm * 256 + rl;
;                 float ss = 0.f;
; #pragma unroll
;                 for (int bj = 0; bj < 2; ++bj)
; #pragma unroll
;                     for (int n = 0; n < 2; ++n) {
;                         size_t off = (size_t)row * DM + pn * 256 + bj * 128 + t.wc * 32 + n * 16 + t.fq * 4;
;                         f32x4 v = xs[mm][bj][n] + acc[ai][bj][m][n] * alpha;
;                         *(f32x4*)(xdst + off) = v;
;                         u32x2 w; w[0] = cvt_pk(v[0], v[1]); w[1] = cvt_pk(v[2], v[3]);
;                         *(u32x2*)(xb + off) = w;
;                         ss += v[0] * v[0] + v[1] * v[1] + v[2] * v[2] + v[3] * v[3];
;                     }
;                 ss += __shfl_xor(ss, 16); ss += __shfl_xor(ss, 32);
;                 if (t.fq == 0) red[t.wc * 256 + rl] = ss;
;             }
;         }
;     __syncthreads();
;     if (t.tid < 256) ssq[(size_t)(pm * 256 + t.tid) * 4 + pn] = red[t.tid] + red[256 + t.tid] + red[512 + t.tid] + red[768 + t.tid];
; }
.LBB0_108:
	s_or_b64 exec, exec, s[40:41]
	s_waitcnt lgkmcnt(0)
	v_lshlrev_b64 v[66:67], 12, v[156:157]
	v_lshl_add_u64 v[66:67], v[158:159], 0, v[66:67]
	s_mov_b64 s[40:41], 0x80000
	v_lshl_add_u64 v[68:69], v[66:67], 0, s[40:41]
	v_add_co_u32_e32 v66, vcc, 0x80000, v66
	v_add_u32_e32 v86, 0x90, v156
	s_nop 0
	v_addc_co_u32_e32 v67, vcc, 0, v67, vcc
	flat_load_dwordx4 v[88:91], v[66:67]
	flat_load_dwordx4 v[92:95], v[68:69] offset:64
	flat_load_dwordx4 v[96:99], v[68:69] offset:512
	flat_load_dwordx4 v[82:85], v[68:69] offset:576
	v_ashrrev_i32_e32 v87, 31, v86
	v_lshlrev_b64 v[66:67], 12, v[86:87]
	v_lshl_add_u64 v[66:67], v[158:159], 0, v[66:67]
	flat_load_dwordx4 v[78:81], v[66:67]
	flat_load_dwordx4 v[74:77], v[66:67] offset:64
	flat_load_dwordx4 v[70:73], v[66:67] offset:512
	s_nop 0
	flat_load_dwordx4 v[66:69], v[66:67] offset:576
	v_add_u32_e32 v100, 0x80, v160
	v_ashrrev_i32_e32 v101, 31, v100
	v_lshlrev_b64 v[100:101], 10, v[100:101]
	v_lshl_add_u64 v[100:101], v[100:101], 0, v[154:155]
	v_mov_b32_e32 v181, v180
	s_waitcnt vmcnt(0) lgkmcnt(0)
	v_pk_fma_f32 v[64:65], v[180:181], v[64:65], v[90:91]
	v_pk_fma_f32 v[62:63], v[182:183], v[62:63], v[88:89]
	v_lshl_add_u64 v[88:89], v[100:101], 2, s[20:21]
	v_lshlrev_b64 v[100:101], 1, v[100:101]
	v_cvt_pk_bf16_f32 v90, v62, v63
	v_cvt_pk_bf16_f32 v91, v64, v65
	v_lshl_add_u64 v[102:103], s[34:35], 0, v[100:101]
	global_store_dwordx4 v[88:89], v[62:65], off
	v_xor_b32_e32 v102, v196, v102
	global_store_dwordx2 v[102:103], v[90:91], off
	v_xor_b32_e32 v102, v196, v102
	v_mul_f32_e32 v90, v63, v63
	v_pk_fma_f32 v[60:61], v[180:181], v[60:61], v[94:95]
	v_pk_fma_f32 v[58:59], v[182:183], v[58:59], v[92:93]
	v_fmac_f32_e32 v90, v62, v62
	global_store_dwordx4 v[88:89], v[58:61], off offset:64
	v_cvt_pk_bf16_f32 v62, v58, v59
	v_fmac_f32_e32 v90, v64, v64
	v_mul_f32_e32 v59, v59, v59
	v_fmac_f32_e32 v59, v58, v58
	v_fmac_f32_e32 v90, v65, v65
	v_or_b32_e32 v64, 32, v100
	v_mov_b32_e32 v65, v101
	v_fmac_f32_e32 v59, v60, v60
	v_cvt_pk_bf16_f32 v63, v60, v61
	v_lshl_add_u64 v[64:65], s[34:35], 0, v[64:65]
	v_fmac_f32_e32 v59, v61, v61
	v_pk_fma_f32 v[56:57], v[180:181], v[56:57], v[98:99]
	v_pk_fma_f32 v[54:55], v[182:183], v[54:55], v[96:97]
	v_or_b32_e32 v60, 0x100, v100
	v_mov_b32_e32 v61, v101
	v_xor_b32_e32 v64, v196, v64
	global_store_dwordx2 v[64:65], v[62:63], off
	v_xor_b32_e32 v64, v196, v64
	v_add_f32_e32 v62, v90, v59
	global_store_dwordx4 v[88:89], v[54:57], off offset:512
	v_cvt_pk_bf16_f32 v58, v54, v55
	v_cvt_pk_bf16_f32 v59, v56, v57
	v_lshl_add_u64 v[60:61], s[34:35], 0, v[60:61]
	v_mul_f32_e32 v55, v55, v55
	v_pk_fma_f32 v[52:53], v[180:181], v[52:53], v[84:85]
	v_pk_fma_f32 v[50:51], v[182:183], v[50:51], v[82:83]
	v_xor_b32_e32 v60, v196, v60
	global_store_dwordx2 v[60:61], v[58:59], off
	v_xor_b32_e32 v60, v196, v60
	v_fmac_f32_e32 v55, v54, v54
	global_store_dwordx4 v[88:89], v[50:53], off offset:576
	v_cvt_pk_bf16_f32 v54, v50, v51
	v_fmac_f32_e32 v55, v56, v56
	v_mul_f32_e32 v51, v51, v51
	v_fmac_f32_e32 v51, v50, v50
	v_fmac_f32_e32 v55, v57, v57
	v_fmac_f32_e32 v51, v52, v52
	v_add_f32_e32 v58, v62, v55
	v_fmac_f32_e32 v51, v53, v53
	v_add_f32_e32 v50, v58, v51
	ds_bpermute_b32 v51, v162, v50
	v_or_b32_e32 v100, 0x120, v100
	v_cvt_pk_bf16_f32 v55, v52, v53
	v_lshl_add_u64 v[56:57], s[34:35], 0, v[100:101]
	v_xor_b32_e32 v56, v196, v56
	global_store_dwordx2 v[56:57], v[54:55], off
	v_xor_b32_e32 v56, v196, v56
	s_waitcnt lgkmcnt(0)
	v_add_f32_e32 v50, v50, v51
	ds_bpermute_b32 v51, v144, v50
	s_and_saveexec_b64 s[40:41], s[36:37]
	s_cbranch_execz .LBB0_110
	s_waitcnt lgkmcnt(0)
	v_add_f32_e32 v50, v50, v51
	ds_write_b32 v134, v50 offset:512
.LBB0_110:
	s_or_b64 exec, exec, s[40:41]
	s_waitcnt lgkmcnt(0)
	v_lshlrev_b64 v[50:51], 10, v[86:87]
	v_lshl_add_u64 v[50:51], v[50:51], 0, v[154:155]
	v_pk_fma_f32 v[48:49], v[180:181], v[48:49], v[80:81]
	v_pk_fma_f32 v[46:47], v[182:183], v[46:47], v[78:79]
	v_lshl_add_u64 v[52:53], v[50:51], 2, s[20:21]
	v_lshlrev_b64 v[50:51], 1, v[50:51]
	v_cvt_pk_bf16_f32 v54, v46, v47
	v_cvt_pk_bf16_f32 v55, v48, v49
	v_lshl_add_u64 v[56:57], s[34:35], 0, v[50:51]
	global_store_dwordx4 v[52:53], v[46:49], off
	v_xor_b32_e32 v56, v196, v56
	global_store_dwordx2 v[56:57], v[54:55], off
	v_xor_b32_e32 v56, v196, v56
	v_mul_f32_e32 v54, v47, v47
	v_fmac_f32_e32 v54, v46, v46
	v_fmac_f32_e32 v54, v48, v48
	v_fmac_f32_e32 v54, v49, v49
	v_pk_fma_f32 v[44:45], v[180:181], v[44:45], v[76:77]
	v_pk_fma_f32 v[42:43], v[182:183], v[42:43], v[74:75]
	v_or_b32_e32 v48, 32, v50
	v_mov_b32_e32 v49, v51
	global_store_dwordx4 v[52:53], v[42:45], off offset:64
	v_cvt_pk_bf16_f32 v46, v42, v43
	v_cvt_pk_bf16_f32 v47, v44, v45
	v_lshl_add_u64 v[48:49], s[34:35], 0, v[48:49]
	v_mul_f32_e32 v43, v43, v43
	v_pk_fma_f32 v[40:41], v[180:181], v[40:41], v[72:73]
	v_pk_fma_f32 v[38:39], v[182:183], v[38:39], v[70:71]
	v_xor_b32_e32 v48, v196, v48
	global_store_dwordx2 v[48:49], v[46:47], off
	v_xor_b32_e32 v48, v196, v48
	v_fmac_f32_e32 v43, v42, v42
	global_store_dwordx4 v[52:53], v[38:41], off offset:512
	v_cvt_pk_bf16_f32 v42, v38, v39
	v_fmac_f32_e32 v43, v44, v44
	v_mul_f32_e32 v39, v39, v39
	v_fmac_f32_e32 v39, v38, v38
	v_fmac_f32_e32 v43, v45, v45
	v_fmac_f32_e32 v39, v40, v40
	v_add_f32_e32 v46, v54, v43
	v_fmac_f32_e32 v39, v41, v41
	v_pk_fma_f32 v[34:35], v[182:183], v[34:35], v[66:67]
	v_add_f32_e32 v38, v46, v39
	v_mul_f32_e32 v39, v35, v35
	v_pk_fma_f32 v[36:37], v[180:181], v[36:37], v[68:69]
	v_fmac_f32_e32 v39, v34, v34
	v_fmac_f32_e32 v39, v36, v36
	v_fmac_f32_e32 v39, v37, v37
	v_cvt_pk_bf16_f32 v43, v40, v41
	v_add_f32_e32 v40, v38, v39
	ds_bpermute_b32 v41, v162, v40
	v_or_b32_e32 v44, 0x100, v50
	v_mov_b32_e32 v45, v51
	v_lshl_add_u64 v[38:39], s[34:35], 0, v[44:45]
	v_xor_b32_e32 v38, v196, v38
	global_store_dwordx2 v[38:39], v[42:43], off
	v_xor_b32_e32 v38, v196, v38
	global_store_dwordx4 v[52:53], v[34:37], off offset:576
	v_cvt_pk_bf16_f32 v38, v34, v35
	v_or_b32_e32 v50, 0x120, v50
	s_waitcnt lgkmcnt(0)
	v_add_f32_e32 v34, v40, v41
	ds_bpermute_b32 v35, v144, v34
	v_cvt_pk_bf16_f32 v39, v36, v37
	v_lshl_add_u64 v[36:37], s[34:35], 0, v[50:51]
	v_xor_b32_e32 v36, v196, v36
	global_store_dwordx2 v[36:37], v[38:39], off
	v_xor_b32_e32 v36, v196, v36
	s_and_saveexec_b64 s[40:41], s[36:37]
	s_cbranch_execz .LBB0_112
	s_waitcnt lgkmcnt(0)
	v_add_f32_e32 v34, v34, v35
	ds_write_b32 v134, v34 offset:576
; #define LAS __attribute__((address_space(3)))
; __device__ __forceinline__ unsigned cvt_pk(float lo, float hi) { f32x2_t v = {lo, hi}; bf16x2_t b = __builtin_convertvector(v, bf16x2_t); return __builtin_bit_cast(unsigned, b); }
; __device__ __forceinline__ void epi_resid(Acc& acc, int pm, int pn, const float* xsrc, float* xdst, bf16_t* xb, float* ssq, float alpha, LAS unsigned char* lds) {
;     TileIdx t = tile_idx();
;     LAS float* red = (LAS float*)lds;
; #pragma unroll
;     for (int ai = 0; ai < 2; ++ai)
; #pragma unroll
;         for (int mp = 0; mp < 2; ++mp) {
;             f32x4 xs[2][2][2];
; #pragma unroll
;             for (int mm = 0; mm < 2; ++mm)
; #pragma unroll
;                 for (int bj = 0; bj < 2; ++bj)
; #pragma unroll
;                     for (int n = 0; n < 2; ++n) {
;                         const int row = pm * 256 + ai * 128 + t.wr * 64 + (mp * 2 + mm) * 16 + t.fr;
;                         xs[mm][bj][n] = *(const f32x4*)(xsrc + (size_t)row * DM + pn * 256 + bj * 128 + t.wc * 32 + n * 16 + t.fq * 4);
;                     }
; #pragma unroll
;             for (int mm = 0; mm < 2; ++mm) {
;                 const int m = mp * 2 + mm;
;                 const int rl = ai * 128 + t.wr * 64 + m * 16 + t.fr;
;                 const int row = pm * 256 + rl;
;                 float ss = 0.f;
; #pragma unroll
;                 for (int bj = 0; bj < 2; ++bj)
; #pragma unroll
;                     for (int n = 0; n < 2; ++n) {
;                         size_t off = (size_t)row * DM + pn * 256 + bj * 128 + t.wc * 32 + n * 16 + t.fq * 4;
;                         f32x4 v = xs[mm][bj][n] + acc[ai][bj][m][n] * alpha;
;                         *(f32x4*)(xdst + off) = v;
;                         u32x2 w; w[0] = cvt_pk(v[0], v[1]); w[1] = cvt_pk(v[2], v[3]);
;                         *(u32x2*)(xb + off) = w;
;                         ss += v[0] * v[0] + v[1] * v[1] + v[2] * v[2] + v[3] * v[3];
;                     }
;                 ss += __shfl_xor(ss, 16); ss += __shfl_xor(ss, 32);
;                 if (t.fq == 0) red[t.wc * 256 + rl] = ss;
;             }
;         }
;     __syncthreads();
;     if (t.tid < 256) ssq[(size_t)(pm * 256 + t.tid) * 4 + pn] = red[t.tid] + red[256 + t.tid] + red[512 + t.tid] + red[768 + t.tid];
; }
.LBB0_112:
	s_or_b64 exec, exec, s[40:41]
	s_waitcnt lgkmcnt(0)
	v_lshlrev_b64 v[34:35], 12, v[156:157]
	v_lshl_add_u64 v[34:35], v[158:159], 0, v[34:35]
	s_mov_b64 s[40:41], 0xa0000
	v_lshl_add_u64 v[36:37], v[34:35], 0, s[40:41]
	v_add_co_u32_e32 v34, vcc, 0xa0000, v34
	v_add_u32_e32 v54, 0xb0, v156
	s_nop 0
	v_addc_co_u32_e32 v35, vcc, 0, v35, vcc
	flat_load_dwordx4 v[56:59], v[34:35]
	flat_load_dwordx4 v[60:63], v[36:37] offset:64
	flat_load_dwordx4 v[64:67], v[36:37] offset:512
	flat_load_dwordx4 v[50:53], v[36:37] offset:576
	v_ashrrev_i32_e32 v55, 31, v54
	v_lshlrev_b64 v[34:35], 12, v[54:55]
	v_lshl_add_u64 v[34:35], v[158:159], 0, v[34:35]
	flat_load_dwordx4 v[46:49], v[34:35]
	flat_load_dwordx4 v[42:45], v[34:35] offset:64
	flat_load_dwordx4 v[38:41], v[34:35] offset:512
	s_nop 0
	flat_load_dwordx4 v[34:37], v[34:35] offset:576
	v_add_u32_e32 v68, 0xa0, v160
	v_ashrrev_i32_e32 v69, 31, v68
	v_lshlrev_b64 v[68:69], 10, v[68:69]
	v_lshl_add_u64 v[68:69], v[68:69], 0, v[154:155]
	v_mov_b32_e32 v181, v180
	s_waitcnt vmcnt(0) lgkmcnt(0)
	v_pk_fma_f32 v[32:33], v[180:181], v[32:33], v[58:59]
	v_pk_fma_f32 v[30:31], v[182:183], v[30:31], v[56:57]
	v_lshl_add_u64 v[56:57], v[68:69], 2, s[20:21]
	v_lshlrev_b64 v[68:69], 1, v[68:69]
	v_cvt_pk_bf16_f32 v58, v30, v31
	v_cvt_pk_bf16_f32 v59, v32, v33
	v_lshl_add_u64 v[70:71], s[34:35], 0, v[68:69]
	global_store_dwordx4 v[56:57], v[30:33], off
	v_xor_b32_e32 v70, v196, v70
	global_store_dwordx2 v[70:71], v[58:59], off
	v_xor_b32_e32 v70, v196, v70
	v_mul_f32_e32 v58, v31, v31
	v_pk_fma_f32 v[28:29], v[180:181], v[28:29], v[62:63]
	v_pk_fma_f32 v[26:27], v[182:183], v[26:27], v[60:61]
	v_fmac_f32_e32 v58, v30, v30
	global_store_dwordx4 v[56:57], v[26:29], off offset:64
	v_cvt_pk_bf16_f32 v30, v26, v27
	v_fmac_f32_e32 v58, v32, v32
	v_mul_f32_e32 v27, v27, v27
	v_fmac_f32_e32 v27, v26, v26
	v_fmac_f32_e32 v58, v33, v33
	v_or_b32_e32 v32, 32, v68
	v_mov_b32_e32 v33, v69
	v_fmac_f32_e32 v27, v28, v28
	v_cvt_pk_bf16_f32 v31, v28, v29
	v_lshl_add_u64 v[32:33], s[34:35], 0, v[32:33]
	v_fmac_f32_e32 v27, v29, v29
	v_pk_fma_f32 v[24:25], v[180:181], v[24:25], v[66:67]
	v_pk_fma_f32 v[22:23], v[182:183], v[22:23], v[64:65]
	v_or_b32_e32 v28, 0x100, v68
	v_mov_b32_e32 v29, v69
	v_xor_b32_e32 v32, v196, v32
	global_store_dwordx2 v[32:33], v[30:31], off
	v_xor_b32_e32 v32, v196, v32
	v_add_f32_e32 v30, v58, v27
	global_store_dwordx4 v[56:57], v[22:25], off offset:512
	v_cvt_pk_bf16_f32 v26, v22, v23
	v_cvt_pk_bf16_f32 v27, v24, v25
	v_lshl_add_u64 v[28:29], s[34:35], 0, v[28:29]
	v_mul_f32_e32 v23, v23, v23
	v_pk_fma_f32 v[20:21], v[180:181], v[20:21], v[52:53]
	v_pk_fma_f32 v[18:19], v[182:183], v[18:19], v[50:51]
	v_xor_b32_e32 v28, v196, v28
	global_store_dwordx2 v[28:29], v[26:27], off
	v_xor_b32_e32 v28, v196, v28
	v_fmac_f32_e32 v23, v22, v22
	global_store_dwordx4 v[56:57], v[18:21], off offset:576
	v_cvt_pk_bf16_f32 v22, v18, v19
	v_fmac_f32_e32 v23, v24, v24
	v_mul_f32_e32 v19, v19, v19
	v_fmac_f32_e32 v19, v18, v18
	v_fmac_f32_e32 v23, v25, v25
	v_fmac_f32_e32 v19, v20, v20
	v_add_f32_e32 v26, v30, v23
	v_fmac_f32_e32 v19, v21, v21
	v_add_f32_e32 v18, v26, v19
	ds_bpermute_b32 v19, v162, v18
	v_or_b32_e32 v68, 0x120, v68
	v_cvt_pk_bf16_f32 v23, v20, v21
	v_lshl_add_u64 v[24:25], s[34:35], 0, v[68:69]
	v_xor_b32_e32 v24, v196, v24
	global_store_dwordx2 v[24:25], v[22:23], off
	v_xor_b32_e32 v24, v196, v24
	s_waitcnt lgkmcnt(0)
	v_add_f32_e32 v18, v18, v19
	ds_bpermute_b32 v19, v144, v18
	s_and_saveexec_b64 s[40:41], s[36:37]
	s_cbranch_execz .LBB0_114
	s_waitcnt lgkmcnt(0)
	v_add_f32_e32 v18, v18, v19
	ds_write_b32 v134, v18 offset:640
.LBB0_114:
	s_or_b64 exec, exec, s[40:41]
	s_waitcnt lgkmcnt(0)
	v_lshlrev_b64 v[18:19], 10, v[54:55]
	v_lshl_add_u64 v[18:19], v[18:19], 0, v[154:155]
	v_pk_fma_f32 v[16:17], v[180:181], v[16:17], v[48:49]
	v_pk_fma_f32 v[14:15], v[182:183], v[14:15], v[46:47]
	v_lshl_add_u64 v[20:21], v[18:19], 2, s[20:21]
	v_lshlrev_b64 v[18:19], 1, v[18:19]
	v_cvt_pk_bf16_f32 v22, v14, v15
	v_cvt_pk_bf16_f32 v23, v16, v17
	v_lshl_add_u64 v[24:25], s[34:35], 0, v[18:19]
	global_store_dwordx4 v[20:21], v[14:17], off
	v_xor_b32_e32 v24, v196, v24
	global_store_dwordx2 v[24:25], v[22:23], off
	v_xor_b32_e32 v24, v196, v24
	v_mul_f32_e32 v22, v15, v15
	v_fmac_f32_e32 v22, v14, v14
	v_fmac_f32_e32 v22, v16, v16
	v_fmac_f32_e32 v22, v17, v17
	v_pk_fma_f32 v[12:13], v[180:181], v[12:13], v[44:45]
	v_pk_fma_f32 v[10:11], v[182:183], v[10:11], v[42:43]
	v_or_b32_e32 v16, 32, v18
	v_mov_b32_e32 v17, v19
	global_store_dwordx4 v[20:21], v[10:13], off offset:64
	v_cvt_pk_bf16_f32 v14, v10, v11
	v_cvt_pk_bf16_f32 v15, v12, v13
	v_lshl_add_u64 v[16:17], s[34:35], 0, v[16:17]
	v_mul_f32_e32 v11, v11, v11
	v_pk_fma_f32 v[8:9], v[180:181], v[8:9], v[40:41]
	v_pk_fma_f32 v[6:7], v[182:183], v[6:7], v[38:39]
	v_xor_b32_e32 v16, v196, v16
	global_store_dwordx2 v[16:17], v[14:15], off
	v_xor_b32_e32 v16, v196, v16
	v_fmac_f32_e32 v11, v10, v10
	global_store_dwordx4 v[20:21], v[6:9], off offset:512
	v_cvt_pk_bf16_f32 v10, v6, v7
	v_fmac_f32_e32 v11, v12, v12
	v_mul_f32_e32 v7, v7, v7
	v_fmac_f32_e32 v7, v6, v6
	v_fmac_f32_e32 v11, v13, v13
	v_fmac_f32_e32 v7, v8, v8
	v_add_f32_e32 v14, v22, v11
	v_fmac_f32_e32 v7, v9, v9
	v_pk_fma_f32 v[2:3], v[182:183], v[2:3], v[34:35]
	v_add_f32_e32 v6, v14, v7
	v_mul_f32_e32 v7, v3, v3
	v_pk_fma_f32 v[4:5], v[180:181], v[4:5], v[36:37]
	v_fmac_f32_e32 v7, v2, v2
	v_fmac_f32_e32 v7, v4, v4
	v_fmac_f32_e32 v7, v5, v5
	v_cvt_pk_bf16_f32 v11, v8, v9
	v_add_f32_e32 v8, v6, v7
	ds_bpermute_b32 v9, v162, v8
	v_or_b32_e32 v12, 0x100, v18
	v_mov_b32_e32 v13, v19
	v_lshl_add_u64 v[6:7], s[34:35], 0, v[12:13]
	v_xor_b32_e32 v6, v196, v6
	global_store_dwordx2 v[6:7], v[10:11], off
	v_xor_b32_e32 v6, v196, v6
	global_store_dwordx4 v[20:21], v[2:5], off offset:576
	v_cvt_pk_bf16_f32 v6, v2, v3
	v_or_b32_e32 v18, 0x120, v18
	s_waitcnt lgkmcnt(0)
	v_add_f32_e32 v2, v8, v9
	ds_bpermute_b32 v3, v144, v2
	v_cvt_pk_bf16_f32 v7, v4, v5
	v_lshl_add_u64 v[4:5], s[34:35], 0, v[18:19]
	v_xor_b32_e32 v4, v196, v4
	global_store_dwordx2 v[4:5], v[6:7], off
	v_xor_b32_e32 v4, v196, v4
	s_and_saveexec_b64 s[40:41], s[36:37]
	s_cbranch_execz .LBB0_116
	s_waitcnt lgkmcnt(0)
	v_add_f32_e32 v2, v2, v3
	ds_write_b32 v134, v2 offset:704

; #define LAS __attribute__((address_space(3)))
; __device__ __forceinline__ int fresh_tid() { int t; asm volatile("v_mov_b32 %0, %1" : "=v"(t) : "v"(threadIdx.x)); return t; }
; __device__ __forceinline__ void gemm_stage_first(const bf16_t* __restrict__ A, int lda, const bf16_t* __restrict__ Bt, int ldb, int brow, int bcol, LAS unsigned char* lds) {
;     const int tid = fresh_tid();
;     const int wvu = __builtin_amdgcn_readfirstlane(tid >> 6);
;     unsigned offA, offB;
;     { int _r, _c; stage_rc(tid * 16, _r, _c); offA = (unsigned)(_r * lda + _c) * 2u; offB = (unsigned)(_r * ldb + _c) * 2u; }
;     STAGE(SBo(0, 0), Bt, ldb, bcol, 0, offB); STAGE(SAo(0, 0), A, lda, brow, 0, offA);
;     STAGE(SBo(0, 1), Bt, ldb, bcol + HALF, 0, offB); STAGE(SAo(0, 1), A, lda, brow + HALF, 0, offA);
; }
.LBB0_119:
	s_and_b64 vcc, exec, s[0:1]
	s_cbranch_vccz .LBB0_123
	s_mov_b32 s0, s2
	s_cmpk_gt_i32 s0, 0x57f
	s_cbranch_scc1 .LBB0_122
	s_ashr_i32 s1, s0, 31
	s_lshr_b32 s1, s1, 26
	s_add_i32 s1, s0, s1
	v_mov_b32 v1, v179
	s_and_b32 s12, s1, 0xffffc0
	s_waitcnt vmcnt(0) lgkmcnt(0)
	v_ashrrev_i32_e32 v3, 31, v1
	s_lshl_b32 s1, s1, 2
	v_lshrrev_b32_e32 v3, 26, v3
	s_sub_i32 s0, s0, s12
	s_and_b32 s12, s1, 0xffffff00
	v_readfirstlane_b32 s1, v1
	v_lshlrev_b32_e32 v2, 4, v1
	v_add_u32_e32 v3, v1, v3
	v_bfe_i32 v1, v1, 27, 1
	v_lshrrev_b32_e32 v1, 22, v1
	v_add_u32_e32 v1, v2, v1
	v_and_b32_e32 v1, 0xfffffc00, v1
	v_sub_u32_e32 v1, v2, v1
	v_lshrrev_b32_e32 v2, 4, v1
	v_bitop3_b32 v2, v2, v1, 32 bitop3:0x6c
	v_ashrrev_i32_e32 v1, 31, v1
	v_lshrrev_b32_e32 v1, 26, v1
	v_add_u32_e32 v1, v2, v1
	s_ashr_i32 s26, s1, 6
	v_ashrrev_i32_e32 v1, 6, v1
	v_ashrrev_i32_e32 v3, 6, v3
	v_mul_i32_i24_e32 v5, 64, v1
	s_mov_b32 s40, s27
	s_mov_b32 s1, s26
	v_lshlrev_b32_e32 v4, 3, v3
	v_lshlrev_b32_e32 v3, 5, v3
	v_sub_u32_e32 v2, v2, v5
	s_ashr_i32 s41, s40, 31
	s_lshl_b32 s0, s0, 8
	v_and_b32_e32 v4, 0x1ffff0, v4
	v_and_b32_e32 v3, 32, v3
	v_ashrrev_i16_sdwa v2, v194, sext(v2) dst_sel:DWORD dst_unused:UNUSED_PAD src0_sel:DWORD src1_sel:BYTE_0
	s_lshl_b64 s[40:41], s[40:41], 7
	v_add_u32_sdwa v2, v3, sext(v2) dst_sel:DWORD dst_unused:UNUSED_PAD src0_sel:DWORD src1_sel:WORD_0
	v_add_lshl_u32 v1, v1, v4, 11
	s_add_u32 s40, s76, s40
	v_lshl_add_u32 v144, v2, 1, v1
	s_addc_u32 s41, s77, s41
	s_ashr_i32 s13, s12, 31
	v_lshl_add_u64 v[2:3], s[40:41], 0, v[144:145]
	s_lshl_b64 s[40:41], s[12:13], 11
	s_lshl_b32 s1, s1, 10
	v_lshl_add_u64 v[4:5], v[2:3], 0, s[40:41]
	s_or_b32 s40, s12, 64
	s_add_i32 s1, s1, 0
	s_ashr_i32 s41, s40, 31
	s_add_i32 m0, s1, 0x10000
	s_lshl_b64 s[40:41], s[40:41], 11
	v_xor_b32_e32 v4, v197, v4
	global_load_lds_dwordx4 v[4:5], off
	v_lshl_add_u64 v[2:3], v[2:3], 0, s[40:41]
	s_add_i32 m0, s1, 0x12000
	s_mov_b32 s40, s27
	s_mov_b32 s1, s26
	v_xor_b32_e32 v2, v197, v2
	global_load_lds_dwordx4 v[2:3], off
	s_ashr_i32 s41, s40, 31
	s_lshl_b64 s[40:41], s[40:41], 7
	s_add_u32 s40, s34, s40
	s_addc_u32 s41, s35, s41
	s_lshl_b32 s1, s1, 10
	s_add_i32 s13, s1, 0
	s_ashr_i32 s1, s0, 31
	v_lshl_add_u64 v[2:3], s[40:41], 0, v[144:145]
	s_lshl_b64 s[40:41], s[0:1], 11
	v_lshl_add_u64 v[4:5], v[2:3], 0, s[40:41]
	s_or_b32 s40, s0, 64
	s_ashr_i32 s41, s40, 31
	s_mov_b32 m0, s13
	s_lshl_b64 s[40:41], s[40:41], 11
	v_xor_b32_e32 v4, v197, v4
	global_load_lds_dwordx4 v[4:5], off
	v_lshl_add_u64 v[2:3], v[2:3], 0, s[40:41]
	s_add_i32 m0, s13, 0x2000
	s_mov_b32 s40, s27
	s_mov_b32 s1, s26
	v_xor_b32_e32 v2, v197, v2
	global_load_lds_dwordx4 v[2:3], off
	s_ashr_i32 s41, s40, 31
	s_or_b32 s42, s12, 0x80
	s_lshl_b64 s[40:41], s[40:41], 7
	s_add_u32 s40, s76, s40
	s_addc_u32 s41, s77, s41
	s_lshl_b32 s1, s1, 10
	s_ashr_i32 s43, s42, 31
	s_or_b32 s12, s12, 0xc0
	v_lshl_add_u64 v[2:3], s[40:41], 0, v[144:145]
	s_add_i32 s1, s1, 0
	s_lshl_b64 s[40:41], s[42:43], 11
	s_ashr_i32 s13, s12, 31
	s_add_i32 m0, s1, 0x14000
	v_lshl_add_u64 v[4:5], v[2:3], 0, s[40:41]
	s_lshl_b64 s[12:13], s[12:13], 11
	v_xor_b32_e32 v4, v197, v4
	global_load_lds_dwordx4 v[4:5], off
	v_lshl_add_u64 v[2:3], v[2:3], 0, s[12:13]
	s_add_i32 m0, s1, 0x16000
	s_mov_b32 s12, s27
	v_xor_b32_e32 v2, v197, v2
	global_load_lds_dwordx4 v[2:3], off
	s_ashr_i32 s13, s12, 31
	s_or_b32 s40, s0, 0x80
	s_lshl_b64 s[12:13], s[12:13], 7
	s_add_u32 s12, s34, s12
	s_addc_u32 s13, s35, s13
	s_lshl_b32 s1, s26, 10
	s_ashr_i32 s41, s40, 31
	s_or_b32 s0, s0, 0xc0
	v_lshl_add_u64 v[2:3], s[12:13], 0, v[144:145]
	s_add_i32 s26, s1, 0
	s_lshl_b64 s[12:13], s[40:41], 11
	s_ashr_i32 s1, s0, 31
	s_add_i32 m0, s26, 0x4000
	v_lshl_add_u64 v[4:5], v[2:3], 0, s[12:13]
	s_lshl_b64 s[0:1], s[0:1], 11
	v_xor_b32_e32 v4, v197, v4
	global_load_lds_dwordx4 v[4:5], off
	v_lshl_add_u64 v[2:3], v[2:3], 0, s[0:1]
	s_add_i32 m0, s26, 0x6000
	s_nop 0
	v_xor_b32_e32 v2, v197, v2
	global_load_lds_dwordx4 v[2:3], off

; __device__ __forceinline__ int fresh_tid() { int t; asm volatile("v_mov_b32 %0, %1" : "=v"(t) : "v"(threadIdx.x)); return t; }
; #define WAIT_V(n) asm volatile("s_waitcnt vmcnt(" #n ")" ::: "memory")
; #define BAR __builtin_amdgcn_s_barrier()
; template <bool PRE = false>
; __device__ __forceinline__ void gemm_kloop(Acc& acc, const bf16_t* __restrict__ A, int lda, const bf16_t* __restrict__ Bt, int ldb,
;                                            int brow, int bcol, int nt, LAS unsigned char* lds) {
;     const int tid = fresh_tid();
;     const int wid = tid >> 6, lane = tid & 63, wr = wid >> 2, wc = wid & 3, fr = lane & 15, fq = lane >> 4;
;     const int wvu = __builtin_amdgcn_readfirstlane(tid >> 6);
;     unsigned offA, offB;
;     { int _r, _c; stage_rc(tid * 16, _r, _c); offA = (unsigned)(_r * lda + _c) * 2u; offB = (unsigned)(_r * ldb + _c) * 2u; }
;     ...
;     bf16x8 At[4][2], B0[2][2], B1[2][2];
;     if (!PRE) {
;     STAGE(SBo(0, 0), Bt, ldb, bcol, 0, offB); STAGE(SAo(0, 0), A, lda, brow, 0, offA);
;     STAGE(SBo(0, 1), Bt, ldb, bcol + HALF, 0, offB); STAGE(SAo(0, 1), A, lda, brow + HALF, 0, offA);
;     }
;     if (wr == 1) BAR;
;     WAIT_V(4); BAR;
;     STAGE(SBo(1, 0), Bt, ldb, bcol, 1, offB); STAGE(SAo(1, 0), A, lda, brow, 1, offA); STAGE(SBo(1, 1), Bt, ldb, bcol + HALF, 1, offB);
;     WAIT_V(6); BAR;
.LBB0_129:
	s_or_b64 exec, exec, s[0:1]
	v_bfe_i32 v6, v1, 27, 1
	v_lshlrev_b32_e32 v4, 4, v1
	v_lshrrev_b32_e32 v6, 22, v6
	v_add_u32_e32 v6, v4, v6
	v_and_b32_e32 v6, 0xfffffc00, v6
	v_sub_u32_e32 v4, v4, v6
	v_lshrrev_b32_e32 v6, 4, v4
	v_bitop3_b32 v6, v6, v4, 32 bitop3:0x6c
	v_ashrrev_i32_e32 v4, 31, v4
	s_ashr_i32 s0, s26, 31
	v_ashrrev_i32_e32 v5, 31, v1
	v_lshrrev_b32_e32 v4, 26, v4
	s_lshr_b32 s0, s0, 26
	v_lshrrev_b32_e32 v5, 26, v5
	v_add_u32_e32 v4, v6, v4
	s_add_i32 s0, s26, s0
	v_add_u32_e32 v5, v1, v5
	v_ashrrev_i32_e32 v4, 6, v4
	s_ashr_i32 s56, s0, 6
	s_and_b32 s0, s0, 0xffffc0
	v_ashrrev_i32_e32 v5, 6, v5
	v_mul_i32_i24_e32 v10, 64, v4
	s_mov_b32 s12, 1
	s_mov_b32 s1, s57
	s_sub_i32 s0, s26, s0
	v_lshlrev_b32_e32 v7, 3, v5
	v_lshlrev_b32_e32 v5, 5, v5
	v_sub_u32_e32 v6, v6, v10
	s_waitcnt vmcnt(4)
	s_barrier
	s_ashr_i32 s13, s12, 31
	s_lshl_b32 s0, s0, 8
	s_lshl_b32 s48, s56, 8
	v_and_b32_e32 v7, 0x1ffff0, v7
	v_and_b32_e32 v5, 32, v5
	v_ashrrev_i16_sdwa v6, v194, sext(v6) dst_sel:DWORD dst_unused:UNUSED_PAD src0_sel:DWORD src1_sel:BYTE_0
	s_lshl_b64 s[12:13], s[12:13], 7
	v_add_u32_sdwa v5, v5, sext(v6) dst_sel:DWORD dst_unused:UNUSED_PAD src0_sel:DWORD src1_sel:WORD_0
	v_add_lshl_u32 v4, v4, v7, 11
	s_add_u32 s12, s76, s12
	v_lshl_add_u32 v144, v5, 1, v4
	s_addc_u32 s13, s77, s13
	s_lshl_b32 s1, s1, 10
	s_ashr_i32 s49, s48, 31
	s_or_b32 s40, s48, 64
	v_lshl_add_u64 v[4:5], s[12:13], 0, v[144:145]
	s_add_i32 s1, s31, s1
	s_lshl_b64 s[12:13], s[48:49], 11
	s_ashr_i32 s41, s40, 31
	v_lshl_add_u64 v[6:7], v[4:5], 0, s[12:13]
	s_mov_b32 m0, s1
	s_lshl_b64 s[40:41], s[40:41], 11
	v_xor_b32_e32 v6, v197, v6
	global_load_lds_dwordx4 v[6:7], off
	v_lshl_add_u64 v[4:5], v[4:5], 0, s[40:41]
	s_add_i32 m0, s1, 0x2000
	s_mov_b32 s42, 1
	s_mov_b32 s1, s57
	v_xor_b32_e32 v4, v197, v4
	global_load_lds_dwordx4 v[4:5], off
	s_ashr_i32 s43, s42, 31
	s_lshl_b64 s[42:43], s[42:43], 7
	s_add_u32 s42, s34, s42
	s_addc_u32 s43, s35, s43
	s_lshl_b32 s1, s1, 10
	s_add_i32 s30, s1, 0
	s_ashr_i32 s1, s0, 31
	s_or_b32 s44, s0, 64
	v_lshl_add_u64 v[4:5], s[42:43], 0, v[144:145]
	s_lshl_b64 s[42:43], s[0:1], 11
	s_ashr_i32 s45, s44, 31
	s_add_i32 m0, s30, 0x8000
	v_lshl_add_u64 v[6:7], v[4:5], 0, s[42:43]
	s_lshl_b64 s[44:45], s[44:45], 11
	v_xor_b32_e32 v6, v197, v6
	global_load_lds_dwordx4 v[6:7], off
	v_lshl_add_u64 v[4:5], v[4:5], 0, s[44:45]
	s_add_i32 m0, s30, 0xa000
	s_mov_b32 s46, 1
	s_mov_b32 s1, s57
	v_xor_b32_e32 v4, v197, v4
	global_load_lds_dwordx4 v[4:5], off
	s_ashr_i32 s47, s46, 31
	s_or_b32 s50, s48, 0x80
	s_lshl_b64 s[46:47], s[46:47], 7
	s_add_u32 s46, s76, s46
	s_addc_u32 s47, s77, s47
	s_lshl_b32 s1, s1, 10
	s_ashr_i32 s51, s50, 31
	s_or_b32 s48, s48, 0xc0
	v_lshl_add_u64 v[4:5], s[46:47], 0, v[144:145]
	s_add_i32 s1, s24, s1
	s_lshl_b64 s[46:47], s[50:51], 11
	s_ashr_i32 s49, s48, 31
	v_lshl_add_u64 v[6:7], v[4:5], 0, s[46:47]
	s_mov_b32 m0, s1
	s_lshl_b64 s[48:49], s[48:49], 11
	v_xor_b32_e32 v6, v197, v6
	global_load_lds_dwordx4 v[6:7], off
	v_lshl_add_u64 v[4:5], v[4:5], 0, s[48:49]
	s_add_i32 m0, s1, 0x2000
	v_and_b32_e32 v8, 15, v1
	v_xor_b32_e32 v4, v197, v4
	global_load_lds_dwordx4 v[4:5], off
	v_lshlrev_b32_e32 v5, 2, v1
	v_and_b32_e32 v9, 48, v1
	v_lshlrev_b32_e32 v4, 6, v8
	v_and_b32_e32 v5, 32, v5
	v_bitop3_b32 v4, v4, v5, v9 bitop3:0x36
	s_add_i32 s1, 0, 0x10000
	v_lshlrev_b32_e32 v11, 13, v2
	v_lshlrev_b32_e32 v2, 6, v1
	s_waitcnt vmcnt(6)
	v_lshlrev_b32_e32 v3, 12, v3
	v_add_u32_e32 v6, s1, v4
	s_or_b32 s50, s0, 0x80
	s_add_i32 s1, 0, 0x14000
	v_and_or_b32 v2, v2, s25, v9
	s_or_b32 s52, s0, 0xc0
	v_and_b32_e32 v3, 0x3000, v3
	v_add_u32_e32 v7, s1, v4
	v_add_u32_e32 v8, s31, v4
	v_add_u32_e32 v10, s24, v4
	v_add_u32_e32 v4, 0, v4
	v_xad_u32 v5, v2, v5, 0
	v_or_b32_e32 v9, 0x800, v11
	v_or_b32_e32 v12, 0x1000, v11
	v_or_b32_e32 v13, 0x1800, v11
	s_ashr_i32 s51, s50, 31
	s_ashr_i32 s53, s52, 31
	v_mov_b32_e32 v2, 0
	s_lshl_b64 s[50:51], s[50:51], 11
	s_lshl_b64 s[52:53], s[52:53], 11
	s_mov_b32 s1, -2
	v_add_u32_e32 v141, v6, v3
	v_add_u32_e32 v137, v4, v11
	v_add_u32_e32 v136, v5, v9
	v_add_u32_e32 v135, v5, v12
	v_add_u32_e32 v134, v5, v13
	v_add_u32_e32 v140, v7, v3
	v_add_u32_e32 v139, v8, v3
	v_add_u32_e32 v138, v10, v3
	v_mov_b32_e32 v3, v2
	v_mov_b32_e32 v4, v2
	v_mov_b32_e32 v5, v2
	v_mov_b32_e32 v6, v2
	v_mov_b32_e32 v7, v2
	v_mov_b32_e32 v8, v2
	v_mov_b32_e32 v9, v2
	v_mov_b32_e32 v10, v2
	v_mov_b32_e32 v11, v2
	v_mov_b32_e32 v12, v2
	v_mov_b32_e32 v13, v2
	v_mov_b32_e32 v14, v2
	v_mov_b32_e32 v15, v2
	v_mov_b32_e32 v16, v2
	v_mov_b32_e32 v17, v2
	v_mov_b32_e32 v18, v2
	v_mov_b32_e32 v19, v2
	v_mov_b32_e32 v20, v2
	v_mov_b32_e32 v21, v2
	v_mov_b32_e32 v22, v2
	v_mov_b32_e32 v23, v2
	v_mov_b32_e32 v24, v2
	v_mov_b32_e32 v25, v2
	v_mov_b32_e32 v26, v2
	v_mov_b32_e32 v27, v2
	v_mov_b32_e32 v28, v2
	v_mov_b32_e32 v29, v2
	v_mov_b32_e32 v30, v2
	v_mov_b32_e32 v31, v2
	v_mov_b32_e32 v32, v2
	v_mov_b32_e32 v33, v2
	v_mov_b32_e32 v34, v2
	v_mov_b32_e32 v35, v2
	v_mov_b32_e32 v36, v2
	v_mov_b32_e32 v37, v2
	v_mov_b32_e32 v38, v2
	v_mov_b32_e32 v39, v2
	v_mov_b32_e32 v40, v2
	v_mov_b32_e32 v41, v2
	v_mov_b32_e32 v42, v2
	v_mov_b32_e32 v43, v2
	v_mov_b32_e32 v44, v2
	v_mov_b32_e32 v45, v2
	v_mov_b32_e32 v46, v2
	v_mov_b32_e32 v47, v2
	v_mov_b32_e32 v48, v2
	v_mov_b32_e32 v49, v2
	v_mov_b32_e32 v50, v2
	v_mov_b32_e32 v51, v2
	v_mov_b32_e32 v52, v2
	v_mov_b32_e32 v53, v2
	v_mov_b32_e32 v54, v2
	v_mov_b32_e32 v55, v2
	v_mov_b32_e32 v56, v2
	v_mov_b32_e32 v57, v2
	v_mov_b32_e32 v58, v2
	v_mov_b32_e32 v59, v2
	v_mov_b32_e32 v60, v2
	v_mov_b32_e32 v61, v2
	v_mov_b32_e32 v62, v2
	v_mov_b32_e32 v63, v2
	v_mov_b32_e32 v64, v2
; #define LDA(dst, b, h) _Pragma("unroll") for (int m = 0; m < 4; ++m) _Pragma("unroll") for (int k = 0; k < 2; ++k) \
;     dst[m][k] = *reinterpret_cast<const LAS bf16x8*>(lds + SAo(b, h) + lds_byte(wr * 64 + m * 16 + fr, k * 32 + fq * 8))
; #define LDB(dst, b, h) _Pragma("unroll") for (int n = 0; n < 2; ++n) _Pragma("unroll") for (int k = 0; k < 2; ++k) \
;     dst[n][k] = *reinterpret_cast<const LAS bf16x8*>(lds + SBo(b, h) + lds_byte(wc * 32 + n * 16 + fr, k * 32 + fq * 8))
; #define MMA(ai, bj, At_, Bt_) do { __builtin_amdgcn_s_setprio(1); \
;     _Pragma("unroll") for (int m = 0; m < 4; ++m) _Pragma("unroll") for (int n = 0; n < 2; ++n) _Pragma("unroll") for (int k = 0; k < 2; ++k) \
;       acc[ai][bj][m][n] = __builtin_amdgcn_mfma_f32_16x16x32_bf16(Bt_[n][k], At_[m][k], acc[ai][bj][m][n], 0, 0, 0); \
;     __builtin_amdgcn_s_setprio(0); } while (0)
; #define WAIT_V(n) asm volatile("s_waitcnt vmcnt(" #n ")" ::: "memory")
; #define WAIT_L(n) asm volatile("s_waitcnt lgkmcnt(" #n ")" ::: "memory")
; #define BAR __builtin_amdgcn_s_barrier()
; #define SCHED __builtin_amdgcn_sched_barrier(0)
; template <bool PRE = false>
; __device__ __forceinline__ void gemm_kloop(Acc& acc, const bf16_t* __restrict__ A, int lda, const bf16_t* __restrict__ Bt, int ldb,
;                                            int brow, int bcol, int nt, LAS unsigned char* lds) {
;     ...
;     for (int t = 0; t < nt - 2; t += 2) {
;         LDB(B0, 0, 0); SCHED; LDA(At, 0, 0); STAGE(SAo(1, 1), A, lda, brow + HALF, t + 1, offA);
;         WAIT_L(8); BAR; WAIT_L(0); MMA(0, 0, At, B0); BAR; SCHED;
;         LDB(B1, 0, 1); STAGE(SBo(0, 0), Bt, ldb, bcol, t + 2, offB);
;         BAR; WAIT_L(0); MMA(0, 1, At, B1); BAR;
;         LDA(At, 0, 1); STAGE(SAo(0, 0), A, lda, brow, t + 2, offA);
;         BAR; WAIT_L(0); MMA(1, 0, At, B0); BAR; SCHED;
;         STAGE(SBo(0, 1), Bt, ldb, bcol + HALF, t + 2, offB);
;         WAIT_V(6); BAR; MMA(1, 1, At, B1); BAR;
	v_mov_b32_e32 v65, v2
	v_mov_b32_e32 v66, v2
	v_mov_b32_e32 v67, v2
	v_mov_b32_e32 v68, v2
	v_mov_b32_e32 v69, v2
	v_mov_b32_e32 v70, v2
	v_mov_b32_e32 v71, v2
	v_mov_b32_e32 v72, v2
	v_mov_b32_e32 v73, v2
	v_mov_b32_e32 v74, v2
	v_mov_b32_e32 v75, v2
	v_mov_b32_e32 v76, v2
	v_mov_b32_e32 v77, v2
	v_mov_b32_e32 v78, v2
	v_mov_b32_e32 v79, v2
	v_mov_b32_e32 v80, v2
	v_mov_b32_e32 v81, v2
	v_mov_b32_e32 v82, v2
	v_mov_b32_e32 v83, v2
	v_mov_b32_e32 v84, v2
	v_mov_b32_e32 v85, v2
	v_mov_b32_e32 v86, v2
	v_mov_b32_e32 v87, v2
	v_mov_b32_e32 v88, v2
	v_mov_b32_e32 v89, v2
	v_mov_b32_e32 v90, v2
	v_mov_b32_e32 v91, v2
	v_mov_b32_e32 v92, v2
	v_mov_b32_e32 v93, v2
	v_mov_b32_e32 v94, v2
	v_mov_b32_e32 v95, v2
	v_mov_b32_e32 v96, v2
	v_mov_b32_e32 v97, v2
	v_mov_b32_e32 v98, v2
	v_mov_b32_e32 v99, v2
	v_mov_b32_e32 v100, v2
	v_mov_b32_e32 v101, v2
	v_mov_b32_e32 v102, v2
	v_mov_b32_e32 v103, v2
	v_mov_b32_e32 v104, v2
	v_mov_b32_e32 v105, v2
	v_mov_b32_e32 v106, v2
	v_mov_b32_e32 v107, v2
	v_mov_b32_e32 v108, v2
	v_mov_b32_e32 v109, v2
	v_mov_b32_e32 v110, v2
	v_mov_b32_e32 v111, v2
	v_mov_b32_e32 v112, v2
	v_mov_b32_e32 v113, v2
	v_mov_b32_e32 v114, v2
	v_mov_b32_e32 v115, v2
	v_mov_b32_e32 v116, v2
	v_mov_b32_e32 v117, v2
	v_mov_b32_e32 v118, v2
	v_mov_b32_e32 v119, v2
	v_mov_b32_e32 v120, v2
	v_mov_b32_e32 v121, v2
	v_mov_b32_e32 v122, v2
	v_mov_b32_e32 v123, v2
	v_mov_b32_e32 v124, v2
	v_mov_b32_e32 v125, v2
	v_mov_b32_e32 v126, v2
	v_mov_b32_e32 v127, v2
	v_mov_b32_e32 v128, v2
	v_mov_b32_e32 v129, v2
	v_lshl_add_u64 v[130:131], s[34:35], 0, v[144:145]
	v_lshl_add_u64 v[132:133], s[76:77], 0, v[144:145]
	s_barrier
	s_waitcnt vmcnt(0)
.LBB0_130:
	ds_read_b128 v[146:149], v141
	ds_read_b128 v[150:153], v141 offset:1024
	ds_read_b128 v[154:157], v141 offset:2048
	ds_read_b128 v[158:161], v141 offset:3072
	s_add_i32 s54, s1, 3
	s_mov_b32 s30, s57
	ds_read_b128 v[162:165], v137
	ds_read_b128 v[166:169], v137 offset:1024
	ds_read_b128 v[170:173], v136
	ds_read_b128 v[174:177], v136 offset:1024
	ds_read_b128 v[184:187], v135
	ds_read_b128 v[188:191], v135 offset:1024
	ds_read_b128 v[204:207], v134
	ds_read_b128 v[208:211], v134 offset:1024
	s_ashr_i32 s55, s54, 31
	s_lshl_b64 s[54:55], s[54:55], 7
	s_lshl_b32 s30, s30, 10
	v_lshl_add_u64 v[142:143], v[130:131], 0, s[54:55]
	s_add_i32 s30, s30, 0
	s_add_i32 m0, s30, 0xc000
	v_lshl_add_u64 v[192:193], v[142:143], 0, s[50:51]
	v_xor_b32_e32 v192, v197, v192
	global_load_lds_dwordx4 v[192:193], off
	v_lshl_add_u64 v[142:143], v[142:143], 0, s[52:53]
	s_add_i32 m0, s30, 0xe000
	s_nop 0
	v_xor_b32_e32 v142, v197, v142
	global_load_lds_dwordx4 v[142:143], off
	s_waitcnt lgkmcnt(8)
	s_barrier
	s_waitcnt lgkmcnt(0)
	s_setprio 1
	s_waitcnt lgkmcnt(0)
	v_mfma_f32_16x16x32_bf16 v[126:129], v[146:149], v[162:165], v[126:129]
	v_mfma_f32_16x16x32_bf16 v[122:125], v[154:157], v[162:165], v[122:125]
	v_mfma_f32_16x16x32_bf16 v[118:121], v[146:149], v[170:173], v[118:121]
	v_mfma_f32_16x16x32_bf16 v[114:117], v[154:157], v[170:173], v[114:117]
	v_mfma_f32_16x16x32_bf16 v[110:113], v[146:149], v[184:187], v[110:113]
	v_mfma_f32_16x16x32_bf16 v[106:109], v[154:157], v[184:187], v[106:109]
	v_mfma_f32_16x16x32_bf16 v[102:105], v[146:149], v[204:207], v[102:105]
	v_mfma_f32_16x16x32_bf16 v[98:101], v[154:157], v[204:207], v[98:101]
	v_mfma_f32_16x16x32_bf16 v[126:129], v[150:153], v[166:169], v[126:129]
	v_mfma_f32_16x16x32_bf16 v[122:125], v[158:161], v[166:169], v[122:125]
	v_mfma_f32_16x16x32_bf16 v[118:121], v[150:153], v[174:177], v[118:121]
	v_mfma_f32_16x16x32_bf16 v[114:117], v[158:161], v[174:177], v[114:117]
	v_mfma_f32_16x16x32_bf16 v[110:113], v[150:153], v[188:191], v[110:113]
	v_mfma_f32_16x16x32_bf16 v[106:109], v[158:161], v[188:191], v[106:109]
	v_mfma_f32_16x16x32_bf16 v[102:105], v[150:153], v[208:211], v[102:105]
	v_mfma_f32_16x16x32_bf16 v[98:101], v[158:161], v[208:211], v[98:101]
	s_setprio 0
	s_barrier
	s_add_i32 s54, s1, 4
	s_mov_b32 s30, s57
	s_mov_b32 s58, s54
	ds_read_b128 v[212:215], v140
	ds_read_b128 v[216:219], v140 offset:1024
	ds_read_b128 v[220:223], v140 offset:2048
	ds_read_b128 v[224:227], v140 offset:3072
	s_ashr_i32 s59, s58, 31
	s_lshl_b64 s[58:59], s[58:59], 7
	s_lshl_b32 s30, s30, 10
	v_lshl_add_u64 v[142:143], v[132:133], 0, s[58:59]
	s_add_i32 s30, s30, 0
	s_add_i32 m0, s30, 0x10000
	v_lshl_add_u64 v[192:193], v[142:143], 0, s[12:13]
	v_xor_b32_e32 v192, v197, v192
	global_load_lds_dwordx4 v[192:193], off
	v_lshl_add_u64 v[142:143], v[142:143], 0, s[40:41]
	s_add_i32 m0, s30, 0x12000
	s_nop 0
	v_xor_b32_e32 v142, v197, v142
	global_load_lds_dwordx4 v[142:143], off
	s_barrier
	s_waitcnt lgkmcnt(0)
	s_setprio 1
	s_waitcnt lgkmcnt(0)
	v_mfma_f32_16x16x32_bf16 v[94:97], v[212:215], v[162:165], v[94:97]
	v_mfma_f32_16x16x32_bf16 v[90:93], v[220:223], v[162:165], v[90:93]
	v_mfma_f32_16x16x32_bf16 v[86:89], v[212:215], v[170:173], v[86:89]
	v_mfma_f32_16x16x32_bf16 v[82:85], v[220:223], v[170:173], v[82:85]
	v_mfma_f32_16x16x32_bf16 v[78:81], v[212:215], v[184:187], v[78:81]
	v_mfma_f32_16x16x32_bf16 v[74:77], v[220:223], v[184:187], v[74:77]
	v_mfma_f32_16x16x32_bf16 v[70:73], v[212:215], v[204:207], v[70:73]
	v_mfma_f32_16x16x32_bf16 v[66:69], v[220:223], v[204:207], v[66:69]
	v_mfma_f32_16x16x32_bf16 v[94:97], v[216:219], v[166:169], v[94:97]
	v_mfma_f32_16x16x32_bf16 v[90:93], v[224:227], v[166:169], v[90:93]
	v_mfma_f32_16x16x32_bf16 v[86:89], v[216:219], v[174:177], v[86:89]
	v_mfma_f32_16x16x32_bf16 v[82:85], v[224:227], v[174:177], v[82:85]
	v_mfma_f32_16x16x32_bf16 v[78:81], v[216:219], v[188:191], v[78:81]
	v_mfma_f32_16x16x32_bf16 v[74:77], v[224:227], v[188:191], v[74:77]
	v_mfma_f32_16x16x32_bf16 v[70:73], v[216:219], v[208:211], v[70:73]
	v_mfma_f32_16x16x32_bf16 v[66:69], v[224:227], v[208:211], v[66:69]
	s_setprio 0
	s_mov_b32 s30, s57
	s_mov_b32 s58, s54
	s_barrier
; #define LDA(dst, b, h) _Pragma("unroll") for (int m = 0; m < 4; ++m) _Pragma("unroll") for (int k = 0; k < 2; ++k) \
;     dst[m][k] = *reinterpret_cast<const LAS bf16x8*>(lds + SAo(b, h) + lds_byte(wr * 64 + m * 16 + fr, k * 32 + fq * 8))
; #define LDB(dst, b, h) _Pragma("unroll") for (int n = 0; n < 2; ++n) _Pragma("unroll") for (int k = 0; k < 2; ++k) \
;     dst[n][k] = *reinterpret_cast<const LAS bf16x8*>(lds + SBo(b, h) + lds_byte(wc * 32 + n * 16 + fr, k * 32 + fq * 8))
; #define MMA(ai, bj, At_, Bt_) do { __builtin_amdgcn_s_setprio(1); \
;     _Pragma("unroll") for (int m = 0; m < 4; ++m) _Pragma("unroll") for (int n = 0; n < 2; ++n) _Pragma("unroll") for (int k = 0; k < 2; ++k) \
;       acc[ai][bj][m][n] = __builtin_amdgcn_mfma_f32_16x16x32_bf16(Bt_[n][k], At_[m][k], acc[ai][bj][m][n], 0, 0, 0); \
;     __builtin_amdgcn_s_setprio(0); } while (0)
; #define WAIT_V(n) asm volatile("s_waitcnt vmcnt(" #n ")" ::: "memory")
; #define WAIT_L(n) asm volatile("s_waitcnt lgkmcnt(" #n ")" ::: "memory")
; #define BAR __builtin_amdgcn_s_barrier()
; #define SCHED __builtin_amdgcn_sched_barrier(0)
; template <bool PRE = false>
; __device__ __forceinline__ void gemm_kloop(Acc& acc, const bf16_t* __restrict__ A, int lda, const bf16_t* __restrict__ Bt, int ldb,
;                                            int brow, int bcol, int nt, LAS unsigned char* lds) {
;     ...
;         LDB(B1, 0, 1); STAGE(SBo(0, 0), Bt, ldb, bcol, t + 2, offB);
;         BAR; WAIT_L(0); MMA(0, 1, At, B1); BAR;
;         LDA(At, 0, 1); STAGE(SAo(0, 0), A, lda, brow, t + 2, offA);
;         BAR; WAIT_L(0); MMA(1, 0, At, B0); BAR; SCHED;
;         STAGE(SBo(0, 1), Bt, ldb, bcol + HALF, t + 2, offB);
;         WAIT_V(6); BAR; MMA(1, 1, At, B1); BAR;
;         LDB(B0, 1, 0); SCHED; LDA(At, 1, 0); STAGE(SAo(0, 1), A, lda, brow + HALF, t + 2, offA);
;         WAIT_L(8); BAR; WAIT_L(0); MMA(0, 0, At, B0); BAR; SCHED;
	ds_read_b128 v[162:165], v137 offset:16384
	ds_read_b128 v[166:169], v137 offset:17408
	ds_read_b128 v[170:173], v136 offset:16384
	ds_read_b128 v[174:177], v136 offset:17408
	ds_read_b128 v[184:187], v135 offset:16384
	ds_read_b128 v[188:191], v135 offset:17408
	ds_read_b128 v[204:207], v134 offset:16384
	ds_read_b128 v[208:211], v134 offset:17408
	s_ashr_i32 s59, s58, 31
	s_lshl_b64 s[58:59], s[58:59], 7
	s_lshl_b32 s30, s30, 10
	v_lshl_add_u64 v[142:143], v[130:131], 0, s[58:59]
	s_add_i32 s30, s30, 0
	v_lshl_add_u64 v[192:193], v[142:143], 0, s[42:43]
	s_mov_b32 m0, s30
	v_lshl_add_u64 v[142:143], v[142:143], 0, s[44:45]
	v_xor_b32_e32 v192, v197, v192
	global_load_lds_dwordx4 v[192:193], off
	s_add_i32 m0, s30, 0x2000
	s_nop 0
	v_xor_b32_e32 v142, v197, v142
	global_load_lds_dwordx4 v[142:143], off
	s_barrier
	s_waitcnt lgkmcnt(0)
	s_setprio 1
	s_waitcnt lgkmcnt(0)
	v_mfma_f32_16x16x32_bf16 v[62:65], v[146:149], v[162:165], v[62:65]
	v_mfma_f32_16x16x32_bf16 v[58:61], v[154:157], v[162:165], v[58:61]
	v_mfma_f32_16x16x32_bf16 v[54:57], v[146:149], v[170:173], v[54:57]
	v_mfma_f32_16x16x32_bf16 v[50:53], v[154:157], v[170:173], v[50:53]
	v_mfma_f32_16x16x32_bf16 v[46:49], v[146:149], v[184:187], v[46:49]
	v_mfma_f32_16x16x32_bf16 v[42:45], v[154:157], v[184:187], v[42:45]
	v_mfma_f32_16x16x32_bf16 v[38:41], v[146:149], v[204:207], v[38:41]
	v_mfma_f32_16x16x32_bf16 v[34:37], v[154:157], v[204:207], v[34:37]
	v_mfma_f32_16x16x32_bf16 v[62:65], v[150:153], v[166:169], v[62:65]
	v_mfma_f32_16x16x32_bf16 v[58:61], v[158:161], v[166:169], v[58:61]
	v_mfma_f32_16x16x32_bf16 v[54:57], v[150:153], v[174:177], v[54:57]
	v_mfma_f32_16x16x32_bf16 v[50:53], v[158:161], v[174:177], v[50:53]
	v_mfma_f32_16x16x32_bf16 v[46:49], v[150:153], v[188:191], v[46:49]
	v_mfma_f32_16x16x32_bf16 v[42:45], v[158:161], v[188:191], v[42:45]
	v_mfma_f32_16x16x32_bf16 v[38:41], v[150:153], v[208:211], v[38:41]
	v_mfma_f32_16x16x32_bf16 v[34:37], v[158:161], v[208:211], v[34:37]
	s_setprio 0
	s_barrier
	s_mov_b32 s30, s57
	s_mov_b32 s58, s54
	s_ashr_i32 s59, s58, 31
	s_lshl_b64 s[58:59], s[58:59], 7
	s_lshl_b32 s30, s30, 10
	v_lshl_add_u64 v[142:143], v[132:133], 0, s[58:59]
	s_add_i32 s30, s30, 0
	s_add_i32 m0, s30, 0x14000
	v_lshl_add_u64 v[146:147], v[142:143], 0, s[46:47]
	v_xor_b32_e32 v146, v197, v146
	global_load_lds_dwordx4 v[146:147], off
	v_lshl_add_u64 v[142:143], v[142:143], 0, s[48:49]
	s_add_i32 m0, s30, 0x16000
	s_nop 0
	v_xor_b32_e32 v142, v197, v142
	global_load_lds_dwordx4 v[142:143], off
	s_waitcnt vmcnt(6)
	s_barrier
	s_setprio 1
	v_mfma_f32_16x16x32_bf16 v[30:33], v[212:215], v[162:165], v[30:33]
	v_mfma_f32_16x16x32_bf16 v[26:29], v[220:223], v[162:165], v[26:29]
	v_mfma_f32_16x16x32_bf16 v[22:25], v[212:215], v[170:173], v[22:25]
	v_mfma_f32_16x16x32_bf16 v[18:21], v[220:223], v[170:173], v[18:21]
	v_mfma_f32_16x16x32_bf16 v[14:17], v[212:215], v[184:187], v[14:17]
	v_mfma_f32_16x16x32_bf16 v[10:13], v[220:223], v[184:187], v[10:13]
	v_mfma_f32_16x16x32_bf16 v[6:9], v[212:215], v[204:207], v[6:9]
	v_mfma_f32_16x16x32_bf16 v[2:5], v[220:223], v[204:207], v[2:5]
	v_mfma_f32_16x16x32_bf16 v[30:33], v[216:219], v[166:169], v[30:33]
	v_mfma_f32_16x16x32_bf16 v[26:29], v[224:227], v[166:169], v[26:29]
	v_mfma_f32_16x16x32_bf16 v[22:25], v[216:219], v[174:177], v[22:25]
	v_mfma_f32_16x16x32_bf16 v[18:21], v[224:227], v[174:177], v[18:21]
	v_mfma_f32_16x16x32_bf16 v[14:17], v[216:219], v[188:191], v[14:17]
	v_mfma_f32_16x16x32_bf16 v[10:13], v[224:227], v[188:191], v[10:13]
	v_mfma_f32_16x16x32_bf16 v[6:9], v[216:219], v[208:211], v[6:9]
	v_mfma_f32_16x16x32_bf16 v[2:5], v[224:227], v[208:211], v[2:5]
	s_setprio 0
	s_barrier
	ds_read_b128 v[146:149], v139
	ds_read_b128 v[150:153], v139 offset:1024
	ds_read_b128 v[154:157], v139 offset:2048
	ds_read_b128 v[158:161], v139 offset:3072
	s_mov_b32 s30, s57
	ds_read_b128 v[162:165], v137 offset:32768
	ds_read_b128 v[166:169], v137 offset:33792
	ds_read_b128 v[170:173], v136 offset:32768
	ds_read_b128 v[174:177], v136 offset:33792
	ds_read_b128 v[184:187], v135 offset:32768
	ds_read_b128 v[188:191], v135 offset:33792
	ds_read_b128 v[204:207], v134 offset:32768
	ds_read_b128 v[208:211], v134 offset:33792
	s_ashr_i32 s55, s54, 31
	s_lshl_b64 s[54:55], s[54:55], 7
	s_lshl_b32 s30, s30, 10
	v_lshl_add_u64 v[142:143], v[130:131], 0, s[54:55]
	s_add_i32 s30, s30, 0
	s_add_i32 m0, s30, 0x4000
	v_lshl_add_u64 v[192:193], v[142:143], 0, s[50:51]
	v_xor_b32_e32 v192, v197, v192
	global_load_lds_dwordx4 v[192:193], off
	v_lshl_add_u64 v[142:143], v[142:143], 0, s[52:53]
	s_add_i32 m0, s30, 0x6000
	s_nop 0
	v_xor_b32_e32 v142, v197, v142
	global_load_lds_dwordx4 v[142:143], off
	s_waitcnt lgkmcnt(8)
	s_barrier
	s_waitcnt lgkmcnt(0)
	s_setprio 1
	s_waitcnt lgkmcnt(0)
	v_mfma_f32_16x16x32_bf16 v[126:129], v[146:149], v[162:165], v[126:129]
	v_mfma_f32_16x16x32_bf16 v[122:125], v[154:157], v[162:165], v[122:125]
	v_mfma_f32_16x16x32_bf16 v[118:121], v[146:149], v[170:173], v[118:121]
	v_mfma_f32_16x16x32_bf16 v[114:117], v[154:157], v[170:173], v[114:117]
	v_mfma_f32_16x16x32_bf16 v[110:113], v[146:149], v[184:187], v[110:113]
	v_mfma_f32_16x16x32_bf16 v[106:109], v[154:157], v[184:187], v[106:109]
	v_mfma_f32_16x16x32_bf16 v[102:105], v[146:149], v[204:207], v[102:105]
	v_mfma_f32_16x16x32_bf16 v[98:101], v[154:157], v[204:207], v[98:101]
	v_mfma_f32_16x16x32_bf16 v[126:129], v[150:153], v[166:169], v[126:129]
	v_mfma_f32_16x16x32_bf16 v[122:125], v[158:161], v[166:169], v[122:125]
	v_mfma_f32_16x16x32_bf16 v[118:121], v[150:153], v[174:177], v[118:121]
	v_mfma_f32_16x16x32_bf16 v[114:117], v[158:161], v[174:177], v[114:117]
	v_mfma_f32_16x16x32_bf16 v[110:113], v[150:153], v[188:191], v[110:113]
	v_mfma_f32_16x16x32_bf16 v[106:109], v[158:161], v[188:191], v[106:109]
	v_mfma_f32_16x16x32_bf16 v[102:105], v[150:153], v[208:211], v[102:105]
	v_mfma_f32_16x16x32_bf16 v[98:101], v[158:161], v[208:211], v[98:101]
	s_setprio 0
	s_barrier
; #define LDA(dst, b, h) _Pragma("unroll") for (int m = 0; m < 4; ++m) _Pragma("unroll") for (int k = 0; k < 2; ++k) \
;     dst[m][k] = *reinterpret_cast<const LAS bf16x8*>(lds + SAo(b, h) + lds_byte(wr * 64 + m * 16 + fr, k * 32 + fq * 8))
; #define LDB(dst, b, h) _Pragma("unroll") for (int n = 0; n < 2; ++n) _Pragma("unroll") for (int k = 0; k < 2; ++k) \
;     dst[n][k] = *reinterpret_cast<const LAS bf16x8*>(lds + SBo(b, h) + lds_byte(wc * 32 + n * 16 + fr, k * 32 + fq * 8))
; #define MMA(ai, bj, At_, Bt_) do { __builtin_amdgcn_s_setprio(1); \
;     _Pragma("unroll") for (int m = 0; m < 4; ++m) _Pragma("unroll") for (int n = 0; n < 2; ++n) _Pragma("unroll") for (int k = 0; k < 2; ++k) \
;       acc[ai][bj][m][n] = __builtin_amdgcn_mfma_f32_16x16x32_bf16(Bt_[n][k], At_[m][k], acc[ai][bj][m][n], 0, 0, 0); \
;     __builtin_amdgcn_s_setprio(0); } while (0)
; #define WAIT_V(n) asm volatile("s_waitcnt vmcnt(" #n ")" ::: "memory")
; #define WAIT_L(n) asm volatile("s_waitcnt lgkmcnt(" #n ")" ::: "memory")
; #define BAR __builtin_amdgcn_s_barrier()
; #define SCHED __builtin_amdgcn_sched_barrier(0)
; template <bool PRE = false>
; __device__ __forceinline__ void gemm_kloop(Acc& acc, const bf16_t* __restrict__ A, int lda, const bf16_t* __restrict__ Bt, int ldb,
;                                            int brow, int bcol, int nt, LAS unsigned char* lds) {
;     ...
;         LDB(B0, 1, 0); SCHED; LDA(At, 1, 0); STAGE(SAo(0, 1), A, lda, brow + HALF, t + 2, offA);
;         WAIT_L(8); BAR; WAIT_L(0); MMA(0, 0, At, B0); BAR; SCHED;
;         LDB(B1, 1, 1); STAGE(SBo(1, 0), Bt, ldb, bcol, t + 3, offB);
;         BAR; WAIT_L(0); MMA(0, 1, At, B1); BAR;
;         LDA(At, 1, 1); STAGE(SAo(1, 0), A, lda, brow, t + 3, offA);
;         BAR; WAIT_L(0); MMA(1, 0, At, B0); BAR; SCHED;
;         STAGE(SBo(1, 1), Bt, ldb, bcol + HALF, t + 3, offB);
;         WAIT_V(6); BAR; MMA(1, 1, At, B1); BAR;
;     }
	s_add_i32 s54, s1, 5
	s_mov_b32 s30, s57
	s_mov_b32 s58, s54
	ds_read_b128 v[212:215], v138
	ds_read_b128 v[216:219], v138 offset:1024
	ds_read_b128 v[220:223], v138 offset:2048
	ds_read_b128 v[224:227], v138 offset:3072
	s_ashr_i32 s59, s58, 31
	s_lshl_b64 s[58:59], s[58:59], 7
	s_lshl_b32 s30, s30, 10
	v_lshl_add_u64 v[142:143], v[132:133], 0, s[58:59]
	s_add_i32 s30, s30, 0
	s_add_i32 m0, s30, 0x18000
	v_lshl_add_u64 v[192:193], v[142:143], 0, s[12:13]
	v_xor_b32_e32 v192, v197, v192
	global_load_lds_dwordx4 v[192:193], off
	v_lshl_add_u64 v[142:143], v[142:143], 0, s[40:41]
	s_add_i32 m0, s30, 0x1a000
	s_nop 0
	v_xor_b32_e32 v142, v197, v142
	global_load_lds_dwordx4 v[142:143], off
	s_barrier
	s_waitcnt lgkmcnt(0)
	s_setprio 1
	s_waitcnt lgkmcnt(0)
	v_mfma_f32_16x16x32_bf16 v[94:97], v[212:215], v[162:165], v[94:97]
	v_mfma_f32_16x16x32_bf16 v[90:93], v[220:223], v[162:165], v[90:93]
	v_mfma_f32_16x16x32_bf16 v[86:89], v[212:215], v[170:173], v[86:89]
	v_mfma_f32_16x16x32_bf16 v[82:85], v[220:223], v[170:173], v[82:85]
	v_mfma_f32_16x16x32_bf16 v[78:81], v[212:215], v[184:187], v[78:81]
	v_mfma_f32_16x16x32_bf16 v[74:77], v[220:223], v[184:187], v[74:77]
	v_mfma_f32_16x16x32_bf16 v[70:73], v[212:215], v[204:207], v[70:73]
	v_mfma_f32_16x16x32_bf16 v[66:69], v[220:223], v[204:207], v[66:69]
	v_mfma_f32_16x16x32_bf16 v[94:97], v[216:219], v[166:169], v[94:97]
	v_mfma_f32_16x16x32_bf16 v[90:93], v[224:227], v[166:169], v[90:93]
	v_mfma_f32_16x16x32_bf16 v[86:89], v[216:219], v[174:177], v[86:89]
	v_mfma_f32_16x16x32_bf16 v[82:85], v[224:227], v[174:177], v[82:85]
	v_mfma_f32_16x16x32_bf16 v[78:81], v[216:219], v[188:191], v[78:81]
	v_mfma_f32_16x16x32_bf16 v[74:77], v[224:227], v[188:191], v[74:77]
	v_mfma_f32_16x16x32_bf16 v[70:73], v[216:219], v[208:211], v[70:73]
	v_mfma_f32_16x16x32_bf16 v[66:69], v[224:227], v[208:211], v[66:69]
	s_setprio 0
	s_mov_b32 s30, s57
	s_mov_b32 s58, s54
	s_barrier
	ds_read_b128 v[162:165], v137 offset:49152
	ds_read_b128 v[166:169], v137 offset:50176
	ds_read_b128 v[170:173], v136 offset:49152
	ds_read_b128 v[174:177], v136 offset:50176
	ds_read_b128 v[184:187], v135 offset:49152
	ds_read_b128 v[188:191], v135 offset:50176
	ds_read_b128 v[204:207], v134 offset:49152
	ds_read_b128 v[208:211], v134 offset:50176
	s_ashr_i32 s59, s58, 31
	s_lshl_b64 s[58:59], s[58:59], 7
	s_lshl_b32 s30, s30, 10
	v_lshl_add_u64 v[142:143], v[130:131], 0, s[58:59]
	s_add_i32 s30, s30, 0
	s_add_i32 m0, s30, 0x8000
	v_lshl_add_u64 v[192:193], v[142:143], 0, s[42:43]
	v_xor_b32_e32 v192, v197, v192
	global_load_lds_dwordx4 v[192:193], off
	v_lshl_add_u64 v[142:143], v[142:143], 0, s[44:45]
	s_add_i32 m0, s30, 0xa000
	s_nop 0
	v_xor_b32_e32 v142, v197, v142
	global_load_lds_dwordx4 v[142:143], off
	s_barrier
	s_waitcnt lgkmcnt(0)
	s_setprio 1
	s_waitcnt lgkmcnt(0)
	v_mfma_f32_16x16x32_bf16 v[62:65], v[146:149], v[162:165], v[62:65]
	v_mfma_f32_16x16x32_bf16 v[58:61], v[154:157], v[162:165], v[58:61]
	v_mfma_f32_16x16x32_bf16 v[54:57], v[146:149], v[170:173], v[54:57]
	v_mfma_f32_16x16x32_bf16 v[50:53], v[154:157], v[170:173], v[50:53]
	v_mfma_f32_16x16x32_bf16 v[46:49], v[146:149], v[184:187], v[46:49]
	v_mfma_f32_16x16x32_bf16 v[42:45], v[154:157], v[184:187], v[42:45]
	v_mfma_f32_16x16x32_bf16 v[38:41], v[146:149], v[204:207], v[38:41]
	v_mfma_f32_16x16x32_bf16 v[34:37], v[154:157], v[204:207], v[34:37]
	v_mfma_f32_16x16x32_bf16 v[62:65], v[150:153], v[166:169], v[62:65]
	v_mfma_f32_16x16x32_bf16 v[58:61], v[158:161], v[166:169], v[58:61]
	v_mfma_f32_16x16x32_bf16 v[54:57], v[150:153], v[174:177], v[54:57]
	v_mfma_f32_16x16x32_bf16 v[50:53], v[158:161], v[174:177], v[50:53]
	v_mfma_f32_16x16x32_bf16 v[46:49], v[150:153], v[188:191], v[46:49]
	v_mfma_f32_16x16x32_bf16 v[42:45], v[158:161], v[188:191], v[42:45]
	v_mfma_f32_16x16x32_bf16 v[38:41], v[150:153], v[208:211], v[38:41]
	v_mfma_f32_16x16x32_bf16 v[34:37], v[158:161], v[208:211], v[34:37]
	s_setprio 0
	s_barrier
	s_mov_b32 s30, s57
	s_ashr_i32 s55, s54, 31
	s_lshl_b64 s[54:55], s[54:55], 7
	s_lshl_b32 s30, s30, 10
	v_lshl_add_u64 v[142:143], v[132:133], 0, s[54:55]
	s_add_i32 s30, s30, 0
	s_add_i32 m0, s30, 0x1c000
	v_lshl_add_u64 v[146:147], v[142:143], 0, s[46:47]
	v_xor_b32_e32 v146, v197, v146
	global_load_lds_dwordx4 v[146:147], off
	v_lshl_add_u64 v[142:143], v[142:143], 0, s[48:49]
	s_add_i32 m0, s30, 0x1e000
	s_nop 0
	v_xor_b32_e32 v142, v197, v142
	global_load_lds_dwordx4 v[142:143], off
	s_waitcnt vmcnt(6)
	s_barrier
	s_setprio 1
	v_mfma_f32_16x16x32_bf16 v[30:33], v[212:215], v[162:165], v[30:33]
	v_mfma_f32_16x16x32_bf16 v[26:29], v[220:223], v[162:165], v[26:29]
	v_mfma_f32_16x16x32_bf16 v[22:25], v[212:215], v[170:173], v[22:25]
	v_mfma_f32_16x16x32_bf16 v[18:21], v[220:223], v[170:173], v[18:21]
	v_mfma_f32_16x16x32_bf16 v[14:17], v[212:215], v[184:187], v[14:17]
	v_mfma_f32_16x16x32_bf16 v[10:13], v[220:223], v[184:187], v[10:13]
	v_mfma_f32_16x16x32_bf16 v[6:9], v[212:215], v[204:207], v[6:9]
	v_mfma_f32_16x16x32_bf16 v[2:5], v[220:223], v[204:207], v[2:5]
	v_mfma_f32_16x16x32_bf16 v[30:33], v[216:219], v[166:169], v[30:33]
	v_mfma_f32_16x16x32_bf16 v[26:29], v[224:227], v[166:169], v[26:29]
	v_mfma_f32_16x16x32_bf16 v[22:25], v[216:219], v[174:177], v[22:25]
	v_mfma_f32_16x16x32_bf16 v[18:21], v[224:227], v[174:177], v[18:21]
	v_mfma_f32_16x16x32_bf16 v[14:17], v[216:219], v[188:191], v[14:17]
	v_mfma_f32_16x16x32_bf16 v[10:13], v[224:227], v[188:191], v[10:13]
	v_mfma_f32_16x16x32_bf16 v[6:9], v[216:219], v[208:211], v[6:9]
	v_mfma_f32_16x16x32_bf16 v[2:5], v[224:227], v[208:211], v[2:5]
	s_setprio 0
	s_add_i32 s1, s1, 2
	s_cmp_lt_u32 s1, 12
	s_barrier
; #define LDA(dst, b, h) _Pragma("unroll") for (int m = 0; m < 4; ++m) _Pragma("unroll") for (int k = 0; k < 2; ++k) \
;     dst[m][k] = *reinterpret_cast<const LAS bf16x8*>(lds + SAo(b, h) + lds_byte(wr * 64 + m * 16 + fr, k * 32 + fq * 8))
; #define LDB(dst, b, h) _Pragma("unroll") for (int n = 0; n < 2; ++n) _Pragma("unroll") for (int k = 0; k < 2; ++k) \
;     dst[n][k] = *reinterpret_cast<const LAS bf16x8*>(lds + SBo(b, h) + lds_byte(wc * 32 + n * 16 + fr, k * 32 + fq * 8))
; #define MMA(ai, bj, At_, Bt_) do { __builtin_amdgcn_s_setprio(1); \
;     _Pragma("unroll") for (int m = 0; m < 4; ++m) _Pragma("unroll") for (int n = 0; n < 2; ++n) _Pragma("unroll") for (int k = 0; k < 2; ++k) \
;       acc[ai][bj][m][n] = __builtin_amdgcn_mfma_f32_16x16x32_bf16(Bt_[n][k], At_[m][k], acc[ai][bj][m][n], 0, 0, 0); \
;     __builtin_amdgcn_s_setprio(0); } while (0)
; #define WAIT_V(n) asm volatile("s_waitcnt vmcnt(" #n ")" ::: "memory")
; #define WAIT_L(n) asm volatile("s_waitcnt lgkmcnt(" #n ")" ::: "memory")
; #define BAR __builtin_amdgcn_s_barrier()
; template <bool PRE = false>
; __device__ __forceinline__ void gemm_kloop(Acc& acc, const bf16_t* __restrict__ A, int lda, const bf16_t* __restrict__ Bt, int ldb,
;                                            int brow, int bcol, int nt, LAS unsigned char* lds) {
;     ...
;     }
;     { LDB(B0, 0, 0); LDA(At, 0, 0); STAGE(SAo(1, 1), A, lda, brow + HALF, nt - 1, offA);
;       BAR; WAIT_L(0); MMA(0, 0, At, B0); BAR;
;       LDB(B1, 0, 1); BAR; WAIT_L(0); MMA(0, 1, At, B1); BAR;
;       LDA(At, 0, 1); WAIT_V(4); BAR; WAIT_L(0); MMA(1, 0, At, B0); MMA(1, 1, At, B1); BAR; }
	s_cbranch_scc1 .LBB0_130
	s_mov_b32 s12, 15
	ds_read_b128 v[130:133], v141
	ds_read_b128 v[146:149], v141 offset:1024
	ds_read_b128 v[150:153], v141 offset:2048
	ds_read_b128 v[154:157], v141 offset:3072
	ds_read_b128 v[158:161], v137
	ds_read_b128 v[162:165], v137 offset:1024
	ds_read_b128 v[166:169], v136
	ds_read_b128 v[170:173], v136 offset:1024
	ds_read_b128 v[174:177], v135
	ds_read_b128 v[184:187], v135 offset:1024
	ds_read_b128 v[188:191], v134
	ds_read_b128 v[204:207], v134 offset:1024
	s_ashr_i32 s13, s12, 31
	s_lshl_b64 s[12:13], s[12:13], 7
	s_add_u32 s12, s34, s12
	s_addc_u32 s13, s35, s13
	s_lshl_b32 s1, s57, 10
	v_lshl_add_u64 v[142:143], s[12:13], 0, v[144:145]
	s_add_i32 s1, s1, 0
	s_add_i32 m0, s1, 0xc000
	v_lshl_add_u64 v[192:193], v[142:143], 0, s[50:51]
	v_xor_b32_e32 v192, v197, v192
	global_load_lds_dwordx4 v[192:193], off
	v_lshl_add_u64 v[142:143], v[142:143], 0, s[52:53]
	s_add_i32 m0, s1, 0xe000
	s_nop 0
	v_xor_b32_e32 v142, v197, v142
	global_load_lds_dwordx4 v[142:143], off
	s_barrier
	s_waitcnt lgkmcnt(0)
	s_setprio 1
	s_waitcnt lgkmcnt(0)
	v_mfma_f32_16x16x32_bf16 v[126:129], v[130:133], v[158:161], v[126:129]
	v_mfma_f32_16x16x32_bf16 v[118:121], v[130:133], v[166:169], v[118:121]
	v_mfma_f32_16x16x32_bf16 v[110:113], v[130:133], v[174:177], v[110:113]
	v_mfma_f32_16x16x32_bf16 v[102:105], v[130:133], v[188:191], v[102:105]
	v_mfma_f32_16x16x32_bf16 v[126:129], v[146:149], v[162:165], v[126:129]
	v_mfma_f32_16x16x32_bf16 v[122:125], v[150:153], v[158:161], v[122:125]
	v_mfma_f32_16x16x32_bf16 v[118:121], v[146:149], v[170:173], v[118:121]
	v_mfma_f32_16x16x32_bf16 v[114:117], v[150:153], v[166:169], v[114:117]
	v_mfma_f32_16x16x32_bf16 v[110:113], v[146:149], v[184:187], v[110:113]
	v_mfma_f32_16x16x32_bf16 v[106:109], v[150:153], v[174:177], v[106:109]
	v_mfma_f32_16x16x32_bf16 v[102:105], v[146:149], v[204:207], v[102:105]
	v_mfma_f32_16x16x32_bf16 v[98:101], v[150:153], v[188:191], v[98:101]
	v_mfma_f32_16x16x32_bf16 v[208:211], v[154:157], v[162:165], v[122:125]
	v_mfma_f32_16x16x32_bf16 v[212:215], v[154:157], v[170:173], v[114:117]
	v_mfma_f32_16x16x32_bf16 v[216:219], v[154:157], v[184:187], v[106:109]
	v_mfma_f32_16x16x32_bf16 v[220:223], v[154:157], v[204:207], v[98:101]
	s_setprio 0
	s_barrier
	s_nop 1
	ds_read_b128 v[98:101], v140
	ds_read_b128 v[106:109], v140 offset:1024
	ds_read_b128 v[114:117], v140 offset:2048
	ds_read_b128 v[122:125], v140 offset:3072
	s_barrier
	s_waitcnt lgkmcnt(0)
	s_setprio 1
	s_waitcnt lgkmcnt(0)
	v_mfma_f32_16x16x32_bf16 v[94:97], v[98:101], v[158:161], v[94:97]
	v_mfma_f32_16x16x32_bf16 v[86:89], v[98:101], v[166:169], v[86:89]
	v_mfma_f32_16x16x32_bf16 v[78:81], v[98:101], v[174:177], v[78:81]
	v_mfma_f32_16x16x32_bf16 v[70:73], v[98:101], v[188:191], v[70:73]
	v_mfma_f32_16x16x32_bf16 v[94:97], v[106:109], v[162:165], v[94:97]
	v_mfma_f32_16x16x32_bf16 v[90:93], v[114:117], v[158:161], v[90:93]
	v_mfma_f32_16x16x32_bf16 v[86:89], v[106:109], v[170:173], v[86:89]
	v_mfma_f32_16x16x32_bf16 v[82:85], v[114:117], v[166:169], v[82:85]
	v_mfma_f32_16x16x32_bf16 v[78:81], v[106:109], v[184:187], v[78:81]
	v_mfma_f32_16x16x32_bf16 v[74:77], v[114:117], v[174:177], v[74:77]
	v_mfma_f32_16x16x32_bf16 v[70:73], v[106:109], v[204:207], v[70:73]
	v_mfma_f32_16x16x32_bf16 v[66:69], v[114:117], v[188:191], v[66:69]
	v_mfma_f32_16x16x32_bf16 v[140:143], v[122:125], v[162:165], v[90:93]
	v_mfma_f32_16x16x32_bf16 v[158:161], v[122:125], v[170:173], v[82:85]
	v_mfma_f32_16x16x32_bf16 v[162:165], v[122:125], v[184:187], v[74:77]
	v_mfma_f32_16x16x32_bf16 v[166:169], v[122:125], v[204:207], v[66:69]
	s_setprio 0
	s_barrier
	s_nop 1
	ds_read_b128 v[66:69], v137 offset:16384
	ds_read_b128 v[74:77], v137 offset:17408
	ds_read_b128 v[82:85], v136 offset:16384
	ds_read_b128 v[90:93], v136 offset:17408
	ds_read_b128 v[170:173], v135 offset:16384
	ds_read_b128 v[174:177], v135 offset:17408
	ds_read_b128 v[184:187], v134 offset:16384
	ds_read_b128 v[188:191], v134 offset:17408
	s_waitcnt vmcnt(4)
	s_barrier
	s_waitcnt lgkmcnt(0)
	s_setprio 1
	s_waitcnt lgkmcnt(0)
	v_mfma_f32_16x16x32_bf16 v[62:65], v[130:133], v[66:69], v[62:65]
	v_mfma_f32_16x16x32_bf16 v[54:57], v[130:133], v[82:85], v[54:57]
	v_mfma_f32_16x16x32_bf16 v[46:49], v[130:133], v[170:173], v[46:49]
	v_mfma_f32_16x16x32_bf16 v[38:41], v[130:133], v[184:187], v[38:41]
	v_mfma_f32_16x16x32_bf16 v[62:65], v[146:149], v[74:77], v[62:65]
	v_mfma_f32_16x16x32_bf16 v[58:61], v[150:153], v[66:69], v[58:61]
	v_mfma_f32_16x16x32_bf16 v[54:57], v[146:149], v[90:93], v[54:57]
	v_mfma_f32_16x16x32_bf16 v[50:53], v[150:153], v[82:85], v[50:53]
	v_mfma_f32_16x16x32_bf16 v[46:49], v[146:149], v[174:177], v[46:49]
	v_mfma_f32_16x16x32_bf16 v[42:45], v[150:153], v[170:173], v[42:45]
	v_mfma_f32_16x16x32_bf16 v[38:41], v[146:149], v[188:191], v[38:41]
	v_mfma_f32_16x16x32_bf16 v[34:37], v[150:153], v[184:187], v[34:37]
	v_mfma_f32_16x16x32_bf16 v[204:207], v[154:157], v[74:77], v[58:61]
	v_mfma_f32_16x16x32_bf16 v[224:227], v[154:157], v[90:93], v[50:53]
	v_mfma_f32_16x16x32_bf16 v[228:231], v[154:157], v[174:177], v[42:45]
	v_mfma_f32_16x16x32_bf16 v[130:133], v[154:157], v[188:191], v[34:37]
	s_setprio 0
	s_setprio 1
	v_mfma_f32_16x16x32_bf16 v[30:33], v[98:101], v[66:69], v[30:33]
	v_mfma_f32_16x16x32_bf16 v[22:25], v[98:101], v[82:85], v[22:25]
	v_mfma_f32_16x16x32_bf16 v[14:17], v[98:101], v[170:173], v[14:17]
	v_mfma_f32_16x16x32_bf16 v[6:9], v[98:101], v[184:187], v[6:9]
	v_mfma_f32_16x16x32_bf16 v[30:33], v[106:109], v[74:77], v[30:33]
	v_mfma_f32_16x16x32_bf16 v[26:29], v[114:117], v[66:69], v[26:29]
	v_mfma_f32_16x16x32_bf16 v[22:25], v[106:109], v[90:93], v[22:25]
	v_mfma_f32_16x16x32_bf16 v[18:21], v[114:117], v[82:85], v[18:21]
	v_mfma_f32_16x16x32_bf16 v[14:17], v[106:109], v[174:177], v[14:17]
	v_mfma_f32_16x16x32_bf16 v[10:13], v[114:117], v[170:173], v[10:13]
	v_mfma_f32_16x16x32_bf16 v[6:9], v[106:109], v[188:191], v[6:9]
	v_mfma_f32_16x16x32_bf16 v[2:5], v[114:117], v[184:187], v[2:5]
	v_mfma_f32_16x16x32_bf16 v[146:149], v[122:125], v[74:77], v[26:29]
	v_mfma_f32_16x16x32_bf16 v[150:153], v[122:125], v[90:93], v[18:21]
	v_mfma_f32_16x16x32_bf16 v[154:157], v[122:125], v[174:177], v[10:13]
	v_mfma_f32_16x16x32_bf16 v[170:173], v[122:125], v[188:191], v[2:5]
	s_setprio 0
	s_barrier
; #define LDA(dst, b, h) _Pragma("unroll") for (int m = 0; m < 4; ++m) _Pragma("unroll") for (int k = 0; k < 2; ++k) \
;     dst[m][k] = *reinterpret_cast<const LAS bf16x8*>(lds + SAo(b, h) + lds_byte(wr * 64 + m * 16 + fr, k * 32 + fq * 8))
; #define LDB(dst, b, h) _Pragma("unroll") for (int n = 0; n < 2; ++n) _Pragma("unroll") for (int k = 0; k < 2; ++k) \
;     dst[n][k] = *reinterpret_cast<const LAS bf16x8*>(lds + SBo(b, h) + lds_byte(wc * 32 + n * 16 + fr, k * 32 + fq * 8))
; #define MMA(ai, bj, At_, Bt_) do { __builtin_amdgcn_s_setprio(1); \
;     _Pragma("unroll") for (int m = 0; m < 4; ++m) _Pragma("unroll") for (int n = 0; n < 2; ++n) _Pragma("unroll") for (int k = 0; k < 2; ++k) \
;       acc[ai][bj][m][n] = __builtin_amdgcn_mfma_f32_16x16x32_bf16(Bt_[n][k], At_[m][k], acc[ai][bj][m][n], 0, 0, 0); \
;     __builtin_amdgcn_s_setprio(0); } while (0)
; #define WAIT_V(n) asm volatile("s_waitcnt vmcnt(" #n ")" ::: "memory")
; #define WAIT_L(n) asm volatile("s_waitcnt lgkmcnt(" #n ")" ::: "memory")
; #define BAR __builtin_amdgcn_s_barrier()
; template <bool PRE = false>
; __device__ __forceinline__ void gemm_kloop(Acc& acc, const bf16_t* __restrict__ A, int lda, const bf16_t* __restrict__ Bt, int ldb,
;                                            int brow, int bcol, int nt, LAS unsigned char* lds) {
;     ...
;       LDA(At, 0, 1); WAIT_V(4); BAR; WAIT_L(0); MMA(1, 0, At, B0); MMA(1, 1, At, B1); BAR; }
;     { LDB(B0, 1, 0); LDA(At, 1, 0); WAIT_V(2); BAR; WAIT_L(0); MMA(0, 0, At, B0); BAR;
;       LDB(B1, 1, 1); WAIT_V(0); BAR; WAIT_L(0); MMA(0, 1, At, B1); BAR;
;       LDA(At, 1, 1); BAR; WAIT_L(0); MMA(1, 0, At, B0); MMA(1, 1, At, B1); BAR; }
;     if (wr == 0) BAR;
	s_nop 1
	ds_read_b128 v[2:5], v139
	ds_read_b128 v[10:13], v139 offset:1024
	ds_read_b128 v[174:177], v139 offset:2048
	ds_read_b128 v[184:187], v139 offset:3072
	ds_read_b128 v[18:21], v137 offset:32768
	ds_read_b128 v[26:29], v137 offset:33792
	ds_read_b128 v[34:37], v136 offset:32768
	ds_read_b128 v[42:45], v136 offset:33792
	ds_read_b128 v[50:53], v135 offset:32768
	ds_read_b128 v[58:61], v135 offset:33792
	ds_read_b128 v[188:191], v134 offset:32768
	ds_read_b128 v[232:235], v134 offset:33792
	s_waitcnt vmcnt(2)
	s_barrier
	s_waitcnt lgkmcnt(0)
	s_setprio 1
	s_waitcnt lgkmcnt(0)
	v_mfma_f32_16x16x32_bf16 v[66:69], v[2:5], v[18:21], v[126:129]
	v_mfma_f32_16x16x32_bf16 v[122:125], v[10:13], v[26:29], v[66:69]
	v_mfma_f32_16x16x32_bf16 v[66:69], v[174:177], v[18:21], v[208:211]
	v_mfma_f32_16x16x32_bf16 v[114:117], v[184:187], v[26:29], v[66:69]
	v_mfma_f32_16x16x32_bf16 v[66:69], v[2:5], v[34:37], v[118:121]
	v_mfma_f32_16x16x32_bf16 v[106:109], v[10:13], v[42:45], v[66:69]
	v_mfma_f32_16x16x32_bf16 v[66:69], v[174:177], v[34:37], v[212:215]
	v_mfma_f32_16x16x32_bf16 v[98:101], v[184:187], v[42:45], v[66:69]
	v_mfma_f32_16x16x32_bf16 v[66:69], v[2:5], v[50:53], v[110:113]
	v_mfma_f32_16x16x32_bf16 v[90:93], v[10:13], v[58:61], v[66:69]
	v_mfma_f32_16x16x32_bf16 v[66:69], v[174:177], v[50:53], v[216:219]
	v_mfma_f32_16x16x32_bf16 v[82:85], v[184:187], v[58:61], v[66:69]
	v_mfma_f32_16x16x32_bf16 v[66:69], v[2:5], v[188:191], v[102:105]
	v_mfma_f32_16x16x32_bf16 v[74:77], v[10:13], v[232:235], v[66:69]
	v_mfma_f32_16x16x32_bf16 v[66:69], v[174:177], v[188:191], v[220:223]
	v_mfma_f32_16x16x32_bf16 v[66:69], v[184:187], v[232:235], v[66:69]
	s_setprio 0
	s_barrier
	ds_read_b128 v[208:211], v138
	ds_read_b128 v[212:215], v138 offset:1024
	ds_read_b128 v[216:219], v138 offset:2048
	ds_read_b128 v[220:223], v138 offset:3072
	s_waitcnt vmcnt(0)
	s_barrier
	s_waitcnt lgkmcnt(0)
	s_setprio 1
	s_waitcnt lgkmcnt(0)
	v_mfma_f32_16x16x32_bf16 v[94:97], v[208:211], v[18:21], v[94:97]
	v_mfma_f32_16x16x32_bf16 v[18:21], v[216:219], v[18:21], v[140:143]
	v_mfma_f32_16x16x32_bf16 v[118:121], v[220:223], v[26:29], v[18:21]
	v_mfma_f32_16x16x32_bf16 v[18:21], v[208:211], v[34:37], v[86:89]
	v_mfma_f32_16x16x32_bf16 v[110:113], v[212:215], v[42:45], v[18:21]
	v_mfma_f32_16x16x32_bf16 v[18:21], v[216:219], v[34:37], v[158:161]
	v_mfma_f32_16x16x32_bf16 v[102:105], v[220:223], v[42:45], v[18:21]
	v_mfma_f32_16x16x32_bf16 v[18:21], v[208:211], v[50:53], v[78:81]
	v_mfma_f32_16x16x32_bf16 v[126:129], v[212:215], v[26:29], v[94:97]
	v_mfma_f32_16x16x32_bf16 v[94:97], v[212:215], v[58:61], v[18:21]
	v_mfma_f32_16x16x32_bf16 v[18:21], v[216:219], v[50:53], v[162:165]
	v_mfma_f32_16x16x32_bf16 v[86:89], v[220:223], v[58:61], v[18:21]
	v_mfma_f32_16x16x32_bf16 v[18:21], v[208:211], v[188:191], v[70:73]
	v_mfma_f32_16x16x32_bf16 v[78:81], v[212:215], v[232:235], v[18:21]
	v_mfma_f32_16x16x32_bf16 v[18:21], v[216:219], v[188:191], v[166:169]
	v_mfma_f32_16x16x32_bf16 v[70:73], v[220:223], v[232:235], v[18:21]
	s_setprio 0
	s_barrier
	ds_read_b128 v[138:141], v137 offset:49152
	ds_read_b128 v[158:161], v137 offset:50176
	ds_read_b128 v[162:165], v136 offset:49152
	ds_read_b128 v[166:169], v136 offset:50176
	ds_read_b128 v[188:191], v135 offset:49152
	ds_read_b128 v[232:235], v135 offset:50176
	ds_read_b128 v[236:239], v134 offset:49152
	ds_read_b128 v[134:137], v134 offset:50176
	s_barrier
	s_waitcnt lgkmcnt(0)
	s_setprio 1
	s_waitcnt lgkmcnt(0)
	v_mfma_f32_16x16x32_bf16 v[18:21], v[2:5], v[138:141], v[62:65]
	v_mfma_f32_16x16x32_bf16 v[58:61], v[10:13], v[158:161], v[18:21]
	v_mfma_f32_16x16x32_bf16 v[18:21], v[174:177], v[138:141], v[204:207]
	v_mfma_f32_16x16x32_bf16 v[50:53], v[184:187], v[158:161], v[18:21]
	v_mfma_f32_16x16x32_bf16 v[18:21], v[2:5], v[162:165], v[54:57]
	v_mfma_f32_16x16x32_bf16 v[42:45], v[10:13], v[166:169], v[18:21]
	v_mfma_f32_16x16x32_bf16 v[18:21], v[174:177], v[162:165], v[224:227]
	v_mfma_f32_16x16x32_bf16 v[34:37], v[184:187], v[166:169], v[18:21]
	v_mfma_f32_16x16x32_bf16 v[18:21], v[2:5], v[188:191], v[46:49]
	v_mfma_f32_16x16x32_bf16 v[2:5], v[2:5], v[236:239], v[38:41]
	v_mfma_f32_16x16x32_bf16 v[26:29], v[10:13], v[232:235], v[18:21]
	v_mfma_f32_16x16x32_bf16 v[18:21], v[174:177], v[188:191], v[228:231]
	v_mfma_f32_16x16x32_bf16 v[10:13], v[10:13], v[134:137], v[2:5]
	v_mfma_f32_16x16x32_bf16 v[2:5], v[174:177], v[236:239], v[130:133]
	v_mfma_f32_16x16x32_bf16 v[18:21], v[184:187], v[232:235], v[18:21]
	v_mfma_f32_16x16x32_bf16 v[2:5], v[184:187], v[134:137], v[2:5]
	s_setprio 0
	s_setprio 1
	v_mfma_f32_16x16x32_bf16 v[30:33], v[208:211], v[138:141], v[30:33]
	v_mfma_f32_16x16x32_bf16 v[62:65], v[212:215], v[158:161], v[30:33]
	v_mfma_f32_16x16x32_bf16 v[30:33], v[216:219], v[138:141], v[146:149]
	v_mfma_f32_16x16x32_bf16 v[22:25], v[208:211], v[162:165], v[22:25]
	v_mfma_f32_16x16x32_bf16 v[14:17], v[208:211], v[188:191], v[14:17]
	v_mfma_f32_16x16x32_bf16 v[54:57], v[220:223], v[158:161], v[30:33]
	v_mfma_f32_16x16x32_bf16 v[46:49], v[212:215], v[166:169], v[22:25]
	v_mfma_f32_16x16x32_bf16 v[22:25], v[216:219], v[162:165], v[150:153]
	v_mfma_f32_16x16x32_bf16 v[30:33], v[212:215], v[232:235], v[14:17]
	v_mfma_f32_16x16x32_bf16 v[14:17], v[216:219], v[188:191], v[154:157]
	v_mfma_f32_16x16x32_bf16 v[6:9], v[208:211], v[236:239], v[6:9]
	v_mfma_f32_16x16x32_bf16 v[38:41], v[220:223], v[166:169], v[22:25]
	v_mfma_f32_16x16x32_bf16 v[22:25], v[220:223], v[232:235], v[14:17]
	v_mfma_f32_16x16x32_bf16 v[14:17], v[212:215], v[134:137], v[6:9]
	v_mfma_f32_16x16x32_bf16 v[6:9], v[216:219], v[236:239], v[170:173]
	v_mfma_f32_16x16x32_bf16 v[6:9], v[220:223], v[134:137], v[6:9]
	s_setprio 0
	v_cmp_gt_u32_e32 vcc, s85, v1
	s_barrier
	s_and_saveexec_b64 s[12:13], vcc
	s_cbranch_execz .LBB0_133
	s_barrier
; #define LAS __attribute__((address_space(3)))
; __device__ __forceinline__ int fresh_tid() { int t; asm volatile("v_mov_b32 %0, %1" : "=v"(t) : "v"(threadIdx.x)); return t; }
; __device__ __forceinline__ int fresh_bid() { int t; asm volatile("s_mov_b32 %0, %1" : "=s"(t) : "s"(blockIdx.x)); return t; }
; #define ACC_ZERO(acc) _Pragma("unroll") for (int _a = 0; _a < 2; ++_a) _Pragma("unroll") for (int _b = 0; _b < 2; ++_b) _Pragma("unroll") for (int _m = 0; _m < 4; ++_m) \
;     _Pragma("unroll") for (int _n = 0; _n < 2; ++_n) acc[_a][_b][_m][_n] = (f32x4){0.f, 0.f, 0.f, 0.f}
; __device__ __forceinline__ void gemm_stage_first(const bf16_t* __restrict__ A, int lda, const bf16_t* __restrict__ Bt, int ldb, int brow, int bcol, LAS unsigned char* lds) {
;     const int tid = fresh_tid();
;     const int wvu = __builtin_amdgcn_readfirstlane(tid >> 6);
;     unsigned offA, offB;
;     { int _r, _c; stage_rc(tid * 16, _r, _c); offA = (unsigned)(_r * lda + _c) * 2u; offB = (unsigned)(_r * ldb + _c) * 2u; }
;     STAGE(SBo(0, 0), Bt, ldb, bcol, 0, offB); STAGE(SAo(0, 0), A, lda, brow, 0, offA);
;     STAGE(SBo(0, 1), Bt, ldb, bcol + HALF, 0, offB); STAGE(SAo(0, 1), A, lda, brow + HALF, 0, offA);
; }
; __device__ __forceinline__ void phase_ffn1(const Ctx& a, const bf16_t* W, LAS unsigned char* lds) {
;     ...
;     for (int w = fresh_bid(); w < ntile; w += gridDim.x) {
;         int pm, pn; tile_of(w, nM, pm, pn);
;         Acc acc; ACC_ZERO(acc);
;         gemm_kloop<true>(acc, xb, DM, W, DM, pm * 256, pn * 256, DM / 64, lds);
;         { const int wn = w + (int)gridDim.x; if (wn < ntile) { int pm2, pn2; tile_of(wn, nM, pm2, pn2); gemm_stage_first(xb, DM, W, DM, pm2 * 256, pn2 * 256, lds); } }
.LBB0_133:
	s_or_b64 exec, exec, s[12:13]
	s_load_dword s1, s[74:75], 0x0
	s_waitcnt lgkmcnt(0)
	s_add_i32 s26, s1, s26
	s_cmpk_gt_i32 s26, 0x57f
	s_cselect_b64 s[12:13], -1, 0
	s_and_b64 vcc, exec, s[12:13]
	s_cbranch_vccnz .LBB0_126
	s_ashr_i32 s1, s26, 31
	s_lshr_b32 s1, s1, 26
	s_add_i32 s1, s26, s1
	v_mov_b32 v1, v179
	s_and_b32 s30, s1, 0xffffc0
	v_ashrrev_i32_e32 v131, 31, v1
	s_lshl_b32 s1, s1, 2
	v_lshrrev_b32_e32 v131, 26, v131
	s_and_b32 s42, s1, 0xffffff00
	v_readfirstlane_b32 s1, v1
	v_lshlrev_b32_e32 v130, 4, v1
	v_add_u32_e32 v131, v1, v131
	v_bfe_i32 v1, v1, 27, 1
	v_lshrrev_b32_e32 v1, 22, v1
	v_add_u32_e32 v1, v130, v1
	v_and_b32_e32 v1, 0xfffffc00, v1
	v_sub_u32_e32 v1, v130, v1
	v_lshrrev_b32_e32 v130, 4, v1
	v_bitop3_b32 v130, v130, v1, 32 bitop3:0x6c
	v_ashrrev_i32_e32 v1, 31, v1
	v_lshrrev_b32_e32 v1, 26, v1
	v_add_u32_e32 v1, v130, v1
	s_sub_i32 s30, s26, s30
	s_ashr_i32 s1, s1, 6
	v_ashrrev_i32_e32 v1, 6, v1
	s_lshl_b32 s40, s30, 8
	v_ashrrev_i32_e32 v131, 6, v131
	v_mul_i32_i24_e32 v133, 64, v1
	s_mov_b32 s44, s27
	s_mov_b32 s30, s1
	v_lshlrev_b32_e32 v132, 3, v131
	v_lshlrev_b32_e32 v131, 5, v131
	v_sub_u32_e32 v130, v130, v133
	s_ashr_i32 s45, s44, 31
	v_and_b32_e32 v132, 0x1ffff0, v132
	v_and_b32_e32 v131, 32, v131
	v_ashrrev_i16_sdwa v130, v194, sext(v130) dst_sel:DWORD dst_unused:UNUSED_PAD src0_sel:DWORD src1_sel:BYTE_0
	s_lshl_b64 s[44:45], s[44:45], 7
	v_add_u32_sdwa v130, v131, sext(v130) dst_sel:DWORD dst_unused:UNUSED_PAD src0_sel:DWORD src1_sel:WORD_0
	v_add_lshl_u32 v1, v1, v132, 11
	s_add_u32 s44, s76, s44
	v_lshl_add_u32 v144, v130, 1, v1
	s_addc_u32 s45, s77, s45
	s_ashr_i32 s43, s42, 31
	v_lshl_add_u64 v[130:131], s[44:45], 0, v[144:145]
	s_lshl_b64 s[44:45], s[42:43], 11
	s_lshl_b32 s30, s30, 10
	v_lshl_add_u64 v[132:133], v[130:131], 0, s[44:45]
	s_or_b32 s44, s42, 64
	s_add_i32 s30, s30, 0
	s_ashr_i32 s45, s44, 31
	s_add_i32 m0, s30, 0x10000
	s_lshl_b64 s[44:45], s[44:45], 11
	v_xor_b32_e32 v132, v197, v132
	global_load_lds_dwordx4 v[132:133], off
	v_lshl_add_u64 v[130:131], v[130:131], 0, s[44:45]
	s_add_i32 m0, s30, 0x12000
	s_mov_b32 s44, s27
	s_mov_b32 s30, s1
	v_xor_b32_e32 v130, v197, v130
	global_load_lds_dwordx4 v[130:131], off
	s_ashr_i32 s45, s44, 31
	s_lshl_b64 s[44:45], s[44:45], 7
	s_add_u32 s44, s34, s44
	s_addc_u32 s45, s35, s45
	s_ashr_i32 s41, s40, 31
	v_lshl_add_u64 v[130:131], s[44:45], 0, v[144:145]
	s_lshl_b64 s[44:45], s[40:41], 11
	s_lshl_b32 s30, s30, 10
	v_lshl_add_u64 v[132:133], v[130:131], 0, s[44:45]
	s_or_b32 s44, s40, 64
	s_add_i32 s30, s30, 0
	s_ashr_i32 s45, s44, 31
	s_mov_b32 m0, s30
	s_lshl_b64 s[44:45], s[44:45], 11
	v_xor_b32_e32 v132, v197, v132
	global_load_lds_dwordx4 v[132:133], off
	v_lshl_add_u64 v[130:131], v[130:131], 0, s[44:45]
	s_add_i32 m0, s30, 0x2000
	s_mov_b32 s44, s27
	s_mov_b32 s30, s1
	v_xor_b32_e32 v130, v197, v130
	global_load_lds_dwordx4 v[130:131], off
	s_ashr_i32 s45, s44, 31
	s_or_b32 s46, s42, 0x80
	s_lshl_b64 s[44:45], s[44:45], 7
	s_add_u32 s44, s76, s44
	s_addc_u32 s45, s77, s45
	s_lshl_b32 s30, s30, 10
	s_ashr_i32 s47, s46, 31
	s_or_b32 s42, s42, 0xc0
	v_lshl_add_u64 v[130:131], s[44:45], 0, v[144:145]
	s_add_i32 s30, s30, 0
	s_lshl_b64 s[44:45], s[46:47], 11
	s_ashr_i32 s43, s42, 31
	s_add_i32 m0, s30, 0x14000
	v_lshl_add_u64 v[132:133], v[130:131], 0, s[44:45]
	s_lshl_b64 s[42:43], s[42:43], 11
	v_xor_b32_e32 v132, v197, v132
	global_load_lds_dwordx4 v[132:133], off
	v_lshl_add_u64 v[130:131], v[130:131], 0, s[42:43]
	s_add_i32 m0, s30, 0x16000
	s_mov_b32 s42, s27
	v_xor_b32_e32 v130, v197, v130
	global_load_lds_dwordx4 v[130:131], off
	s_ashr_i32 s43, s42, 31
	s_or_b32 s44, s40, 0x80
	s_lshl_b64 s[42:43], s[42:43], 7
	s_add_u32 s42, s34, s42
	s_addc_u32 s43, s35, s43
	s_lshl_b32 s1, s1, 10
	s_ashr_i32 s45, s44, 31
	s_or_b32 s40, s40, 0xc0
	v_lshl_add_u64 v[130:131], s[42:43], 0, v[144:145]
	s_add_i32 s1, s1, 0
	s_lshl_b64 s[42:43], s[44:45], 11
	s_ashr_i32 s41, s40, 31
	s_add_i32 m0, s1, 0x4000
	v_lshl_add_u64 v[132:133], v[130:131], 0, s[42:43]
	s_lshl_b64 s[40:41], s[40:41], 11
	v_xor_b32_e32 v132, v197, v132
	global_load_lds_dwordx4 v[132:133], off
	v_lshl_add_u64 v[130:131], v[130:131], 0, s[40:41]
	s_add_i32 m0, s1, 0x6000
	s_nop 0
	v_xor_b32_e32 v130, v197, v130
	global_load_lds_dwordx4 v[130:131], off
	s_branch .LBB0_126

; __device__ __forceinline__ int fresh_tid() { int t; asm volatile("v_mov_b32 %0, %1" : "=v"(t) : "v"(threadIdx.x)); return t; }
; #define BAR __builtin_amdgcn_s_barrier()
; template <bool PRE = false>
; __device__ __forceinline__ void gemm_kloop(Acc& acc, const bf16_t* __restrict__ A, int lda, const bf16_t* __restrict__ Bt, int ldb,
;                                            int brow, int bcol, int nt, LAS unsigned char* lds) {
;     const int tid = fresh_tid();
;     const int wid = tid >> 6, lane = tid & 63, wr = wid >> 2, wc = wid & 3, fr = lane & 15, fq = lane >> 4;
;     const int wvu = __builtin_amdgcn_readfirstlane(tid >> 6);
;     unsigned offA, offB;
;     { int _r, _c; stage_rc(tid * 16, _r, _c); offA = (unsigned)(_r * lda + _c) * 2u; offB = (unsigned)(_r * ldb + _c) * 2u; }
;     ...
;     bf16x8 At[4][2], B0[2][2], B1[2][2];
;     if (!PRE) {
;     STAGE(SBo(0, 0), Bt, ldb, bcol, 0, offB); STAGE(SAo(0, 0), A, lda, brow, 0, offA);
;     STAGE(SBo(0, 1), Bt, ldb, bcol + HALF, 0, offB); STAGE(SAo(0, 1), A, lda, brow + HALF, 0, offA);
;     }
;     if (wr == 1) BAR;
.LBB0_327:
	v_mov_b32 v1, v179
	s_ashr_i32 s0, s9, 31
	s_waitcnt vmcnt(0) lgkmcnt(0)
	v_bfe_i32 v5, v1, 27, 1
	v_lshlrev_b32_e32 v2, 4, v1
	v_lshrrev_b32_e32 v5, 22, v5
	v_add_u32_e32 v5, v2, v5
	v_and_b32_e32 v5, 0xfffffc00, v5
	v_ashrrev_i32_e32 v3, 31, v1
	v_sub_u32_e32 v2, v2, v5
	v_lshrrev_b32_e32 v3, 26, v3
	v_lshrrev_b32_e32 v5, 4, v2
	v_add_u32_e32 v3, v1, v3
	v_bitop3_b32 v5, v5, v2, 32 bitop3:0x6c
	v_ashrrev_i32_e32 v2, 31, v2
	v_ashrrev_i32_e32 v3, 6, v3
	v_lshrrev_b32_e32 v2, 26, v2
	s_lshr_b32 s0, s0, 27
	v_lshlrev_b32_e32 v6, 3, v3
	v_add_u32_e32 v2, v5, v2
	s_add_i32 s0, s9, s0
	v_and_b32_e32 v6, -16, v6
	v_ashrrev_i32_e32 v2, 6, v2
	s_and_b32 s1, s0, 0xffffe0
	v_add_u32_e32 v8, v2, v6
	v_mul_i32_i24_e32 v2, 64, v2
	s_sub_i32 s1, s9, s1
	v_ashrrev_i32_e32 v4, 6, v1
	v_lshlrev_b32_e32 v3, 5, v3
	v_sub_u32_e32 v2, v5, v2
	s_lshl_b32 s12, s1, 8
	v_readfirstlane_b32 s26, v4
	v_and_b32_e32 v3, 32, v3
	v_ashrrev_i16_sdwa v2, v194, sext(v2) dst_sel:DWORD dst_unused:UNUSED_PAD src0_sel:DWORD src1_sel:BYTE_0
	s_movk_i32 s1, 0x180
	v_add_u32_sdwa v5, v3, sext(v2) dst_sel:DWORD dst_unused:UNUSED_PAD src0_sel:DWORD src1_sel:WORD_0
	v_mul_lo_u32 v2, v8, s1
	s_mov_b32 s1, s26
	s_mov_b32 s36, s27
	s_lshl_b32 s0, s0, 3
	s_ashr_i32 s37, s36, 31
	s_and_b32 s0, s0, 0xffffff00
	s_lshl_b64 s[36:37], s[36:37], 7
	s_add_u32 s36, s90, s36
	v_add_lshl_u32 v144, v5, v2, 1
	s_addc_u32 s37, s91, s37
	s_lshl_b32 s1, s1, 10
	v_lshl_add_u64 v[2:3], s[36:37], 0, v[144:145]
	s_add_i32 s8, s1, 0
	s_mul_hi_i32 s37, s0, 0x180
	s_mul_i32 s36, s0, 0x180
	s_or_b32 s13, s0, 64
	s_add_i32 m0, s8, 0x10000
	v_lshl_add_u64 v[6:7], s[36:37], 1, v[2:3]
	s_mul_hi_i32 s39, s13, 0x180
	s_mul_i32 s38, s13, 0x180
	v_xor_b32_e32 v6, v197, v6
	global_load_lds_dwordx4 v[6:7], off
	v_lshl_add_u64 v[2:3], s[38:39], 1, v[2:3]
	s_add_i32 m0, s8, 0x12000
	s_mov_b32 s8, s26
	s_mov_b32 s40, s27
	v_xor_b32_e32 v2, v197, v2
	global_load_lds_dwordx4 v[2:3], off
	s_ashr_i32 s41, s40, 31
	s_ashr_i32 s1, s0, 31
	s_lshl_b64 s[40:41], s[40:41], 7
	v_lshlrev_b32_e32 v2, 13, v8
	s_add_u32 s40, s70, s40
	v_lshl_add_u32 v2, v5, 1, v2
	s_addc_u32 s41, s71, s41
	v_mov_b32_e32 v3, v145
	s_lshl_b32 s8, s8, 10
	s_ashr_i32 s13, s12, 31
	s_or_b32 s46, s12, 64
	v_lshl_add_u64 v[6:7], s[40:41], 0, v[2:3]
	s_add_i32 s8, s8, 0
	s_lshl_b64 s[42:43], s[12:13], 13
	s_ashr_i32 s47, s46, 31
	v_lshl_add_u64 v[8:9], v[6:7], 0, s[42:43]
	s_mov_b32 m0, s8
	s_lshl_b64 s[42:43], s[46:47], 12
	s_lshl_b64 s[46:47], s[46:47], 13
	v_xor_b32_e32 v8, v197, v8
	global_load_lds_dwordx4 v[8:9], off
	v_lshl_add_u64 v[6:7], v[6:7], 0, s[46:47]
	s_add_i32 m0, s8, 0x2000
	s_mov_b32 s8, s26
	s_mov_b32 s46, s27
	v_xor_b32_e32 v6, v197, v6
	global_load_lds_dwordx4 v[6:7], off
	s_ashr_i32 s47, s46, 31
	s_lshl_b64 s[40:41], s[12:13], 12
	s_or_b32 s13, s0, 0x80
	s_lshl_b64 s[46:47], s[46:47], 7
	s_add_u32 s46, s90, s46
	s_addc_u32 s47, s91, s47
	s_lshl_b32 s8, s8, 10
	v_lshl_add_u64 v[6:7], s[46:47], 0, v[144:145]
	s_add_i32 s8, s8, 0
	s_mul_hi_i32 s55, s13, 0x180
	s_mul_i32 s54, s13, 0x180
	s_or_b32 s13, s0, 0xc0
	s_add_i32 m0, s8, 0x14000
	v_lshl_add_u64 v[8:9], s[54:55], 1, v[6:7]
	s_mul_hi_i32 s57, s13, 0x180
	s_mul_i32 s56, s13, 0x180
	v_xor_b32_e32 v8, v197, v8
	global_load_lds_dwordx4 v[8:9], off
	v_lshl_add_u64 v[6:7], s[56:57], 1, v[6:7]
	s_add_i32 m0, s8, 0x16000
	s_mov_b32 s8, s26
	s_mov_b32 s46, s27
	v_xor_b32_e32 v6, v197, v6
	global_load_lds_dwordx4 v[6:7], off
	s_ashr_i32 s47, s46, 31
	s_or_b32 s48, s12, 0x80
	s_lshl_b64 s[46:47], s[46:47], 7
	s_add_u32 s46, s70, s46
	s_addc_u32 s47, s71, s47
	s_ashr_i32 s49, s48, 31
	v_lshl_add_u64 v[6:7], s[46:47], 0, v[2:3]
	s_lshl_b64 s[46:47], s[48:49], 13
	s_lshl_b32 s8, s8, 10
	v_lshl_add_u64 v[8:9], v[6:7], 0, s[46:47]
	s_or_b32 s46, s12, 0xc0
	s_add_i32 s8, s8, 0
	s_ashr_i32 s47, s46, 31
	s_add_i32 m0, s8, 0x4000
	s_lshl_b64 s[50:51], s[46:47], 13
	v_xor_b32_e32 v8, v197, v8
	global_load_lds_dwordx4 v[8:9], off
	v_lshl_add_u64 v[6:7], v[6:7], 0, s[50:51]
	s_add_i32 m0, s8, 0x6000
	v_ashrrev_i32_e32 v8, 8, v1
	v_xor_b32_e32 v6, v197, v6
	global_load_lds_dwordx4 v[6:7], off
	s_lshl_b64 s[50:51], s[48:49], 12
	s_lshl_b64 s[52:53], s[46:47], 12
	v_cmp_eq_u32_e32 vcc, 1, v8
	s_and_saveexec_b64 s[46:47], vcc
	s_cbranch_execz .LBB0_329
	s_barrier
; #define LDA(dst, b, h) _Pragma("unroll") for (int m = 0; m < 4; ++m) _Pragma("unroll") for (int k = 0; k < 2; ++k) \
;     dst[m][k] = *reinterpret_cast<const LAS bf16x8*>(lds + SAo(b, h) + lds_byte(wr * 64 + m * 16 + fr, k * 32 + fq * 8))
; #define LDB(dst, b, h) _Pragma("unroll") for (int n = 0; n < 2; ++n) _Pragma("unroll") for (int k = 0; k < 2; ++k) \
;     dst[n][k] = *reinterpret_cast<const LAS bf16x8*>(lds + SBo(b, h) + lds_byte(wc * 32 + n * 16 + fr, k * 32 + fq * 8))
; #define MMA(ai, bj, At_, Bt_) do { __builtin_amdgcn_s_setprio(1); \
;     _Pragma("unroll") for (int m = 0; m < 4; ++m) _Pragma("unroll") for (int n = 0; n < 2; ++n) _Pragma("unroll") for (int k = 0; k < 2; ++k) \
;       acc[ai][bj][m][n] = __builtin_amdgcn_mfma_f32_16x16x32_bf16(Bt_[n][k], At_[m][k], acc[ai][bj][m][n], 0, 0, 0); \
;     __builtin_amdgcn_s_setprio(0); } while (0)
; #define WAIT_V(n) asm volatile("s_waitcnt vmcnt(" #n ")" ::: "memory")
; #define WAIT_L(n) asm volatile("s_waitcnt lgkmcnt(" #n ")" ::: "memory")
; #define BAR __builtin_amdgcn_s_barrier()
; #define SCHED __builtin_amdgcn_sched_barrier(0)
; template <bool PRE = false>
; __device__ __forceinline__ void gemm_kloop(Acc& acc, const bf16_t* __restrict__ A, int lda, const bf16_t* __restrict__ Bt, int ldb,
;                                            int brow, int bcol, int nt, LAS unsigned char* lds) {
;     ...
;     if (wr == 1) BAR;
;     WAIT_V(4); BAR;
;     STAGE(SBo(1, 0), Bt, ldb, bcol, 1, offB); STAGE(SAo(1, 0), A, lda, brow, 1, offA); STAGE(SBo(1, 1), Bt, ldb, bcol + HALF, 1, offB);
;     WAIT_V(6); BAR;
;     for (int t = 0; t < nt - 2; t += 2) {
;         LDB(B0, 0, 0); SCHED; LDA(At, 0, 0); STAGE(SAo(1, 1), A, lda, brow + HALF, t + 1, offA);
;         WAIT_L(8); BAR; WAIT_L(0); MMA(0, 0, At, B0); BAR; SCHED;
.LBB0_329:
	s_or_b64 exec, exec, s[46:47]
	s_mov_b32 s46, 1
	s_mov_b32 s8, s26
	s_waitcnt vmcnt(4)
	s_barrier
	s_ashr_i32 s47, s46, 31
	s_lshl_b64 s[46:47], s[46:47], 7
	s_add_u32 s46, s90, s46
	s_addc_u32 s47, s91, s47
	s_lshl_b32 s8, s8, 10
	v_lshl_add_u64 v[6:7], s[46:47], 0, v[144:145]
	s_add_i32 s8, s31, s8
	s_lshl_b64 s[46:47], s[36:37], 1
	v_lshl_add_u64 v[10:11], v[6:7], 0, s[46:47]
	s_mov_b32 m0, s8
	s_lshl_b64 s[48:49], s[38:39], 1
	v_xor_b32_e32 v10, v197, v10
	global_load_lds_dwordx4 v[10:11], off
	v_lshl_add_u64 v[6:7], v[6:7], 0, s[48:49]
	s_add_i32 m0, s8, 0x2000
	s_mov_b32 s36, 1
	s_mov_b32 s8, s26
	v_xor_b32_e32 v6, v197, v6
	global_load_lds_dwordx4 v[6:7], off
	s_ashr_i32 s37, s36, 31
	s_lshl_b64 s[36:37], s[36:37], 7
	s_add_u32 s36, s70, s36
	s_addc_u32 s37, s71, s37
	s_lshl_b32 s8, s8, 10
	v_lshl_add_u64 v[6:7], s[36:37], 0, v[2:3]
	s_add_i32 s8, s8, 0
	s_lshl_b64 s[40:41], s[40:41], 1
	s_add_i32 m0, s8, 0x8000
	v_lshl_add_u64 v[10:11], v[6:7], 0, s[40:41]
	s_lshl_b64 s[42:43], s[42:43], 1
	v_xor_b32_e32 v10, v197, v10
	global_load_lds_dwordx4 v[10:11], off
	v_lshl_add_u64 v[6:7], v[6:7], 0, s[42:43]
	s_add_i32 m0, s8, 0xa000
	s_mov_b32 s36, 1
	s_mov_b32 s8, s26
	v_xor_b32_e32 v6, v197, v6
	global_load_lds_dwordx4 v[6:7], off
	s_ashr_i32 s37, s36, 31
	s_lshl_b64 s[36:37], s[36:37], 7
	s_add_u32 s36, s90, s36
	s_addc_u32 s37, s91, s37
	s_lshl_b32 s8, s8, 10
	v_lshl_add_u64 v[6:7], s[36:37], 0, v[144:145]
	s_add_i32 s8, s24, s8
	s_lshl_b64 s[36:37], s[54:55], 1
	v_lshl_add_u64 v[10:11], v[6:7], 0, s[36:37]
	s_mov_b32 m0, s8
	s_lshl_b64 s[38:39], s[56:57], 1
	v_xor_b32_e32 v10, v197, v10
	global_load_lds_dwordx4 v[10:11], off
	v_lshl_add_u64 v[6:7], v[6:7], 0, s[38:39]
	s_add_i32 m0, s8, 0x2000
	v_and_b32_e32 v5, 15, v1
	v_xor_b32_e32 v6, v197, v6
	global_load_lds_dwordx4 v[6:7], off
	v_lshlrev_b32_e32 v4, 12, v4
	v_and_b32_e32 v10, 0x3000, v4
	v_lshlrev_b32_e32 v4, 6, v5
	v_lshlrev_b32_e32 v5, 2, v1
	v_and_b32_e32 v12, 48, v1
	v_and_b32_e32 v11, 32, v5
	v_lshlrev_b32_e32 v15, 6, v1
	v_bitop3_b32 v14, v4, v11, v12 bitop3:0x36
	s_add_i32 s54, 0, 0x10000
	v_and_b32_e32 v15, 0x3c0, v15
	s_add_i32 s13, 0, 0x14000
	v_add3_u32 v13, s54, v14, v10
	v_lshlrev_b32_e32 v8, 13, v8
	v_bitop3_b32 v11, v15, v11, v12 bitop3:0x36
	s_waitcnt vmcnt(6)
	s_barrier
	v_add3_u32 v9, 0, v14, v8
	v_add3_u32 v8, 0, v11, v8
	v_add3_u32 v12, s13, v14, v10
	v_add3_u32 v11, s31, v14, v10
	v_add3_u32 v10, s24, v14, v10
	ds_read_b128 v[14:17], v13
	ds_read_b128 v[18:21], v13 offset:1024
	ds_read_b128 v[22:25], v13 offset:2048
	ds_read_b128 v[26:29], v13 offset:3072
	v_lshl_add_u64 v[6:7], s[70:71], 0, v[2:3]
	v_lshl_add_u64 v[4:5], s[90:91], 0, v[144:145]
	s_mov_b32 s56, 1
	s_mov_b32 s8, s26
	ds_read_b128 v[30:33], v9
	ds_read_b128 v[34:37], v9 offset:1024
	ds_read_b128 v[38:41], v8 offset:2048
	ds_read_b128 v[42:45], v8 offset:3072
	ds_read_b128 v[46:49], v8 offset:4096
	ds_read_b128 v[50:53], v8 offset:5120
	ds_read_b128 v[54:57], v8 offset:6144
	ds_read_b128 v[58:61], v8 offset:7168
	s_ashr_i32 s57, s56, 31
	s_lshl_b64 s[56:57], s[56:57], 7
	s_lshl_b32 s8, s8, 10
	v_lshl_add_u64 v[62:63], v[6:7], 0, s[56:57]
	s_add_i32 s8, s8, 0
	s_lshl_b64 s[50:51], s[50:51], 1
	s_add_i32 m0, s8, 0xc000
	v_lshl_add_u64 v[64:65], v[62:63], 0, s[50:51]
	s_lshl_b64 s[52:53], s[52:53], 1
	v_xor_b32_e32 v64, v197, v64
	global_load_lds_dwordx4 v[64:65], off
	v_lshl_add_u64 v[62:63], v[62:63], 0, s[52:53]
	s_add_i32 m0, s8, 0xe000
	s_nop 0
	v_xor_b32_e32 v62, v197, v62
	global_load_lds_dwordx4 v[62:63], off
	s_waitcnt lgkmcnt(8)
	s_barrier
	s_waitcnt lgkmcnt(0)
	s_setprio 1
	s_waitcnt lgkmcnt(0)
	v_mfma_f32_16x16x32_bf16 v[62:65], v[14:17], v[30:33], 0
	v_mfma_f32_16x16x32_bf16 v[66:69], v[22:25], v[30:33], 0
	v_mfma_f32_16x16x32_bf16 v[70:73], v[14:17], v[38:41], 0
	v_mfma_f32_16x16x32_bf16 v[74:77], v[22:25], v[38:41], 0
	v_mfma_f32_16x16x32_bf16 v[78:81], v[14:17], v[46:49], 0
	v_mfma_f32_16x16x32_bf16 v[82:85], v[22:25], v[46:49], 0
	v_mfma_f32_16x16x32_bf16 v[86:89], v[14:17], v[54:57], 0
	v_mfma_f32_16x16x32_bf16 v[90:93], v[22:25], v[54:57], 0
	v_mfma_f32_16x16x32_bf16 v[62:65], v[18:21], v[34:37], v[62:65]
	v_mfma_f32_16x16x32_bf16 v[66:69], v[26:29], v[34:37], v[66:69]
	v_mfma_f32_16x16x32_bf16 v[70:73], v[18:21], v[42:45], v[70:73]
	v_mfma_f32_16x16x32_bf16 v[74:77], v[26:29], v[42:45], v[74:77]
	v_mfma_f32_16x16x32_bf16 v[78:81], v[18:21], v[50:53], v[78:81]
	v_mfma_f32_16x16x32_bf16 v[82:85], v[26:29], v[50:53], v[82:85]
	v_mfma_f32_16x16x32_bf16 v[86:89], v[18:21], v[58:61], v[86:89]
	v_mfma_f32_16x16x32_bf16 v[90:93], v[26:29], v[58:61], v[90:93]
	s_setprio 0
	s_barrier
	s_mov_b32 s56, 2
	s_mov_b32 s8, s26
	ds_read_b128 v[94:97], v12
	ds_read_b128 v[98:101], v12 offset:1024
	ds_read_b128 v[102:105], v12 offset:2048
	ds_read_b128 v[106:109], v12 offset:3072
	s_ashr_i32 s57, s56, 31
	s_lshl_b64 s[56:57], s[56:57], 7
	s_lshl_b32 s8, s8, 10
	v_lshl_add_u64 v[110:111], v[4:5], 0, s[56:57]
	s_add_i32 s8, s54, s8
	v_lshl_add_u64 v[112:113], v[110:111], 0, s[46:47]
	s_mov_b32 m0, s8
	v_lshl_add_u64 v[110:111], v[110:111], 0, s[48:49]
	v_xor_b32_e32 v112, v197, v112
	global_load_lds_dwordx4 v[112:113], off
	s_add_i32 m0, s8, 0x2000
	s_nop 0
	v_xor_b32_e32 v110, v197, v110
	global_load_lds_dwordx4 v[110:111], off
	s_barrier
; #define LDA(dst, b, h) _Pragma("unroll") for (int m = 0; m < 4; ++m) _Pragma("unroll") for (int k = 0; k < 2; ++k) \
;     dst[m][k] = *reinterpret_cast<const LAS bf16x8*>(lds + SAo(b, h) + lds_byte(wr * 64 + m * 16 + fr, k * 32 + fq * 8))
; #define LDB(dst, b, h) _Pragma("unroll") for (int n = 0; n < 2; ++n) _Pragma("unroll") for (int k = 0; k < 2; ++k) \
;     dst[n][k] = *reinterpret_cast<const LAS bf16x8*>(lds + SBo(b, h) + lds_byte(wc * 32 + n * 16 + fr, k * 32 + fq * 8))
; #define MMA(ai, bj, At_, Bt_) do { __builtin_amdgcn_s_setprio(1); \
;     _Pragma("unroll") for (int m = 0; m < 4; ++m) _Pragma("unroll") for (int n = 0; n < 2; ++n) _Pragma("unroll") for (int k = 0; k < 2; ++k) \
;       acc[ai][bj][m][n] = __builtin_amdgcn_mfma_f32_16x16x32_bf16(Bt_[n][k], At_[m][k], acc[ai][bj][m][n], 0, 0, 0); \
;     __builtin_amdgcn_s_setprio(0); } while (0)
; #define WAIT_V(n) asm volatile("s_waitcnt vmcnt(" #n ")" ::: "memory")
; #define WAIT_L(n) asm volatile("s_waitcnt lgkmcnt(" #n ")" ::: "memory")
; #define BAR __builtin_amdgcn_s_barrier()
; #define SCHED __builtin_amdgcn_sched_barrier(0)
; template <bool PRE = false>
; __device__ __forceinline__ void gemm_kloop(Acc& acc, const bf16_t* __restrict__ A, int lda, const bf16_t* __restrict__ Bt, int ldb,
;                                            int brow, int bcol, int nt, LAS unsigned char* lds) {
;     ...
;         WAIT_L(8); BAR; WAIT_L(0); MMA(0, 0, At, B0); BAR; SCHED;
;         LDB(B1, 0, 1); STAGE(SBo(0, 0), Bt, ldb, bcol, t + 2, offB);
;         BAR; WAIT_L(0); MMA(0, 1, At, B1); BAR;
;         LDA(At, 0, 1); STAGE(SAo(0, 0), A, lda, brow, t + 2, offA);
;         BAR; WAIT_L(0); MMA(1, 0, At, B0); BAR; SCHED;
;         STAGE(SBo(0, 1), Bt, ldb, bcol + HALF, t + 2, offB);
;         WAIT_V(6); BAR; MMA(1, 1, At, B1); BAR;
;         LDB(B0, 1, 0); SCHED; LDA(At, 1, 0); STAGE(SAo(0, 1), A, lda, brow + HALF, t + 2, offA);
	s_waitcnt lgkmcnt(0)
	s_setprio 1
	s_waitcnt lgkmcnt(0)
	v_mfma_f32_16x16x32_bf16 v[110:113], v[94:97], v[30:33], 0
	v_mfma_f32_16x16x32_bf16 v[30:33], v[102:105], v[30:33], 0
	v_mfma_f32_16x16x32_bf16 v[110:113], v[98:101], v[34:37], v[110:113]
	v_mfma_f32_16x16x32_bf16 v[30:33], v[106:109], v[34:37], v[30:33]
	v_mfma_f32_16x16x32_bf16 v[34:37], v[94:97], v[38:41], 0
	v_mfma_f32_16x16x32_bf16 v[38:41], v[102:105], v[38:41], 0
	v_mfma_f32_16x16x32_bf16 v[34:37], v[98:101], v[42:45], v[34:37]
	v_mfma_f32_16x16x32_bf16 v[38:41], v[106:109], v[42:45], v[38:41]
	v_mfma_f32_16x16x32_bf16 v[42:45], v[94:97], v[46:49], 0
	v_mfma_f32_16x16x32_bf16 v[46:49], v[102:105], v[46:49], 0
	v_mfma_f32_16x16x32_bf16 v[42:45], v[98:101], v[50:53], v[42:45]
	v_mfma_f32_16x16x32_bf16 v[46:49], v[106:109], v[50:53], v[46:49]
	v_mfma_f32_16x16x32_bf16 v[50:53], v[94:97], v[54:57], 0
	v_mfma_f32_16x16x32_bf16 v[54:57], v[102:105], v[54:57], 0
	v_mfma_f32_16x16x32_bf16 v[50:53], v[98:101], v[58:61], v[50:53]
	v_mfma_f32_16x16x32_bf16 v[54:57], v[106:109], v[58:61], v[54:57]
	s_setprio 0
	s_mov_b32 s56, 2
	s_mov_b32 s8, s26
	s_barrier
	ds_read_b128 v[58:61], v9 offset:16384
	ds_read_b128 v[114:117], v9 offset:17408
	ds_read_b128 v[118:121], v8 offset:18432
	ds_read_b128 v[122:125], v8 offset:19456
	ds_read_b128 v[126:129], v8 offset:20480
	ds_read_b128 v[130:133], v8 offset:21504
	ds_read_b128 v[134:137], v8 offset:22528
	ds_read_b128 v[138:141], v8 offset:23552
	s_ashr_i32 s57, s56, 31
	s_lshl_b64 s[56:57], s[56:57], 7
	s_lshl_b32 s8, s8, 10
	v_lshl_add_u64 v[142:143], v[6:7], 0, s[56:57]
	s_add_i32 s8, s8, 0
	v_lshl_add_u64 v[146:147], v[142:143], 0, s[40:41]
	s_mov_b32 m0, s8
	v_lshl_add_u64 v[142:143], v[142:143], 0, s[42:43]
	v_xor_b32_e32 v146, v197, v146
	global_load_lds_dwordx4 v[146:147], off
	s_add_i32 m0, s8, 0x2000
	s_nop 0
	v_xor_b32_e32 v142, v197, v142
	global_load_lds_dwordx4 v[142:143], off
	s_barrier
	s_waitcnt lgkmcnt(0)
	s_setprio 1
	s_waitcnt lgkmcnt(0)
	v_mfma_f32_16x16x32_bf16 v[146:149], v[14:17], v[58:61], 0
	v_mfma_f32_16x16x32_bf16 v[154:157], v[14:17], v[118:121], 0
	v_mfma_f32_16x16x32_bf16 v[162:165], v[14:17], v[126:129], 0
	v_mfma_f32_16x16x32_bf16 v[14:17], v[14:17], v[134:137], 0
	v_mfma_f32_16x16x32_bf16 v[146:149], v[18:21], v[114:117], v[146:149]
	v_mfma_f32_16x16x32_bf16 v[154:157], v[18:21], v[122:125], v[154:157]
	v_mfma_f32_16x16x32_bf16 v[162:165], v[18:21], v[130:133], v[162:165]
	v_mfma_f32_16x16x32_bf16 v[14:17], v[18:21], v[138:141], v[14:17]
	v_mfma_f32_16x16x32_bf16 v[18:21], v[22:25], v[134:137], 0
	v_mfma_f32_16x16x32_bf16 v[150:153], v[22:25], v[58:61], 0
	v_mfma_f32_16x16x32_bf16 v[158:161], v[22:25], v[118:121], 0
	v_mfma_f32_16x16x32_bf16 v[166:169], v[22:25], v[126:129], 0
	v_mfma_f32_16x16x32_bf16 v[18:21], v[26:29], v[138:141], v[18:21]
	v_mfma_f32_16x16x32_bf16 v[150:153], v[26:29], v[114:117], v[150:153]
	v_mfma_f32_16x16x32_bf16 v[158:161], v[26:29], v[122:125], v[158:161]
	v_mfma_f32_16x16x32_bf16 v[166:169], v[26:29], v[130:133], v[166:169]
	s_setprio 0
	s_barrier
	s_mov_b32 s56, 2
	s_mov_b32 s8, s26
	s_ashr_i32 s57, s56, 31
	s_lshl_b64 s[56:57], s[56:57], 7
	s_lshl_b32 s8, s8, 10
	v_lshl_add_u64 v[22:23], v[4:5], 0, s[56:57]
	s_add_i32 s8, s13, s8
	v_lshl_add_u64 v[24:25], v[22:23], 0, s[36:37]
	s_mov_b32 m0, s8
	v_lshl_add_u64 v[22:23], v[22:23], 0, s[38:39]
	v_xor_b32_e32 v24, v197, v24
	global_load_lds_dwordx4 v[24:25], off
	s_add_i32 m0, s8, 0x2000
	s_nop 0
	v_xor_b32_e32 v22, v197, v22
	global_load_lds_dwordx4 v[22:23], off
	s_waitcnt vmcnt(6)
	s_barrier
	s_setprio 1
	v_mfma_f32_16x16x32_bf16 v[22:25], v[94:97], v[58:61], 0
	v_mfma_f32_16x16x32_bf16 v[26:29], v[102:105], v[58:61], 0
	v_mfma_f32_16x16x32_bf16 v[22:25], v[98:101], v[114:117], v[22:25]
	v_mfma_f32_16x16x32_bf16 v[26:29], v[106:109], v[114:117], v[26:29]
	v_mfma_f32_16x16x32_bf16 v[58:61], v[94:97], v[118:121], 0
	v_mfma_f32_16x16x32_bf16 v[114:117], v[102:105], v[118:121], 0
	v_mfma_f32_16x16x32_bf16 v[118:121], v[94:97], v[126:129], 0
	v_mfma_f32_16x16x32_bf16 v[94:97], v[94:97], v[134:137], 0
	v_mfma_f32_16x16x32_bf16 v[58:61], v[98:101], v[122:125], v[58:61]
	v_mfma_f32_16x16x32_bf16 v[114:117], v[106:109], v[122:125], v[114:117]
	v_mfma_f32_16x16x32_bf16 v[118:121], v[98:101], v[130:133], v[118:121]
	v_mfma_f32_16x16x32_bf16 v[122:125], v[102:105], v[126:129], 0
	v_mfma_f32_16x16x32_bf16 v[94:97], v[98:101], v[138:141], v[94:97]
	v_mfma_f32_16x16x32_bf16 v[98:101], v[102:105], v[134:137], 0
	v_mfma_f32_16x16x32_bf16 v[122:125], v[106:109], v[130:133], v[122:125]
	v_mfma_f32_16x16x32_bf16 v[98:101], v[106:109], v[138:141], v[98:101]
	s_setprio 0
	s_barrier
	ds_read_b128 v[102:105], v11
	ds_read_b128 v[106:109], v11 offset:1024
	ds_read_b128 v[126:129], v11 offset:2048
	ds_read_b128 v[130:133], v11 offset:3072
	s_mov_b32 s56, 2
	s_mov_b32 s8, s26
	ds_read_b128 v[134:137], v9 offset:32768
	ds_read_b128 v[138:141], v9 offset:33792
	ds_read_b128 v[170:173], v8 offset:34816
	ds_read_b128 v[174:177], v8 offset:35840
	ds_read_b128 v[184:187], v8 offset:36864
	ds_read_b128 v[188:191], v8 offset:37888
	ds_read_b128 v[204:207], v8 offset:38912
	ds_read_b128 v[208:211], v8 offset:39936
	s_ashr_i32 s57, s56, 31
	s_lshl_b64 s[56:57], s[56:57], 7
	s_lshl_b32 s8, s8, 10
	v_lshl_add_u64 v[142:143], v[6:7], 0, s[56:57]
	s_add_i32 s8, s8, 0
	s_add_i32 m0, s8, 0x4000
	v_lshl_add_u64 v[192:193], v[142:143], 0, s[50:51]
	v_xor_b32_e32 v192, v197, v192
	global_load_lds_dwordx4 v[192:193], off
	v_lshl_add_u64 v[142:143], v[142:143], 0, s[52:53]
	s_add_i32 m0, s8, 0x6000
	s_nop 0
	v_xor_b32_e32 v142, v197, v142
	global_load_lds_dwordx4 v[142:143], off
	s_waitcnt lgkmcnt(8)
	s_barrier
; #define LDA(dst, b, h) _Pragma("unroll") for (int m = 0; m < 4; ++m) _Pragma("unroll") for (int k = 0; k < 2; ++k) \
;     dst[m][k] = *reinterpret_cast<const LAS bf16x8*>(lds + SAo(b, h) + lds_byte(wr * 64 + m * 16 + fr, k * 32 + fq * 8))
; #define LDB(dst, b, h) _Pragma("unroll") for (int n = 0; n < 2; ++n) _Pragma("unroll") for (int k = 0; k < 2; ++k) \
;     dst[n][k] = *reinterpret_cast<const LAS bf16x8*>(lds + SBo(b, h) + lds_byte(wc * 32 + n * 16 + fr, k * 32 + fq * 8))
; #define MMA(ai, bj, At_, Bt_) do { __builtin_amdgcn_s_setprio(1); \
;     _Pragma("unroll") for (int m = 0; m < 4; ++m) _Pragma("unroll") for (int n = 0; n < 2; ++n) _Pragma("unroll") for (int k = 0; k < 2; ++k) \
;       acc[ai][bj][m][n] = __builtin_amdgcn_mfma_f32_16x16x32_bf16(Bt_[n][k], At_[m][k], acc[ai][bj][m][n], 0, 0, 0); \
;     __builtin_amdgcn_s_setprio(0); } while (0)
; #define WAIT_V(n) asm volatile("s_waitcnt vmcnt(" #n ")" ::: "memory")
; #define WAIT_L(n) asm volatile("s_waitcnt lgkmcnt(" #n ")" ::: "memory")
; #define BAR __builtin_amdgcn_s_barrier()
; #define SCHED __builtin_amdgcn_sched_barrier(0)
; template <bool PRE = false>
; __device__ __forceinline__ void gemm_kloop(Acc& acc, const bf16_t* __restrict__ A, int lda, const bf16_t* __restrict__ Bt, int ldb,
;                                            int brow, int bcol, int nt, LAS unsigned char* lds) {
;     ...
;         LDB(B0, 1, 0); SCHED; LDA(At, 1, 0); STAGE(SAo(0, 1), A, lda, brow + HALF, t + 2, offA);
;         WAIT_L(8); BAR; WAIT_L(0); MMA(0, 0, At, B0); BAR; SCHED;
;         LDB(B1, 1, 1); STAGE(SBo(1, 0), Bt, ldb, bcol, t + 3, offB);
;         BAR; WAIT_L(0); MMA(0, 1, At, B1); BAR;
;         LDA(At, 1, 1); STAGE(SAo(1, 0), A, lda, brow, t + 3, offA);
;         BAR; WAIT_L(0); MMA(1, 0, At, B0); BAR; SCHED;
;         STAGE(SBo(1, 1), Bt, ldb, bcol + HALF, t + 3, offB);
;         WAIT_V(6); BAR; MMA(1, 1, At, B1); BAR;
	s_waitcnt lgkmcnt(0)
	s_setprio 1
	s_waitcnt lgkmcnt(0)
	v_mfma_f32_16x16x32_bf16 v[62:65], v[102:105], v[134:137], v[62:65]
	v_mfma_f32_16x16x32_bf16 v[66:69], v[126:129], v[134:137], v[66:69]
	v_mfma_f32_16x16x32_bf16 v[70:73], v[102:105], v[170:173], v[70:73]
	v_mfma_f32_16x16x32_bf16 v[74:77], v[126:129], v[170:173], v[74:77]
	v_mfma_f32_16x16x32_bf16 v[78:81], v[102:105], v[184:187], v[78:81]
	v_mfma_f32_16x16x32_bf16 v[82:85], v[126:129], v[184:187], v[82:85]
	v_mfma_f32_16x16x32_bf16 v[86:89], v[102:105], v[204:207], v[86:89]
	v_mfma_f32_16x16x32_bf16 v[90:93], v[126:129], v[204:207], v[90:93]
	v_mfma_f32_16x16x32_bf16 v[62:65], v[106:109], v[138:141], v[62:65]
	v_mfma_f32_16x16x32_bf16 v[66:69], v[130:133], v[138:141], v[66:69]
	v_mfma_f32_16x16x32_bf16 v[70:73], v[106:109], v[174:177], v[70:73]
	v_mfma_f32_16x16x32_bf16 v[74:77], v[130:133], v[174:177], v[74:77]
	v_mfma_f32_16x16x32_bf16 v[78:81], v[106:109], v[188:191], v[78:81]
	v_mfma_f32_16x16x32_bf16 v[82:85], v[130:133], v[188:191], v[82:85]
	v_mfma_f32_16x16x32_bf16 v[86:89], v[106:109], v[208:211], v[86:89]
	v_mfma_f32_16x16x32_bf16 v[90:93], v[130:133], v[208:211], v[90:93]
	s_setprio 0
	s_barrier
	s_mov_b32 s56, 3
	s_mov_b32 s8, s26
	ds_read_b128 v[212:215], v10
	ds_read_b128 v[216:219], v10 offset:1024
	ds_read_b128 v[220:223], v10 offset:2048
	ds_read_b128 v[224:227], v10 offset:3072
	s_ashr_i32 s57, s56, 31
	s_lshl_b64 s[56:57], s[56:57], 7
	s_lshl_b32 s8, s8, 10
	v_lshl_add_u64 v[142:143], v[4:5], 0, s[56:57]
	s_add_i32 s8, s31, s8
	v_lshl_add_u64 v[192:193], v[142:143], 0, s[46:47]
	s_mov_b32 m0, s8
	v_lshl_add_u64 v[142:143], v[142:143], 0, s[48:49]
	v_xor_b32_e32 v192, v197, v192
	global_load_lds_dwordx4 v[192:193], off
	s_add_i32 m0, s8, 0x2000
	s_nop 0
	v_xor_b32_e32 v142, v197, v142
	global_load_lds_dwordx4 v[142:143], off
	s_barrier
	s_waitcnt lgkmcnt(0)
	s_setprio 1
	s_waitcnt lgkmcnt(0)
	v_mfma_f32_16x16x32_bf16 v[110:113], v[212:215], v[134:137], v[110:113]
	v_mfma_f32_16x16x32_bf16 v[30:33], v[220:223], v[134:137], v[30:33]
	v_mfma_f32_16x16x32_bf16 v[34:37], v[212:215], v[170:173], v[34:37]
	v_mfma_f32_16x16x32_bf16 v[38:41], v[220:223], v[170:173], v[38:41]
	v_mfma_f32_16x16x32_bf16 v[42:45], v[212:215], v[184:187], v[42:45]
	v_mfma_f32_16x16x32_bf16 v[46:49], v[220:223], v[184:187], v[46:49]
	v_mfma_f32_16x16x32_bf16 v[50:53], v[212:215], v[204:207], v[50:53]
	v_mfma_f32_16x16x32_bf16 v[54:57], v[220:223], v[204:207], v[54:57]
	v_mfma_f32_16x16x32_bf16 v[110:113], v[216:219], v[138:141], v[110:113]
	v_mfma_f32_16x16x32_bf16 v[30:33], v[224:227], v[138:141], v[30:33]
	v_mfma_f32_16x16x32_bf16 v[34:37], v[216:219], v[174:177], v[34:37]
	v_mfma_f32_16x16x32_bf16 v[38:41], v[224:227], v[174:177], v[38:41]
	v_mfma_f32_16x16x32_bf16 v[42:45], v[216:219], v[188:191], v[42:45]
	v_mfma_f32_16x16x32_bf16 v[46:49], v[224:227], v[188:191], v[46:49]
	v_mfma_f32_16x16x32_bf16 v[50:53], v[216:219], v[208:211], v[50:53]
	v_mfma_f32_16x16x32_bf16 v[54:57], v[224:227], v[208:211], v[54:57]
	s_setprio 0
	s_mov_b32 s56, 3
	s_mov_b32 s8, s26
	s_barrier
	ds_read_b128 v[134:137], v9 offset:49152
	ds_read_b128 v[138:141], v9 offset:50176
	ds_read_b128 v[170:173], v8 offset:51200
	ds_read_b128 v[174:177], v8 offset:52224
	ds_read_b128 v[184:187], v8 offset:53248
	ds_read_b128 v[188:191], v8 offset:54272
	ds_read_b128 v[204:207], v8 offset:55296
	ds_read_b128 v[208:211], v8 offset:56320
	s_ashr_i32 s57, s56, 31
	s_lshl_b64 s[56:57], s[56:57], 7
	s_lshl_b32 s8, s8, 10
	v_lshl_add_u64 v[142:143], v[6:7], 0, s[56:57]
	s_add_i32 s8, s8, 0
	s_add_i32 m0, s8, 0x8000
	v_lshl_add_u64 v[192:193], v[142:143], 0, s[40:41]
	v_xor_b32_e32 v192, v197, v192
	global_load_lds_dwordx4 v[192:193], off
	v_lshl_add_u64 v[142:143], v[142:143], 0, s[42:43]
	s_add_i32 m0, s8, 0xa000
	s_nop 0
	v_xor_b32_e32 v142, v197, v142
	global_load_lds_dwordx4 v[142:143], off
	s_barrier
	s_waitcnt lgkmcnt(0)
	s_setprio 1
	s_waitcnt lgkmcnt(0)
	v_mfma_f32_16x16x32_bf16 v[14:17], v[102:105], v[204:207], v[14:17]
	v_mfma_f32_16x16x32_bf16 v[18:21], v[126:129], v[204:207], v[18:21]
	v_mfma_f32_16x16x32_bf16 v[146:149], v[102:105], v[134:137], v[146:149]
	v_mfma_f32_16x16x32_bf16 v[150:153], v[126:129], v[134:137], v[150:153]
	v_mfma_f32_16x16x32_bf16 v[154:157], v[102:105], v[170:173], v[154:157]
	v_mfma_f32_16x16x32_bf16 v[158:161], v[126:129], v[170:173], v[158:161]
	v_mfma_f32_16x16x32_bf16 v[162:165], v[102:105], v[184:187], v[162:165]
	v_mfma_f32_16x16x32_bf16 v[166:169], v[126:129], v[184:187], v[166:169]
	v_mfma_f32_16x16x32_bf16 v[14:17], v[106:109], v[208:211], v[14:17]
	v_mfma_f32_16x16x32_bf16 v[18:21], v[130:133], v[208:211], v[18:21]
	v_mfma_f32_16x16x32_bf16 v[146:149], v[106:109], v[138:141], v[146:149]
	v_mfma_f32_16x16x32_bf16 v[150:153], v[130:133], v[138:141], v[150:153]
	v_mfma_f32_16x16x32_bf16 v[154:157], v[106:109], v[174:177], v[154:157]
	v_mfma_f32_16x16x32_bf16 v[158:161], v[130:133], v[174:177], v[158:161]
	v_mfma_f32_16x16x32_bf16 v[162:165], v[106:109], v[188:191], v[162:165]
	v_mfma_f32_16x16x32_bf16 v[166:169], v[130:133], v[188:191], v[166:169]
	s_setprio 0
	s_barrier
	s_mov_b32 s56, 3
	s_mov_b32 s8, s26
	s_ashr_i32 s57, s56, 31
	s_lshl_b64 s[56:57], s[56:57], 7
	s_lshl_b32 s8, s8, 10
	v_lshl_add_u64 v[102:103], v[4:5], 0, s[56:57]
	s_add_i32 s8, s24, s8
	v_lshl_add_u64 v[104:105], v[102:103], 0, s[36:37]
	s_mov_b32 m0, s8
	v_lshl_add_u64 v[102:103], v[102:103], 0, s[38:39]
	v_xor_b32_e32 v104, v197, v104
	global_load_lds_dwordx4 v[104:105], off
	s_add_i32 m0, s8, 0x2000
	s_nop 0
	v_xor_b32_e32 v102, v197, v102
	global_load_lds_dwordx4 v[102:103], off
	s_waitcnt vmcnt(6)
	s_barrier
; #define LDA(dst, b, h) _Pragma("unroll") for (int m = 0; m < 4; ++m) _Pragma("unroll") for (int k = 0; k < 2; ++k) \
;     dst[m][k] = *reinterpret_cast<const LAS bf16x8*>(lds + SAo(b, h) + lds_byte(wr * 64 + m * 16 + fr, k * 32 + fq * 8))
; #define LDB(dst, b, h) _Pragma("unroll") for (int n = 0; n < 2; ++n) _Pragma("unroll") for (int k = 0; k < 2; ++k) \
;     dst[n][k] = *reinterpret_cast<const LAS bf16x8*>(lds + SBo(b, h) + lds_byte(wc * 32 + n * 16 + fr, k * 32 + fq * 8))
; #define MMA(ai, bj, At_, Bt_) do { __builtin_amdgcn_s_setprio(1); \
;     _Pragma("unroll") for (int m = 0; m < 4; ++m) _Pragma("unroll") for (int n = 0; n < 2; ++n) _Pragma("unroll") for (int k = 0; k < 2; ++k) \
;       acc[ai][bj][m][n] = __builtin_amdgcn_mfma_f32_16x16x32_bf16(Bt_[n][k], At_[m][k], acc[ai][bj][m][n], 0, 0, 0); \
;     __builtin_amdgcn_s_setprio(0); } while (0)
; #define WAIT_L(n) asm volatile("s_waitcnt lgkmcnt(" #n ")" ::: "memory")
; #define BAR __builtin_amdgcn_s_barrier()
; #define SCHED __builtin_amdgcn_sched_barrier(0)
; template <bool PRE = false>
; __device__ __forceinline__ void gemm_kloop(Acc& acc, const bf16_t* __restrict__ A, int lda, const bf16_t* __restrict__ Bt, int ldb,
;                                            int brow, int bcol, int nt, LAS unsigned char* lds) {
;     ...
;         LDB(B0, 0, 0); SCHED; LDA(At, 0, 0); STAGE(SAo(1, 1), A, lda, brow + HALF, t + 1, offA);
;         WAIT_L(8); BAR; WAIT_L(0); MMA(0, 0, At, B0); BAR; SCHED;
;         LDB(B1, 0, 1); STAGE(SBo(0, 0), Bt, ldb, bcol, t + 2, offB);
;         BAR; WAIT_L(0); MMA(0, 1, At, B1); BAR;
;         LDA(At, 0, 1); STAGE(SAo(0, 0), A, lda, brow, t + 2, offA);
;         BAR; WAIT_L(0); MMA(1, 0, At, B0); BAR; SCHED;
;         STAGE(SBo(0, 1), Bt, ldb, bcol + HALF, t + 2, offB);
	s_setprio 1
	v_mfma_f32_16x16x32_bf16 v[22:25], v[212:215], v[134:137], v[22:25]
	v_mfma_f32_16x16x32_bf16 v[26:29], v[220:223], v[134:137], v[26:29]
	v_mfma_f32_16x16x32_bf16 v[58:61], v[212:215], v[170:173], v[58:61]
	v_mfma_f32_16x16x32_bf16 v[102:105], v[220:223], v[170:173], v[114:117]
	v_mfma_f32_16x16x32_bf16 v[106:109], v[212:215], v[184:187], v[118:121]
	v_mfma_f32_16x16x32_bf16 v[114:117], v[220:223], v[184:187], v[122:125]
	v_mfma_f32_16x16x32_bf16 v[94:97], v[212:215], v[204:207], v[94:97]
	v_mfma_f32_16x16x32_bf16 v[98:101], v[220:223], v[204:207], v[98:101]
	v_mfma_f32_16x16x32_bf16 v[22:25], v[216:219], v[138:141], v[22:25]
	v_mfma_f32_16x16x32_bf16 v[26:29], v[224:227], v[138:141], v[26:29]
	v_mfma_f32_16x16x32_bf16 v[58:61], v[216:219], v[174:177], v[58:61]
	v_mfma_f32_16x16x32_bf16 v[102:105], v[224:227], v[174:177], v[102:105]
	v_mfma_f32_16x16x32_bf16 v[106:109], v[216:219], v[188:191], v[106:109]
	v_mfma_f32_16x16x32_bf16 v[114:117], v[224:227], v[188:191], v[114:117]
	v_mfma_f32_16x16x32_bf16 v[94:97], v[216:219], v[208:211], v[94:97]
	v_mfma_f32_16x16x32_bf16 v[98:101], v[224:227], v[208:211], v[98:101]
	s_setprio 0
	s_barrier
	ds_read_b128 v[118:121], v13
	ds_read_b128 v[122:125], v13 offset:1024
	ds_read_b128 v[126:129], v13 offset:2048
	ds_read_b128 v[130:133], v13 offset:3072
	s_mov_b32 s56, 3
	s_mov_b32 s8, s26
	ds_read_b128 v[134:137], v9
	ds_read_b128 v[138:141], v9 offset:1024
	ds_read_b128 v[170:173], v8 offset:2048
	ds_read_b128 v[174:177], v8 offset:3072
	ds_read_b128 v[184:187], v8 offset:4096
	ds_read_b128 v[188:191], v8 offset:5120
	ds_read_b128 v[204:207], v8 offset:6144
	ds_read_b128 v[208:211], v8 offset:7168
	s_ashr_i32 s57, s56, 31
	s_lshl_b64 s[56:57], s[56:57], 7
	s_lshl_b32 s8, s8, 10
	v_lshl_add_u64 v[142:143], v[6:7], 0, s[56:57]
	s_add_i32 s8, s8, 0
	s_add_i32 m0, s8, 0xc000
	v_lshl_add_u64 v[192:193], v[142:143], 0, s[50:51]
	v_xor_b32_e32 v192, v197, v192
	global_load_lds_dwordx4 v[192:193], off
	v_lshl_add_u64 v[142:143], v[142:143], 0, s[52:53]
	s_add_i32 m0, s8, 0xe000
	s_nop 0
	v_xor_b32_e32 v142, v197, v142
	global_load_lds_dwordx4 v[142:143], off
	s_waitcnt lgkmcnt(8)
	s_barrier
	s_waitcnt lgkmcnt(0)
	s_setprio 1
	s_waitcnt lgkmcnt(0)
	v_mfma_f32_16x16x32_bf16 v[62:65], v[118:121], v[134:137], v[62:65]
	v_mfma_f32_16x16x32_bf16 v[66:69], v[126:129], v[134:137], v[66:69]
	v_mfma_f32_16x16x32_bf16 v[70:73], v[118:121], v[170:173], v[70:73]
	v_mfma_f32_16x16x32_bf16 v[74:77], v[126:129], v[170:173], v[74:77]
	v_mfma_f32_16x16x32_bf16 v[78:81], v[118:121], v[184:187], v[78:81]
	v_mfma_f32_16x16x32_bf16 v[82:85], v[126:129], v[184:187], v[82:85]
	v_mfma_f32_16x16x32_bf16 v[86:89], v[118:121], v[204:207], v[86:89]
	v_mfma_f32_16x16x32_bf16 v[90:93], v[126:129], v[204:207], v[90:93]
	v_mfma_f32_16x16x32_bf16 v[62:65], v[122:125], v[138:141], v[62:65]
	v_mfma_f32_16x16x32_bf16 v[66:69], v[130:133], v[138:141], v[66:69]
	v_mfma_f32_16x16x32_bf16 v[70:73], v[122:125], v[174:177], v[70:73]
	v_mfma_f32_16x16x32_bf16 v[74:77], v[130:133], v[174:177], v[74:77]
	v_mfma_f32_16x16x32_bf16 v[78:81], v[122:125], v[188:191], v[78:81]
	v_mfma_f32_16x16x32_bf16 v[82:85], v[130:133], v[188:191], v[82:85]
	v_mfma_f32_16x16x32_bf16 v[86:89], v[122:125], v[208:211], v[86:89]
	v_mfma_f32_16x16x32_bf16 v[90:93], v[130:133], v[208:211], v[90:93]
	s_setprio 0
	s_barrier
	s_mov_b32 s56, 4
	s_mov_b32 s8, s26
	ds_read_b128 v[212:215], v12
	ds_read_b128 v[216:219], v12 offset:1024
	ds_read_b128 v[220:223], v12 offset:2048
	ds_read_b128 v[224:227], v12 offset:3072
	s_ashr_i32 s57, s56, 31
	s_lshl_b64 s[56:57], s[56:57], 7
	s_lshl_b32 s8, s8, 10
	v_lshl_add_u64 v[142:143], v[4:5], 0, s[56:57]
	s_add_i32 s8, s54, s8
	v_lshl_add_u64 v[192:193], v[142:143], 0, s[46:47]
	s_mov_b32 m0, s8
	v_lshl_add_u64 v[142:143], v[142:143], 0, s[48:49]
	v_xor_b32_e32 v192, v197, v192
	global_load_lds_dwordx4 v[192:193], off
	s_add_i32 m0, s8, 0x2000
	s_nop 0
	v_xor_b32_e32 v142, v197, v142
	global_load_lds_dwordx4 v[142:143], off
	s_barrier
	s_waitcnt lgkmcnt(0)
	s_setprio 1
	s_waitcnt lgkmcnt(0)
	v_mfma_f32_16x16x32_bf16 v[110:113], v[212:215], v[134:137], v[110:113]
	v_mfma_f32_16x16x32_bf16 v[30:33], v[220:223], v[134:137], v[30:33]
	v_mfma_f32_16x16x32_bf16 v[34:37], v[212:215], v[170:173], v[34:37]
	v_mfma_f32_16x16x32_bf16 v[38:41], v[220:223], v[170:173], v[38:41]
	v_mfma_f32_16x16x32_bf16 v[42:45], v[212:215], v[184:187], v[42:45]
	v_mfma_f32_16x16x32_bf16 v[46:49], v[220:223], v[184:187], v[46:49]
	v_mfma_f32_16x16x32_bf16 v[50:53], v[212:215], v[204:207], v[50:53]
	v_mfma_f32_16x16x32_bf16 v[54:57], v[220:223], v[204:207], v[54:57]
	v_mfma_f32_16x16x32_bf16 v[110:113], v[216:219], v[138:141], v[110:113]
	v_mfma_f32_16x16x32_bf16 v[30:33], v[224:227], v[138:141], v[30:33]
	v_mfma_f32_16x16x32_bf16 v[34:37], v[216:219], v[174:177], v[34:37]
	v_mfma_f32_16x16x32_bf16 v[38:41], v[224:227], v[174:177], v[38:41]
	v_mfma_f32_16x16x32_bf16 v[42:45], v[216:219], v[188:191], v[42:45]
	v_mfma_f32_16x16x32_bf16 v[46:49], v[224:227], v[188:191], v[46:49]
	v_mfma_f32_16x16x32_bf16 v[50:53], v[216:219], v[208:211], v[50:53]
	v_mfma_f32_16x16x32_bf16 v[54:57], v[224:227], v[208:211], v[54:57]
	s_setprio 0
	s_mov_b32 s54, 4
	s_mov_b32 s8, s26
	s_barrier
; #define LDA(dst, b, h) _Pragma("unroll") for (int m = 0; m < 4; ++m) _Pragma("unroll") for (int k = 0; k < 2; ++k) \
;     dst[m][k] = *reinterpret_cast<const LAS bf16x8*>(lds + SAo(b, h) + lds_byte(wr * 64 + m * 16 + fr, k * 32 + fq * 8))
; #define LDB(dst, b, h) _Pragma("unroll") for (int n = 0; n < 2; ++n) _Pragma("unroll") for (int k = 0; k < 2; ++k) \
;     dst[n][k] = *reinterpret_cast<const LAS bf16x8*>(lds + SBo(b, h) + lds_byte(wc * 32 + n * 16 + fr, k * 32 + fq * 8))
; #define MMA(ai, bj, At_, Bt_) do { __builtin_amdgcn_s_setprio(1); \
;     _Pragma("unroll") for (int m = 0; m < 4; ++m) _Pragma("unroll") for (int n = 0; n < 2; ++n) _Pragma("unroll") for (int k = 0; k < 2; ++k) \
;       acc[ai][bj][m][n] = __builtin_amdgcn_mfma_f32_16x16x32_bf16(Bt_[n][k], At_[m][k], acc[ai][bj][m][n], 0, 0, 0); \
;     __builtin_amdgcn_s_setprio(0); } while (0)
; #define WAIT_V(n) asm volatile("s_waitcnt vmcnt(" #n ")" ::: "memory")
; #define WAIT_L(n) asm volatile("s_waitcnt lgkmcnt(" #n ")" ::: "memory")
; #define BAR __builtin_amdgcn_s_barrier()
; #define SCHED __builtin_amdgcn_sched_barrier(0)
; template <bool PRE = false>
; __device__ __forceinline__ void gemm_kloop(Acc& acc, const bf16_t* __restrict__ A, int lda, const bf16_t* __restrict__ Bt, int ldb,
;                                            int brow, int bcol, int nt, LAS unsigned char* lds) {
;     ...
;         LDA(At, 0, 1); STAGE(SAo(0, 0), A, lda, brow, t + 2, offA);
;         BAR; WAIT_L(0); MMA(1, 0, At, B0); BAR; SCHED;
;         STAGE(SBo(0, 1), Bt, ldb, bcol + HALF, t + 2, offB);
;         WAIT_V(6); BAR; MMA(1, 1, At, B1); BAR;
;         LDB(B0, 1, 0); SCHED; LDA(At, 1, 0); STAGE(SAo(0, 1), A, lda, brow + HALF, t + 2, offA);
;         WAIT_L(8); BAR; WAIT_L(0); MMA(0, 0, At, B0); BAR; SCHED;
	ds_read_b128 v[134:137], v9 offset:16384
	ds_read_b128 v[138:141], v9 offset:17408
	ds_read_b128 v[170:173], v8 offset:18432
	ds_read_b128 v[174:177], v8 offset:19456
	ds_read_b128 v[184:187], v8 offset:20480
	ds_read_b128 v[188:191], v8 offset:21504
	ds_read_b128 v[204:207], v8 offset:22528
	ds_read_b128 v[208:211], v8 offset:23552
	s_ashr_i32 s55, s54, 31
	s_lshl_b64 s[54:55], s[54:55], 7
	s_lshl_b32 s8, s8, 10
	v_lshl_add_u64 v[142:143], v[6:7], 0, s[54:55]
	s_add_i32 s8, s8, 0
	v_lshl_add_u64 v[192:193], v[142:143], 0, s[40:41]
	s_mov_b32 m0, s8
	v_lshl_add_u64 v[142:143], v[142:143], 0, s[42:43]
	v_xor_b32_e32 v192, v197, v192
	global_load_lds_dwordx4 v[192:193], off
	s_add_i32 m0, s8, 0x2000
	s_nop 0
	v_xor_b32_e32 v142, v197, v142
	global_load_lds_dwordx4 v[142:143], off
	s_barrier
	s_waitcnt lgkmcnt(0)
	s_setprio 1
	s_waitcnt lgkmcnt(0)
	v_mfma_f32_16x16x32_bf16 v[14:17], v[118:121], v[204:207], v[14:17]
	v_mfma_f32_16x16x32_bf16 v[18:21], v[126:129], v[204:207], v[18:21]
	v_mfma_f32_16x16x32_bf16 v[146:149], v[118:121], v[134:137], v[146:149]
	v_mfma_f32_16x16x32_bf16 v[150:153], v[126:129], v[134:137], v[150:153]
	v_mfma_f32_16x16x32_bf16 v[154:157], v[118:121], v[170:173], v[154:157]
	v_mfma_f32_16x16x32_bf16 v[158:161], v[126:129], v[170:173], v[158:161]
	v_mfma_f32_16x16x32_bf16 v[162:165], v[118:121], v[184:187], v[162:165]
	v_mfma_f32_16x16x32_bf16 v[166:169], v[126:129], v[184:187], v[166:169]
	v_mfma_f32_16x16x32_bf16 v[14:17], v[122:125], v[208:211], v[14:17]
	v_mfma_f32_16x16x32_bf16 v[18:21], v[130:133], v[208:211], v[18:21]
	v_mfma_f32_16x16x32_bf16 v[146:149], v[122:125], v[138:141], v[146:149]
	v_mfma_f32_16x16x32_bf16 v[150:153], v[130:133], v[138:141], v[150:153]
	v_mfma_f32_16x16x32_bf16 v[154:157], v[122:125], v[174:177], v[154:157]
	v_mfma_f32_16x16x32_bf16 v[158:161], v[130:133], v[174:177], v[158:161]
	v_mfma_f32_16x16x32_bf16 v[162:165], v[122:125], v[188:191], v[162:165]
	v_mfma_f32_16x16x32_bf16 v[166:169], v[130:133], v[188:191], v[166:169]
	s_setprio 0
	s_barrier
	s_mov_b32 s54, 4
	s_mov_b32 s8, s26
	s_ashr_i32 s55, s54, 31
	s_lshl_b64 s[54:55], s[54:55], 7
	s_lshl_b32 s8, s8, 10
	v_lshl_add_u64 v[118:119], v[4:5], 0, s[54:55]
	s_add_i32 s8, s13, s8
	v_lshl_add_u64 v[120:121], v[118:119], 0, s[36:37]
	s_mov_b32 m0, s8
	v_lshl_add_u64 v[118:119], v[118:119], 0, s[38:39]
	v_xor_b32_e32 v120, v197, v120
	global_load_lds_dwordx4 v[120:121], off
	s_add_i32 m0, s8, 0x2000
	s_nop 0
	v_xor_b32_e32 v118, v197, v118
	global_load_lds_dwordx4 v[118:119], off
	s_waitcnt vmcnt(6)
	s_barrier
	s_setprio 1
	v_mfma_f32_16x16x32_bf16 v[22:25], v[212:215], v[134:137], v[22:25]
	v_mfma_f32_16x16x32_bf16 v[26:29], v[220:223], v[134:137], v[26:29]
	v_mfma_f32_16x16x32_bf16 v[58:61], v[212:215], v[170:173], v[58:61]
	v_mfma_f32_16x16x32_bf16 v[102:105], v[220:223], v[170:173], v[102:105]
	v_mfma_f32_16x16x32_bf16 v[106:109], v[212:215], v[184:187], v[106:109]
	v_mfma_f32_16x16x32_bf16 v[114:117], v[220:223], v[184:187], v[114:117]
	v_mfma_f32_16x16x32_bf16 v[94:97], v[212:215], v[204:207], v[94:97]
	v_mfma_f32_16x16x32_bf16 v[98:101], v[220:223], v[204:207], v[98:101]
	v_mfma_f32_16x16x32_bf16 v[22:25], v[216:219], v[138:141], v[22:25]
	v_mfma_f32_16x16x32_bf16 v[26:29], v[224:227], v[138:141], v[26:29]
	v_mfma_f32_16x16x32_bf16 v[58:61], v[216:219], v[174:177], v[58:61]
	v_mfma_f32_16x16x32_bf16 v[102:105], v[224:227], v[174:177], v[102:105]
	v_mfma_f32_16x16x32_bf16 v[106:109], v[216:219], v[188:191], v[106:109]
	v_mfma_f32_16x16x32_bf16 v[114:117], v[224:227], v[188:191], v[114:117]
	v_mfma_f32_16x16x32_bf16 v[94:97], v[216:219], v[208:211], v[94:97]
	v_mfma_f32_16x16x32_bf16 v[98:101], v[224:227], v[208:211], v[98:101]
	s_setprio 0
	s_barrier
	ds_read_b128 v[118:121], v11
	ds_read_b128 v[122:125], v11 offset:1024
	ds_read_b128 v[126:129], v11 offset:2048
	ds_read_b128 v[130:133], v11 offset:3072
	s_mov_b32 s54, 4
	s_mov_b32 s8, s26
	ds_read_b128 v[134:137], v9 offset:32768
	ds_read_b128 v[138:141], v9 offset:33792
	ds_read_b128 v[170:173], v8 offset:34816
	ds_read_b128 v[174:177], v8 offset:35840
	ds_read_b128 v[184:187], v8 offset:36864
	ds_read_b128 v[188:191], v8 offset:37888
	ds_read_b128 v[204:207], v8 offset:38912
	ds_read_b128 v[208:211], v8 offset:39936
	s_ashr_i32 s55, s54, 31
	s_lshl_b64 s[54:55], s[54:55], 7
	s_lshl_b32 s8, s8, 10
	v_lshl_add_u64 v[142:143], v[6:7], 0, s[54:55]
	s_add_i32 s8, s8, 0
	s_add_i32 m0, s8, 0x4000
	v_lshl_add_u64 v[192:193], v[142:143], 0, s[50:51]
	v_xor_b32_e32 v192, v197, v192
	global_load_lds_dwordx4 v[192:193], off
	v_lshl_add_u64 v[142:143], v[142:143], 0, s[52:53]
	s_add_i32 m0, s8, 0x6000
	s_nop 0
	v_xor_b32_e32 v142, v197, v142
	global_load_lds_dwordx4 v[142:143], off
	s_waitcnt lgkmcnt(8)
	s_barrier
	s_waitcnt lgkmcnt(0)
	s_setprio 1
	s_waitcnt lgkmcnt(0)
	v_mfma_f32_16x16x32_bf16 v[62:65], v[118:121], v[134:137], v[62:65]
	v_mfma_f32_16x16x32_bf16 v[66:69], v[126:129], v[134:137], v[66:69]
	v_mfma_f32_16x16x32_bf16 v[70:73], v[118:121], v[170:173], v[70:73]
	v_mfma_f32_16x16x32_bf16 v[74:77], v[126:129], v[170:173], v[74:77]
	v_mfma_f32_16x16x32_bf16 v[78:81], v[118:121], v[184:187], v[78:81]
	v_mfma_f32_16x16x32_bf16 v[82:85], v[126:129], v[184:187], v[82:85]
	v_mfma_f32_16x16x32_bf16 v[86:89], v[118:121], v[204:207], v[86:89]
	v_mfma_f32_16x16x32_bf16 v[90:93], v[126:129], v[204:207], v[90:93]
	v_mfma_f32_16x16x32_bf16 v[62:65], v[122:125], v[138:141], v[62:65]
	v_mfma_f32_16x16x32_bf16 v[66:69], v[130:133], v[138:141], v[66:69]
	v_mfma_f32_16x16x32_bf16 v[70:73], v[122:125], v[174:177], v[70:73]
	v_mfma_f32_16x16x32_bf16 v[74:77], v[130:133], v[174:177], v[74:77]
	v_mfma_f32_16x16x32_bf16 v[78:81], v[122:125], v[188:191], v[78:81]
	v_mfma_f32_16x16x32_bf16 v[82:85], v[130:133], v[188:191], v[82:85]
	v_mfma_f32_16x16x32_bf16 v[86:89], v[122:125], v[208:211], v[86:89]
	v_mfma_f32_16x16x32_bf16 v[90:93], v[130:133], v[208:211], v[90:93]
	s_setprio 0
	s_barrier
; #define LDA(dst, b, h) _Pragma("unroll") for (int m = 0; m < 4; ++m) _Pragma("unroll") for (int k = 0; k < 2; ++k) \
;     dst[m][k] = *reinterpret_cast<const LAS bf16x8*>(lds + SAo(b, h) + lds_byte(wr * 64 + m * 16 + fr, k * 32 + fq * 8))
; #define LDB(dst, b, h) _Pragma("unroll") for (int n = 0; n < 2; ++n) _Pragma("unroll") for (int k = 0; k < 2; ++k) \
;     dst[n][k] = *reinterpret_cast<const LAS bf16x8*>(lds + SBo(b, h) + lds_byte(wc * 32 + n * 16 + fr, k * 32 + fq * 8))
; #define MMA(ai, bj, At_, Bt_) do { __builtin_amdgcn_s_setprio(1); \
;     _Pragma("unroll") for (int m = 0; m < 4; ++m) _Pragma("unroll") for (int n = 0; n < 2; ++n) _Pragma("unroll") for (int k = 0; k < 2; ++k) \
;       acc[ai][bj][m][n] = __builtin_amdgcn_mfma_f32_16x16x32_bf16(Bt_[n][k], At_[m][k], acc[ai][bj][m][n], 0, 0, 0); \
;     __builtin_amdgcn_s_setprio(0); } while (0)
; #define WAIT_V(n) asm volatile("s_waitcnt vmcnt(" #n ")" ::: "memory")
; #define WAIT_L(n) asm volatile("s_waitcnt lgkmcnt(" #n ")" ::: "memory")
; #define BAR __builtin_amdgcn_s_barrier()
; #define SCHED __builtin_amdgcn_sched_barrier(0)
; template <bool PRE = false>
; __device__ __forceinline__ void gemm_kloop(Acc& acc, const bf16_t* __restrict__ A, int lda, const bf16_t* __restrict__ Bt, int ldb,
;                                            int brow, int bcol, int nt, LAS unsigned char* lds) {
;     ...
;         LDB(B1, 1, 1); STAGE(SBo(1, 0), Bt, ldb, bcol, t + 3, offB);
;         BAR; WAIT_L(0); MMA(0, 1, At, B1); BAR;
;         LDA(At, 1, 1); STAGE(SAo(1, 0), A, lda, brow, t + 3, offA);
;         BAR; WAIT_L(0); MMA(1, 0, At, B0); BAR; SCHED;
;         STAGE(SBo(1, 1), Bt, ldb, bcol + HALF, t + 3, offB);
;         WAIT_V(6); BAR; MMA(1, 1, At, B1); BAR;
	s_mov_b32 s54, 5
	s_mov_b32 s8, s26
	ds_read_b128 v[212:215], v10
	ds_read_b128 v[216:219], v10 offset:1024
	ds_read_b128 v[220:223], v10 offset:2048
	ds_read_b128 v[224:227], v10 offset:3072
	s_ashr_i32 s55, s54, 31
	s_lshl_b64 s[54:55], s[54:55], 7
	s_lshl_b32 s8, s8, 10
	v_lshl_add_u64 v[142:143], v[4:5], 0, s[54:55]
	s_add_i32 s8, s31, s8
	v_lshl_add_u64 v[192:193], v[142:143], 0, s[46:47]
	s_mov_b32 m0, s8
	v_lshl_add_u64 v[142:143], v[142:143], 0, s[48:49]
	v_xor_b32_e32 v192, v197, v192
	global_load_lds_dwordx4 v[192:193], off
	s_add_i32 m0, s8, 0x2000
	s_nop 0
	v_xor_b32_e32 v142, v197, v142
	global_load_lds_dwordx4 v[142:143], off
	s_barrier
	s_waitcnt lgkmcnt(0)
	s_setprio 1
	s_waitcnt lgkmcnt(0)
	v_mfma_f32_16x16x32_bf16 v[110:113], v[212:215], v[134:137], v[110:113]
	v_mfma_f32_16x16x32_bf16 v[30:33], v[220:223], v[134:137], v[30:33]
	v_mfma_f32_16x16x32_bf16 v[34:37], v[212:215], v[170:173], v[34:37]
	v_mfma_f32_16x16x32_bf16 v[38:41], v[220:223], v[170:173], v[38:41]
	v_mfma_f32_16x16x32_bf16 v[42:45], v[212:215], v[184:187], v[42:45]
	v_mfma_f32_16x16x32_bf16 v[46:49], v[220:223], v[184:187], v[46:49]
	v_mfma_f32_16x16x32_bf16 v[50:53], v[212:215], v[204:207], v[50:53]
	v_mfma_f32_16x16x32_bf16 v[54:57], v[220:223], v[204:207], v[54:57]
	v_mfma_f32_16x16x32_bf16 v[110:113], v[216:219], v[138:141], v[110:113]
	v_mfma_f32_16x16x32_bf16 v[30:33], v[224:227], v[138:141], v[30:33]
	v_mfma_f32_16x16x32_bf16 v[34:37], v[216:219], v[174:177], v[34:37]
	v_mfma_f32_16x16x32_bf16 v[38:41], v[224:227], v[174:177], v[38:41]
	v_mfma_f32_16x16x32_bf16 v[42:45], v[216:219], v[188:191], v[42:45]
	v_mfma_f32_16x16x32_bf16 v[46:49], v[224:227], v[188:191], v[46:49]
	v_mfma_f32_16x16x32_bf16 v[50:53], v[216:219], v[208:211], v[50:53]
	v_mfma_f32_16x16x32_bf16 v[54:57], v[224:227], v[208:211], v[54:57]
	s_setprio 0
	s_mov_b32 s46, 5
	s_mov_b32 s8, s26
	s_barrier
	ds_read_b128 v[134:137], v9 offset:49152
	ds_read_b128 v[138:141], v9 offset:50176
	ds_read_b128 v[170:173], v8 offset:51200
	ds_read_b128 v[174:177], v8 offset:52224
	ds_read_b128 v[184:187], v8 offset:53248
	ds_read_b128 v[188:191], v8 offset:54272
	ds_read_b128 v[204:207], v8 offset:55296
	ds_read_b128 v[208:211], v8 offset:56320
	s_ashr_i32 s47, s46, 31
	s_lshl_b64 s[46:47], s[46:47], 7
	s_lshl_b32 s8, s8, 10
	v_lshl_add_u64 v[6:7], v[6:7], 0, s[46:47]
	s_add_i32 s8, s8, 0
	s_add_i32 m0, s8, 0x8000
	v_lshl_add_u64 v[142:143], v[6:7], 0, s[40:41]
	v_xor_b32_e32 v142, v197, v142
	global_load_lds_dwordx4 v[142:143], off
	v_lshl_add_u64 v[6:7], v[6:7], 0, s[42:43]
	s_add_i32 m0, s8, 0xa000
	s_nop 0
	v_xor_b32_e32 v6, v197, v6
	global_load_lds_dwordx4 v[6:7], off
	s_barrier
	s_waitcnt lgkmcnt(0)
	s_setprio 1
	s_waitcnt lgkmcnt(0)
	v_mfma_f32_16x16x32_bf16 v[14:17], v[118:121], v[204:207], v[14:17]
	v_mfma_f32_16x16x32_bf16 v[18:21], v[126:129], v[204:207], v[18:21]
	v_mfma_f32_16x16x32_bf16 v[146:149], v[118:121], v[134:137], v[146:149]
	v_mfma_f32_16x16x32_bf16 v[150:153], v[126:129], v[134:137], v[150:153]
	v_mfma_f32_16x16x32_bf16 v[154:157], v[118:121], v[170:173], v[154:157]
	v_mfma_f32_16x16x32_bf16 v[158:161], v[126:129], v[170:173], v[158:161]
	v_mfma_f32_16x16x32_bf16 v[162:165], v[118:121], v[184:187], v[162:165]
	v_mfma_f32_16x16x32_bf16 v[166:169], v[126:129], v[184:187], v[166:169]
	v_mfma_f32_16x16x32_bf16 v[14:17], v[122:125], v[208:211], v[14:17]
	v_mfma_f32_16x16x32_bf16 v[18:21], v[130:133], v[208:211], v[18:21]
	v_mfma_f32_16x16x32_bf16 v[146:149], v[122:125], v[138:141], v[146:149]
	v_mfma_f32_16x16x32_bf16 v[150:153], v[130:133], v[138:141], v[150:153]
	v_mfma_f32_16x16x32_bf16 v[154:157], v[122:125], v[174:177], v[154:157]
	v_mfma_f32_16x16x32_bf16 v[158:161], v[130:133], v[174:177], v[158:161]
	v_mfma_f32_16x16x32_bf16 v[162:165], v[122:125], v[188:191], v[162:165]
	v_mfma_f32_16x16x32_bf16 v[166:169], v[130:133], v[188:191], v[166:169]
	s_setprio 0
	s_barrier
	s_mov_b32 s40, 5
	s_mov_b32 s8, s26
	s_ashr_i32 s41, s40, 31
	s_lshl_b64 s[40:41], s[40:41], 7
	s_lshl_b32 s8, s8, 10
	v_lshl_add_u64 v[4:5], v[4:5], 0, s[40:41]
	s_add_i32 s8, s24, s8
	v_lshl_add_u64 v[6:7], v[4:5], 0, s[36:37]
	s_mov_b32 m0, s8
	v_lshl_add_u64 v[4:5], v[4:5], 0, s[38:39]
	v_xor_b32_e32 v6, v197, v6
	global_load_lds_dwordx4 v[6:7], off
	s_add_i32 m0, s8, 0x2000
	s_nop 0
	v_xor_b32_e32 v4, v197, v4
	global_load_lds_dwordx4 v[4:5], off
	s_waitcnt vmcnt(6)
	s_barrier
	s_setprio 1
	v_mfma_f32_16x16x32_bf16 v[4:7], v[212:215], v[134:137], v[22:25]
	v_mfma_f32_16x16x32_bf16 v[22:25], v[220:223], v[134:137], v[26:29]
	v_mfma_f32_16x16x32_bf16 v[26:29], v[212:215], v[170:173], v[58:61]
	v_mfma_f32_16x16x32_bf16 v[58:61], v[220:223], v[170:173], v[102:105]
	v_mfma_f32_16x16x32_bf16 v[102:105], v[212:215], v[184:187], v[106:109]
	v_mfma_f32_16x16x32_bf16 v[106:109], v[220:223], v[184:187], v[114:117]
	v_mfma_f32_16x16x32_bf16 v[94:97], v[212:215], v[204:207], v[94:97]
	v_mfma_f32_16x16x32_bf16 v[98:101], v[220:223], v[204:207], v[98:101]
	v_mfma_f32_16x16x32_bf16 v[4:7], v[216:219], v[138:141], v[4:7]
	v_mfma_f32_16x16x32_bf16 v[22:25], v[224:227], v[138:141], v[22:25]
	v_mfma_f32_16x16x32_bf16 v[26:29], v[216:219], v[174:177], v[26:29]
	v_mfma_f32_16x16x32_bf16 v[58:61], v[224:227], v[174:177], v[58:61]
	v_mfma_f32_16x16x32_bf16 v[102:105], v[216:219], v[188:191], v[102:105]
	v_mfma_f32_16x16x32_bf16 v[106:109], v[224:227], v[188:191], v[106:109]
	v_mfma_f32_16x16x32_bf16 v[94:97], v[216:219], v[208:211], v[94:97]
	v_mfma_f32_16x16x32_bf16 v[98:101], v[224:227], v[208:211], v[98:101]
	s_setprio 0
	s_mov_b32 s36, 5
	s_barrier
; #define LDA(dst, b, h) _Pragma("unroll") for (int m = 0; m < 4; ++m) _Pragma("unroll") for (int k = 0; k < 2; ++k) \
;     dst[m][k] = *reinterpret_cast<const LAS bf16x8*>(lds + SAo(b, h) + lds_byte(wr * 64 + m * 16 + fr, k * 32 + fq * 8))
; #define LDB(dst, b, h) _Pragma("unroll") for (int n = 0; n < 2; ++n) _Pragma("unroll") for (int k = 0; k < 2; ++k) \
;     dst[n][k] = *reinterpret_cast<const LAS bf16x8*>(lds + SBo(b, h) + lds_byte(wc * 32 + n * 16 + fr, k * 32 + fq * 8))
; #define MMA(ai, bj, At_, Bt_) do { __builtin_amdgcn_s_setprio(1); \
;     _Pragma("unroll") for (int m = 0; m < 4; ++m) _Pragma("unroll") for (int n = 0; n < 2; ++n) _Pragma("unroll") for (int k = 0; k < 2; ++k) \
;       acc[ai][bj][m][n] = __builtin_amdgcn_mfma_f32_16x16x32_bf16(Bt_[n][k], At_[m][k], acc[ai][bj][m][n], 0, 0, 0); \
;     __builtin_amdgcn_s_setprio(0); } while (0)
; #define WAIT_V(n) asm volatile("s_waitcnt vmcnt(" #n ")" ::: "memory")
; #define WAIT_L(n) asm volatile("s_waitcnt lgkmcnt(" #n ")" ::: "memory")
; #define BAR __builtin_amdgcn_s_barrier()
; template <bool PRE = false>
; __device__ __forceinline__ void gemm_kloop(Acc& acc, const bf16_t* __restrict__ A, int lda, const bf16_t* __restrict__ Bt, int ldb,
;                                            int brow, int bcol, int nt, LAS unsigned char* lds) {
;     ...
;     { LDB(B0, 0, 0); LDA(At, 0, 0); STAGE(SAo(1, 1), A, lda, brow + HALF, nt - 1, offA);
;       BAR; WAIT_L(0); MMA(0, 0, At, B0); BAR;
;       LDB(B1, 0, 1); BAR; WAIT_L(0); MMA(0, 1, At, B1); BAR;
;       LDA(At, 0, 1); WAIT_V(4); BAR; WAIT_L(0); MMA(1, 0, At, B0); MMA(1, 1, At, B1); BAR; }
;     { LDB(B0, 1, 0); LDA(At, 1, 0); WAIT_V(2); BAR; WAIT_L(0); MMA(0, 0, At, B0); BAR;
	ds_read_b128 v[114:117], v13
	ds_read_b128 v[118:121], v13 offset:1024
	ds_read_b128 v[122:125], v13 offset:2048
	ds_read_b128 v[126:129], v13 offset:3072
	ds_read_b128 v[130:133], v9
	ds_read_b128 v[134:137], v9 offset:1024
	ds_read_b128 v[138:141], v8 offset:2048
	ds_read_b128 v[170:173], v8 offset:3072
	ds_read_b128 v[174:177], v8 offset:4096
	ds_read_b128 v[184:187], v8 offset:5120
	ds_read_b128 v[188:191], v8 offset:6144
	ds_read_b128 v[204:207], v8 offset:7168
	s_ashr_i32 s37, s36, 31
	s_lshl_b64 s[36:37], s[36:37], 7
	s_add_u32 s36, s70, s36
	s_addc_u32 s37, s71, s37
	s_lshl_b32 s8, s26, 10
	v_lshl_add_u64 v[2:3], s[36:37], 0, v[2:3]
	s_add_i32 s8, s8, 0
	s_add_i32 m0, s8, 0xc000
	v_lshl_add_u64 v[142:143], v[2:3], 0, s[50:51]
	v_xor_b32_e32 v142, v197, v142
	global_load_lds_dwordx4 v[142:143], off
	v_lshl_add_u64 v[2:3], v[2:3], 0, s[52:53]
	s_add_i32 m0, s8, 0xe000
	s_nop 0
	v_xor_b32_e32 v2, v197, v2
	global_load_lds_dwordx4 v[2:3], off
	s_barrier
	s_waitcnt lgkmcnt(0)
	s_setprio 1
	s_waitcnt lgkmcnt(0)
	v_mfma_f32_16x16x32_bf16 v[62:65], v[114:117], v[130:133], v[62:65]
	v_mfma_f32_16x16x32_bf16 v[66:69], v[122:125], v[130:133], v[66:69]
	v_mfma_f32_16x16x32_bf16 v[70:73], v[114:117], v[138:141], v[70:73]
	v_mfma_f32_16x16x32_bf16 v[74:77], v[122:125], v[138:141], v[74:77]
	v_mfma_f32_16x16x32_bf16 v[78:81], v[114:117], v[174:177], v[78:81]
	v_mfma_f32_16x16x32_bf16 v[82:85], v[122:125], v[174:177], v[82:85]
	v_mfma_f32_16x16x32_bf16 v[86:89], v[114:117], v[188:191], v[86:89]
	v_mfma_f32_16x16x32_bf16 v[62:65], v[118:121], v[134:137], v[62:65]
	v_mfma_f32_16x16x32_bf16 v[66:69], v[126:129], v[134:137], v[66:69]
	v_mfma_f32_16x16x32_bf16 v[70:73], v[118:121], v[170:173], v[70:73]
	v_mfma_f32_16x16x32_bf16 v[74:77], v[126:129], v[170:173], v[74:77]
	v_mfma_f32_16x16x32_bf16 v[78:81], v[118:121], v[184:187], v[78:81]
	v_mfma_f32_16x16x32_bf16 v[82:85], v[126:129], v[184:187], v[82:85]
	v_mfma_f32_16x16x32_bf16 v[86:89], v[118:121], v[204:207], v[86:89]
	v_mfma_f32_16x16x32_bf16 v[90:93], v[122:125], v[188:191], v[90:93]
	v_mfma_f32_16x16x32_bf16 v[208:211], v[126:129], v[204:207], v[90:93]
	s_setprio 0
	s_barrier
	s_nop 4
	ds_read_b128 v[90:93], v12
	ds_read_b128 v[212:215], v12 offset:1024
	ds_read_b128 v[216:219], v12 offset:2048
	ds_read_b128 v[220:223], v12 offset:3072
	s_barrier
	s_waitcnt lgkmcnt(0)
	s_setprio 1
	s_waitcnt lgkmcnt(0)
	v_mfma_f32_16x16x32_bf16 v[50:53], v[90:93], v[188:191], v[50:53]
	v_mfma_f32_16x16x32_bf16 v[110:113], v[90:93], v[130:133], v[110:113]
	v_mfma_f32_16x16x32_bf16 v[30:33], v[216:219], v[130:133], v[30:33]
	v_mfma_f32_16x16x32_bf16 v[34:37], v[90:93], v[138:141], v[34:37]
	v_mfma_f32_16x16x32_bf16 v[38:41], v[216:219], v[138:141], v[38:41]
	v_mfma_f32_16x16x32_bf16 v[42:45], v[90:93], v[174:177], v[42:45]
	v_mfma_f32_16x16x32_bf16 v[46:49], v[216:219], v[174:177], v[46:49]
	v_mfma_f32_16x16x32_bf16 v[130:133], v[212:215], v[204:207], v[50:53]
	v_mfma_f32_16x16x32_bf16 v[50:53], v[216:219], v[188:191], v[54:57]
	v_mfma_f32_16x16x32_bf16 v[110:113], v[212:215], v[134:137], v[110:113]
	v_mfma_f32_16x16x32_bf16 v[30:33], v[220:223], v[134:137], v[30:33]
	v_mfma_f32_16x16x32_bf16 v[34:37], v[212:215], v[170:173], v[34:37]
	v_mfma_f32_16x16x32_bf16 v[38:41], v[220:223], v[170:173], v[38:41]
	v_mfma_f32_16x16x32_bf16 v[42:45], v[212:215], v[184:187], v[42:45]
	v_mfma_f32_16x16x32_bf16 v[46:49], v[220:223], v[184:187], v[46:49]
	v_mfma_f32_16x16x32_bf16 v[54:57], v[220:223], v[204:207], v[50:53]
	s_setprio 0
	s_barrier
	s_nop 0
	ds_read_b128 v[50:53], v9 offset:16384
	ds_read_b128 v[134:137], v9 offset:17408
	ds_read_b128 v[138:141], v8 offset:18432
	ds_read_b128 v[170:173], v8 offset:19456
	ds_read_b128 v[174:177], v8 offset:20480
	ds_read_b128 v[184:187], v8 offset:21504
	ds_read_b128 v[188:191], v8 offset:22528
	ds_read_b128 v[204:207], v8 offset:23552
	s_waitcnt vmcnt(4)
	s_barrier
	s_waitcnt lgkmcnt(0)
	s_setprio 1
	s_waitcnt lgkmcnt(0)
	v_mfma_f32_16x16x32_bf16 v[12:15], v[114:117], v[188:191], v[14:17]
	v_mfma_f32_16x16x32_bf16 v[146:149], v[114:117], v[50:53], v[146:149]
	v_mfma_f32_16x16x32_bf16 v[150:153], v[122:125], v[50:53], v[150:153]
	v_mfma_f32_16x16x32_bf16 v[154:157], v[114:117], v[138:141], v[154:157]
	v_mfma_f32_16x16x32_bf16 v[158:161], v[122:125], v[138:141], v[158:161]
	v_mfma_f32_16x16x32_bf16 v[162:165], v[114:117], v[174:177], v[162:165]
	v_mfma_f32_16x16x32_bf16 v[166:169], v[122:125], v[174:177], v[166:169]
	v_mfma_f32_16x16x32_bf16 v[12:15], v[118:121], v[204:207], v[12:15]
	v_mfma_f32_16x16x32_bf16 v[16:19], v[122:125], v[188:191], v[18:21]
	v_mfma_f32_16x16x32_bf16 v[146:149], v[118:121], v[134:137], v[146:149]
	v_mfma_f32_16x16x32_bf16 v[150:153], v[126:129], v[134:137], v[150:153]
	v_mfma_f32_16x16x32_bf16 v[154:157], v[118:121], v[170:173], v[154:157]
	v_mfma_f32_16x16x32_bf16 v[158:161], v[126:129], v[170:173], v[158:161]
	v_mfma_f32_16x16x32_bf16 v[162:165], v[118:121], v[184:187], v[162:165]
	v_mfma_f32_16x16x32_bf16 v[166:169], v[126:129], v[184:187], v[166:169]
	v_mfma_f32_16x16x32_bf16 v[224:227], v[126:129], v[204:207], v[16:19]
	s_setprio 0
	s_setprio 1
	v_mfma_f32_16x16x32_bf16 v[2:5], v[90:93], v[50:53], v[4:7]
	v_mfma_f32_16x16x32_bf16 v[228:231], v[212:215], v[134:137], v[2:5]
	v_mfma_f32_16x16x32_bf16 v[2:5], v[216:219], v[50:53], v[22:25]
	v_mfma_f32_16x16x32_bf16 v[22:25], v[220:223], v[134:137], v[2:5]
	v_mfma_f32_16x16x32_bf16 v[2:5], v[90:93], v[138:141], v[26:29]
	v_mfma_f32_16x16x32_bf16 v[134:137], v[212:215], v[170:173], v[2:5]
	v_mfma_f32_16x16x32_bf16 v[2:5], v[216:219], v[138:141], v[58:61]
	v_mfma_f32_16x16x32_bf16 v[138:141], v[220:223], v[170:173], v[2:5]
	v_mfma_f32_16x16x32_bf16 v[2:5], v[90:93], v[174:177], v[102:105]
	v_mfma_f32_16x16x32_bf16 v[170:173], v[212:215], v[184:187], v[2:5]
	v_mfma_f32_16x16x32_bf16 v[2:5], v[216:219], v[174:177], v[106:109]
	v_mfma_f32_16x16x32_bf16 v[174:177], v[220:223], v[184:187], v[2:5]
	v_mfma_f32_16x16x32_bf16 v[2:5], v[90:93], v[188:191], v[94:97]
	v_mfma_f32_16x16x32_bf16 v[184:187], v[212:215], v[204:207], v[2:5]
	v_mfma_f32_16x16x32_bf16 v[2:5], v[216:219], v[188:191], v[98:101]
	v_mfma_f32_16x16x32_bf16 v[188:191], v[220:223], v[204:207], v[2:5]
	s_setprio 0
	s_barrier
; #define LDA(dst, b, h) _Pragma("unroll") for (int m = 0; m < 4; ++m) _Pragma("unroll") for (int k = 0; k < 2; ++k) \
;     dst[m][k] = *reinterpret_cast<const LAS bf16x8*>(lds + SAo(b, h) + lds_byte(wr * 64 + m * 16 + fr, k * 32 + fq * 8))
; #define LDB(dst, b, h) _Pragma("unroll") for (int n = 0; n < 2; ++n) _Pragma("unroll") for (int k = 0; k < 2; ++k) \
;     dst[n][k] = *reinterpret_cast<const LAS bf16x8*>(lds + SBo(b, h) + lds_byte(wc * 32 + n * 16 + fr, k * 32 + fq * 8))
; #define MMA(ai, bj, At_, Bt_) do { __builtin_amdgcn_s_setprio(1); \
;     _Pragma("unroll") for (int m = 0; m < 4; ++m) _Pragma("unroll") for (int n = 0; n < 2; ++n) _Pragma("unroll") for (int k = 0; k < 2; ++k) \
;       acc[ai][bj][m][n] = __builtin_amdgcn_mfma_f32_16x16x32_bf16(Bt_[n][k], At_[m][k], acc[ai][bj][m][n], 0, 0, 0); \
;     __builtin_amdgcn_s_setprio(0); } while (0)
; #define WAIT_V(n) asm volatile("s_waitcnt vmcnt(" #n ")" ::: "memory")
; #define WAIT_L(n) asm volatile("s_waitcnt lgkmcnt(" #n ")" ::: "memory")
; #define BAR __builtin_amdgcn_s_barrier()
; template <bool PRE = false>
; __device__ __forceinline__ void gemm_kloop(Acc& acc, const bf16_t* __restrict__ A, int lda, const bf16_t* __restrict__ Bt, int ldb,
;                                            int brow, int bcol, int nt, LAS unsigned char* lds) {
;     ...
;     { LDB(B0, 1, 0); LDA(At, 1, 0); WAIT_V(2); BAR; WAIT_L(0); MMA(0, 0, At, B0); BAR;
;       LDB(B1, 1, 1); WAIT_V(0); BAR; WAIT_L(0); MMA(0, 1, At, B1); BAR;
;       LDA(At, 1, 1); BAR; WAIT_L(0); MMA(1, 0, At, B0); MMA(1, 1, At, B1); BAR; }
;     if (wr == 0) BAR;
	s_nop 4
	ds_read_b128 v[2:5], v11
	ds_read_b128 v[58:61], v11 offset:1024
	ds_read_b128 v[204:207], v11 offset:2048
	ds_read_b128 v[212:215], v11 offset:3072
	ds_read_b128 v[16:19], v9 offset:32768
	ds_read_b128 v[26:29], v9 offset:33792
	ds_read_b128 v[106:109], v8 offset:34816
	ds_read_b128 v[216:219], v8 offset:35840
	ds_read_b128 v[220:223], v8 offset:36864
	ds_read_b128 v[232:235], v8 offset:37888
	ds_read_b128 v[236:239], v8 offset:38912
	ds_read_b128 v[240:243], v8 offset:39936
	s_waitcnt vmcnt(2)
	s_barrier
	s_waitcnt lgkmcnt(0)
	s_setprio 1
	s_waitcnt lgkmcnt(0)
	v_mfma_f32_16x16x32_bf16 v[50:53], v[2:5], v[16:19], v[62:65]
	v_mfma_f32_16x16x32_bf16 v[118:121], v[58:61], v[26:29], v[50:53]
	v_mfma_f32_16x16x32_bf16 v[50:53], v[204:207], v[16:19], v[66:69]
	v_mfma_f32_16x16x32_bf16 v[114:117], v[212:215], v[26:29], v[50:53]
	v_mfma_f32_16x16x32_bf16 v[50:53], v[2:5], v[106:109], v[70:73]
	v_mfma_f32_16x16x32_bf16 v[102:105], v[58:61], v[216:219], v[50:53]
	v_mfma_f32_16x16x32_bf16 v[50:53], v[204:207], v[106:109], v[74:77]
	v_mfma_f32_16x16x32_bf16 v[98:101], v[212:215], v[216:219], v[50:53]
	v_mfma_f32_16x16x32_bf16 v[50:53], v[2:5], v[220:223], v[78:81]
	v_mfma_f32_16x16x32_bf16 v[94:97], v[58:61], v[232:235], v[50:53]
	v_mfma_f32_16x16x32_bf16 v[50:53], v[204:207], v[220:223], v[82:85]
	v_mfma_f32_16x16x32_bf16 v[90:93], v[212:215], v[232:235], v[50:53]
	v_mfma_f32_16x16x32_bf16 v[50:53], v[2:5], v[236:239], v[86:89]
	v_mfma_f32_16x16x32_bf16 v[62:65], v[58:61], v[240:243], v[50:53]
	v_mfma_f32_16x16x32_bf16 v[50:53], v[204:207], v[236:239], v[208:211]
	v_mfma_f32_16x16x32_bf16 v[50:53], v[212:215], v[240:243], v[50:53]
	s_setprio 0
	s_barrier
	ds_read_b128 v[208:211], v10
	ds_read_b128 v[244:247], v10 offset:1024
	ds_read_b128 v[248:251], v10 offset:2048
	ds_read_b128 v[200:203], v10 offset:3072
	s_waitcnt vmcnt(0)
	s_barrier
	s_waitcnt lgkmcnt(0)
	s_setprio 1
	s_waitcnt lgkmcnt(0)
	v_mfma_f32_16x16x32_bf16 v[66:69], v[208:211], v[16:19], v[110:113]
	v_mfma_f32_16x16x32_bf16 v[16:19], v[248:251], v[16:19], v[30:33]
	v_mfma_f32_16x16x32_bf16 v[122:125], v[200:203], v[26:29], v[16:19]
	v_mfma_f32_16x16x32_bf16 v[16:19], v[208:211], v[106:109], v[34:37]
	v_mfma_f32_16x16x32_bf16 v[110:113], v[244:247], v[216:219], v[16:19]
	v_mfma_f32_16x16x32_bf16 v[16:19], v[248:251], v[106:109], v[38:41]
	v_mfma_f32_16x16x32_bf16 v[106:109], v[200:203], v[216:219], v[16:19]
	v_mfma_f32_16x16x32_bf16 v[16:19], v[208:211], v[220:223], v[42:45]
	v_mfma_f32_16x16x32_bf16 v[86:89], v[244:247], v[232:235], v[16:19]
	v_mfma_f32_16x16x32_bf16 v[16:19], v[248:251], v[220:223], v[46:49]
	v_mfma_f32_16x16x32_bf16 v[82:85], v[200:203], v[232:235], v[16:19]
	v_mfma_f32_16x16x32_bf16 v[16:19], v[208:211], v[236:239], v[130:133]
	v_mfma_f32_16x16x32_bf16 v[78:81], v[244:247], v[240:243], v[16:19]
	v_mfma_f32_16x16x32_bf16 v[16:19], v[248:251], v[236:239], v[54:57]
	v_mfma_f32_16x16x32_bf16 v[126:129], v[244:247], v[26:29], v[66:69]
	v_mfma_f32_16x16x32_bf16 v[66:69], v[200:203], v[240:243], v[16:19]
	s_setprio 0
	s_barrier
	ds_read_b128 v[30:33], v9 offset:49152
	ds_read_b128 v[38:41], v9 offset:50176
	ds_read_b128 v[130:133], v8 offset:51200
	ds_read_b128 v[216:219], v8 offset:52224
	ds_read_b128 v[220:223], v8 offset:53248
	ds_read_b128 v[232:235], v8 offset:54272
	ds_read_b128 v[236:239], v8 offset:55296
	ds_read_b128 v[6:9], v8 offset:56320
	s_barrier
	s_waitcnt lgkmcnt(0)
	s_setprio 1
	s_waitcnt lgkmcnt(0)
	v_mfma_f32_16x16x32_bf16 v[16:19], v[2:5], v[30:33], v[146:149]
	v_mfma_f32_16x16x32_bf16 v[70:73], v[58:61], v[38:41], v[16:19]
	v_mfma_f32_16x16x32_bf16 v[16:19], v[204:207], v[30:33], v[150:153]
	v_mfma_f32_16x16x32_bf16 v[54:57], v[212:215], v[38:41], v[16:19]
	v_mfma_f32_16x16x32_bf16 v[16:19], v[2:5], v[130:133], v[154:157]
	v_mfma_f32_16x16x32_bf16 v[42:45], v[58:61], v[216:219], v[16:19]
	v_mfma_f32_16x16x32_bf16 v[16:19], v[204:207], v[130:133], v[158:161]
	v_mfma_f32_16x16x32_bf16 v[34:37], v[212:215], v[216:219], v[16:19]
	v_mfma_f32_16x16x32_bf16 v[16:19], v[2:5], v[220:223], v[162:165]
	v_mfma_f32_16x16x32_bf16 v[2:5], v[2:5], v[236:239], v[12:15]
	v_mfma_f32_16x16x32_bf16 v[26:29], v[58:61], v[232:235], v[16:19]
	v_mfma_f32_16x16x32_bf16 v[16:19], v[204:207], v[220:223], v[166:169]
	v_mfma_f32_16x16x32_bf16 v[10:13], v[58:61], v[6:9], v[2:5]
	v_mfma_f32_16x16x32_bf16 v[2:5], v[204:207], v[236:239], v[224:227]
	v_mfma_f32_16x16x32_bf16 v[18:21], v[212:215], v[232:235], v[16:19]
	v_mfma_f32_16x16x32_bf16 v[2:5], v[212:215], v[6:9], v[2:5]
	s_setprio 0
	s_setprio 1
	v_mfma_f32_16x16x32_bf16 v[14:17], v[208:211], v[30:33], v[228:231]
	v_mfma_f32_16x16x32_bf16 v[74:77], v[244:247], v[38:41], v[14:17]
	v_mfma_f32_16x16x32_bf16 v[14:17], v[248:251], v[30:33], v[22:25]
	v_mfma_f32_16x16x32_bf16 v[58:61], v[200:203], v[38:41], v[14:17]
	v_mfma_f32_16x16x32_bf16 v[14:17], v[208:211], v[130:133], v[134:137]
	v_mfma_f32_16x16x32_bf16 v[46:49], v[244:247], v[216:219], v[14:17]
	v_mfma_f32_16x16x32_bf16 v[14:17], v[248:251], v[130:133], v[138:141]
	v_mfma_f32_16x16x32_bf16 v[38:41], v[200:203], v[216:219], v[14:17]
	v_mfma_f32_16x16x32_bf16 v[14:17], v[208:211], v[220:223], v[170:173]
	v_mfma_f32_16x16x32_bf16 v[30:33], v[244:247], v[232:235], v[14:17]
	v_mfma_f32_16x16x32_bf16 v[14:17], v[248:251], v[220:223], v[174:177]
	v_mfma_f32_16x16x32_bf16 v[22:25], v[200:203], v[232:235], v[14:17]
	v_mfma_f32_16x16x32_bf16 v[14:17], v[208:211], v[236:239], v[184:187]
	v_mfma_f32_16x16x32_bf16 v[130:133], v[248:251], v[236:239], v[188:191]
	v_mfma_f32_16x16x32_bf16 v[14:17], v[244:247], v[6:9], v[14:17]
	v_mfma_f32_16x16x32_bf16 v[6:9], v[200:203], v[6:9], v[130:133]
	s_setprio 0
	v_cmp_gt_u32_e32 vcc, s85, v1
	s_barrier
	s_and_saveexec_b64 s[36:37], vcc
	s_cbranch_execz .LBB0_326
	s_barrier
	s_branch .LBB0_326

; #define LAS __attribute__((address_space(3)))
; __device__ __forceinline__ int fresh_tid() { int t; asm volatile("v_mov_b32 %0, %1" : "=v"(t) : "v"(threadIdx.x)); return t; }
; __device__ __forceinline__ int fresh_bid() { int t; asm volatile("s_mov_b32 %0, %1" : "=s"(t) : "s"(blockIdx.x)); return t; }
; __device__ __forceinline__ void gemm_stage_first(const bf16_t* __restrict__ A, int lda, const bf16_t* __restrict__ Bt, int ldb, int brow, int bcol, LAS unsigned char* lds) {
;     const int tid = fresh_tid();
;     const int wvu = __builtin_amdgcn_readfirstlane(tid >> 6);
;     unsigned offA, offB;
;     { int _r, _c; stage_rc(tid * 16, _r, _c); offA = (unsigned)(_r * lda + _c) * 2u; offB = (unsigned)(_r * ldb + _c) * 2u; }
;     STAGE(SBo(0, 0), Bt, ldb, bcol, 0, offB); STAGE(SAo(0, 0), A, lda, brow, 0, offA);
;     STAGE(SBo(0, 1), Bt, ldb, bcol + HALF, 0, offB); STAGE(SAo(0, 1), A, lda, brow + HALF, 0, offA);
; }
; __device__ __forceinline__ void phase_proj(const Ctx& a, int b, LAS unsigned char* lds) {
;     ...
;     const int nM = SEQ / 256, ntile = nM * (PA / 256);
;     { const int w0 = fresh_bid(); if (w0 < ntile) { int pm0, pn0; tile_of(w0, nM, pm0, pn0); gemm_stage_first(xb, DM, W, DM, pm0 * 256, pn0 * 256, lds); } }
.LBB0_531:
	s_andn2_b64 vcc, exec, s[44:45]
	s_cbranch_vccnz .LBB0_535
	s_mov_b32 s0, s2
	s_cmpk_gt_i32 s0, 0x1ff
	s_cbranch_scc1 .LBB0_534
	s_ashr_i32 s1, s0, 31
	s_lshr_b32 s1, s1, 27
	s_add_i32 s1, s0, s1
	v_mov_b32 v1, v179
	s_and_b32 s8, s1, 0xffffe0
	s_waitcnt vmcnt(0) lgkmcnt(0)
	v_ashrrev_i32_e32 v3, 31, v1
	s_lshl_b32 s1, s1, 3
	v_lshrrev_b32_e32 v3, 26, v3
	s_and_b32 s12, s1, 0xffffff00
	v_readfirstlane_b32 s1, v1
	v_lshlrev_b32_e32 v2, 4, v1
	v_add_u32_e32 v3, v1, v3
	v_bfe_i32 v1, v1, 27, 1
	v_lshrrev_b32_e32 v1, 22, v1
	v_add_u32_e32 v1, v2, v1
	v_and_b32_e32 v1, 0xfffffc00, v1
	v_sub_u32_e32 v1, v2, v1
	v_lshrrev_b32_e32 v2, 4, v1
	v_bitop3_b32 v2, v2, v1, 32 bitop3:0x6c
	v_ashrrev_i32_e32 v1, 31, v1
	v_lshrrev_b32_e32 v1, 26, v1
	v_add_u32_e32 v1, v2, v1
	s_sub_i32 s0, s0, s8
	s_ashr_i32 s8, s1, 6
	v_ashrrev_i32_e32 v1, 6, v1
	v_ashrrev_i32_e32 v3, 6, v3
	v_mul_i32_i24_e32 v5, 64, v1
	s_mov_b32 s1, s8
	s_mov_b32 s36, s27
	v_lshlrev_b32_e32 v4, 3, v3
	v_lshlrev_b32_e32 v3, 5, v3
	v_sub_u32_e32 v2, v2, v5
	s_ashr_i32 s37, s36, 31
	s_lshl_b32 s0, s0, 8
	v_and_b32_e32 v4, 0x1ffff0, v4
	v_and_b32_e32 v3, 32, v3
	v_ashrrev_i16_sdwa v2, v194, sext(v2) dst_sel:DWORD dst_unused:UNUSED_PAD src0_sel:DWORD src1_sel:BYTE_0
	s_lshl_b64 s[36:37], s[36:37], 7
	v_add_u32_sdwa v2, v3, sext(v2) dst_sel:DWORD dst_unused:UNUSED_PAD src0_sel:DWORD src1_sel:WORD_0
	v_add_lshl_u32 v1, v1, v4, 11
	s_add_u32 s36, s86, s36
	v_lshl_add_u32 v144, v2, 1, v1
	s_addc_u32 s37, s87, s37
	s_ashr_i32 s13, s12, 31
	v_lshl_add_u64 v[2:3], s[36:37], 0, v[144:145]
	s_lshl_b64 s[36:37], s[12:13], 11
	s_lshl_b32 s1, s1, 10
	v_lshl_add_u64 v[4:5], v[2:3], 0, s[36:37]
	s_or_b32 s36, s12, 64
	s_add_i32 s1, s1, 0
	s_ashr_i32 s37, s36, 31
	s_add_i32 m0, s1, 0x10000
	s_lshl_b64 s[36:37], s[36:37], 11
	v_xor_b32_e32 v4, v197, v4
	global_load_lds_dwordx4 v[4:5], off
	v_lshl_add_u64 v[2:3], v[2:3], 0, s[36:37]
	s_add_i32 m0, s1, 0x12000
	s_mov_b32 s1, s8
	s_mov_b32 s36, s27
	v_xor_b32_e32 v2, v197, v2
	global_load_lds_dwordx4 v[2:3], off
	s_ashr_i32 s37, s36, 31
	s_lshl_b64 s[36:37], s[36:37], 7
	v_readlane_b32 s6, v254, 54
	v_readlane_b32 s7, v254, 55
	s_add_u32 s36, s6, s36
	s_addc_u32 s37, s7, s37
	s_lshl_b32 s1, s1, 10
	s_add_i32 s9, s1, 0
	s_ashr_i32 s1, s0, 31
	v_lshl_add_u64 v[2:3], s[36:37], 0, v[144:145]
	s_lshl_b64 s[36:37], s[0:1], 11
	v_lshl_add_u64 v[4:5], v[2:3], 0, s[36:37]
	s_or_b32 s36, s0, 64
	s_ashr_i32 s37, s36, 31
	s_mov_b32 m0, s9
	s_lshl_b64 s[36:37], s[36:37], 11
	v_xor_b32_e32 v4, v197, v4
	global_load_lds_dwordx4 v[4:5], off
	v_lshl_add_u64 v[2:3], v[2:3], 0, s[36:37]
	s_add_i32 m0, s9, 0x2000
	s_mov_b32 s1, s8
	s_mov_b32 s36, s27
	v_xor_b32_e32 v2, v197, v2
	global_load_lds_dwordx4 v[2:3], off
	s_ashr_i32 s37, s36, 31
	s_or_b32 s38, s12, 0x80
	s_lshl_b64 s[36:37], s[36:37], 7
	s_add_u32 s36, s86, s36
	s_addc_u32 s37, s87, s37
	s_lshl_b32 s1, s1, 10
	s_ashr_i32 s39, s38, 31
	s_or_b32 s12, s12, 0xc0
	v_lshl_add_u64 v[2:3], s[36:37], 0, v[144:145]
	s_add_i32 s1, s1, 0
	s_lshl_b64 s[36:37], s[38:39], 11
	s_ashr_i32 s13, s12, 31
	s_add_i32 m0, s1, 0x14000
	v_lshl_add_u64 v[4:5], v[2:3], 0, s[36:37]
	s_lshl_b64 s[12:13], s[12:13], 11
	v_xor_b32_e32 v4, v197, v4
	global_load_lds_dwordx4 v[4:5], off
	v_lshl_add_u64 v[2:3], v[2:3], 0, s[12:13]
	s_add_i32 m0, s1, 0x16000
	s_mov_b32 s12, s27
	v_xor_b32_e32 v2, v197, v2
	global_load_lds_dwordx4 v[2:3], off
	s_ashr_i32 s13, s12, 31
	s_or_b32 s36, s0, 0x80
	s_lshl_b64 s[12:13], s[12:13], 7
	s_add_u32 s12, s6, s12
	s_addc_u32 s13, s7, s13
	s_lshl_b32 s1, s8, 10
	s_ashr_i32 s37, s36, 31
	s_or_b32 s0, s0, 0xc0
	v_lshl_add_u64 v[2:3], s[12:13], 0, v[144:145]
	s_add_i32 s8, s1, 0
	s_lshl_b64 s[12:13], s[36:37], 11
	s_ashr_i32 s1, s0, 31
	s_add_i32 m0, s8, 0x4000
	v_lshl_add_u64 v[4:5], v[2:3], 0, s[12:13]
	s_lshl_b64 s[0:1], s[0:1], 11
	v_xor_b32_e32 v4, v197, v4
	global_load_lds_dwordx4 v[4:5], off
	v_lshl_add_u64 v[2:3], v[2:3], 0, s[0:1]
	s_add_i32 m0, s8, 0x6000
	s_nop 0
	v_xor_b32_e32 v2, v197, v2
	global_load_lds_dwordx4 v[2:3], off

; __device__ __forceinline__ int fresh_tid() { int t; asm volatile("v_mov_b32 %0, %1" : "=v"(t) : "v"(threadIdx.x)); return t; }
; #define WAIT_V(n) asm volatile("s_waitcnt vmcnt(" #n ")" ::: "memory")
; #define BAR __builtin_amdgcn_s_barrier()
; template <bool PRE = false>
; __device__ __forceinline__ void gemm_kloop(Acc& acc, const bf16_t* __restrict__ A, int lda, const bf16_t* __restrict__ Bt, int ldb,
;                                            int brow, int bcol, int nt, LAS unsigned char* lds) {
;     const int tid = fresh_tid();
;     const int wid = tid >> 6, lane = tid & 63, wr = wid >> 2, wc = wid & 3, fr = lane & 15, fq = lane >> 4;
;     const int wvu = __builtin_amdgcn_readfirstlane(tid >> 6);
;     unsigned offA, offB;
;     { int _r, _c; stage_rc(tid * 16, _r, _c); offA = (unsigned)(_r * lda + _c) * 2u; offB = (unsigned)(_r * ldb + _c) * 2u; }
;     ...
;     bf16x8 At[4][2], B0[2][2], B1[2][2];
;     if (!PRE) {
;     STAGE(SBo(0, 0), Bt, ldb, bcol, 0, offB); STAGE(SAo(0, 0), A, lda, brow, 0, offA);
;     STAGE(SBo(0, 1), Bt, ldb, bcol + HALF, 0, offB); STAGE(SAo(0, 1), A, lda, brow + HALF, 0, offA);
;     }
;     if (wr == 1) BAR;
;     WAIT_V(4); BAR;
;     STAGE(SBo(1, 0), Bt, ldb, bcol, 1, offB); STAGE(SAo(1, 0), A, lda, brow, 1, offA); STAGE(SBo(1, 1), Bt, ldb, bcol + HALF, 1, offB);
;     WAIT_V(6); BAR;
.LBB0_542:
	s_or_b64 exec, exec, s[0:1]
	v_bfe_i32 v6, v1, 27, 1
	v_lshlrev_b32_e32 v4, 4, v1
	v_lshrrev_b32_e32 v6, 22, v6
	v_add_u32_e32 v6, v4, v6
	v_and_b32_e32 v6, 0xfffffc00, v6
	v_sub_u32_e32 v4, v4, v6
	v_lshrrev_b32_e32 v6, 4, v4
	s_ashr_i32 s0, s9, 31
	v_bitop3_b32 v6, v6, v4, 32 bitop3:0x6c
	v_ashrrev_i32_e32 v4, 31, v4
	s_lshr_b32 s0, s0, 27
	v_ashrrev_i32_e32 v5, 31, v1
	v_lshrrev_b32_e32 v4, 26, v4
	s_add_i32 s1, s9, s0
	v_lshrrev_b32_e32 v5, 26, v5
	v_add_u32_e32 v4, v6, v4
	s_and_b32 s0, s1, 0xffffe0
	s_lshl_b32 s1, s1, 3
	v_add_u32_e32 v5, v1, v5
	v_ashrrev_i32_e32 v4, 6, v4
	s_and_b32 s12, s1, 0xffffff00
	v_ashrrev_i32_e32 v5, 6, v5
	v_mul_i32_i24_e32 v10, 64, v4
	s_mov_b32 s36, 1
	s_mov_b32 s1, s26
	s_sub_i32 s0, s9, s0
	v_lshlrev_b32_e32 v7, 3, v5
	v_lshlrev_b32_e32 v5, 5, v5
	v_sub_u32_e32 v6, v6, v10
	s_waitcnt vmcnt(4)
	s_barrier
	s_ashr_i32 s37, s36, 31
	s_lshl_b32 s0, s0, 8
	v_and_b32_e32 v7, 0x1ffff0, v7
	v_and_b32_e32 v5, 32, v5
	v_ashrrev_i16_sdwa v6, v194, sext(v6) dst_sel:DWORD dst_unused:UNUSED_PAD src0_sel:DWORD src1_sel:BYTE_0
	s_lshl_b64 s[36:37], s[36:37], 7
	v_add_u32_sdwa v5, v5, sext(v6) dst_sel:DWORD dst_unused:UNUSED_PAD src0_sel:DWORD src1_sel:WORD_0
	v_add_lshl_u32 v4, v4, v7, 11
	s_add_u32 s36, s86, s36
	v_lshl_add_u32 v144, v5, 1, v4
	s_addc_u32 s37, s87, s37
	s_lshl_b32 s1, s1, 10
	s_ashr_i32 s13, s12, 31
	s_or_b32 s38, s12, 64
	v_lshl_add_u64 v[4:5], s[36:37], 0, v[144:145]
	s_add_i32 s1, s31, s1
	s_lshl_b64 s[36:37], s[12:13], 11
	s_ashr_i32 s39, s38, 31
	v_lshl_add_u64 v[6:7], v[4:5], 0, s[36:37]
	s_mov_b32 m0, s1
	s_lshl_b64 s[38:39], s[38:39], 11
	v_xor_b32_e32 v6, v197, v6
	global_load_lds_dwordx4 v[6:7], off
	v_lshl_add_u64 v[4:5], v[4:5], 0, s[38:39]
	s_add_i32 m0, s1, 0x2000
	s_mov_b32 s40, 1
	s_mov_b32 s1, s26
	v_xor_b32_e32 v4, v197, v4
	global_load_lds_dwordx4 v[4:5], off
	s_ashr_i32 s41, s40, 31
	s_lshl_b64 s[40:41], s[40:41], 7
	v_readlane_b32 s6, v254, 54
	v_readlane_b32 s7, v254, 55
	s_add_u32 s40, s6, s40
	s_addc_u32 s41, s7, s41
	s_lshl_b32 s1, s1, 10
	s_add_i32 s8, s1, 0
	s_ashr_i32 s1, s0, 31
	s_or_b32 s42, s0, 64
	v_lshl_add_u64 v[4:5], s[40:41], 0, v[144:145]
	s_lshl_b64 s[40:41], s[0:1], 11
	s_ashr_i32 s43, s42, 31
	s_add_i32 m0, s8, 0x8000
	v_lshl_add_u64 v[6:7], v[4:5], 0, s[40:41]
	s_lshl_b64 s[42:43], s[42:43], 11
	v_xor_b32_e32 v6, v197, v6
	global_load_lds_dwordx4 v[6:7], off
	v_lshl_add_u64 v[4:5], v[4:5], 0, s[42:43]
	s_add_i32 m0, s8, 0xa000
	s_mov_b32 s44, 1
	s_mov_b32 s1, s26
	v_xor_b32_e32 v4, v197, v4
	global_load_lds_dwordx4 v[4:5], off
	s_ashr_i32 s45, s44, 31
	s_or_b32 s46, s12, 0x80
	s_lshl_b64 s[44:45], s[44:45], 7
	s_add_u32 s44, s86, s44
	s_addc_u32 s45, s87, s45
	s_ashr_i32 s47, s46, 31
	v_lshl_add_u64 v[4:5], s[44:45], 0, v[144:145]
	s_lshl_b32 s1, s1, 10
	s_lshl_b64 s[44:45], s[46:47], 11
	s_or_b32 s46, s12, 0xc0
	s_add_i32 s1, s24, s1
	s_ashr_i32 s47, s46, 31
	v_lshl_add_u64 v[6:7], v[4:5], 0, s[44:45]
	s_mov_b32 m0, s1
	s_lshl_b64 s[46:47], s[46:47], 11
	v_xor_b32_e32 v6, v197, v6
	global_load_lds_dwordx4 v[6:7], off
	v_lshl_add_u64 v[4:5], v[4:5], 0, s[46:47]
	s_add_i32 m0, s1, 0x2000
	v_and_b32_e32 v8, 15, v1
	v_xor_b32_e32 v4, v197, v4
	global_load_lds_dwordx4 v[4:5], off
	v_lshlrev_b32_e32 v5, 2, v1
	v_and_b32_e32 v9, 48, v1
	v_lshlrev_b32_e32 v4, 6, v8
	v_and_b32_e32 v5, 32, v5
	v_bitop3_b32 v4, v4, v5, v9 bitop3:0x36
	s_add_i32 s1, 0, 0x10000
	v_lshlrev_b32_e32 v11, 13, v2
	v_lshlrev_b32_e32 v2, 6, v1
	s_waitcnt vmcnt(6)
	v_lshlrev_b32_e32 v3, 12, v3
	v_add_u32_e32 v6, s1, v4
	s_or_b32 s48, s0, 0x80
	s_add_i32 s1, 0, 0x14000
	v_and_or_b32 v2, v2, s25, v9
	s_or_b32 s50, s0, 0xc0
	v_and_b32_e32 v3, 0x3000, v3
	v_add_u32_e32 v7, s1, v4
	v_add_u32_e32 v8, s31, v4
	v_add_u32_e32 v10, s24, v4
	v_add_u32_e32 v4, 0, v4
	v_xad_u32 v5, v2, v5, 0
	v_or_b32_e32 v9, 0x800, v11
	v_or_b32_e32 v12, 0x1000, v11
	v_or_b32_e32 v13, 0x1800, v11
	s_ashr_i32 s49, s48, 31
	s_ashr_i32 s51, s50, 31
	v_mov_b32_e32 v2, 0
	v_lshl_add_u64 v[130:131], s[6:7], 0, v[144:145]
	v_lshl_add_u64 v[132:133], s[86:87], 0, v[144:145]
	s_lshl_b64 s[48:49], s[48:49], 11
	s_lshl_b64 s[50:51], s[50:51], 11
	s_mov_b32 s1, -2
	v_add_u32_e32 v141, v6, v3
	v_add_u32_e32 v137, v4, v11
	v_add_u32_e32 v136, v5, v9
	v_add_u32_e32 v135, v5, v12
	v_add_u32_e32 v134, v5, v13
	v_add_u32_e32 v140, v7, v3
	v_add_u32_e32 v139, v8, v3
	v_add_u32_e32 v138, v10, v3
	v_mov_b32_e32 v3, v2
	v_mov_b32_e32 v4, v2
	v_mov_b32_e32 v5, v2
	v_mov_b32_e32 v6, v2
	v_mov_b32_e32 v7, v2
	v_mov_b32_e32 v8, v2
	v_mov_b32_e32 v9, v2
	v_mov_b32_e32 v10, v2
	v_mov_b32_e32 v11, v2
	v_mov_b32_e32 v12, v2
	v_mov_b32_e32 v13, v2
	v_mov_b32_e32 v14, v2
	v_mov_b32_e32 v15, v2
	v_mov_b32_e32 v16, v2
	v_mov_b32_e32 v17, v2
	v_mov_b32_e32 v18, v2
	v_mov_b32_e32 v19, v2
	v_mov_b32_e32 v20, v2
	v_mov_b32_e32 v21, v2
	v_mov_b32_e32 v22, v2
	v_mov_b32_e32 v23, v2
	v_mov_b32_e32 v24, v2
	v_mov_b32_e32 v25, v2
	v_mov_b32_e32 v26, v2
	v_mov_b32_e32 v27, v2
	v_mov_b32_e32 v28, v2
	v_mov_b32_e32 v29, v2
	v_mov_b32_e32 v30, v2
	v_mov_b32_e32 v31, v2
	v_mov_b32_e32 v32, v2
	v_mov_b32_e32 v33, v2
	v_mov_b32_e32 v34, v2
	v_mov_b32_e32 v35, v2
	v_mov_b32_e32 v36, v2
	v_mov_b32_e32 v37, v2
	v_mov_b32_e32 v38, v2
	v_mov_b32_e32 v39, v2
	v_mov_b32_e32 v40, v2
	v_mov_b32_e32 v41, v2
	v_mov_b32_e32 v42, v2
	v_mov_b32_e32 v43, v2
	v_mov_b32_e32 v44, v2
	v_mov_b32_e32 v45, v2
	v_mov_b32_e32 v46, v2
	v_mov_b32_e32 v47, v2
	v_mov_b32_e32 v48, v2
	v_mov_b32_e32 v49, v2
	v_mov_b32_e32 v50, v2
	v_mov_b32_e32 v51, v2
	v_mov_b32_e32 v52, v2
	v_mov_b32_e32 v53, v2
	v_mov_b32_e32 v54, v2
	v_mov_b32_e32 v55, v2
	v_mov_b32_e32 v56, v2
	v_mov_b32_e32 v57, v2
; #define LDA(dst, b, h) _Pragma("unroll") for (int m = 0; m < 4; ++m) _Pragma("unroll") for (int k = 0; k < 2; ++k) \
;     dst[m][k] = *reinterpret_cast<const LAS bf16x8*>(lds + SAo(b, h) + lds_byte(wr * 64 + m * 16 + fr, k * 32 + fq * 8))
; #define LDB(dst, b, h) _Pragma("unroll") for (int n = 0; n < 2; ++n) _Pragma("unroll") for (int k = 0; k < 2; ++k) \
;     dst[n][k] = *reinterpret_cast<const LAS bf16x8*>(lds + SBo(b, h) + lds_byte(wc * 32 + n * 16 + fr, k * 32 + fq * 8))
; #define MMA(ai, bj, At_, Bt_) do { __builtin_amdgcn_s_setprio(1); \
;     _Pragma("unroll") for (int m = 0; m < 4; ++m) _Pragma("unroll") for (int n = 0; n < 2; ++n) _Pragma("unroll") for (int k = 0; k < 2; ++k) \
;       acc[ai][bj][m][n] = __builtin_amdgcn_mfma_f32_16x16x32_bf16(Bt_[n][k], At_[m][k], acc[ai][bj][m][n], 0, 0, 0); \
;     __builtin_amdgcn_s_setprio(0); } while (0)
; #define WAIT_L(n) asm volatile("s_waitcnt lgkmcnt(" #n ")" ::: "memory")
; #define BAR __builtin_amdgcn_s_barrier()
; #define SCHED __builtin_amdgcn_sched_barrier(0)
; template <bool PRE = false>
; __device__ __forceinline__ void gemm_kloop(Acc& acc, const bf16_t* __restrict__ A, int lda, const bf16_t* __restrict__ Bt, int ldb,
;                                            int brow, int bcol, int nt, LAS unsigned char* lds) {
;     ...
;     for (int t = 0; t < nt - 2; t += 2) {
;         LDB(B0, 0, 0); SCHED; LDA(At, 0, 0); STAGE(SAo(1, 1), A, lda, brow + HALF, t + 1, offA);
;         WAIT_L(8); BAR; WAIT_L(0); MMA(0, 0, At, B0); BAR; SCHED;
;         LDB(B1, 0, 1); STAGE(SBo(0, 0), Bt, ldb, bcol, t + 2, offB);
;         BAR; WAIT_L(0); MMA(0, 1, At, B1); BAR;
	v_mov_b32_e32 v58, v2
	v_mov_b32_e32 v59, v2
	v_mov_b32_e32 v60, v2
	v_mov_b32_e32 v61, v2
	v_mov_b32_e32 v62, v2
	v_mov_b32_e32 v63, v2
	v_mov_b32_e32 v64, v2
	v_mov_b32_e32 v65, v2
	v_mov_b32_e32 v66, v2
	v_mov_b32_e32 v67, v2
	v_mov_b32_e32 v68, v2
	v_mov_b32_e32 v69, v2
	v_mov_b32_e32 v70, v2
	v_mov_b32_e32 v71, v2
	v_mov_b32_e32 v72, v2
	v_mov_b32_e32 v73, v2
	v_mov_b32_e32 v74, v2
	v_mov_b32_e32 v75, v2
	v_mov_b32_e32 v76, v2
	v_mov_b32_e32 v77, v2
	v_mov_b32_e32 v78, v2
	v_mov_b32_e32 v79, v2
	v_mov_b32_e32 v80, v2
	v_mov_b32_e32 v81, v2
	v_mov_b32_e32 v82, v2
	v_mov_b32_e32 v83, v2
	v_mov_b32_e32 v84, v2
	v_mov_b32_e32 v85, v2
	v_mov_b32_e32 v86, v2
	v_mov_b32_e32 v87, v2
	v_mov_b32_e32 v88, v2
	v_mov_b32_e32 v89, v2
	v_mov_b32_e32 v90, v2
	v_mov_b32_e32 v91, v2
	v_mov_b32_e32 v92, v2
	v_mov_b32_e32 v93, v2
	v_mov_b32_e32 v94, v2
	v_mov_b32_e32 v95, v2
	v_mov_b32_e32 v96, v2
	v_mov_b32_e32 v97, v2
	v_mov_b32_e32 v98, v2
	v_mov_b32_e32 v99, v2
	v_mov_b32_e32 v100, v2
	v_mov_b32_e32 v101, v2
	v_mov_b32_e32 v102, v2
	v_mov_b32_e32 v103, v2
	v_mov_b32_e32 v104, v2
	v_mov_b32_e32 v105, v2
	v_mov_b32_e32 v106, v2
	v_mov_b32_e32 v107, v2
	v_mov_b32_e32 v108, v2
	v_mov_b32_e32 v109, v2
	v_mov_b32_e32 v110, v2
	v_mov_b32_e32 v111, v2
	v_mov_b32_e32 v112, v2
	v_mov_b32_e32 v113, v2
	v_mov_b32_e32 v114, v2
	v_mov_b32_e32 v115, v2
	v_mov_b32_e32 v116, v2
	v_mov_b32_e32 v117, v2
	v_mov_b32_e32 v118, v2
	v_mov_b32_e32 v119, v2
	v_mov_b32_e32 v120, v2
	v_mov_b32_e32 v121, v2
	v_mov_b32_e32 v122, v2
	v_mov_b32_e32 v123, v2
	v_mov_b32_e32 v124, v2
	v_mov_b32_e32 v125, v2
	v_mov_b32_e32 v126, v2
	v_mov_b32_e32 v127, v2
	v_mov_b32_e32 v128, v2
	v_mov_b32_e32 v129, v2
	s_barrier
.LBB0_543:
	ds_read_b128 v[146:149], v141
	ds_read_b128 v[150:153], v141 offset:1024
	ds_read_b128 v[154:157], v141 offset:2048
	ds_read_b128 v[158:161], v141 offset:3072
	s_add_i32 s52, s1, 3
	s_mov_b32 s8, s26
	ds_read_b128 v[162:165], v137
	ds_read_b128 v[166:169], v137 offset:1024
	ds_read_b128 v[170:173], v136
	ds_read_b128 v[174:177], v136 offset:1024
	ds_read_b128 v[184:187], v135
	ds_read_b128 v[188:191], v135 offset:1024
	ds_read_b128 v[204:207], v134
	ds_read_b128 v[208:211], v134 offset:1024
	s_ashr_i32 s53, s52, 31
	s_lshl_b64 s[52:53], s[52:53], 7
	s_lshl_b32 s8, s8, 10
	v_lshl_add_u64 v[142:143], v[130:131], 0, s[52:53]
	s_add_i32 s8, s8, 0
	s_add_i32 m0, s8, 0xc000
	v_lshl_add_u64 v[192:193], v[142:143], 0, s[48:49]
	v_xor_b32_e32 v192, v197, v192
	global_load_lds_dwordx4 v[192:193], off
	v_lshl_add_u64 v[142:143], v[142:143], 0, s[50:51]
	s_add_i32 m0, s8, 0xe000
	s_nop 0
	v_xor_b32_e32 v142, v197, v142
	global_load_lds_dwordx4 v[142:143], off
	s_waitcnt lgkmcnt(8)
	s_barrier
	s_waitcnt lgkmcnt(0)
	s_setprio 1
	s_waitcnt lgkmcnt(0)
	v_mfma_f32_16x16x32_bf16 v[126:129], v[146:149], v[162:165], v[126:129]
	v_mfma_f32_16x16x32_bf16 v[122:125], v[154:157], v[162:165], v[122:125]
	v_mfma_f32_16x16x32_bf16 v[118:121], v[146:149], v[170:173], v[118:121]
	v_mfma_f32_16x16x32_bf16 v[114:117], v[154:157], v[170:173], v[114:117]
	v_mfma_f32_16x16x32_bf16 v[110:113], v[146:149], v[184:187], v[110:113]
	v_mfma_f32_16x16x32_bf16 v[106:109], v[154:157], v[184:187], v[106:109]
	v_mfma_f32_16x16x32_bf16 v[102:105], v[146:149], v[204:207], v[102:105]
	v_mfma_f32_16x16x32_bf16 v[98:101], v[154:157], v[204:207], v[98:101]
	v_mfma_f32_16x16x32_bf16 v[126:129], v[150:153], v[166:169], v[126:129]
	v_mfma_f32_16x16x32_bf16 v[122:125], v[158:161], v[166:169], v[122:125]
	v_mfma_f32_16x16x32_bf16 v[118:121], v[150:153], v[174:177], v[118:121]
	v_mfma_f32_16x16x32_bf16 v[114:117], v[158:161], v[174:177], v[114:117]
	v_mfma_f32_16x16x32_bf16 v[110:113], v[150:153], v[188:191], v[110:113]
	v_mfma_f32_16x16x32_bf16 v[106:109], v[158:161], v[188:191], v[106:109]
	v_mfma_f32_16x16x32_bf16 v[102:105], v[150:153], v[208:211], v[102:105]
	v_mfma_f32_16x16x32_bf16 v[98:101], v[158:161], v[208:211], v[98:101]
	s_setprio 0
	s_barrier
	s_add_i32 s52, s1, 4
	s_mov_b32 s54, s52
	s_mov_b32 s8, s26
	ds_read_b128 v[212:215], v140
	ds_read_b128 v[216:219], v140 offset:1024
	ds_read_b128 v[220:223], v140 offset:2048
	ds_read_b128 v[224:227], v140 offset:3072
	s_ashr_i32 s55, s54, 31
	s_lshl_b64 s[54:55], s[54:55], 7
	s_lshl_b32 s8, s8, 10
	v_lshl_add_u64 v[142:143], v[132:133], 0, s[54:55]
	s_add_i32 s8, s8, 0
	s_add_i32 m0, s8, 0x10000
	v_lshl_add_u64 v[192:193], v[142:143], 0, s[36:37]
	v_xor_b32_e32 v192, v197, v192
	global_load_lds_dwordx4 v[192:193], off
	v_lshl_add_u64 v[142:143], v[142:143], 0, s[38:39]
	s_add_i32 m0, s8, 0x12000
	s_nop 0
	v_xor_b32_e32 v142, v197, v142
	global_load_lds_dwordx4 v[142:143], off
	s_barrier
	s_waitcnt lgkmcnt(0)
	s_setprio 1
	s_waitcnt lgkmcnt(0)
	v_mfma_f32_16x16x32_bf16 v[94:97], v[212:215], v[162:165], v[94:97]
	v_mfma_f32_16x16x32_bf16 v[90:93], v[220:223], v[162:165], v[90:93]
	v_mfma_f32_16x16x32_bf16 v[86:89], v[212:215], v[170:173], v[86:89]
	v_mfma_f32_16x16x32_bf16 v[82:85], v[220:223], v[170:173], v[82:85]
	v_mfma_f32_16x16x32_bf16 v[78:81], v[212:215], v[184:187], v[78:81]
	v_mfma_f32_16x16x32_bf16 v[74:77], v[220:223], v[184:187], v[74:77]
	v_mfma_f32_16x16x32_bf16 v[70:73], v[212:215], v[204:207], v[70:73]
	v_mfma_f32_16x16x32_bf16 v[66:69], v[220:223], v[204:207], v[66:69]
	v_mfma_f32_16x16x32_bf16 v[94:97], v[216:219], v[166:169], v[94:97]
	v_mfma_f32_16x16x32_bf16 v[90:93], v[224:227], v[166:169], v[90:93]
	v_mfma_f32_16x16x32_bf16 v[86:89], v[216:219], v[174:177], v[86:89]
	v_mfma_f32_16x16x32_bf16 v[82:85], v[224:227], v[174:177], v[82:85]
	v_mfma_f32_16x16x32_bf16 v[78:81], v[216:219], v[188:191], v[78:81]
	v_mfma_f32_16x16x32_bf16 v[74:77], v[224:227], v[188:191], v[74:77]
	v_mfma_f32_16x16x32_bf16 v[70:73], v[216:219], v[208:211], v[70:73]
	v_mfma_f32_16x16x32_bf16 v[66:69], v[224:227], v[208:211], v[66:69]
	s_setprio 0
	s_mov_b32 s54, s52
	s_mov_b32 s8, s26
	s_barrier
; #define LDA(dst, b, h) _Pragma("unroll") for (int m = 0; m < 4; ++m) _Pragma("unroll") for (int k = 0; k < 2; ++k) \
;     dst[m][k] = *reinterpret_cast<const LAS bf16x8*>(lds + SAo(b, h) + lds_byte(wr * 64 + m * 16 + fr, k * 32 + fq * 8))
; #define LDB(dst, b, h) _Pragma("unroll") for (int n = 0; n < 2; ++n) _Pragma("unroll") for (int k = 0; k < 2; ++k) \
;     dst[n][k] = *reinterpret_cast<const LAS bf16x8*>(lds + SBo(b, h) + lds_byte(wc * 32 + n * 16 + fr, k * 32 + fq * 8))
; #define MMA(ai, bj, At_, Bt_) do { __builtin_amdgcn_s_setprio(1); \
;     _Pragma("unroll") for (int m = 0; m < 4; ++m) _Pragma("unroll") for (int n = 0; n < 2; ++n) _Pragma("unroll") for (int k = 0; k < 2; ++k) \
;       acc[ai][bj][m][n] = __builtin_amdgcn_mfma_f32_16x16x32_bf16(Bt_[n][k], At_[m][k], acc[ai][bj][m][n], 0, 0, 0); \
;     __builtin_amdgcn_s_setprio(0); } while (0)
; #define WAIT_V(n) asm volatile("s_waitcnt vmcnt(" #n ")" ::: "memory")
; #define WAIT_L(n) asm volatile("s_waitcnt lgkmcnt(" #n ")" ::: "memory")
; template <bool PRE = false>
; __device__ __forceinline__ void gemm_kloop(Acc& acc, const bf16_t* __restrict__ A, int lda, const bf16_t* __restrict__ Bt, int ldb,
;                                            int brow, int bcol, int nt, LAS unsigned char* lds) {
;     ...
;     for (int t = 0; t < nt - 2; t += 2) {
;         LDB(B0, 0, 0); SCHED; LDA(At, 0, 0); STAGE(SAo(1, 1), A, lda, brow + HALF, t + 1, offA);
;         WAIT_L(8); BAR; WAIT_L(0); MMA(0, 0, At, B0); BAR; SCHED;
;         LDB(B1, 0, 1); STAGE(SBo(0, 0), Bt, ldb, bcol, t + 2, offB);
;         BAR; WAIT_L(0); MMA(0, 1, At, B1); BAR;
;         LDA(At, 0, 1); STAGE(SAo(0, 0), A, lda, brow, t + 2, offA);
;         BAR; WAIT_L(0); MMA(1, 0, At, B0); BAR; SCHED;
;         STAGE(SBo(0, 1), Bt, ldb, bcol + HALF, t + 2, offB);
;         WAIT_V(6); BAR; MMA(1, 1, At, B1); BAR;
;         LDB(B0, 1, 0); SCHED; LDA(At, 1, 0); STAGE(SAo(0, 1), A, lda, brow + HALF, t + 2, offA);
;         WAIT_L(8); BAR; WAIT_L(0); MMA(0, 0, At, B0); BAR; SCHED;
;         LDB(B1, 1, 1); STAGE(SBo(1, 0), Bt, ldb, bcol, t + 3, offB);
;         BAR; WAIT_L(0); MMA(0, 1, At, B1); BAR;
;         LDA(At, 1, 1); STAGE(SAo(1, 0), A, lda, brow, t + 3, offA);
;         BAR; WAIT_L(0); MMA(1, 0, At, B0); BAR; SCHED;
;         STAGE(SBo(1, 1), Bt, ldb, bcol + HALF, t + 3, offB);
;         WAIT_V(6); BAR; MMA(1, 1, At, B1); BAR;
;     }
	ds_read_b128 v[162:165], v137 offset:16384
	ds_read_b128 v[166:169], v137 offset:17408
	ds_read_b128 v[170:173], v136 offset:16384
	ds_read_b128 v[174:177], v136 offset:17408
	ds_read_b128 v[184:187], v135 offset:16384
	ds_read_b128 v[188:191], v135 offset:17408
	ds_read_b128 v[204:207], v134 offset:16384
	ds_read_b128 v[208:211], v134 offset:17408
	s_ashr_i32 s55, s54, 31
	s_lshl_b64 s[54:55], s[54:55], 7
	s_lshl_b32 s8, s8, 10
	v_lshl_add_u64 v[142:143], v[130:131], 0, s[54:55]
	s_add_i32 s8, s8, 0
	v_lshl_add_u64 v[192:193], v[142:143], 0, s[40:41]
	s_mov_b32 m0, s8
	v_lshl_add_u64 v[142:143], v[142:143], 0, s[42:43]
	v_xor_b32_e32 v192, v197, v192
	global_load_lds_dwordx4 v[192:193], off
	s_add_i32 m0, s8, 0x2000
	s_nop 0
	v_xor_b32_e32 v142, v197, v142
	global_load_lds_dwordx4 v[142:143], off
	s_barrier
	s_waitcnt lgkmcnt(0)
	s_setprio 1
	s_waitcnt lgkmcnt(0)
	v_mfma_f32_16x16x32_bf16 v[62:65], v[146:149], v[162:165], v[62:65]
	v_mfma_f32_16x16x32_bf16 v[58:61], v[154:157], v[162:165], v[58:61]
	v_mfma_f32_16x16x32_bf16 v[54:57], v[146:149], v[170:173], v[54:57]
	v_mfma_f32_16x16x32_bf16 v[50:53], v[154:157], v[170:173], v[50:53]
	v_mfma_f32_16x16x32_bf16 v[46:49], v[146:149], v[184:187], v[46:49]
	v_mfma_f32_16x16x32_bf16 v[42:45], v[154:157], v[184:187], v[42:45]
	v_mfma_f32_16x16x32_bf16 v[38:41], v[146:149], v[204:207], v[38:41]
	v_mfma_f32_16x16x32_bf16 v[34:37], v[154:157], v[204:207], v[34:37]
	v_mfma_f32_16x16x32_bf16 v[62:65], v[150:153], v[166:169], v[62:65]
	v_mfma_f32_16x16x32_bf16 v[58:61], v[158:161], v[166:169], v[58:61]
	v_mfma_f32_16x16x32_bf16 v[54:57], v[150:153], v[174:177], v[54:57]
	v_mfma_f32_16x16x32_bf16 v[50:53], v[158:161], v[174:177], v[50:53]
	v_mfma_f32_16x16x32_bf16 v[46:49], v[150:153], v[188:191], v[46:49]
	v_mfma_f32_16x16x32_bf16 v[42:45], v[158:161], v[188:191], v[42:45]
	v_mfma_f32_16x16x32_bf16 v[38:41], v[150:153], v[208:211], v[38:41]
	v_mfma_f32_16x16x32_bf16 v[34:37], v[158:161], v[208:211], v[34:37]
	s_setprio 0
	s_barrier
	s_mov_b32 s54, s52
	s_mov_b32 s8, s26
	s_ashr_i32 s55, s54, 31
	s_lshl_b64 s[54:55], s[54:55], 7
	s_lshl_b32 s8, s8, 10
	v_lshl_add_u64 v[142:143], v[132:133], 0, s[54:55]
	s_add_i32 s8, s8, 0
	s_add_i32 m0, s8, 0x14000
	v_lshl_add_u64 v[146:147], v[142:143], 0, s[44:45]
	v_xor_b32_e32 v146, v197, v146
	global_load_lds_dwordx4 v[146:147], off
	v_lshl_add_u64 v[142:143], v[142:143], 0, s[46:47]
	s_add_i32 m0, s8, 0x16000
	s_nop 0
	v_xor_b32_e32 v142, v197, v142
	global_load_lds_dwordx4 v[142:143], off
	s_waitcnt vmcnt(6)
	s_barrier
	s_setprio 1
	v_mfma_f32_16x16x32_bf16 v[30:33], v[212:215], v[162:165], v[30:33]
	v_mfma_f32_16x16x32_bf16 v[26:29], v[220:223], v[162:165], v[26:29]
	v_mfma_f32_16x16x32_bf16 v[22:25], v[212:215], v[170:173], v[22:25]
	v_mfma_f32_16x16x32_bf16 v[18:21], v[220:223], v[170:173], v[18:21]
	v_mfma_f32_16x16x32_bf16 v[14:17], v[212:215], v[184:187], v[14:17]
	v_mfma_f32_16x16x32_bf16 v[10:13], v[220:223], v[184:187], v[10:13]
	v_mfma_f32_16x16x32_bf16 v[6:9], v[212:215], v[204:207], v[6:9]
	v_mfma_f32_16x16x32_bf16 v[2:5], v[220:223], v[204:207], v[2:5]
	v_mfma_f32_16x16x32_bf16 v[30:33], v[216:219], v[166:169], v[30:33]
	v_mfma_f32_16x16x32_bf16 v[26:29], v[224:227], v[166:169], v[26:29]
	v_mfma_f32_16x16x32_bf16 v[22:25], v[216:219], v[174:177], v[22:25]
	v_mfma_f32_16x16x32_bf16 v[18:21], v[224:227], v[174:177], v[18:21]
	v_mfma_f32_16x16x32_bf16 v[14:17], v[216:219], v[188:191], v[14:17]
	v_mfma_f32_16x16x32_bf16 v[10:13], v[224:227], v[188:191], v[10:13]
	v_mfma_f32_16x16x32_bf16 v[6:9], v[216:219], v[208:211], v[6:9]
	v_mfma_f32_16x16x32_bf16 v[2:5], v[224:227], v[208:211], v[2:5]
	s_setprio 0
	s_barrier
	ds_read_b128 v[146:149], v139
	ds_read_b128 v[150:153], v139 offset:1024
	ds_read_b128 v[154:157], v139 offset:2048
	ds_read_b128 v[158:161], v139 offset:3072
	s_mov_b32 s8, s26
	ds_read_b128 v[162:165], v137 offset:32768
	ds_read_b128 v[166:169], v137 offset:33792
	ds_read_b128 v[170:173], v136 offset:32768
	ds_read_b128 v[174:177], v136 offset:33792
	ds_read_b128 v[184:187], v135 offset:32768
	ds_read_b128 v[188:191], v135 offset:33792
	ds_read_b128 v[204:207], v134 offset:32768
	ds_read_b128 v[208:211], v134 offset:33792
	s_ashr_i32 s53, s52, 31
	s_lshl_b64 s[52:53], s[52:53], 7
	s_lshl_b32 s8, s8, 10
	v_lshl_add_u64 v[142:143], v[130:131], 0, s[52:53]
	s_add_i32 s8, s8, 0
	s_add_i32 m0, s8, 0x4000
	v_lshl_add_u64 v[192:193], v[142:143], 0, s[48:49]
	v_xor_b32_e32 v192, v197, v192
	global_load_lds_dwordx4 v[192:193], off
	v_lshl_add_u64 v[142:143], v[142:143], 0, s[50:51]
	s_add_i32 m0, s8, 0x6000
	s_nop 0
	v_xor_b32_e32 v142, v197, v142
	global_load_lds_dwordx4 v[142:143], off
	s_waitcnt lgkmcnt(8)
	s_barrier
	s_waitcnt lgkmcnt(0)
	s_setprio 1
	s_waitcnt lgkmcnt(0)
	v_mfma_f32_16x16x32_bf16 v[126:129], v[146:149], v[162:165], v[126:129]
	v_mfma_f32_16x16x32_bf16 v[122:125], v[154:157], v[162:165], v[122:125]
	v_mfma_f32_16x16x32_bf16 v[118:121], v[146:149], v[170:173], v[118:121]
	v_mfma_f32_16x16x32_bf16 v[114:117], v[154:157], v[170:173], v[114:117]
	v_mfma_f32_16x16x32_bf16 v[110:113], v[146:149], v[184:187], v[110:113]
	v_mfma_f32_16x16x32_bf16 v[106:109], v[154:157], v[184:187], v[106:109]
	v_mfma_f32_16x16x32_bf16 v[102:105], v[146:149], v[204:207], v[102:105]
	v_mfma_f32_16x16x32_bf16 v[98:101], v[154:157], v[204:207], v[98:101]
	v_mfma_f32_16x16x32_bf16 v[126:129], v[150:153], v[166:169], v[126:129]
	v_mfma_f32_16x16x32_bf16 v[122:125], v[158:161], v[166:169], v[122:125]
	v_mfma_f32_16x16x32_bf16 v[118:121], v[150:153], v[174:177], v[118:121]
	v_mfma_f32_16x16x32_bf16 v[114:117], v[158:161], v[174:177], v[114:117]
	v_mfma_f32_16x16x32_bf16 v[110:113], v[150:153], v[188:191], v[110:113]
	v_mfma_f32_16x16x32_bf16 v[106:109], v[158:161], v[188:191], v[106:109]
	v_mfma_f32_16x16x32_bf16 v[102:105], v[150:153], v[208:211], v[102:105]
	v_mfma_f32_16x16x32_bf16 v[98:101], v[158:161], v[208:211], v[98:101]
	s_setprio 0
	s_barrier
; #define LDA(dst, b, h) _Pragma("unroll") for (int m = 0; m < 4; ++m) _Pragma("unroll") for (int k = 0; k < 2; ++k) \
;     dst[m][k] = *reinterpret_cast<const LAS bf16x8*>(lds + SAo(b, h) + lds_byte(wr * 64 + m * 16 + fr, k * 32 + fq * 8))
; #define LDB(dst, b, h) _Pragma("unroll") for (int n = 0; n < 2; ++n) _Pragma("unroll") for (int k = 0; k < 2; ++k) \
;     dst[n][k] = *reinterpret_cast<const LAS bf16x8*>(lds + SBo(b, h) + lds_byte(wc * 32 + n * 16 + fr, k * 32 + fq * 8))
; #define MMA(ai, bj, At_, Bt_) do { __builtin_amdgcn_s_setprio(1); \
;     _Pragma("unroll") for (int m = 0; m < 4; ++m) _Pragma("unroll") for (int n = 0; n < 2; ++n) _Pragma("unroll") for (int k = 0; k < 2; ++k) \
;       acc[ai][bj][m][n] = __builtin_amdgcn_mfma_f32_16x16x32_bf16(Bt_[n][k], At_[m][k], acc[ai][bj][m][n], 0, 0, 0); \
;     __builtin_amdgcn_s_setprio(0); } while (0)
; #define WAIT_V(n) asm volatile("s_waitcnt vmcnt(" #n ")" ::: "memory")
; #define WAIT_L(n) asm volatile("s_waitcnt lgkmcnt(" #n ")" ::: "memory")
; template <bool PRE = false>
; __device__ __forceinline__ void gemm_kloop(Acc& acc, const bf16_t* __restrict__ A, int lda, const bf16_t* __restrict__ Bt, int ldb,
;                                            int brow, int bcol, int nt, LAS unsigned char* lds) {
;     ...
;     for (int t = 0; t < nt - 2; t += 2) {
;         LDB(B0, 0, 0); SCHED; LDA(At, 0, 0); STAGE(SAo(1, 1), A, lda, brow + HALF, t + 1, offA);
;         WAIT_L(8); BAR; WAIT_L(0); MMA(0, 0, At, B0); BAR; SCHED;
;         LDB(B1, 0, 1); STAGE(SBo(0, 0), Bt, ldb, bcol, t + 2, offB);
;         BAR; WAIT_L(0); MMA(0, 1, At, B1); BAR;
;         LDA(At, 0, 1); STAGE(SAo(0, 0), A, lda, brow, t + 2, offA);
;         BAR; WAIT_L(0); MMA(1, 0, At, B0); BAR; SCHED;
;         STAGE(SBo(0, 1), Bt, ldb, bcol + HALF, t + 2, offB);
;         WAIT_V(6); BAR; MMA(1, 1, At, B1); BAR;
;         LDB(B0, 1, 0); SCHED; LDA(At, 1, 0); STAGE(SAo(0, 1), A, lda, brow + HALF, t + 2, offA);
;         WAIT_L(8); BAR; WAIT_L(0); MMA(0, 0, At, B0); BAR; SCHED;
;         LDB(B1, 1, 1); STAGE(SBo(1, 0), Bt, ldb, bcol, t + 3, offB);
;         BAR; WAIT_L(0); MMA(0, 1, At, B1); BAR;
;         LDA(At, 1, 1); STAGE(SAo(1, 0), A, lda, brow, t + 3, offA);
;         BAR; WAIT_L(0); MMA(1, 0, At, B0); BAR; SCHED;
;         STAGE(SBo(1, 1), Bt, ldb, bcol + HALF, t + 3, offB);
;         WAIT_V(6); BAR; MMA(1, 1, At, B1); BAR;
;     }
	s_add_i32 s52, s1, 5
	s_mov_b32 s54, s52
	s_mov_b32 s8, s26
	ds_read_b128 v[212:215], v138
	ds_read_b128 v[216:219], v138 offset:1024
	ds_read_b128 v[220:223], v138 offset:2048
	ds_read_b128 v[224:227], v138 offset:3072
	s_ashr_i32 s55, s54, 31
	s_lshl_b64 s[54:55], s[54:55], 7
	s_lshl_b32 s8, s8, 10
	v_lshl_add_u64 v[142:143], v[132:133], 0, s[54:55]
	s_add_i32 s8, s8, 0
	s_add_i32 m0, s8, 0x18000
	v_lshl_add_u64 v[192:193], v[142:143], 0, s[36:37]
	v_xor_b32_e32 v192, v197, v192
	global_load_lds_dwordx4 v[192:193], off
	v_lshl_add_u64 v[142:143], v[142:143], 0, s[38:39]
	s_add_i32 m0, s8, 0x1a000
	s_nop 0
	v_xor_b32_e32 v142, v197, v142
	global_load_lds_dwordx4 v[142:143], off
	s_barrier
	s_waitcnt lgkmcnt(0)
	s_setprio 1
	s_waitcnt lgkmcnt(0)
	v_mfma_f32_16x16x32_bf16 v[94:97], v[212:215], v[162:165], v[94:97]
	v_mfma_f32_16x16x32_bf16 v[90:93], v[220:223], v[162:165], v[90:93]
	v_mfma_f32_16x16x32_bf16 v[86:89], v[212:215], v[170:173], v[86:89]
	v_mfma_f32_16x16x32_bf16 v[82:85], v[220:223], v[170:173], v[82:85]
	v_mfma_f32_16x16x32_bf16 v[78:81], v[212:215], v[184:187], v[78:81]
	v_mfma_f32_16x16x32_bf16 v[74:77], v[220:223], v[184:187], v[74:77]
	v_mfma_f32_16x16x32_bf16 v[70:73], v[212:215], v[204:207], v[70:73]
	v_mfma_f32_16x16x32_bf16 v[66:69], v[220:223], v[204:207], v[66:69]
	v_mfma_f32_16x16x32_bf16 v[94:97], v[216:219], v[166:169], v[94:97]
	v_mfma_f32_16x16x32_bf16 v[90:93], v[224:227], v[166:169], v[90:93]
	v_mfma_f32_16x16x32_bf16 v[86:89], v[216:219], v[174:177], v[86:89]
	v_mfma_f32_16x16x32_bf16 v[82:85], v[224:227], v[174:177], v[82:85]
	v_mfma_f32_16x16x32_bf16 v[78:81], v[216:219], v[188:191], v[78:81]
	v_mfma_f32_16x16x32_bf16 v[74:77], v[224:227], v[188:191], v[74:77]
	v_mfma_f32_16x16x32_bf16 v[70:73], v[216:219], v[208:211], v[70:73]
	v_mfma_f32_16x16x32_bf16 v[66:69], v[224:227], v[208:211], v[66:69]
	s_setprio 0
	s_mov_b32 s54, s52
	s_mov_b32 s8, s26
	s_barrier
	ds_read_b128 v[162:165], v137 offset:49152
	ds_read_b128 v[166:169], v137 offset:50176
	ds_read_b128 v[170:173], v136 offset:49152
	ds_read_b128 v[174:177], v136 offset:50176
	ds_read_b128 v[184:187], v135 offset:49152
	ds_read_b128 v[188:191], v135 offset:50176
	ds_read_b128 v[204:207], v134 offset:49152
	ds_read_b128 v[208:211], v134 offset:50176
	s_ashr_i32 s55, s54, 31
	s_lshl_b64 s[54:55], s[54:55], 7
	s_lshl_b32 s8, s8, 10
	v_lshl_add_u64 v[142:143], v[130:131], 0, s[54:55]
	s_add_i32 s8, s8, 0
	s_add_i32 m0, s8, 0x8000
	v_lshl_add_u64 v[192:193], v[142:143], 0, s[40:41]
	v_xor_b32_e32 v192, v197, v192
	global_load_lds_dwordx4 v[192:193], off
	v_lshl_add_u64 v[142:143], v[142:143], 0, s[42:43]
	s_add_i32 m0, s8, 0xa000
	s_nop 0
	v_xor_b32_e32 v142, v197, v142
	global_load_lds_dwordx4 v[142:143], off
	s_barrier
	s_waitcnt lgkmcnt(0)
	s_setprio 1
	s_waitcnt lgkmcnt(0)
	v_mfma_f32_16x16x32_bf16 v[62:65], v[146:149], v[162:165], v[62:65]
	v_mfma_f32_16x16x32_bf16 v[58:61], v[154:157], v[162:165], v[58:61]
	v_mfma_f32_16x16x32_bf16 v[54:57], v[146:149], v[170:173], v[54:57]
	v_mfma_f32_16x16x32_bf16 v[50:53], v[154:157], v[170:173], v[50:53]
	v_mfma_f32_16x16x32_bf16 v[46:49], v[146:149], v[184:187], v[46:49]
	v_mfma_f32_16x16x32_bf16 v[42:45], v[154:157], v[184:187], v[42:45]
	v_mfma_f32_16x16x32_bf16 v[38:41], v[146:149], v[204:207], v[38:41]
	v_mfma_f32_16x16x32_bf16 v[34:37], v[154:157], v[204:207], v[34:37]
	v_mfma_f32_16x16x32_bf16 v[62:65], v[150:153], v[166:169], v[62:65]
	v_mfma_f32_16x16x32_bf16 v[58:61], v[158:161], v[166:169], v[58:61]
	v_mfma_f32_16x16x32_bf16 v[54:57], v[150:153], v[174:177], v[54:57]
	v_mfma_f32_16x16x32_bf16 v[50:53], v[158:161], v[174:177], v[50:53]
	v_mfma_f32_16x16x32_bf16 v[46:49], v[150:153], v[188:191], v[46:49]
	v_mfma_f32_16x16x32_bf16 v[42:45], v[158:161], v[188:191], v[42:45]
	v_mfma_f32_16x16x32_bf16 v[38:41], v[150:153], v[208:211], v[38:41]
	v_mfma_f32_16x16x32_bf16 v[34:37], v[158:161], v[208:211], v[34:37]
	s_setprio 0
	s_barrier
	s_mov_b32 s8, s26
	s_ashr_i32 s53, s52, 31
	s_lshl_b64 s[52:53], s[52:53], 7
	s_lshl_b32 s8, s8, 10
	v_lshl_add_u64 v[142:143], v[132:133], 0, s[52:53]
	s_add_i32 s8, s8, 0
	s_add_i32 m0, s8, 0x1c000
	v_lshl_add_u64 v[146:147], v[142:143], 0, s[44:45]
	v_xor_b32_e32 v146, v197, v146
	global_load_lds_dwordx4 v[146:147], off
	v_lshl_add_u64 v[142:143], v[142:143], 0, s[46:47]
	s_add_i32 m0, s8, 0x1e000
	s_nop 0
	v_xor_b32_e32 v142, v197, v142
	global_load_lds_dwordx4 v[142:143], off
	s_waitcnt vmcnt(6)
	s_barrier
	s_setprio 1
	v_mfma_f32_16x16x32_bf16 v[30:33], v[212:215], v[162:165], v[30:33]
	v_mfma_f32_16x16x32_bf16 v[26:29], v[220:223], v[162:165], v[26:29]
	v_mfma_f32_16x16x32_bf16 v[22:25], v[212:215], v[170:173], v[22:25]
	v_mfma_f32_16x16x32_bf16 v[18:21], v[220:223], v[170:173], v[18:21]
	v_mfma_f32_16x16x32_bf16 v[14:17], v[212:215], v[184:187], v[14:17]
	v_mfma_f32_16x16x32_bf16 v[10:13], v[220:223], v[184:187], v[10:13]
	v_mfma_f32_16x16x32_bf16 v[6:9], v[212:215], v[204:207], v[6:9]
	v_mfma_f32_16x16x32_bf16 v[2:5], v[220:223], v[204:207], v[2:5]
	v_mfma_f32_16x16x32_bf16 v[30:33], v[216:219], v[166:169], v[30:33]
	v_mfma_f32_16x16x32_bf16 v[26:29], v[224:227], v[166:169], v[26:29]
	v_mfma_f32_16x16x32_bf16 v[22:25], v[216:219], v[174:177], v[22:25]
	v_mfma_f32_16x16x32_bf16 v[18:21], v[224:227], v[174:177], v[18:21]
	v_mfma_f32_16x16x32_bf16 v[14:17], v[216:219], v[188:191], v[14:17]
	v_mfma_f32_16x16x32_bf16 v[10:13], v[224:227], v[188:191], v[10:13]
	v_mfma_f32_16x16x32_bf16 v[6:9], v[216:219], v[208:211], v[6:9]
	v_mfma_f32_16x16x32_bf16 v[2:5], v[224:227], v[208:211], v[2:5]
	s_setprio 0
	s_add_i32 s1, s1, 2
	s_cmp_lt_u32 s1, 12
	s_barrier
	s_cbranch_scc1 .LBB0_543
; #define LDA(dst, b, h) _Pragma("unroll") for (int m = 0; m < 4; ++m) _Pragma("unroll") for (int k = 0; k < 2; ++k) \
;     dst[m][k] = *reinterpret_cast<const LAS bf16x8*>(lds + SAo(b, h) + lds_byte(wr * 64 + m * 16 + fr, k * 32 + fq * 8))
; #define LDB(dst, b, h) _Pragma("unroll") for (int n = 0; n < 2; ++n) _Pragma("unroll") for (int k = 0; k < 2; ++k) \
;     dst[n][k] = *reinterpret_cast<const LAS bf16x8*>(lds + SBo(b, h) + lds_byte(wc * 32 + n * 16 + fr, k * 32 + fq * 8))
; #define MMA(ai, bj, At_, Bt_) do { __builtin_amdgcn_s_setprio(1); \
;     _Pragma("unroll") for (int m = 0; m < 4; ++m) _Pragma("unroll") for (int n = 0; n < 2; ++n) _Pragma("unroll") for (int k = 0; k < 2; ++k) \
;       acc[ai][bj][m][n] = __builtin_amdgcn_mfma_f32_16x16x32_bf16(Bt_[n][k], At_[m][k], acc[ai][bj][m][n], 0, 0, 0); \
;     __builtin_amdgcn_s_setprio(0); } while (0)
; #define WAIT_V(n) asm volatile("s_waitcnt vmcnt(" #n ")" ::: "memory")
; #define WAIT_L(n) asm volatile("s_waitcnt lgkmcnt(" #n ")" ::: "memory")
; #define BAR __builtin_amdgcn_s_barrier()
; template <bool PRE = false>
; __device__ __forceinline__ void gemm_kloop(Acc& acc, const bf16_t* __restrict__ A, int lda, const bf16_t* __restrict__ Bt, int ldb,
;                                            int brow, int bcol, int nt, LAS unsigned char* lds) {
;     ...
;     { LDB(B0, 0, 0); LDA(At, 0, 0); STAGE(SAo(1, 1), A, lda, brow + HALF, nt - 1, offA);
;       BAR; WAIT_L(0); MMA(0, 0, At, B0); BAR;
;       LDB(B1, 0, 1); BAR; WAIT_L(0); MMA(0, 1, At, B1); BAR;
;       LDA(At, 0, 1); WAIT_V(4); BAR; WAIT_L(0); MMA(1, 0, At, B0); MMA(1, 1, At, B1); BAR; }
	s_mov_b32 s36, 15
	ds_read_b128 v[130:133], v141
	ds_read_b128 v[146:149], v141 offset:1024
	ds_read_b128 v[150:153], v141 offset:2048
	ds_read_b128 v[154:157], v141 offset:3072
	ds_read_b128 v[158:161], v137
	ds_read_b128 v[162:165], v137 offset:1024
	ds_read_b128 v[166:169], v136
	ds_read_b128 v[170:173], v136 offset:1024
	ds_read_b128 v[174:177], v135
	ds_read_b128 v[184:187], v135 offset:1024
	ds_read_b128 v[188:191], v134
	ds_read_b128 v[204:207], v134 offset:1024
	s_ashr_i32 s37, s36, 31
	s_lshl_b64 s[36:37], s[36:37], 7
	v_readlane_b32 s6, v254, 54
	v_readlane_b32 s7, v254, 55
	s_add_u32 s36, s6, s36
	s_addc_u32 s37, s7, s37
	s_lshl_b32 s1, s26, 10
	v_lshl_add_u64 v[142:143], s[36:37], 0, v[144:145]
	s_add_i32 s1, s1, 0
	s_add_i32 m0, s1, 0xc000
	v_lshl_add_u64 v[192:193], v[142:143], 0, s[48:49]
	v_xor_b32_e32 v192, v197, v192
	global_load_lds_dwordx4 v[192:193], off
	v_lshl_add_u64 v[142:143], v[142:143], 0, s[50:51]
	s_add_i32 m0, s1, 0xe000
	s_nop 0
	v_xor_b32_e32 v142, v197, v142
	global_load_lds_dwordx4 v[142:143], off
	s_barrier
	s_waitcnt lgkmcnt(0)
	s_setprio 1
	s_waitcnt lgkmcnt(0)
	v_mfma_f32_16x16x32_bf16 v[126:129], v[130:133], v[158:161], v[126:129]
	v_mfma_f32_16x16x32_bf16 v[122:125], v[150:153], v[158:161], v[122:125]
	v_mfma_f32_16x16x32_bf16 v[110:113], v[130:133], v[174:177], v[110:113]
	v_mfma_f32_16x16x32_bf16 v[106:109], v[150:153], v[174:177], v[106:109]
	v_mfma_f32_16x16x32_bf16 v[126:129], v[146:149], v[162:165], v[126:129]
	v_mfma_f32_16x16x32_bf16 v[122:125], v[154:157], v[162:165], v[122:125]
	v_mfma_f32_16x16x32_bf16 v[118:121], v[130:133], v[166:169], v[118:121]
	v_mfma_f32_16x16x32_bf16 v[114:117], v[150:153], v[166:169], v[114:117]
	v_mfma_f32_16x16x32_bf16 v[110:113], v[146:149], v[184:187], v[110:113]
	v_mfma_f32_16x16x32_bf16 v[106:109], v[154:157], v[184:187], v[106:109]
	v_mfma_f32_16x16x32_bf16 v[102:105], v[130:133], v[188:191], v[102:105]
	v_mfma_f32_16x16x32_bf16 v[98:101], v[150:153], v[188:191], v[98:101]
	v_mfma_f32_16x16x32_bf16 v[208:211], v[146:149], v[170:173], v[118:121]
	v_mfma_f32_16x16x32_bf16 v[212:215], v[154:157], v[170:173], v[114:117]
	v_mfma_f32_16x16x32_bf16 v[216:219], v[146:149], v[204:207], v[102:105]
	v_mfma_f32_16x16x32_bf16 v[220:223], v[154:157], v[204:207], v[98:101]
	s_setprio 0
	s_barrier
	s_nop 1
	ds_read_b128 v[98:101], v140
	ds_read_b128 v[102:105], v140 offset:1024
	ds_read_b128 v[114:117], v140 offset:2048
	ds_read_b128 v[118:121], v140 offset:3072
	s_barrier
	s_waitcnt lgkmcnt(0)
	s_setprio 1
	s_waitcnt lgkmcnt(0)
	v_mfma_f32_16x16x32_bf16 v[94:97], v[98:101], v[158:161], v[94:97]
	v_mfma_f32_16x16x32_bf16 v[90:93], v[114:117], v[158:161], v[90:93]
	v_mfma_f32_16x16x32_bf16 v[78:81], v[98:101], v[174:177], v[78:81]
	v_mfma_f32_16x16x32_bf16 v[74:77], v[114:117], v[174:177], v[74:77]
	v_mfma_f32_16x16x32_bf16 v[70:73], v[98:101], v[188:191], v[70:73]
	v_mfma_f32_16x16x32_bf16 v[66:69], v[114:117], v[188:191], v[66:69]
	v_mfma_f32_16x16x32_bf16 v[94:97], v[102:105], v[162:165], v[94:97]
	v_mfma_f32_16x16x32_bf16 v[90:93], v[118:121], v[162:165], v[90:93]
	v_mfma_f32_16x16x32_bf16 v[86:89], v[98:101], v[166:169], v[86:89]
	v_mfma_f32_16x16x32_bf16 v[82:85], v[114:117], v[166:169], v[82:85]
	v_mfma_f32_16x16x32_bf16 v[78:81], v[102:105], v[184:187], v[78:81]
	v_mfma_f32_16x16x32_bf16 v[74:77], v[118:121], v[184:187], v[74:77]
	v_mfma_f32_16x16x32_bf16 v[70:73], v[102:105], v[204:207], v[70:73]
	v_mfma_f32_16x16x32_bf16 v[66:69], v[118:121], v[204:207], v[66:69]
	v_mfma_f32_16x16x32_bf16 v[140:143], v[102:105], v[170:173], v[86:89]
	v_mfma_f32_16x16x32_bf16 v[158:161], v[118:121], v[170:173], v[82:85]
	s_setprio 0
	s_barrier
	s_nop 0
	ds_read_b128 v[82:85], v137 offset:16384
	ds_read_b128 v[86:89], v137 offset:17408
	ds_read_b128 v[162:165], v136 offset:16384
	ds_read_b128 v[166:169], v136 offset:17408
	ds_read_b128 v[170:173], v135 offset:16384
	ds_read_b128 v[174:177], v135 offset:17408
	ds_read_b128 v[184:187], v134 offset:16384
	ds_read_b128 v[188:191], v134 offset:17408
	s_waitcnt vmcnt(4)
	s_barrier
	s_waitcnt lgkmcnt(0)
	s_setprio 1
	s_waitcnt lgkmcnt(0)
	v_mfma_f32_16x16x32_bf16 v[58:61], v[150:153], v[82:85], v[58:61]
	v_mfma_f32_16x16x32_bf16 v[46:49], v[130:133], v[170:173], v[46:49]
	v_mfma_f32_16x16x32_bf16 v[38:41], v[130:133], v[184:187], v[38:41]
	v_mfma_f32_16x16x32_bf16 v[62:65], v[130:133], v[82:85], v[62:65]
	v_mfma_f32_16x16x32_bf16 v[58:61], v[154:157], v[86:89], v[58:61]
	v_mfma_f32_16x16x32_bf16 v[54:57], v[130:133], v[162:165], v[54:57]
	v_mfma_f32_16x16x32_bf16 v[50:53], v[150:153], v[162:165], v[50:53]
	v_mfma_f32_16x16x32_bf16 v[46:49], v[146:149], v[174:177], v[46:49]
	v_mfma_f32_16x16x32_bf16 v[42:45], v[150:153], v[170:173], v[42:45]
	v_mfma_f32_16x16x32_bf16 v[38:41], v[146:149], v[188:191], v[38:41]
	v_mfma_f32_16x16x32_bf16 v[34:37], v[150:153], v[184:187], v[34:37]
	v_mfma_f32_16x16x32_bf16 v[204:207], v[146:149], v[86:89], v[62:65]
	v_mfma_f32_16x16x32_bf16 v[224:227], v[146:149], v[166:169], v[54:57]
	v_mfma_f32_16x16x32_bf16 v[228:231], v[154:157], v[166:169], v[50:53]
	v_mfma_f32_16x16x32_bf16 v[232:235], v[154:157], v[174:177], v[42:45]
	v_mfma_f32_16x16x32_bf16 v[130:133], v[154:157], v[188:191], v[34:37]
	s_setprio 0
	s_setprio 1
	v_mfma_f32_16x16x32_bf16 v[30:33], v[98:101], v[82:85], v[30:33]
	v_mfma_f32_16x16x32_bf16 v[22:25], v[98:101], v[162:165], v[22:25]
	v_mfma_f32_16x16x32_bf16 v[14:17], v[98:101], v[170:173], v[14:17]
	v_mfma_f32_16x16x32_bf16 v[6:9], v[98:101], v[184:187], v[6:9]
	v_mfma_f32_16x16x32_bf16 v[30:33], v[102:105], v[86:89], v[30:33]
	v_mfma_f32_16x16x32_bf16 v[26:29], v[114:117], v[82:85], v[26:29]
	v_mfma_f32_16x16x32_bf16 v[22:25], v[102:105], v[166:169], v[22:25]
	v_mfma_f32_16x16x32_bf16 v[18:21], v[114:117], v[162:165], v[18:21]
	v_mfma_f32_16x16x32_bf16 v[14:17], v[102:105], v[174:177], v[14:17]
	v_mfma_f32_16x16x32_bf16 v[10:13], v[114:117], v[170:173], v[10:13]
	v_mfma_f32_16x16x32_bf16 v[6:9], v[102:105], v[188:191], v[6:9]
	v_mfma_f32_16x16x32_bf16 v[2:5], v[114:117], v[184:187], v[2:5]
	v_mfma_f32_16x16x32_bf16 v[146:149], v[118:121], v[86:89], v[26:29]
	v_mfma_f32_16x16x32_bf16 v[150:153], v[118:121], v[166:169], v[18:21]
	v_mfma_f32_16x16x32_bf16 v[154:157], v[118:121], v[174:177], v[10:13]
	v_mfma_f32_16x16x32_bf16 v[162:165], v[118:121], v[188:191], v[2:5]
	s_setprio 0
	s_barrier
; #define LDA(dst, b, h) _Pragma("unroll") for (int m = 0; m < 4; ++m) _Pragma("unroll") for (int k = 0; k < 2; ++k) \
;     dst[m][k] = *reinterpret_cast<const LAS bf16x8*>(lds + SAo(b, h) + lds_byte(wr * 64 + m * 16 + fr, k * 32 + fq * 8))
; #define LDB(dst, b, h) _Pragma("unroll") for (int n = 0; n < 2; ++n) _Pragma("unroll") for (int k = 0; k < 2; ++k) \
;     dst[n][k] = *reinterpret_cast<const LAS bf16x8*>(lds + SBo(b, h) + lds_byte(wc * 32 + n * 16 + fr, k * 32 + fq * 8))
; #define MMA(ai, bj, At_, Bt_) do { __builtin_amdgcn_s_setprio(1); \
;     _Pragma("unroll") for (int m = 0; m < 4; ++m) _Pragma("unroll") for (int n = 0; n < 2; ++n) _Pragma("unroll") for (int k = 0; k < 2; ++k) \
;       acc[ai][bj][m][n] = __builtin_amdgcn_mfma_f32_16x16x32_bf16(Bt_[n][k], At_[m][k], acc[ai][bj][m][n], 0, 0, 0); \
;     __builtin_amdgcn_s_setprio(0); } while (0)
; #define WAIT_V(n) asm volatile("s_waitcnt vmcnt(" #n ")" ::: "memory")
; #define WAIT_L(n) asm volatile("s_waitcnt lgkmcnt(" #n ")" ::: "memory")
; #define BAR __builtin_amdgcn_s_barrier()
; template <bool PRE = false>
; __device__ __forceinline__ void gemm_kloop(Acc& acc, const bf16_t* __restrict__ A, int lda, const bf16_t* __restrict__ Bt, int ldb,
;                                            int brow, int bcol, int nt, LAS unsigned char* lds) {
;     ...
;       LDA(At, 0, 1); WAIT_V(4); BAR; WAIT_L(0); MMA(1, 0, At, B0); MMA(1, 1, At, B1); BAR; }
;     { LDB(B0, 1, 0); LDA(At, 1, 0); WAIT_V(2); BAR; WAIT_L(0); MMA(0, 0, At, B0); BAR;
;       LDB(B1, 1, 1); WAIT_V(0); BAR; WAIT_L(0); MMA(0, 1, At, B1); BAR;
;       LDA(At, 1, 1); BAR; WAIT_L(0); MMA(1, 0, At, B0); MMA(1, 1, At, B1); BAR; }
;     if (wr == 0) BAR;
	s_nop 1
	ds_read_b128 v[2:5], v139
	ds_read_b128 v[10:13], v139 offset:1024
	ds_read_b128 v[166:169], v139 offset:2048
	ds_read_b128 v[170:173], v139 offset:3072
	ds_read_b128 v[18:21], v137 offset:32768
	ds_read_b128 v[26:29], v137 offset:33792
	ds_read_b128 v[34:37], v136 offset:32768
	ds_read_b128 v[42:45], v136 offset:33792
	ds_read_b128 v[54:57], v135 offset:32768
	ds_read_b128 v[174:177], v135 offset:33792
	ds_read_b128 v[184:187], v134 offset:32768
	ds_read_b128 v[188:191], v134 offset:33792
	s_waitcnt vmcnt(2)
	s_barrier
	s_waitcnt lgkmcnt(0)
	s_setprio 1
	s_waitcnt lgkmcnt(0)
	v_mfma_f32_16x16x32_bf16 v[50:53], v[2:5], v[18:21], v[126:129]
	v_mfma_f32_16x16x32_bf16 v[118:121], v[10:13], v[26:29], v[50:53]
	v_mfma_f32_16x16x32_bf16 v[50:53], v[166:169], v[18:21], v[122:125]
	v_mfma_f32_16x16x32_bf16 v[114:117], v[170:173], v[26:29], v[50:53]
	v_mfma_f32_16x16x32_bf16 v[50:53], v[2:5], v[34:37], v[208:211]
	v_mfma_f32_16x16x32_bf16 v[102:105], v[10:13], v[42:45], v[50:53]
	v_mfma_f32_16x16x32_bf16 v[50:53], v[166:169], v[34:37], v[212:215]
	v_mfma_f32_16x16x32_bf16 v[98:101], v[170:173], v[42:45], v[50:53]
	v_mfma_f32_16x16x32_bf16 v[50:53], v[2:5], v[54:57], v[110:113]
	v_mfma_f32_16x16x32_bf16 v[86:89], v[10:13], v[174:177], v[50:53]
	v_mfma_f32_16x16x32_bf16 v[50:53], v[166:169], v[54:57], v[106:109]
	v_mfma_f32_16x16x32_bf16 v[82:85], v[170:173], v[174:177], v[50:53]
	v_mfma_f32_16x16x32_bf16 v[50:53], v[2:5], v[184:187], v[216:219]
	v_mfma_f32_16x16x32_bf16 v[62:65], v[10:13], v[188:191], v[50:53]
	v_mfma_f32_16x16x32_bf16 v[50:53], v[166:169], v[184:187], v[220:223]
	v_mfma_f32_16x16x32_bf16 v[50:53], v[170:173], v[188:191], v[50:53]
	s_setprio 0
	s_barrier
	ds_read_b128 v[208:211], v138
	ds_read_b128 v[212:215], v138 offset:1024
	ds_read_b128 v[216:219], v138 offset:2048
	ds_read_b128 v[220:223], v138 offset:3072
	s_waitcnt vmcnt(0)
	s_barrier
	s_waitcnt lgkmcnt(0)
	s_setprio 1
	s_waitcnt lgkmcnt(0)
	v_mfma_f32_16x16x32_bf16 v[94:97], v[208:211], v[18:21], v[94:97]
	v_mfma_f32_16x16x32_bf16 v[18:21], v[216:219], v[18:21], v[90:93]
	v_mfma_f32_16x16x32_bf16 v[122:125], v[220:223], v[26:29], v[18:21]
	v_mfma_f32_16x16x32_bf16 v[18:21], v[208:211], v[34:37], v[140:143]
	v_mfma_f32_16x16x32_bf16 v[110:113], v[212:215], v[42:45], v[18:21]
	v_mfma_f32_16x16x32_bf16 v[18:21], v[216:219], v[34:37], v[158:161]
	v_mfma_f32_16x16x32_bf16 v[106:109], v[220:223], v[42:45], v[18:21]
	v_mfma_f32_16x16x32_bf16 v[18:21], v[208:211], v[54:57], v[78:81]
	v_mfma_f32_16x16x32_bf16 v[126:129], v[212:215], v[26:29], v[94:97]
	v_mfma_f32_16x16x32_bf16 v[94:97], v[212:215], v[174:177], v[18:21]
	v_mfma_f32_16x16x32_bf16 v[18:21], v[216:219], v[54:57], v[74:77]
	v_mfma_f32_16x16x32_bf16 v[90:93], v[220:223], v[174:177], v[18:21]
	v_mfma_f32_16x16x32_bf16 v[18:21], v[208:211], v[184:187], v[70:73]
	v_mfma_f32_16x16x32_bf16 v[78:81], v[212:215], v[188:191], v[18:21]
	v_mfma_f32_16x16x32_bf16 v[18:21], v[216:219], v[184:187], v[66:69]
	v_mfma_f32_16x16x32_bf16 v[66:69], v[220:223], v[188:191], v[18:21]
	s_setprio 0
	s_barrier
	ds_read_b128 v[138:141], v137 offset:49152
	ds_read_b128 v[158:161], v137 offset:50176
	ds_read_b128 v[174:177], v136 offset:49152
	ds_read_b128 v[184:187], v136 offset:50176
	ds_read_b128 v[188:191], v135 offset:49152
	ds_read_b128 v[236:239], v135 offset:50176
	ds_read_b128 v[240:243], v134 offset:49152
	ds_read_b128 v[134:137], v134 offset:50176
	s_barrier
	s_waitcnt lgkmcnt(0)
	s_setprio 1
	s_waitcnt lgkmcnt(0)
	v_mfma_f32_16x16x32_bf16 v[18:21], v[2:5], v[138:141], v[204:207]
	v_mfma_f32_16x16x32_bf16 v[70:73], v[10:13], v[158:161], v[18:21]
	v_mfma_f32_16x16x32_bf16 v[18:21], v[166:169], v[138:141], v[58:61]
	v_mfma_f32_16x16x32_bf16 v[54:57], v[170:173], v[158:161], v[18:21]
	v_mfma_f32_16x16x32_bf16 v[18:21], v[2:5], v[174:177], v[224:227]
	v_mfma_f32_16x16x32_bf16 v[42:45], v[10:13], v[184:187], v[18:21]
	v_mfma_f32_16x16x32_bf16 v[18:21], v[166:169], v[174:177], v[228:231]
	v_mfma_f32_16x16x32_bf16 v[34:37], v[170:173], v[184:187], v[18:21]
	v_mfma_f32_16x16x32_bf16 v[18:21], v[2:5], v[188:191], v[46:49]
	v_mfma_f32_16x16x32_bf16 v[2:5], v[2:5], v[240:243], v[38:41]
	v_mfma_f32_16x16x32_bf16 v[26:29], v[10:13], v[236:239], v[18:21]
	v_mfma_f32_16x16x32_bf16 v[18:21], v[166:169], v[188:191], v[232:235]
	v_mfma_f32_16x16x32_bf16 v[10:13], v[10:13], v[134:137], v[2:5]
	v_mfma_f32_16x16x32_bf16 v[2:5], v[166:169], v[240:243], v[130:133]
	v_mfma_f32_16x16x32_bf16 v[18:21], v[170:173], v[236:239], v[18:21]
	v_mfma_f32_16x16x32_bf16 v[2:5], v[170:173], v[134:137], v[2:5]
	s_setprio 0
	s_setprio 1
	v_mfma_f32_16x16x32_bf16 v[30:33], v[208:211], v[138:141], v[30:33]
	v_mfma_f32_16x16x32_bf16 v[74:77], v[212:215], v[158:161], v[30:33]
	v_mfma_f32_16x16x32_bf16 v[30:33], v[216:219], v[138:141], v[146:149]
	v_mfma_f32_16x16x32_bf16 v[22:25], v[208:211], v[174:177], v[22:25]
	v_mfma_f32_16x16x32_bf16 v[14:17], v[208:211], v[188:191], v[14:17]
	v_mfma_f32_16x16x32_bf16 v[58:61], v[220:223], v[158:161], v[30:33]
	v_mfma_f32_16x16x32_bf16 v[46:49], v[212:215], v[184:187], v[22:25]
	v_mfma_f32_16x16x32_bf16 v[22:25], v[216:219], v[174:177], v[150:153]
	v_mfma_f32_16x16x32_bf16 v[30:33], v[212:215], v[236:239], v[14:17]
	v_mfma_f32_16x16x32_bf16 v[14:17], v[216:219], v[188:191], v[154:157]
	v_mfma_f32_16x16x32_bf16 v[6:9], v[208:211], v[240:243], v[6:9]
	v_mfma_f32_16x16x32_bf16 v[38:41], v[220:223], v[184:187], v[22:25]
	v_mfma_f32_16x16x32_bf16 v[22:25], v[220:223], v[236:239], v[14:17]
	v_mfma_f32_16x16x32_bf16 v[14:17], v[212:215], v[134:137], v[6:9]
	v_mfma_f32_16x16x32_bf16 v[6:9], v[216:219], v[240:243], v[162:165]
	v_mfma_f32_16x16x32_bf16 v[6:9], v[220:223], v[134:137], v[6:9]
	s_setprio 0
	v_cmp_gt_u32_e32 vcc, s85, v1
	s_barrier
	s_and_saveexec_b64 s[36:37], vcc
	s_cbranch_execz .LBB0_546
	s_barrier
; #define LAS __attribute__((address_space(3)))
; __device__ __forceinline__ int fresh_tid() { int t; asm volatile("v_mov_b32 %0, %1" : "=v"(t) : "v"(threadIdx.x)); return t; }
; __device__ __forceinline__ int fresh_bid() { int t; asm volatile("s_mov_b32 %0, %1" : "=s"(t) : "s"(blockIdx.x)); return t; }
; #define ACC_ZERO(acc) _Pragma("unroll") for (int _a = 0; _a < 2; ++_a) _Pragma("unroll") for (int _b = 0; _b < 2; ++_b) _Pragma("unroll") for (int _m = 0; _m < 4; ++_m) \
;     _Pragma("unroll") for (int _n = 0; _n < 2; ++_n) acc[_a][_b][_m][_n] = (f32x4){0.f, 0.f, 0.f, 0.f}
; __device__ __forceinline__ void gemm_stage_first(const bf16_t* __restrict__ A, int lda, const bf16_t* __restrict__ Bt, int ldb, int brow, int bcol, LAS unsigned char* lds) {
;     const int tid = fresh_tid();
;     const int wvu = __builtin_amdgcn_readfirstlane(tid >> 6);
;     unsigned offA, offB;
;     { int _r, _c; stage_rc(tid * 16, _r, _c); offA = (unsigned)(_r * lda + _c) * 2u; offB = (unsigned)(_r * ldb + _c) * 2u; }
;     STAGE(SBo(0, 0), Bt, ldb, bcol, 0, offB); STAGE(SAo(0, 0), A, lda, brow, 0, offA);
;     STAGE(SBo(0, 1), Bt, ldb, bcol + HALF, 0, offB); STAGE(SAo(0, 1), A, lda, brow + HALF, 0, offA);
; }
; __device__ __forceinline__ void phase_proj(const Ctx& a, int b, LAS unsigned char* lds) {
;     ...
;     for (int w = fresh_bid(); w < ntile; w += gridDim.x) {
;         int pm, pn; tile_of(w, nM, pm, pn);
;         Acc acc; ACC_ZERO(acc);
;         gemm_kloop<true>(acc, xb, DM, W, DM, pm * 256, pn * 256, DM / 64, lds);
;         { const int wn = w + (int)gridDim.x; if (wn < ntile) { int pm2, pn2; tile_of(wn, nM, pm2, pn2); gemm_stage_first(xb, DM, W, DM, pm2 * 256, pn2 * 256, lds); } }
.LBB0_546:
	s_or_b64 exec, exec, s[36:37]
	s_load_dword s1, s[74:75], 0x0
	s_waitcnt lgkmcnt(0)
	s_add_i32 s9, s1, s9
	s_cmpk_gt_i32 s9, 0x1ff
	s_cselect_b64 s[36:37], -1, 0
	s_and_b64 vcc, exec, s[36:37]
	s_cbranch_vccnz .LBB0_539
	s_ashr_i32 s1, s9, 31
	s_lshr_b32 s1, s1, 27
	s_add_i32 s1, s9, s1
	v_mov_b32 v1, v179
	s_and_b32 s8, s1, 0xffffe0
	v_ashrrev_i32_e32 v131, 31, v1
	s_lshl_b32 s1, s1, 3
	v_lshrrev_b32_e32 v131, 26, v131
	s_and_b32 s40, s1, 0xffffff00
	v_readfirstlane_b32 s1, v1
	v_lshlrev_b32_e32 v130, 4, v1
	v_add_u32_e32 v131, v1, v131
	v_bfe_i32 v1, v1, 27, 1
	v_lshrrev_b32_e32 v1, 22, v1
	v_add_u32_e32 v1, v130, v1
	v_and_b32_e32 v1, 0xfffffc00, v1
	v_sub_u32_e32 v1, v130, v1
	v_lshrrev_b32_e32 v130, 4, v1
	v_bitop3_b32 v130, v130, v1, 32 bitop3:0x6c
	v_ashrrev_i32_e32 v1, 31, v1
	v_lshrrev_b32_e32 v1, 26, v1
	v_add_u32_e32 v1, v130, v1
	s_sub_i32 s8, s9, s8
	s_ashr_i32 s1, s1, 6
	v_ashrrev_i32_e32 v1, 6, v1
	s_lshl_b32 s38, s8, 8
	v_ashrrev_i32_e32 v131, 6, v131
	v_mul_i32_i24_e32 v133, 64, v1
	s_mov_b32 s8, s1
	s_mov_b32 s42, s27
	v_lshlrev_b32_e32 v132, 3, v131
	v_lshlrev_b32_e32 v131, 5, v131
	v_sub_u32_e32 v130, v130, v133
	s_ashr_i32 s43, s42, 31
	v_and_b32_e32 v132, 0x1ffff0, v132
	v_and_b32_e32 v131, 32, v131
	v_ashrrev_i16_sdwa v130, v194, sext(v130) dst_sel:DWORD dst_unused:UNUSED_PAD src0_sel:DWORD src1_sel:BYTE_0
	s_lshl_b64 s[42:43], s[42:43], 7
	v_add_u32_sdwa v130, v131, sext(v130) dst_sel:DWORD dst_unused:UNUSED_PAD src0_sel:DWORD src1_sel:WORD_0
	v_add_lshl_u32 v1, v1, v132, 11
	s_add_u32 s42, s86, s42
	v_lshl_add_u32 v144, v130, 1, v1
	s_addc_u32 s43, s87, s43
	s_ashr_i32 s41, s40, 31
	v_lshl_add_u64 v[130:131], s[42:43], 0, v[144:145]
	s_lshl_b64 s[42:43], s[40:41], 11
	s_lshl_b32 s8, s8, 10
	v_lshl_add_u64 v[132:133], v[130:131], 0, s[42:43]
	s_or_b32 s42, s40, 64
	s_add_i32 s8, s8, 0
	s_ashr_i32 s43, s42, 31
	s_add_i32 m0, s8, 0x10000
	s_lshl_b64 s[42:43], s[42:43], 11
	v_xor_b32_e32 v132, v197, v132
	global_load_lds_dwordx4 v[132:133], off
	v_lshl_add_u64 v[130:131], v[130:131], 0, s[42:43]
	s_add_i32 m0, s8, 0x12000
	s_mov_b32 s8, s1
	s_mov_b32 s42, s27
	v_xor_b32_e32 v130, v197, v130
	global_load_lds_dwordx4 v[130:131], off
	s_ashr_i32 s43, s42, 31
	s_lshl_b64 s[42:43], s[42:43], 7
	v_readlane_b32 s6, v254, 54
	v_readlane_b32 s7, v254, 55
	s_add_u32 s42, s6, s42
	s_addc_u32 s43, s7, s43
	s_ashr_i32 s39, s38, 31
	v_lshl_add_u64 v[130:131], s[42:43], 0, v[144:145]
	s_lshl_b64 s[42:43], s[38:39], 11
	s_lshl_b32 s8, s8, 10
	v_lshl_add_u64 v[132:133], v[130:131], 0, s[42:43]
	s_or_b32 s42, s38, 64
	s_add_i32 s8, s8, 0
	s_ashr_i32 s43, s42, 31
	s_mov_b32 m0, s8
	s_lshl_b64 s[42:43], s[42:43], 11
	v_xor_b32_e32 v132, v197, v132
	global_load_lds_dwordx4 v[132:133], off
	v_lshl_add_u64 v[130:131], v[130:131], 0, s[42:43]
	s_add_i32 m0, s8, 0x2000
	s_mov_b32 s8, s1
	s_mov_b32 s42, s27
	v_xor_b32_e32 v130, v197, v130
	global_load_lds_dwordx4 v[130:131], off
	s_ashr_i32 s43, s42, 31
	s_or_b32 s44, s40, 0x80
	s_lshl_b64 s[42:43], s[42:43], 7
	s_add_u32 s42, s86, s42
	s_addc_u32 s43, s87, s43
	s_lshl_b32 s8, s8, 10
	s_ashr_i32 s45, s44, 31
	s_or_b32 s40, s40, 0xc0
	v_lshl_add_u64 v[130:131], s[42:43], 0, v[144:145]
	s_add_i32 s8, s8, 0
	s_lshl_b64 s[42:43], s[44:45], 11
	s_ashr_i32 s41, s40, 31
	s_add_i32 m0, s8, 0x14000
	v_lshl_add_u64 v[132:133], v[130:131], 0, s[42:43]
	s_lshl_b64 s[40:41], s[40:41], 11
	v_xor_b32_e32 v132, v197, v132
	global_load_lds_dwordx4 v[132:133], off
	v_lshl_add_u64 v[130:131], v[130:131], 0, s[40:41]
	s_add_i32 m0, s8, 0x16000
	s_mov_b32 s40, s27
	v_xor_b32_e32 v130, v197, v130
	global_load_lds_dwordx4 v[130:131], off
	s_ashr_i32 s41, s40, 31
	s_or_b32 s42, s38, 0x80
	s_lshl_b64 s[40:41], s[40:41], 7
	s_add_u32 s40, s6, s40
	s_addc_u32 s41, s7, s41
	s_lshl_b32 s1, s1, 10
	s_ashr_i32 s43, s42, 31
	s_or_b32 s38, s38, 0xc0
	v_lshl_add_u64 v[130:131], s[40:41], 0, v[144:145]
	s_add_i32 s1, s1, 0
	s_lshl_b64 s[40:41], s[42:43], 11
	s_ashr_i32 s39, s38, 31
	s_add_i32 m0, s1, 0x4000
	v_lshl_add_u64 v[132:133], v[130:131], 0, s[40:41]
	s_lshl_b64 s[38:39], s[38:39], 11
	v_xor_b32_e32 v132, v197, v132
	global_load_lds_dwordx4 v[132:133], off
	v_lshl_add_u64 v[130:131], v[130:131], 0, s[38:39]
	s_add_i32 m0, s1, 0x6000
	s_nop 0
	v_xor_b32_e32 v130, v197, v130
	global_load_lds_dwordx4 v[130:131], off
	s_branch .LBB0_539

; __device__ __forceinline__ int fresh_tid() { int t; asm volatile("v_mov_b32 %0, %1" : "=v"(t) : "v"(threadIdx.x)); return t; }
; #define WAIT_V(n) asm volatile("s_waitcnt vmcnt(" #n ")" ::: "memory")
; #define BAR __builtin_amdgcn_s_barrier()
; template <bool PRE = false>
; __device__ __forceinline__ void gemm_kloop(Acc& acc, const bf16_t* __restrict__ A, int lda, const bf16_t* __restrict__ Bt, int ldb,
;                                            int brow, int bcol, int nt, LAS unsigned char* lds) {
;     const int tid = fresh_tid();
;     const int wid = tid >> 6, lane = tid & 63, wr = wid >> 2, wc = wid & 3, fr = lane & 15, fq = lane >> 4;
;     const int wvu = __builtin_amdgcn_readfirstlane(tid >> 6);
;     unsigned offA, offB;
;     { int _r, _c; stage_rc(tid * 16, _r, _c); offA = (unsigned)(_r * lda + _c) * 2u; offB = (unsigned)(_r * ldb + _c) * 2u; }
;     ...
;     bf16x8 At[4][2], B0[2][2], B1[2][2];
;     if (!PRE) {
;     STAGE(SBo(0, 0), Bt, ldb, bcol, 0, offB); STAGE(SAo(0, 0), A, lda, brow, 0, offA);
;     STAGE(SBo(0, 1), Bt, ldb, bcol + HALF, 0, offB); STAGE(SAo(0, 1), A, lda, brow + HALF, 0, offA);
;     }
;     if (wr == 1) BAR;
;     WAIT_V(4); BAR;
;     STAGE(SBo(1, 0), Bt, ldb, bcol, 1, offB); STAGE(SAo(1, 0), A, lda, brow, 1, offA); STAGE(SBo(1, 1), Bt, ldb, bcol + HALF, 1, offB);
;     WAIT_V(6); BAR;
.LBB0_552:
	v_mov_b32 v1, v179
	s_lshl_b32 s8, s9, 10
	v_bfe_i32 v9, v1, 27, 1
	v_lshlrev_b32_e32 v7, 4, v1
	v_lshrrev_b32_e32 v9, 22, v9
	v_add_u32_e32 v9, v7, v9
	v_and_b32_e32 v9, 0xfffffc00, v9
	v_ashrrev_i32_e32 v8, 31, v1
	v_sub_u32_e32 v7, v7, v9
	v_lshrrev_b32_e32 v8, 26, v8
	v_lshrrev_b32_e32 v9, 4, v7
	v_add_u32_e32 v8, v1, v8
	v_bitop3_b32 v9, v9, v7, 32 bitop3:0x6c
	v_ashrrev_i32_e32 v7, 31, v7
	v_ashrrev_i32_e32 v8, 6, v8
	v_lshrrev_b32_e32 v7, 26, v7
	s_add_u32 s12, s18, s8
	v_lshlrev_b32_e32 v134, 3, v8
	v_add_u32_e32 v7, v9, v7
	s_addc_u32 s13, s19, 0
	v_ashrrev_i32_e32 v6, 6, v1
	v_and_b32_e32 v134, 0x7ffff0, v134
	v_ashrrev_i32_e32 v7, 6, v7
	s_add_u32 s36, s78, s8
	v_readfirstlane_b32 s92, v6
	v_add_u32_e32 v134, v7, v134
	v_mul_i32_i24_e32 v7, 64, v7
	s_movk_i32 s8, 0x600
	v_sub_u32_e32 v7, v9, v7
	v_mul_lo_u32 v9, v134, s8
	s_mov_b32 s8, s92
	s_mov_b32 s52, 0
	s_addc_u32 s37, s79, 0
	s_ashr_i32 s53, s52, 31
	v_lshlrev_b32_e32 v8, 5, v8
	v_ashrrev_i16_sdwa v7, v194, sext(v7) dst_sel:DWORD dst_unused:UNUSED_PAD src0_sel:DWORD src1_sel:BYTE_0
	s_lshl_b64 s[52:53], s[52:53], 7
	v_bfe_i32 v7, v7, 0, 16
	v_and_or_b32 v8, v8, 32, v9
	s_add_u32 s52, s36, s52
	v_add_lshl_u32 v144, v8, v7, 1
	s_addc_u32 s53, s37, s53
	s_lshl_b32 s8, s8, 10
	v_lshl_add_u64 v[8:9], s[52:53], 0, v[144:145]
	s_add_i32 s8, s8, 0
	s_add_i32 m0, s8, 0x10000
	v_lshl_add_u64 v[134:135], s[0:1], 1, v[8:9]
	v_xor_b32_e32 v134, v197, v134
	global_load_lds_dwordx4 v[134:135], off
	v_lshl_add_u64 v[8:9], s[38:39], 1, v[8:9]
	s_add_i32 m0, s8, 0x12000
	s_mov_b32 s8, s92
	s_mov_b32 s52, 0
	v_xor_b32_e32 v8, v197, v8
	global_load_lds_dwordx4 v[8:9], off
	s_ashr_i32 s53, s52, 31
	s_lshl_b64 s[52:53], s[52:53], 7
	s_add_u32 s52, s12, s52
	s_addc_u32 s53, s13, s53
	s_lshl_b32 s8, s8, 10
	v_lshl_add_u64 v[8:9], s[52:53], 0, v[144:145]
	s_add_i32 s8, s8, 0
	v_lshl_add_u64 v[134:135], s[40:41], 1, v[8:9]
	s_mov_b32 m0, s8
	v_lshl_add_u64 v[8:9], s[42:43], 1, v[8:9]
	v_xor_b32_e32 v134, v197, v134
	global_load_lds_dwordx4 v[134:135], off
	s_add_i32 m0, s8, 0x2000
	s_mov_b32 s8, s92
	s_mov_b32 s52, 0
	v_xor_b32_e32 v8, v197, v8
	global_load_lds_dwordx4 v[8:9], off
	s_ashr_i32 s53, s52, 31
	s_lshl_b64 s[52:53], s[52:53], 7
	s_add_u32 s52, s36, s52
	s_addc_u32 s53, s37, s53
	s_lshl_b32 s8, s8, 10
	v_lshl_add_u64 v[8:9], s[52:53], 0, v[144:145]
	s_add_i32 s8, s8, 0
	s_add_i32 m0, s8, 0x14000
	v_lshl_add_u64 v[134:135], s[44:45], 1, v[8:9]
	v_xor_b32_e32 v134, v197, v134
	global_load_lds_dwordx4 v[134:135], off
	v_lshl_add_u64 v[8:9], s[46:47], 1, v[8:9]
	s_add_i32 m0, s8, 0x16000
	s_mov_b32 s8, s92
	s_mov_b32 s52, 0
	v_xor_b32_e32 v8, v197, v8
	global_load_lds_dwordx4 v[8:9], off
	s_ashr_i32 s53, s52, 31
	s_lshl_b64 s[52:53], s[52:53], 7
	s_add_u32 s52, s12, s52
	s_addc_u32 s53, s13, s53
	s_lshl_b32 s8, s8, 10
	v_lshl_add_u64 v[8:9], s[52:53], 0, v[144:145]
	s_add_i32 s8, s8, 0
	s_add_i32 m0, s8, 0x4000
	v_lshl_add_u64 v[134:135], s[48:49], 1, v[8:9]
	v_xor_b32_e32 v134, v197, v134
	global_load_lds_dwordx4 v[134:135], off
	v_lshl_add_u64 v[8:9], s[50:51], 1, v[8:9]
	s_add_i32 m0, s8, 0x6000
	v_ashrrev_i32_e32 v134, 8, v1
	v_xor_b32_e32 v8, v197, v8
	global_load_lds_dwordx4 v[8:9], off
	v_cmp_eq_u32_e32 vcc, 1, v134
	s_and_saveexec_b64 s[52:53], vcc
	s_cbranch_execz .LBB0_554
	s_barrier
.LBB0_554:
	s_or_b64 exec, exec, s[52:53]
	s_mov_b32 s52, 1
	s_mov_b32 s8, s92
	s_waitcnt vmcnt(4)
	s_barrier
	s_ashr_i32 s53, s52, 31
	s_lshl_b64 s[52:53], s[52:53], 7
	s_add_u32 s52, s36, s52
	s_addc_u32 s53, s37, s53
	s_lshl_b32 s8, s8, 10
	v_lshl_add_u64 v[8:9], s[52:53], 0, v[144:145]
	s_add_i32 s8, s31, s8
	v_lshl_add_u64 v[136:137], s[0:1], 1, v[8:9]
	s_mov_b32 m0, s8
	v_lshl_add_u64 v[8:9], s[38:39], 1, v[8:9]
	v_xor_b32_e32 v136, v197, v136
	global_load_lds_dwordx4 v[136:137], off
	s_add_i32 m0, s8, 0x2000
	s_mov_b32 s52, 1
	s_mov_b32 s8, s92
	v_xor_b32_e32 v8, v197, v8
	global_load_lds_dwordx4 v[8:9], off
	s_ashr_i32 s53, s52, 31
	s_lshl_b64 s[52:53], s[52:53], 7
	s_add_u32 s52, s12, s52
	s_addc_u32 s53, s13, s53
	s_lshl_b32 s8, s8, 10
	v_lshl_add_u64 v[8:9], s[52:53], 0, v[144:145]
	s_add_i32 s8, s8, 0
	s_add_i32 m0, s8, 0x8000
	v_lshl_add_u64 v[136:137], s[40:41], 1, v[8:9]
	v_xor_b32_e32 v136, v197, v136
	global_load_lds_dwordx4 v[136:137], off
	v_lshl_add_u64 v[8:9], s[42:43], 1, v[8:9]
	s_add_i32 m0, s8, 0xa000
	s_mov_b32 s52, 1
	s_mov_b32 s8, s92
	v_xor_b32_e32 v8, v197, v8
	global_load_lds_dwordx4 v[8:9], off
	s_ashr_i32 s53, s52, 31
	s_lshl_b64 s[52:53], s[52:53], 7
	s_add_u32 s52, s36, s52
	s_addc_u32 s53, s37, s53
	s_lshl_b32 s8, s8, 10
	v_lshl_add_u64 v[8:9], s[52:53], 0, v[144:145]
	s_add_i32 s8, s24, s8
	v_lshl_add_u64 v[136:137], s[44:45], 1, v[8:9]
	s_mov_b32 m0, s8
	v_lshl_add_u64 v[8:9], s[46:47], 1, v[8:9]
	v_xor_b32_e32 v136, v197, v136
	global_load_lds_dwordx4 v[136:137], off
	s_add_i32 m0, s8, 0x2000
	v_and_b32_e32 v7, 15, v1
	v_xor_b32_e32 v8, v197, v8
	global_load_lds_dwordx4 v[8:9], off
	v_lshlrev_b32_e32 v6, 12, v6
	v_and_b32_e32 v138, 0x3000, v6
	v_lshlrev_b32_e32 v6, 6, v7
	v_lshlrev_b32_e32 v7, 2, v1
	v_and_b32_e32 v135, 48, v1
	v_and_b32_e32 v136, 32, v7
	v_bitop3_b32 v137, v6, v136, v135 bitop3:0x36
	s_add_i32 s8, 0, 0x10000
	v_lshlrev_b32_e32 v141, 6, v1
	s_waitcnt vmcnt(6)
	v_add_u32_e32 v139, s8, v137
	s_add_i32 s8, 0, 0x14000
	v_lshlrev_b32_e32 v134, 13, v134
	v_and_or_b32 v135, v141, s25, v135
	v_add_u32_e32 v140, s8, v137
	v_add_u32_e32 v142, s31, v137
	v_add_u32_e32 v143, s24, v137
	v_add_u32_e32 v137, 0, v137
	v_xad_u32 v146, v135, v136, 0
	v_or_b32_e32 v135, 0x800, v134
	v_or_b32_e32 v147, 0x1000, v134
	v_or_b32_e32 v148, 0x1800, v134
	v_lshl_add_u64 v[6:7], s[12:13], 0, v[144:145]
	v_lshl_add_u64 v[8:9], s[36:37], 0, v[144:145]
	s_mov_b32 s93, -2
	v_add_u32_e32 v141, v139, v138
	v_add_u32_e32 v137, v137, v134
	v_add_u32_e32 v136, v146, v135
	v_add_u32_e32 v135, v146, v147
	v_add_u32_e32 v134, v146, v148
	v_add_u32_e32 v140, v140, v138
	v_add_u32_e32 v139, v142, v138
	v_add_u32_e32 v138, v143, v138
	s_barrier
; #define LDA(dst, b, h) _Pragma("unroll") for (int m = 0; m < 4; ++m) _Pragma("unroll") for (int k = 0; k < 2; ++k) \
;     dst[m][k] = *reinterpret_cast<const LAS bf16x8*>(lds + SAo(b, h) + lds_byte(wr * 64 + m * 16 + fr, k * 32 + fq * 8))
; #define LDB(dst, b, h) _Pragma("unroll") for (int n = 0; n < 2; ++n) _Pragma("unroll") for (int k = 0; k < 2; ++k) \
;     dst[n][k] = *reinterpret_cast<const LAS bf16x8*>(lds + SBo(b, h) + lds_byte(wc * 32 + n * 16 + fr, k * 32 + fq * 8))
; #define MMA(ai, bj, At_, Bt_) do { __builtin_amdgcn_s_setprio(1); \
;     _Pragma("unroll") for (int m = 0; m < 4; ++m) _Pragma("unroll") for (int n = 0; n < 2; ++n) _Pragma("unroll") for (int k = 0; k < 2; ++k) \
;       acc[ai][bj][m][n] = __builtin_amdgcn_mfma_f32_16x16x32_bf16(Bt_[n][k], At_[m][k], acc[ai][bj][m][n], 0, 0, 0); \
;     __builtin_amdgcn_s_setprio(0); } while (0)
; #define WAIT_V(n) asm volatile("s_waitcnt vmcnt(" #n ")" ::: "memory")
; #define WAIT_L(n) asm volatile("s_waitcnt lgkmcnt(" #n ")" ::: "memory")
; template <bool PRE = false>
; __device__ __forceinline__ void gemm_kloop(Acc& acc, const bf16_t* __restrict__ A, int lda, const bf16_t* __restrict__ Bt, int ldb,
;                                            int brow, int bcol, int nt, LAS unsigned char* lds) {
;     ...
;     for (int t = 0; t < nt - 2; t += 2) {
;         LDB(B0, 0, 0); SCHED; LDA(At, 0, 0); STAGE(SAo(1, 1), A, lda, brow + HALF, t + 1, offA);
;         WAIT_L(8); BAR; WAIT_L(0); MMA(0, 0, At, B0); BAR; SCHED;
;         LDB(B1, 0, 1); STAGE(SBo(0, 0), Bt, ldb, bcol, t + 2, offB);
;         BAR; WAIT_L(0); MMA(0, 1, At, B1); BAR;
;         LDA(At, 0, 1); STAGE(SAo(0, 0), A, lda, brow, t + 2, offA);
;         BAR; WAIT_L(0); MMA(1, 0, At, B0); BAR; SCHED;
;         STAGE(SBo(0, 1), Bt, ldb, bcol + HALF, t + 2, offB);
;         WAIT_V(6); BAR; MMA(1, 1, At, B1); BAR;
;         LDB(B0, 1, 0); SCHED; LDA(At, 1, 0); STAGE(SAo(0, 1), A, lda, brow + HALF, t + 2, offA);
;         WAIT_L(8); BAR; WAIT_L(0); MMA(0, 0, At, B0); BAR; SCHED;
;         LDB(B1, 1, 1); STAGE(SBo(1, 0), Bt, ldb, bcol, t + 3, offB);
;         BAR; WAIT_L(0); MMA(0, 1, At, B1); BAR;
;         LDA(At, 1, 1); STAGE(SAo(1, 0), A, lda, brow, t + 3, offA);
;         BAR; WAIT_L(0); MMA(1, 0, At, B0); BAR; SCHED;
;         STAGE(SBo(1, 1), Bt, ldb, bcol + HALF, t + 3, offB);
;         WAIT_V(6); BAR; MMA(1, 1, At, B1); BAR;
;     }
.LBB0_555:
	ds_read_b128 v[146:149], v141
	ds_read_b128 v[150:153], v141 offset:1024
	ds_read_b128 v[154:157], v141 offset:2048
	ds_read_b128 v[158:161], v141 offset:3072
	s_add_i32 s36, s93, 3
	s_mov_b32 s8, s92
	ds_read_b128 v[162:165], v137
	ds_read_b128 v[166:169], v137 offset:1024
	ds_read_b128 v[170:173], v136
	ds_read_b128 v[174:177], v136 offset:1024
	ds_read_b128 v[184:187], v135
	ds_read_b128 v[188:191], v135 offset:1024
	ds_read_b128 v[200:203], v134
	ds_read_b128 v[204:207], v134 offset:1024
	s_ashr_i32 s37, s36, 31
	s_lshl_b64 s[36:37], s[36:37], 7
	s_lshl_b32 s8, s8, 10
	v_lshl_add_u64 v[142:143], v[6:7], 0, s[36:37]
	s_add_i32 s8, s8, 0
	s_lshl_b64 s[36:37], s[48:49], 1
	s_add_i32 m0, s8, 0xc000
	v_lshl_add_u64 v[192:193], v[142:143], 0, s[36:37]
	s_lshl_b64 s[52:53], s[50:51], 1
	v_xor_b32_e32 v192, v197, v192
	global_load_lds_dwordx4 v[192:193], off
	v_lshl_add_u64 v[142:143], v[142:143], 0, s[52:53]
	s_add_i32 m0, s8, 0xe000
	s_nop 0
	v_xor_b32_e32 v142, v197, v142
	global_load_lds_dwordx4 v[142:143], off
	s_waitcnt lgkmcnt(8)
	s_barrier
	s_waitcnt lgkmcnt(0)
	s_setprio 1
	s_waitcnt lgkmcnt(0)
	v_mfma_f32_16x16x32_bf16 v[2:5], v[146:149], v[162:165], v[2:5]
	v_mfma_f32_16x16x32_bf16 v[10:13], v[154:157], v[162:165], v[10:13]
	v_mfma_f32_16x16x32_bf16 v[34:37], v[146:149], v[170:173], v[34:37]
	v_mfma_f32_16x16x32_bf16 v[42:45], v[154:157], v[170:173], v[42:45]
	v_mfma_f32_16x16x32_bf16 v[66:69], v[146:149], v[184:187], v[66:69]
	v_mfma_f32_16x16x32_bf16 v[74:77], v[154:157], v[184:187], v[74:77]
	v_mfma_f32_16x16x32_bf16 v[98:101], v[146:149], v[200:203], v[98:101]
	v_mfma_f32_16x16x32_bf16 v[106:109], v[154:157], v[200:203], v[106:109]
	v_mfma_f32_16x16x32_bf16 v[2:5], v[150:153], v[166:169], v[2:5]
	v_mfma_f32_16x16x32_bf16 v[10:13], v[158:161], v[166:169], v[10:13]
	v_mfma_f32_16x16x32_bf16 v[34:37], v[150:153], v[174:177], v[34:37]
	v_mfma_f32_16x16x32_bf16 v[42:45], v[158:161], v[174:177], v[42:45]
	v_mfma_f32_16x16x32_bf16 v[66:69], v[150:153], v[188:191], v[66:69]
	v_mfma_f32_16x16x32_bf16 v[74:77], v[158:161], v[188:191], v[74:77]
	v_mfma_f32_16x16x32_bf16 v[98:101], v[150:153], v[204:207], v[98:101]
	v_mfma_f32_16x16x32_bf16 v[106:109], v[158:161], v[204:207], v[106:109]
	s_setprio 0
	s_barrier
	s_add_i32 s66, s93, 4
	s_mov_b32 s54, s66
	s_mov_b32 s8, s92
	ds_read_b128 v[208:211], v140
	ds_read_b128 v[212:215], v140 offset:1024
	ds_read_b128 v[216:219], v140 offset:2048
	ds_read_b128 v[220:223], v140 offset:3072
	s_ashr_i32 s55, s54, 31
	s_lshl_b64 s[54:55], s[54:55], 7
	s_lshl_b32 s8, s8, 10
	v_lshl_add_u64 v[142:143], v[8:9], 0, s[54:55]
	s_add_i32 s8, s8, 0
	s_lshl_b64 s[54:55], s[0:1], 1
	s_add_i32 m0, s8, 0x10000
	v_lshl_add_u64 v[192:193], v[142:143], 0, s[54:55]
	s_lshl_b64 s[56:57], s[38:39], 1
	v_xor_b32_e32 v192, v197, v192
	global_load_lds_dwordx4 v[192:193], off
	v_lshl_add_u64 v[142:143], v[142:143], 0, s[56:57]
	s_add_i32 m0, s8, 0x12000
	s_nop 0
	v_xor_b32_e32 v142, v197, v142
	global_load_lds_dwordx4 v[142:143], off
	s_barrier
	s_waitcnt lgkmcnt(0)
	s_setprio 1
	s_waitcnt lgkmcnt(0)
	v_mfma_f32_16x16x32_bf16 v[18:21], v[208:211], v[162:165], v[18:21]
	v_mfma_f32_16x16x32_bf16 v[26:29], v[216:219], v[162:165], v[26:29]
	v_mfma_f32_16x16x32_bf16 v[50:53], v[208:211], v[170:173], v[50:53]
	v_mfma_f32_16x16x32_bf16 v[58:61], v[216:219], v[170:173], v[58:61]
	v_mfma_f32_16x16x32_bf16 v[82:85], v[208:211], v[184:187], v[82:85]
	v_mfma_f32_16x16x32_bf16 v[90:93], v[216:219], v[184:187], v[90:93]
	v_mfma_f32_16x16x32_bf16 v[114:117], v[208:211], v[200:203], v[114:117]
	v_mfma_f32_16x16x32_bf16 v[122:125], v[216:219], v[200:203], v[122:125]
	v_mfma_f32_16x16x32_bf16 v[18:21], v[212:215], v[166:169], v[18:21]
	v_mfma_f32_16x16x32_bf16 v[26:29], v[220:223], v[166:169], v[26:29]
	v_mfma_f32_16x16x32_bf16 v[50:53], v[212:215], v[174:177], v[50:53]
	v_mfma_f32_16x16x32_bf16 v[58:61], v[220:223], v[174:177], v[58:61]
	v_mfma_f32_16x16x32_bf16 v[82:85], v[212:215], v[188:191], v[82:85]
	v_mfma_f32_16x16x32_bf16 v[90:93], v[220:223], v[188:191], v[90:93]
	v_mfma_f32_16x16x32_bf16 v[114:117], v[212:215], v[204:207], v[114:117]
	v_mfma_f32_16x16x32_bf16 v[122:125], v[220:223], v[204:207], v[122:125]
	s_setprio 0
	s_mov_b32 s58, s66
	s_mov_b32 s8, s92
	s_barrier
	ds_read_b128 v[162:165], v137 offset:16384
	ds_read_b128 v[166:169], v137 offset:17408
	ds_read_b128 v[170:173], v136 offset:16384
	ds_read_b128 v[174:177], v136 offset:17408
	ds_read_b128 v[184:187], v135 offset:16384
	ds_read_b128 v[188:191], v135 offset:17408
	ds_read_b128 v[200:203], v134 offset:16384
	ds_read_b128 v[204:207], v134 offset:17408
	s_ashr_i32 s59, s58, 31
	s_lshl_b64 s[58:59], s[58:59], 7
	s_lshl_b32 s8, s8, 10
	v_lshl_add_u64 v[142:143], v[6:7], 0, s[58:59]
	s_add_i32 s8, s8, 0
	s_lshl_b64 s[58:59], s[40:41], 1
	v_lshl_add_u64 v[192:193], v[142:143], 0, s[58:59]
	s_mov_b32 m0, s8
	s_lshl_b64 s[60:61], s[42:43], 1
	v_xor_b32_e32 v192, v197, v192
	global_load_lds_dwordx4 v[192:193], off
	v_lshl_add_u64 v[142:143], v[142:143], 0, s[60:61]
	s_add_i32 m0, s8, 0x2000
	s_nop 0
	v_xor_b32_e32 v142, v197, v142
	global_load_lds_dwordx4 v[142:143], off
	s_barrier
; #define LDA(dst, b, h) _Pragma("unroll") for (int m = 0; m < 4; ++m) _Pragma("unroll") for (int k = 0; k < 2; ++k) \
;     dst[m][k] = *reinterpret_cast<const LAS bf16x8*>(lds + SAo(b, h) + lds_byte(wr * 64 + m * 16 + fr, k * 32 + fq * 8))
; #define LDB(dst, b, h) _Pragma("unroll") for (int n = 0; n < 2; ++n) _Pragma("unroll") for (int k = 0; k < 2; ++k) \
;     dst[n][k] = *reinterpret_cast<const LAS bf16x8*>(lds + SBo(b, h) + lds_byte(wc * 32 + n * 16 + fr, k * 32 + fq * 8))
; #define MMA(ai, bj, At_, Bt_) do { __builtin_amdgcn_s_setprio(1); \
;     _Pragma("unroll") for (int m = 0; m < 4; ++m) _Pragma("unroll") for (int n = 0; n < 2; ++n) _Pragma("unroll") for (int k = 0; k < 2; ++k) \
;       acc[ai][bj][m][n] = __builtin_amdgcn_mfma_f32_16x16x32_bf16(Bt_[n][k], At_[m][k], acc[ai][bj][m][n], 0, 0, 0); \
;     __builtin_amdgcn_s_setprio(0); } while (0)
; #define WAIT_V(n) asm volatile("s_waitcnt vmcnt(" #n ")" ::: "memory")
; #define WAIT_L(n) asm volatile("s_waitcnt lgkmcnt(" #n ")" ::: "memory")
; template <bool PRE = false>
; __device__ __forceinline__ void gemm_kloop(Acc& acc, const bf16_t* __restrict__ A, int lda, const bf16_t* __restrict__ Bt, int ldb,
;                                            int brow, int bcol, int nt, LAS unsigned char* lds) {
;     ...
;     for (int t = 0; t < nt - 2; t += 2) {
;         LDB(B0, 0, 0); SCHED; LDA(At, 0, 0); STAGE(SAo(1, 1), A, lda, brow + HALF, t + 1, offA);
;         WAIT_L(8); BAR; WAIT_L(0); MMA(0, 0, At, B0); BAR; SCHED;
;         LDB(B1, 0, 1); STAGE(SBo(0, 0), Bt, ldb, bcol, t + 2, offB);
;         BAR; WAIT_L(0); MMA(0, 1, At, B1); BAR;
;         LDA(At, 0, 1); STAGE(SAo(0, 0), A, lda, brow, t + 2, offA);
;         BAR; WAIT_L(0); MMA(1, 0, At, B0); BAR; SCHED;
;         STAGE(SBo(0, 1), Bt, ldb, bcol + HALF, t + 2, offB);
;         WAIT_V(6); BAR; MMA(1, 1, At, B1); BAR;
;         LDB(B0, 1, 0); SCHED; LDA(At, 1, 0); STAGE(SAo(0, 1), A, lda, brow + HALF, t + 2, offA);
;         WAIT_L(8); BAR; WAIT_L(0); MMA(0, 0, At, B0); BAR; SCHED;
;         LDB(B1, 1, 1); STAGE(SBo(1, 0), Bt, ldb, bcol, t + 3, offB);
;         BAR; WAIT_L(0); MMA(0, 1, At, B1); BAR;
;         LDA(At, 1, 1); STAGE(SAo(1, 0), A, lda, brow, t + 3, offA);
;         BAR; WAIT_L(0); MMA(1, 0, At, B0); BAR; SCHED;
;         STAGE(SBo(1, 1), Bt, ldb, bcol + HALF, t + 3, offB);
;         WAIT_V(6); BAR; MMA(1, 1, At, B1); BAR;
;     }
	s_waitcnt lgkmcnt(0)
	s_setprio 1
	s_waitcnt lgkmcnt(0)
	v_mfma_f32_16x16x32_bf16 v[130:133], v[146:149], v[162:165], v[130:133]
	v_mfma_f32_16x16x32_bf16 v[126:129], v[154:157], v[162:165], v[126:129]
	v_mfma_f32_16x16x32_bf16 v[102:105], v[146:149], v[170:173], v[102:105]
	v_mfma_f32_16x16x32_bf16 v[94:97], v[154:157], v[170:173], v[94:97]
	v_mfma_f32_16x16x32_bf16 v[70:73], v[146:149], v[184:187], v[70:73]
	v_mfma_f32_16x16x32_bf16 v[62:65], v[154:157], v[184:187], v[62:65]
	v_mfma_f32_16x16x32_bf16 v[38:41], v[146:149], v[200:203], v[38:41]
	v_mfma_f32_16x16x32_bf16 v[30:33], v[154:157], v[200:203], v[30:33]
	v_mfma_f32_16x16x32_bf16 v[130:133], v[150:153], v[166:169], v[130:133]
	v_mfma_f32_16x16x32_bf16 v[126:129], v[158:161], v[166:169], v[126:129]
	v_mfma_f32_16x16x32_bf16 v[102:105], v[150:153], v[174:177], v[102:105]
	v_mfma_f32_16x16x32_bf16 v[94:97], v[158:161], v[174:177], v[94:97]
	v_mfma_f32_16x16x32_bf16 v[70:73], v[150:153], v[188:191], v[70:73]
	v_mfma_f32_16x16x32_bf16 v[62:65], v[158:161], v[188:191], v[62:65]
	v_mfma_f32_16x16x32_bf16 v[38:41], v[150:153], v[204:207], v[38:41]
	v_mfma_f32_16x16x32_bf16 v[30:33], v[158:161], v[204:207], v[30:33]
	s_setprio 0
	s_barrier
	s_mov_b32 s62, s66
	s_mov_b32 s8, s92
	s_ashr_i32 s63, s62, 31
	s_lshl_b64 s[62:63], s[62:63], 7
	s_lshl_b32 s8, s8, 10
	v_lshl_add_u64 v[142:143], v[8:9], 0, s[62:63]
	s_add_i32 s8, s8, 0
	s_lshl_b64 s[62:63], s[44:45], 1
	s_add_i32 m0, s8, 0x14000
	v_lshl_add_u64 v[146:147], v[142:143], 0, s[62:63]
	s_lshl_b64 s[64:65], s[46:47], 1
	v_xor_b32_e32 v146, v197, v146
	global_load_lds_dwordx4 v[146:147], off
	v_lshl_add_u64 v[142:143], v[142:143], 0, s[64:65]
	s_add_i32 m0, s8, 0x16000
	s_nop 0
	v_xor_b32_e32 v142, v197, v142
	global_load_lds_dwordx4 v[142:143], off
	s_waitcnt vmcnt(6)
	s_barrier
	s_setprio 1
	v_mfma_f32_16x16x32_bf16 v[118:121], v[208:211], v[162:165], v[118:121]
	v_mfma_f32_16x16x32_bf16 v[110:113], v[216:219], v[162:165], v[110:113]
	v_mfma_f32_16x16x32_bf16 v[86:89], v[208:211], v[170:173], v[86:89]
	v_mfma_f32_16x16x32_bf16 v[78:81], v[216:219], v[170:173], v[78:81]
	v_mfma_f32_16x16x32_bf16 v[54:57], v[208:211], v[184:187], v[54:57]
	v_mfma_f32_16x16x32_bf16 v[46:49], v[216:219], v[184:187], v[46:49]
	v_mfma_f32_16x16x32_bf16 v[22:25], v[208:211], v[200:203], v[22:25]
	v_mfma_f32_16x16x32_bf16 v[14:17], v[216:219], v[200:203], v[14:17]
	v_mfma_f32_16x16x32_bf16 v[118:121], v[212:215], v[166:169], v[118:121]
	v_mfma_f32_16x16x32_bf16 v[110:113], v[220:223], v[166:169], v[110:113]
	v_mfma_f32_16x16x32_bf16 v[86:89], v[212:215], v[174:177], v[86:89]
	v_mfma_f32_16x16x32_bf16 v[78:81], v[220:223], v[174:177], v[78:81]
	v_mfma_f32_16x16x32_bf16 v[54:57], v[212:215], v[188:191], v[54:57]
	v_mfma_f32_16x16x32_bf16 v[46:49], v[220:223], v[188:191], v[46:49]
	v_mfma_f32_16x16x32_bf16 v[22:25], v[212:215], v[204:207], v[22:25]
	v_mfma_f32_16x16x32_bf16 v[14:17], v[220:223], v[204:207], v[14:17]
	s_setprio 0
	s_barrier
	ds_read_b128 v[146:149], v139
	ds_read_b128 v[150:153], v139 offset:1024
	ds_read_b128 v[154:157], v139 offset:2048
	ds_read_b128 v[158:161], v139 offset:3072
	s_mov_b32 s8, s92
	ds_read_b128 v[162:165], v137 offset:32768
	ds_read_b128 v[166:169], v137 offset:33792
	ds_read_b128 v[170:173], v136 offset:32768
	ds_read_b128 v[174:177], v136 offset:33792
	ds_read_b128 v[184:187], v135 offset:32768
	ds_read_b128 v[188:191], v135 offset:33792
	ds_read_b128 v[200:203], v134 offset:32768
	ds_read_b128 v[204:207], v134 offset:33792
	s_ashr_i32 s67, s66, 31
	s_lshl_b64 s[66:67], s[66:67], 7
	s_lshl_b32 s8, s8, 10
	v_lshl_add_u64 v[142:143], v[6:7], 0, s[66:67]
	s_add_i32 s8, s8, 0
	s_add_i32 m0, s8, 0x4000
	v_lshl_add_u64 v[192:193], v[142:143], 0, s[36:37]
	v_xor_b32_e32 v192, v197, v192
	global_load_lds_dwordx4 v[192:193], off
	v_lshl_add_u64 v[142:143], v[142:143], 0, s[52:53]
	s_add_i32 m0, s8, 0x6000
	s_nop 0
	v_xor_b32_e32 v142, v197, v142
	global_load_lds_dwordx4 v[142:143], off
	s_waitcnt lgkmcnt(8)
	s_barrier
	s_waitcnt lgkmcnt(0)
	s_setprio 1
	s_waitcnt lgkmcnt(0)
	v_mfma_f32_16x16x32_bf16 v[2:5], v[146:149], v[162:165], v[2:5]
	v_mfma_f32_16x16x32_bf16 v[10:13], v[154:157], v[162:165], v[10:13]
	v_mfma_f32_16x16x32_bf16 v[34:37], v[146:149], v[170:173], v[34:37]
	v_mfma_f32_16x16x32_bf16 v[42:45], v[154:157], v[170:173], v[42:45]
	v_mfma_f32_16x16x32_bf16 v[66:69], v[146:149], v[184:187], v[66:69]
	v_mfma_f32_16x16x32_bf16 v[74:77], v[154:157], v[184:187], v[74:77]
	v_mfma_f32_16x16x32_bf16 v[98:101], v[146:149], v[200:203], v[98:101]
	v_mfma_f32_16x16x32_bf16 v[106:109], v[154:157], v[200:203], v[106:109]
	v_mfma_f32_16x16x32_bf16 v[2:5], v[150:153], v[166:169], v[2:5]
	v_mfma_f32_16x16x32_bf16 v[10:13], v[158:161], v[166:169], v[10:13]
	v_mfma_f32_16x16x32_bf16 v[34:37], v[150:153], v[174:177], v[34:37]
	v_mfma_f32_16x16x32_bf16 v[42:45], v[158:161], v[174:177], v[42:45]
	v_mfma_f32_16x16x32_bf16 v[66:69], v[150:153], v[188:191], v[66:69]
	v_mfma_f32_16x16x32_bf16 v[74:77], v[158:161], v[188:191], v[74:77]
	v_mfma_f32_16x16x32_bf16 v[98:101], v[150:153], v[204:207], v[98:101]
	v_mfma_f32_16x16x32_bf16 v[106:109], v[158:161], v[204:207], v[106:109]
	s_setprio 0
	s_barrier
	s_add_i32 s36, s93, 5
	s_mov_b32 s52, s36
	s_mov_b32 s8, s92
	ds_read_b128 v[208:211], v138
	ds_read_b128 v[212:215], v138 offset:1024
	ds_read_b128 v[216:219], v138 offset:2048
	ds_read_b128 v[220:223], v138 offset:3072
	s_ashr_i32 s53, s52, 31
	s_lshl_b64 s[52:53], s[52:53], 7
	s_lshl_b32 s8, s8, 10
	v_lshl_add_u64 v[142:143], v[8:9], 0, s[52:53]
	s_add_i32 s8, s8, 0
	s_add_i32 m0, s8, 0x18000
	v_lshl_add_u64 v[192:193], v[142:143], 0, s[54:55]
	v_xor_b32_e32 v192, v197, v192
	global_load_lds_dwordx4 v[192:193], off
	v_lshl_add_u64 v[142:143], v[142:143], 0, s[56:57]
	s_add_i32 m0, s8, 0x1a000
	s_nop 0
	v_xor_b32_e32 v142, v197, v142
	global_load_lds_dwordx4 v[142:143], off
	s_barrier
; #define LDA(dst, b, h) _Pragma("unroll") for (int m = 0; m < 4; ++m) _Pragma("unroll") for (int k = 0; k < 2; ++k) \
;     dst[m][k] = *reinterpret_cast<const LAS bf16x8*>(lds + SAo(b, h) + lds_byte(wr * 64 + m * 16 + fr, k * 32 + fq * 8))
; #define LDB(dst, b, h) _Pragma("unroll") for (int n = 0; n < 2; ++n) _Pragma("unroll") for (int k = 0; k < 2; ++k) \
;     dst[n][k] = *reinterpret_cast<const LAS bf16x8*>(lds + SBo(b, h) + lds_byte(wc * 32 + n * 16 + fr, k * 32 + fq * 8))
; #define MMA(ai, bj, At_, Bt_) do { __builtin_amdgcn_s_setprio(1); \
;     _Pragma("unroll") for (int m = 0; m < 4; ++m) _Pragma("unroll") for (int n = 0; n < 2; ++n) _Pragma("unroll") for (int k = 0; k < 2; ++k) \
;       acc[ai][bj][m][n] = __builtin_amdgcn_mfma_f32_16x16x32_bf16(Bt_[n][k], At_[m][k], acc[ai][bj][m][n], 0, 0, 0); \
;     __builtin_amdgcn_s_setprio(0); } while (0)
; #define BAR __builtin_amdgcn_s_barrier()
; template <bool PRE = false>
; __device__ __forceinline__ void gemm_kloop(Acc& acc, const bf16_t* __restrict__ A, int lda, const bf16_t* __restrict__ Bt, int ldb,
;                                            int brow, int bcol, int nt, LAS unsigned char* lds) {
;     ...
;     for (int t = 0; t < nt - 2; t += 2) {
;         LDB(B0, 0, 0); SCHED; LDA(At, 0, 0); STAGE(SAo(1, 1), A, lda, brow + HALF, t + 1, offA);
;         WAIT_L(8); BAR; WAIT_L(0); MMA(0, 0, At, B0); BAR; SCHED;
;         LDB(B1, 0, 1); STAGE(SBo(0, 0), Bt, ldb, bcol, t + 2, offB);
;         BAR; WAIT_L(0); MMA(0, 1, At, B1); BAR;
;         LDA(At, 0, 1); STAGE(SAo(0, 0), A, lda, brow, t + 2, offA);
;         BAR; WAIT_L(0); MMA(1, 0, At, B0); BAR; SCHED;
;         STAGE(SBo(0, 1), Bt, ldb, bcol + HALF, t + 2, offB);
;         WAIT_V(6); BAR; MMA(1, 1, At, B1); BAR;
;         LDB(B0, 1, 0); SCHED; LDA(At, 1, 0); STAGE(SAo(0, 1), A, lda, brow + HALF, t + 2, offA);
;         WAIT_L(8); BAR; WAIT_L(0); MMA(0, 0, At, B0); BAR; SCHED;
;         LDB(B1, 1, 1); STAGE(SBo(1, 0), Bt, ldb, bcol, t + 3, offB);
;         BAR; WAIT_L(0); MMA(0, 1, At, B1); BAR;
;         LDA(At, 1, 1); STAGE(SAo(1, 0), A, lda, brow, t + 3, offA);
;         BAR; WAIT_L(0); MMA(1, 0, At, B0); BAR; SCHED;
;         STAGE(SBo(1, 1), Bt, ldb, bcol + HALF, t + 3, offB);
;         WAIT_V(6); BAR; MMA(1, 1, At, B1); BAR;
;     }
;     { LDB(B0, 0, 0); LDA(At, 0, 0); STAGE(SAo(1, 1), A, lda, brow + HALF, nt - 1, offA);
	s_waitcnt lgkmcnt(0)
	s_setprio 1
	s_waitcnt lgkmcnt(0)
	v_mfma_f32_16x16x32_bf16 v[18:21], v[208:211], v[162:165], v[18:21]
	v_mfma_f32_16x16x32_bf16 v[26:29], v[216:219], v[162:165], v[26:29]
	v_mfma_f32_16x16x32_bf16 v[50:53], v[208:211], v[170:173], v[50:53]
	v_mfma_f32_16x16x32_bf16 v[58:61], v[216:219], v[170:173], v[58:61]
	v_mfma_f32_16x16x32_bf16 v[82:85], v[208:211], v[184:187], v[82:85]
	v_mfma_f32_16x16x32_bf16 v[90:93], v[216:219], v[184:187], v[90:93]
	v_mfma_f32_16x16x32_bf16 v[114:117], v[208:211], v[200:203], v[114:117]
	v_mfma_f32_16x16x32_bf16 v[122:125], v[216:219], v[200:203], v[122:125]
	v_mfma_f32_16x16x32_bf16 v[18:21], v[212:215], v[166:169], v[18:21]
	v_mfma_f32_16x16x32_bf16 v[26:29], v[220:223], v[166:169], v[26:29]
	v_mfma_f32_16x16x32_bf16 v[50:53], v[212:215], v[174:177], v[50:53]
	v_mfma_f32_16x16x32_bf16 v[58:61], v[220:223], v[174:177], v[58:61]
	v_mfma_f32_16x16x32_bf16 v[82:85], v[212:215], v[188:191], v[82:85]
	v_mfma_f32_16x16x32_bf16 v[90:93], v[220:223], v[188:191], v[90:93]
	v_mfma_f32_16x16x32_bf16 v[114:117], v[212:215], v[204:207], v[114:117]
	v_mfma_f32_16x16x32_bf16 v[122:125], v[220:223], v[204:207], v[122:125]
	s_setprio 0
	s_mov_b32 s52, s36
	s_mov_b32 s8, s92
	s_barrier
	ds_read_b128 v[162:165], v137 offset:49152
	ds_read_b128 v[166:169], v137 offset:50176
	ds_read_b128 v[170:173], v136 offset:49152
	ds_read_b128 v[174:177], v136 offset:50176
	ds_read_b128 v[184:187], v135 offset:49152
	ds_read_b128 v[188:191], v135 offset:50176
	ds_read_b128 v[200:203], v134 offset:49152
	ds_read_b128 v[204:207], v134 offset:50176
	s_ashr_i32 s53, s52, 31
	s_lshl_b64 s[52:53], s[52:53], 7
	s_lshl_b32 s8, s8, 10
	v_lshl_add_u64 v[142:143], v[6:7], 0, s[52:53]
	s_add_i32 s8, s8, 0
	s_add_i32 m0, s8, 0x8000
	v_lshl_add_u64 v[192:193], v[142:143], 0, s[58:59]
	v_xor_b32_e32 v192, v197, v192
	global_load_lds_dwordx4 v[192:193], off
	v_lshl_add_u64 v[142:143], v[142:143], 0, s[60:61]
	s_add_i32 m0, s8, 0xa000
	s_nop 0
	v_xor_b32_e32 v142, v197, v142
	global_load_lds_dwordx4 v[142:143], off
	s_barrier
	s_waitcnt lgkmcnt(0)
	s_setprio 1
	s_waitcnt lgkmcnt(0)
	v_mfma_f32_16x16x32_bf16 v[130:133], v[146:149], v[162:165], v[130:133]
	v_mfma_f32_16x16x32_bf16 v[126:129], v[154:157], v[162:165], v[126:129]
	v_mfma_f32_16x16x32_bf16 v[102:105], v[146:149], v[170:173], v[102:105]
	v_mfma_f32_16x16x32_bf16 v[94:97], v[154:157], v[170:173], v[94:97]
	v_mfma_f32_16x16x32_bf16 v[70:73], v[146:149], v[184:187], v[70:73]
	v_mfma_f32_16x16x32_bf16 v[62:65], v[154:157], v[184:187], v[62:65]
	v_mfma_f32_16x16x32_bf16 v[38:41], v[146:149], v[200:203], v[38:41]
	v_mfma_f32_16x16x32_bf16 v[30:33], v[154:157], v[200:203], v[30:33]
	v_mfma_f32_16x16x32_bf16 v[130:133], v[150:153], v[166:169], v[130:133]
	v_mfma_f32_16x16x32_bf16 v[126:129], v[158:161], v[166:169], v[126:129]
	v_mfma_f32_16x16x32_bf16 v[102:105], v[150:153], v[174:177], v[102:105]
	v_mfma_f32_16x16x32_bf16 v[94:97], v[158:161], v[174:177], v[94:97]
	v_mfma_f32_16x16x32_bf16 v[70:73], v[150:153], v[188:191], v[70:73]
	v_mfma_f32_16x16x32_bf16 v[62:65], v[158:161], v[188:191], v[62:65]
	v_mfma_f32_16x16x32_bf16 v[38:41], v[150:153], v[204:207], v[38:41]
	v_mfma_f32_16x16x32_bf16 v[30:33], v[158:161], v[204:207], v[30:33]
	s_setprio 0
	s_barrier
	s_mov_b32 s8, s92
	s_ashr_i32 s37, s36, 31
	s_lshl_b64 s[36:37], s[36:37], 7
	s_lshl_b32 s8, s8, 10
	v_lshl_add_u64 v[142:143], v[8:9], 0, s[36:37]
	s_add_i32 s8, s8, 0
	s_add_i32 m0, s8, 0x1c000
	v_lshl_add_u64 v[146:147], v[142:143], 0, s[62:63]
	v_xor_b32_e32 v146, v197, v146
	global_load_lds_dwordx4 v[146:147], off
	v_lshl_add_u64 v[142:143], v[142:143], 0, s[64:65]
	s_add_i32 m0, s8, 0x1e000
	s_nop 0
	v_xor_b32_e32 v142, v197, v142
	global_load_lds_dwordx4 v[142:143], off
	s_waitcnt vmcnt(6)
	s_barrier
	s_setprio 1
	v_mfma_f32_16x16x32_bf16 v[118:121], v[208:211], v[162:165], v[118:121]
	v_mfma_f32_16x16x32_bf16 v[110:113], v[216:219], v[162:165], v[110:113]
	v_mfma_f32_16x16x32_bf16 v[86:89], v[208:211], v[170:173], v[86:89]
	v_mfma_f32_16x16x32_bf16 v[78:81], v[216:219], v[170:173], v[78:81]
	v_mfma_f32_16x16x32_bf16 v[54:57], v[208:211], v[184:187], v[54:57]
	v_mfma_f32_16x16x32_bf16 v[46:49], v[216:219], v[184:187], v[46:49]
	v_mfma_f32_16x16x32_bf16 v[22:25], v[208:211], v[200:203], v[22:25]
	v_mfma_f32_16x16x32_bf16 v[14:17], v[216:219], v[200:203], v[14:17]
	v_mfma_f32_16x16x32_bf16 v[118:121], v[212:215], v[166:169], v[118:121]
	v_mfma_f32_16x16x32_bf16 v[110:113], v[220:223], v[166:169], v[110:113]
	v_mfma_f32_16x16x32_bf16 v[86:89], v[212:215], v[174:177], v[86:89]
	v_mfma_f32_16x16x32_bf16 v[78:81], v[220:223], v[174:177], v[78:81]
	v_mfma_f32_16x16x32_bf16 v[54:57], v[212:215], v[188:191], v[54:57]
	v_mfma_f32_16x16x32_bf16 v[46:49], v[220:223], v[188:191], v[46:49]
	v_mfma_f32_16x16x32_bf16 v[22:25], v[212:215], v[204:207], v[22:25]
	v_mfma_f32_16x16x32_bf16 v[14:17], v[220:223], v[204:207], v[14:17]
	s_setprio 0
	s_add_i32 s93, s93, 2
	s_cmp_lt_u32 s93, 4
	s_barrier
	s_cbranch_scc1 .LBB0_555
	s_mov_b32 s36, 7
	ds_read_b128 v[6:9], v141
	ds_read_b128 v[146:149], v141 offset:1024
	ds_read_b128 v[150:153], v141 offset:2048
	ds_read_b128 v[154:157], v141 offset:3072
	ds_read_b128 v[158:161], v137
	ds_read_b128 v[162:165], v137 offset:1024
	ds_read_b128 v[166:169], v136
	ds_read_b128 v[170:173], v136 offset:1024
	ds_read_b128 v[174:177], v135
	ds_read_b128 v[184:187], v135 offset:1024
	ds_read_b128 v[188:191], v134
	ds_read_b128 v[200:203], v134 offset:1024
	s_ashr_i32 s37, s36, 31
	s_lshl_b64 s[36:37], s[36:37], 7
	s_add_u32 s12, s12, s36
	s_addc_u32 s13, s13, s37
	s_lshl_b32 s8, s92, 10
	v_lshl_add_u64 v[142:143], s[12:13], 0, v[144:145]
	s_add_i32 s8, s8, 0
	s_add_i32 m0, s8, 0xc000
	v_lshl_add_u64 v[192:193], s[48:49], 1, v[142:143]
	v_xor_b32_e32 v192, v197, v192
	global_load_lds_dwordx4 v[192:193], off
	v_lshl_add_u64 v[142:143], s[50:51], 1, v[142:143]
	s_add_i32 m0, s8, 0xe000
	s_nop 0
	v_xor_b32_e32 v142, v197, v142
	global_load_lds_dwordx4 v[142:143], off
	s_barrier
; #define LDA(dst, b, h) _Pragma("unroll") for (int m = 0; m < 4; ++m) _Pragma("unroll") for (int k = 0; k < 2; ++k) \
;     dst[m][k] = *reinterpret_cast<const LAS bf16x8*>(lds + SAo(b, h) + lds_byte(wr * 64 + m * 16 + fr, k * 32 + fq * 8))
; #define LDB(dst, b, h) _Pragma("unroll") for (int n = 0; n < 2; ++n) _Pragma("unroll") for (int k = 0; k < 2; ++k) \
;     dst[n][k] = *reinterpret_cast<const LAS bf16x8*>(lds + SBo(b, h) + lds_byte(wc * 32 + n * 16 + fr, k * 32 + fq * 8))
; #define MMA(ai, bj, At_, Bt_) do { __builtin_amdgcn_s_setprio(1); \
;     _Pragma("unroll") for (int m = 0; m < 4; ++m) _Pragma("unroll") for (int n = 0; n < 2; ++n) _Pragma("unroll") for (int k = 0; k < 2; ++k) \
;       acc[ai][bj][m][n] = __builtin_amdgcn_mfma_f32_16x16x32_bf16(Bt_[n][k], At_[m][k], acc[ai][bj][m][n], 0, 0, 0); \
;     __builtin_amdgcn_s_setprio(0); } while (0)
; #define WAIT_V(n) asm volatile("s_waitcnt vmcnt(" #n ")" ::: "memory")
; #define WAIT_L(n) asm volatile("s_waitcnt lgkmcnt(" #n ")" ::: "memory")
; #define BAR __builtin_amdgcn_s_barrier()
; template <bool PRE = false>
; __device__ __forceinline__ void gemm_kloop(Acc& acc, const bf16_t* __restrict__ A, int lda, const bf16_t* __restrict__ Bt, int ldb,
;                                            int brow, int bcol, int nt, LAS unsigned char* lds) {
;     ...
;     { LDB(B0, 0, 0); LDA(At, 0, 0); STAGE(SAo(1, 1), A, lda, brow + HALF, nt - 1, offA);
;       BAR; WAIT_L(0); MMA(0, 0, At, B0); BAR;
;       LDB(B1, 0, 1); BAR; WAIT_L(0); MMA(0, 1, At, B1); BAR;
;       LDA(At, 0, 1); WAIT_V(4); BAR; WAIT_L(0); MMA(1, 0, At, B0); MMA(1, 1, At, B1); BAR; }
;     { LDB(B0, 1, 0); LDA(At, 1, 0); WAIT_V(2); BAR; WAIT_L(0); MMA(0, 0, At, B0); BAR;
;       LDB(B1, 1, 1); WAIT_V(0); BAR; WAIT_L(0); MMA(0, 1, At, B1); BAR;
	s_waitcnt lgkmcnt(0)
	s_setprio 1
	s_waitcnt lgkmcnt(0)
	v_mfma_f32_16x16x32_bf16 v[10:13], v[150:153], v[158:161], v[10:13]
	v_mfma_f32_16x16x32_bf16 v[204:207], v[154:157], v[162:165], v[10:13]
	v_mfma_f32_16x16x32_bf16 v[10:13], v[6:9], v[166:169], v[34:37]
	v_mfma_f32_16x16x32_bf16 v[34:37], v[146:149], v[170:173], v[10:13]
	v_mfma_f32_16x16x32_bf16 v[10:13], v[150:153], v[166:169], v[42:45]
	v_mfma_f32_16x16x32_bf16 v[208:211], v[154:157], v[170:173], v[10:13]
	v_mfma_f32_16x16x32_bf16 v[10:13], v[6:9], v[174:177], v[66:69]
	v_mfma_f32_16x16x32_bf16 v[66:69], v[146:149], v[184:187], v[10:13]
	v_mfma_f32_16x16x32_bf16 v[10:13], v[150:153], v[174:177], v[74:77]
	v_mfma_f32_16x16x32_bf16 v[212:215], v[154:157], v[184:187], v[10:13]
	v_mfma_f32_16x16x32_bf16 v[10:13], v[6:9], v[188:191], v[98:101]
	v_mfma_f32_16x16x32_bf16 v[2:5], v[6:9], v[158:161], v[2:5]
	v_mfma_f32_16x16x32_bf16 v[98:101], v[146:149], v[200:203], v[10:13]
	v_mfma_f32_16x16x32_bf16 v[10:13], v[150:153], v[188:191], v[106:109]
	v_mfma_f32_16x16x32_bf16 v[2:5], v[146:149], v[162:165], v[2:5]
	v_mfma_f32_16x16x32_bf16 v[216:219], v[154:157], v[200:203], v[10:13]
	s_setprio 0
	s_barrier
	s_nop 3
	ds_read_b128 v[10:13], v140
	ds_read_b128 v[42:45], v140 offset:1024
	ds_read_b128 v[74:77], v140 offset:2048
	ds_read_b128 v[106:109], v140 offset:3072
	s_barrier
	s_waitcnt lgkmcnt(0)
	s_setprio 1
	s_waitcnt lgkmcnt(0)
	v_mfma_f32_16x16x32_bf16 v[18:21], v[10:13], v[158:161], v[18:21]
	v_mfma_f32_16x16x32_bf16 v[140:143], v[42:45], v[162:165], v[18:21]
	v_mfma_f32_16x16x32_bf16 v[18:21], v[74:77], v[158:161], v[26:29]
	v_mfma_f32_16x16x32_bf16 v[158:161], v[106:109], v[162:165], v[18:21]
	v_mfma_f32_16x16x32_bf16 v[18:21], v[10:13], v[166:169], v[50:53]
	v_mfma_f32_16x16x32_bf16 v[162:165], v[42:45], v[170:173], v[18:21]
	v_mfma_f32_16x16x32_bf16 v[18:21], v[74:77], v[166:169], v[58:61]
	v_mfma_f32_16x16x32_bf16 v[166:169], v[106:109], v[170:173], v[18:21]
	v_mfma_f32_16x16x32_bf16 v[18:21], v[10:13], v[174:177], v[82:85]
	v_mfma_f32_16x16x32_bf16 v[170:173], v[42:45], v[184:187], v[18:21]
	v_mfma_f32_16x16x32_bf16 v[18:21], v[74:77], v[174:177], v[90:93]
	v_mfma_f32_16x16x32_bf16 v[174:177], v[106:109], v[184:187], v[18:21]
	v_mfma_f32_16x16x32_bf16 v[18:21], v[10:13], v[188:191], v[114:117]
	v_mfma_f32_16x16x32_bf16 v[184:187], v[42:45], v[200:203], v[18:21]
	v_mfma_f32_16x16x32_bf16 v[18:21], v[74:77], v[188:191], v[122:125]
	v_mfma_f32_16x16x32_bf16 v[188:191], v[106:109], v[200:203], v[18:21]
	s_setprio 0
	s_barrier
	s_nop 4
	ds_read_b128 v[18:21], v137 offset:16384
	ds_read_b128 v[26:29], v137 offset:17408
	ds_read_b128 v[50:53], v136 offset:16384
	ds_read_b128 v[58:61], v136 offset:17408
	ds_read_b128 v[82:85], v135 offset:16384
	ds_read_b128 v[90:93], v135 offset:17408
	ds_read_b128 v[114:117], v134 offset:16384
	ds_read_b128 v[122:125], v134 offset:17408
	s_waitcnt vmcnt(4)
	s_barrier
	s_waitcnt lgkmcnt(0)
	s_setprio 1
	s_waitcnt lgkmcnt(0)
	v_mfma_f32_16x16x32_bf16 v[130:133], v[6:9], v[18:21], v[130:133]
	v_mfma_f32_16x16x32_bf16 v[102:105], v[6:9], v[50:53], v[102:105]
	v_mfma_f32_16x16x32_bf16 v[70:73], v[6:9], v[82:85], v[70:73]
	v_mfma_f32_16x16x32_bf16 v[6:9], v[6:9], v[114:117], v[38:41]
	v_mfma_f32_16x16x32_bf16 v[30:33], v[150:153], v[114:117], v[30:33]
	v_mfma_f32_16x16x32_bf16 v[126:129], v[150:153], v[18:21], v[126:129]
	v_mfma_f32_16x16x32_bf16 v[102:105], v[146:149], v[58:61], v[102:105]
	v_mfma_f32_16x16x32_bf16 v[94:97], v[150:153], v[50:53], v[94:97]
	v_mfma_f32_16x16x32_bf16 v[70:73], v[146:149], v[90:93], v[70:73]
	v_mfma_f32_16x16x32_bf16 v[62:65], v[150:153], v[82:85], v[62:65]
	v_mfma_f32_16x16x32_bf16 v[6:9], v[146:149], v[122:125], v[6:9]
	v_mfma_f32_16x16x32_bf16 v[38:41], v[154:157], v[122:125], v[30:33]
	v_mfma_f32_16x16x32_bf16 v[200:203], v[146:149], v[26:29], v[130:133]
	v_mfma_f32_16x16x32_bf16 v[220:223], v[154:157], v[26:29], v[126:129]
	v_mfma_f32_16x16x32_bf16 v[224:227], v[154:157], v[58:61], v[94:97]
	v_mfma_f32_16x16x32_bf16 v[228:231], v[154:157], v[90:93], v[62:65]
	s_setprio 0
	s_setprio 1
	v_mfma_f32_16x16x32_bf16 v[30:33], v[10:13], v[18:21], v[118:121]
	v_mfma_f32_16x16x32_bf16 v[18:21], v[74:77], v[18:21], v[110:113]
	v_mfma_f32_16x16x32_bf16 v[150:153], v[106:109], v[26:29], v[18:21]
	v_mfma_f32_16x16x32_bf16 v[18:21], v[10:13], v[50:53], v[86:89]
	v_mfma_f32_16x16x32_bf16 v[154:157], v[42:45], v[58:61], v[18:21]
	v_mfma_f32_16x16x32_bf16 v[18:21], v[74:77], v[50:53], v[78:81]
	v_mfma_f32_16x16x32_bf16 v[232:235], v[106:109], v[58:61], v[18:21]
	v_mfma_f32_16x16x32_bf16 v[18:21], v[10:13], v[82:85], v[54:57]
	v_mfma_f32_16x16x32_bf16 v[10:13], v[10:13], v[114:117], v[22:25]
	v_mfma_f32_16x16x32_bf16 v[236:239], v[42:45], v[90:93], v[18:21]
	v_mfma_f32_16x16x32_bf16 v[18:21], v[74:77], v[82:85], v[46:49]
	v_mfma_f32_16x16x32_bf16 v[244:247], v[42:45], v[122:125], v[10:13]
	v_mfma_f32_16x16x32_bf16 v[10:13], v[74:77], v[114:117], v[14:17]
	v_mfma_f32_16x16x32_bf16 v[146:149], v[42:45], v[26:29], v[30:33]
	v_mfma_f32_16x16x32_bf16 v[240:243], v[106:109], v[90:93], v[18:21]
	v_mfma_f32_16x16x32_bf16 v[248:251], v[106:109], v[122:125], v[10:13]
	s_setprio 0
	s_barrier
	ds_read_b128 v[14:17], v139
	ds_read_b128 v[22:25], v139 offset:1024
	ds_read_b128 v[46:49], v139 offset:2048
	ds_read_b128 v[78:81], v139 offset:3072
	ds_read_b128 v[30:33], v137 offset:32768
	ds_read_b128 v[54:57], v137 offset:33792
	ds_read_b128 v[62:65], v136 offset:32768
	ds_read_b128 v[86:89], v136 offset:33792
	ds_read_b128 v[94:97], v135 offset:32768
	ds_read_b128 v[110:113], v135 offset:33792
	ds_read_b128 v[118:121], v134 offset:32768
	ds_read_b128 v[126:129], v134 offset:33792
	s_waitcnt vmcnt(2)
	s_barrier
; #define LDA(dst, b, h) _Pragma("unroll") for (int m = 0; m < 4; ++m) _Pragma("unroll") for (int k = 0; k < 2; ++k) \
;     dst[m][k] = *reinterpret_cast<const LAS bf16x8*>(lds + SAo(b, h) + lds_byte(wr * 64 + m * 16 + fr, k * 32 + fq * 8))
; #define LDB(dst, b, h) _Pragma("unroll") for (int n = 0; n < 2; ++n) _Pragma("unroll") for (int k = 0; k < 2; ++k) \
;     dst[n][k] = *reinterpret_cast<const LAS bf16x8*>(lds + SBo(b, h) + lds_byte(wc * 32 + n * 16 + fr, k * 32 + fq * 8))
; #define MMA(ai, bj, At_, Bt_) do { __builtin_amdgcn_s_setprio(1); \
;     _Pragma("unroll") for (int m = 0; m < 4; ++m) _Pragma("unroll") for (int n = 0; n < 2; ++n) _Pragma("unroll") for (int k = 0; k < 2; ++k) \
;       acc[ai][bj][m][n] = __builtin_amdgcn_mfma_f32_16x16x32_bf16(Bt_[n][k], At_[m][k], acc[ai][bj][m][n], 0, 0, 0); \
;     __builtin_amdgcn_s_setprio(0); } while (0)
; #define WAIT_V(n) asm volatile("s_waitcnt vmcnt(" #n ")" ::: "memory")
; #define WAIT_L(n) asm volatile("s_waitcnt lgkmcnt(" #n ")" ::: "memory")
; #define BAR __builtin_amdgcn_s_barrier()
; template <bool PRE = false>
; __device__ __forceinline__ void gemm_kloop(Acc& acc, const bf16_t* __restrict__ A, int lda, const bf16_t* __restrict__ Bt, int ldb,
;                                            int brow, int bcol, int nt, LAS unsigned char* lds) {
;     ...
;     { LDB(B0, 1, 0); LDA(At, 1, 0); WAIT_V(2); BAR; WAIT_L(0); MMA(0, 0, At, B0); BAR;
;       LDB(B1, 1, 1); WAIT_V(0); BAR; WAIT_L(0); MMA(0, 1, At, B1); BAR;
;       LDA(At, 1, 1); BAR; WAIT_L(0); MMA(1, 0, At, B0); MMA(1, 1, At, B1); BAR; }
;     if (wr == 0) BAR;
	s_waitcnt lgkmcnt(0)
	s_setprio 1
	s_waitcnt lgkmcnt(0)
	v_mfma_f32_16x16x32_bf16 v[2:5], v[14:17], v[30:33], v[2:5]
	v_mfma_f32_16x16x32_bf16 v[10:13], v[22:25], v[54:57], v[2:5]
	v_mfma_f32_16x16x32_bf16 v[2:5], v[46:49], v[30:33], v[204:207]
	v_mfma_f32_16x16x32_bf16 v[18:21], v[78:81], v[54:57], v[2:5]
	v_mfma_f32_16x16x32_bf16 v[2:5], v[14:17], v[62:65], v[34:37]
	v_mfma_f32_16x16x32_bf16 v[42:45], v[22:25], v[86:89], v[2:5]
	v_mfma_f32_16x16x32_bf16 v[2:5], v[46:49], v[62:65], v[208:211]
	v_mfma_f32_16x16x32_bf16 v[50:53], v[78:81], v[86:89], v[2:5]
	v_mfma_f32_16x16x32_bf16 v[2:5], v[14:17], v[94:97], v[66:69]
	v_mfma_f32_16x16x32_bf16 v[74:77], v[22:25], v[110:113], v[2:5]
	v_mfma_f32_16x16x32_bf16 v[2:5], v[46:49], v[94:97], v[212:215]
	v_mfma_f32_16x16x32_bf16 v[82:85], v[78:81], v[110:113], v[2:5]
	v_mfma_f32_16x16x32_bf16 v[2:5], v[14:17], v[118:121], v[98:101]
	v_mfma_f32_16x16x32_bf16 v[106:109], v[22:25], v[126:129], v[2:5]
	v_mfma_f32_16x16x32_bf16 v[2:5], v[46:49], v[118:121], v[216:219]
	v_mfma_f32_16x16x32_bf16 v[114:117], v[78:81], v[126:129], v[2:5]
	s_setprio 0
	s_barrier
	s_nop 4
	ds_read_b128 v[2:5], v138
	ds_read_b128 v[204:207], v138 offset:1024
	ds_read_b128 v[208:211], v138 offset:2048
	ds_read_b128 v[212:215], v138 offset:3072
	s_waitcnt vmcnt(0)
	s_barrier
	s_waitcnt lgkmcnt(0)
	s_setprio 1
	s_waitcnt lgkmcnt(0)
	v_mfma_f32_16x16x32_bf16 v[26:29], v[2:5], v[30:33], v[140:143]
	v_mfma_f32_16x16x32_bf16 v[30:33], v[208:211], v[30:33], v[158:161]
	v_mfma_f32_16x16x32_bf16 v[34:37], v[212:215], v[54:57], v[30:33]
	v_mfma_f32_16x16x32_bf16 v[30:33], v[2:5], v[62:65], v[162:165]
	v_mfma_f32_16x16x32_bf16 v[58:61], v[204:207], v[86:89], v[30:33]
	v_mfma_f32_16x16x32_bf16 v[30:33], v[208:211], v[62:65], v[166:169]
	v_mfma_f32_16x16x32_bf16 v[66:69], v[212:215], v[86:89], v[30:33]
	v_mfma_f32_16x16x32_bf16 v[30:33], v[2:5], v[94:97], v[170:173]
	v_mfma_f32_16x16x32_bf16 v[90:93], v[204:207], v[110:113], v[30:33]
	v_mfma_f32_16x16x32_bf16 v[30:33], v[208:211], v[94:97], v[174:177]
	v_mfma_f32_16x16x32_bf16 v[98:101], v[212:215], v[110:113], v[30:33]
	v_mfma_f32_16x16x32_bf16 v[30:33], v[2:5], v[118:121], v[184:187]
	v_mfma_f32_16x16x32_bf16 v[122:125], v[204:207], v[126:129], v[30:33]
	v_mfma_f32_16x16x32_bf16 v[30:33], v[208:211], v[118:121], v[188:191]
	v_mfma_f32_16x16x32_bf16 v[26:29], v[204:207], v[54:57], v[26:29]
	v_mfma_f32_16x16x32_bf16 v[130:133], v[212:215], v[126:129], v[30:33]
	s_setprio 0
	s_barrier
	ds_read_b128 v[138:141], v137 offset:49152
	ds_read_b128 v[158:161], v137 offset:50176
	ds_read_b128 v[162:165], v136 offset:49152
	ds_read_b128 v[166:169], v136 offset:50176
	ds_read_b128 v[170:173], v135 offset:49152
	ds_read_b128 v[174:177], v135 offset:50176
	ds_read_b128 v[184:187], v134 offset:49152
	ds_read_b128 v[134:137], v134 offset:50176
	s_barrier
	s_waitcnt lgkmcnt(0)
	s_setprio 1
	s_waitcnt lgkmcnt(0)
	v_mfma_f32_16x16x32_bf16 v[30:33], v[14:17], v[138:141], v[200:203]
	v_mfma_f32_16x16x32_bf16 v[126:129], v[22:25], v[158:161], v[30:33]
	v_mfma_f32_16x16x32_bf16 v[30:33], v[46:49], v[138:141], v[220:223]
	v_mfma_f32_16x16x32_bf16 v[118:121], v[78:81], v[158:161], v[30:33]
	v_mfma_f32_16x16x32_bf16 v[30:33], v[14:17], v[162:165], v[102:105]
	v_mfma_f32_16x16x32_bf16 v[94:97], v[22:25], v[166:169], v[30:33]
	v_mfma_f32_16x16x32_bf16 v[30:33], v[46:49], v[162:165], v[224:227]
	v_mfma_f32_16x16x32_bf16 v[86:89], v[78:81], v[166:169], v[30:33]
	v_mfma_f32_16x16x32_bf16 v[30:33], v[14:17], v[170:173], v[70:73]
	v_mfma_f32_16x16x32_bf16 v[62:65], v[22:25], v[174:177], v[30:33]
	v_mfma_f32_16x16x32_bf16 v[30:33], v[46:49], v[170:173], v[228:231]
	v_mfma_f32_16x16x32_bf16 v[6:9], v[14:17], v[184:187], v[6:9]
	v_mfma_f32_16x16x32_bf16 v[54:57], v[78:81], v[174:177], v[30:33]
	v_mfma_f32_16x16x32_bf16 v[30:33], v[22:25], v[134:137], v[6:9]
	v_mfma_f32_16x16x32_bf16 v[6:9], v[46:49], v[184:187], v[38:41]
	v_mfma_f32_16x16x32_bf16 v[22:25], v[78:81], v[134:137], v[6:9]
	s_setprio 0
	s_setprio 1
	v_mfma_f32_16x16x32_bf16 v[6:9], v[2:5], v[138:141], v[146:149]
	v_mfma_f32_16x16x32_bf16 v[110:113], v[204:207], v[158:161], v[6:9]
	v_mfma_f32_16x16x32_bf16 v[6:9], v[208:211], v[138:141], v[150:153]
	v_mfma_f32_16x16x32_bf16 v[102:105], v[212:215], v[158:161], v[6:9]
	v_mfma_f32_16x16x32_bf16 v[6:9], v[2:5], v[162:165], v[154:157]
	v_mfma_f32_16x16x32_bf16 v[78:81], v[204:207], v[166:169], v[6:9]
	v_mfma_f32_16x16x32_bf16 v[6:9], v[208:211], v[162:165], v[232:235]
	v_mfma_f32_16x16x32_bf16 v[70:73], v[212:215], v[166:169], v[6:9]
	v_mfma_f32_16x16x32_bf16 v[6:9], v[2:5], v[170:173], v[236:239]
	v_mfma_f32_16x16x32_bf16 v[2:5], v[2:5], v[184:187], v[244:247]
	v_mfma_f32_16x16x32_bf16 v[46:49], v[204:207], v[174:177], v[6:9]
	v_mfma_f32_16x16x32_bf16 v[6:9], v[208:211], v[170:173], v[240:243]
	v_mfma_f32_16x16x32_bf16 v[14:17], v[204:207], v[134:137], v[2:5]
	v_mfma_f32_16x16x32_bf16 v[2:5], v[208:211], v[184:187], v[248:251]
	v_mfma_f32_16x16x32_bf16 v[38:41], v[212:215], v[174:177], v[6:9]
	v_mfma_f32_16x16x32_bf16 v[6:9], v[212:215], v[134:137], v[2:5]
	s_setprio 0
	v_cmp_gt_u32_e32 vcc, s85, v1
	s_barrier
	s_and_saveexec_b64 s[12:13], vcc
	s_cbranch_execz .LBB0_558
	s_barrier

; __device__ __forceinline__ unsigned cvt_pk(float lo, float hi) { f32x2_t v = {lo, hi}; bf16x2_t b = __builtin_convertvector(v, bf16x2_t); return __builtin_bit_cast(unsigned, b); }
; __device__ __forceinline__ float lo_bf(unsigned u) { return __uint_as_float(u << 16); }
; __device__ __forceinline__ float hi_bf(unsigned u) { return __uint_as_float(u & 0xffff0000u); }
; __device__ __forceinline__ void phase_merge(const Ctx& a, LAS unsigned char* lds) {
;     ...
;                             int col = pn * 256 + bj * 128 + t.wc * 32 + n * 16 + t.fq * 4;
;                             const bf16_t* gp = g + (size_t)row * NG + col;
;                             u32x2 gc = *(const u32x2*)(gp + seg * DM);
;                             float c0 = lo_bf(gc[0]), c1 = hi_bf(gc[0]), c2 = lo_bf(gc[1]), c3 = hi_bf(gc[1]);
;                             if (seg < 2) {
;                                 u32x2 gn = *(const u32x2*)(gp + (seg + 1) * DM);
;                                 c0 = c0 / fmaxf(lo_bf(gn[0]), 1e-30f); c1 = c1 / fmaxf(hi_bf(gn[0]), 1e-30f);
;                                 c2 = c2 / fmaxf(lo_bf(gn[1]), 1e-30f); c3 = c3 / fmaxf(hi_bf(gn[1]), 1e-30f);
;                                 acc[ai][bj][m][n][0] *= c0; acc[ai][bj][m][n][1] *= c1; acc[ai][bj][m][n][2] *= c2; acc[ai][bj][m][n][3] *= c3;
;                             } else {
;                                 u32x2 o; o[0] = cvt_pk(acc[ai][bj][m][n][0] * c0, acc[ai][bj][m][n][1] * c1); o[1] = cvt_pk(acc[ai][bj][m][n][2] * c2, acc[ai][bj][m][n][3] * c3);
;                                 *(u32x2*)(mg + (size_t)row * DM + col) = o;
.LBB0_560:
	v_ashrrev_i32_e32 v137, 31, v136
	v_lshlrev_b64 v[140:141], 11, v[136:137]
	v_lshl_add_u64 v[140:141], s[72:73], 0, v[140:141]
	s_andn2_b64 vcc, exec, s[36:37]
	v_lshl_add_u64 v[140:141], v[134:135], 1, v[140:141]
	s_cbranch_vccnz .LBB0_562
	v_pk_mul_f32 v[2:3], v[10:11], v[146:147]
	v_pk_mul_f32 v[4:5], v[12:13], v[142:143]
	v_cvt_pk_bf16_f32 v2, v2, v3
	v_cvt_pk_bf16_f32 v3, v4, v5
	v_add_u32_e32 v140, 1536, v140
	v_xor_b32_e32 v140, v196, v140
	global_store_dwordx2 v[140:141], v[2:3], off
	v_xor_b32_e32 v140, v196, v140
	v_subrev_u32_e32 v140, 1536, v140
	v_mov_b64_e32 v[2:3], v[10:11]
	v_mov_b64_e32 v[4:5], v[12:13]

; __device__ __forceinline__ unsigned cvt_pk(float lo, float hi) { f32x2_t v = {lo, hi}; bf16x2_t b = __builtin_convertvector(v, bf16x2_t); return __builtin_bit_cast(unsigned, b); }
; __device__ __forceinline__ float lo_bf(unsigned u) { return __uint_as_float(u << 16); }
; __device__ __forceinline__ float hi_bf(unsigned u) { return __uint_as_float(u & 0xffff0000u); }
; __device__ __forceinline__ void phase_merge(const Ctx& a, LAS unsigned char* lds) {
;     ...
;                             int col = pn * 256 + bj * 128 + t.wc * 32 + n * 16 + t.fq * 4;
;                             const bf16_t* gp = g + (size_t)row * NG + col;
;                             u32x2 gc = *(const u32x2*)(gp + seg * DM);
;                             float c0 = lo_bf(gc[0]), c1 = hi_bf(gc[0]), c2 = lo_bf(gc[1]), c3 = hi_bf(gc[1]);
;                             if (seg < 2) {
;                                 u32x2 gn = *(const u32x2*)(gp + (seg + 1) * DM);
;                                 c0 = c0 / fmaxf(lo_bf(gn[0]), 1e-30f); c1 = c1 / fmaxf(hi_bf(gn[0]), 1e-30f);
;                                 c2 = c2 / fmaxf(lo_bf(gn[1]), 1e-30f); c3 = c3 / fmaxf(hi_bf(gn[1]), 1e-30f);
;                                 acc[ai][bj][m][n][0] *= c0; acc[ai][bj][m][n][1] *= c1; acc[ai][bj][m][n][2] *= c2; acc[ai][bj][m][n][3] *= c3;
;                             } else {
;                                 u32x2 o; o[0] = cvt_pk(acc[ai][bj][m][n][0] * c0, acc[ai][bj][m][n][1] * c1); o[1] = cvt_pk(acc[ai][bj][m][n][2] * c2, acc[ai][bj][m][n][3] * c3);
;                                 *(u32x2*)(mg + (size_t)row * DM + col) = o;
.LBB0_564:
	s_andn2_b64 vcc, exec, s[12:13]
	s_cbranch_vccnz .LBB0_566
	v_pk_mul_f32 v[10:11], v[18:19], v[146:147]
	v_pk_mul_f32 v[12:13], v[20:21], v[142:143]
	v_cvt_pk_bf16_f32 v10, v10, v11
	v_cvt_pk_bf16_f32 v11, v12, v13
	v_add_u32_e32 v140, 1568, v140
	v_xor_b32_e32 v140, v196, v140
	global_store_dwordx2 v[140:141], v[10:11], off
	v_xor_b32_e32 v140, v196, v140
	v_subrev_u32_e32 v140, 1568, v140
	v_mov_b64_e32 v[10:11], v[18:19]
	v_mov_b64_e32 v[12:13], v[20:21]

; __device__ __forceinline__ unsigned cvt_pk(float lo, float hi) { f32x2_t v = {lo, hi}; bf16x2_t b = __builtin_convertvector(v, bf16x2_t); return __builtin_bit_cast(unsigned, b); }
; __device__ __forceinline__ float lo_bf(unsigned u) { return __uint_as_float(u << 16); }
; __device__ __forceinline__ float hi_bf(unsigned u) { return __uint_as_float(u & 0xffff0000u); }
; __device__ __forceinline__ void phase_merge(const Ctx& a, LAS unsigned char* lds) {
;     ...
;                             int col = pn * 256 + bj * 128 + t.wc * 32 + n * 16 + t.fq * 4;
;                             const bf16_t* gp = g + (size_t)row * NG + col;
;                             u32x2 gc = *(const u32x2*)(gp + seg * DM);
;                             float c0 = lo_bf(gc[0]), c1 = hi_bf(gc[0]), c2 = lo_bf(gc[1]), c3 = hi_bf(gc[1]);
;                             if (seg < 2) {
;                                 u32x2 gn = *(const u32x2*)(gp + (seg + 1) * DM);
;                                 c0 = c0 / fmaxf(lo_bf(gn[0]), 1e-30f); c1 = c1 / fmaxf(hi_bf(gn[0]), 1e-30f);
;                                 c2 = c2 / fmaxf(lo_bf(gn[1]), 1e-30f); c3 = c3 / fmaxf(hi_bf(gn[1]), 1e-30f);
;                                 acc[ai][bj][m][n][0] *= c0; acc[ai][bj][m][n][1] *= c1; acc[ai][bj][m][n][2] *= c2; acc[ai][bj][m][n][3] *= c3;
;                             } else {
;                                 u32x2 o; o[0] = cvt_pk(acc[ai][bj][m][n][0] * c0, acc[ai][bj][m][n][1] * c1); o[1] = cvt_pk(acc[ai][bj][m][n][2] * c2, acc[ai][bj][m][n][3] * c3);
;                                 *(u32x2*)(mg + (size_t)row * DM + col) = o;
.LBB0_568:
	s_andn2_b64 vcc, exec, s[12:13]
	s_cbranch_vccnz .LBB0_570
	v_pk_mul_f32 v[18:19], v[26:27], v[146:147]
	v_pk_mul_f32 v[20:21], v[28:29], v[142:143]
	v_cvt_pk_bf16_f32 v18, v18, v19
	v_cvt_pk_bf16_f32 v19, v20, v21
	v_add_u32_e32 v140, 1792, v140
	v_xor_b32_e32 v140, v196, v140
	global_store_dwordx2 v[140:141], v[18:19], off
	v_xor_b32_e32 v140, v196, v140
	v_subrev_u32_e32 v140, 1792, v140
	v_mov_b64_e32 v[18:19], v[26:27]
	v_mov_b64_e32 v[20:21], v[28:29]

; __device__ __forceinline__ unsigned cvt_pk(float lo, float hi) { f32x2_t v = {lo, hi}; bf16x2_t b = __builtin_convertvector(v, bf16x2_t); return __builtin_bit_cast(unsigned, b); }
; __device__ __forceinline__ float lo_bf(unsigned u) { return __uint_as_float(u << 16); }
; __device__ __forceinline__ float hi_bf(unsigned u) { return __uint_as_float(u & 0xffff0000u); }
; __device__ __forceinline__ void phase_merge(const Ctx& a, LAS unsigned char* lds) {
;     ...
;                             int col = pn * 256 + bj * 128 + t.wc * 32 + n * 16 + t.fq * 4;
;                             const bf16_t* gp = g + (size_t)row * NG + col;
;                             u32x2 gc = *(const u32x2*)(gp + seg * DM);
;                             float c0 = lo_bf(gc[0]), c1 = hi_bf(gc[0]), c2 = lo_bf(gc[1]), c3 = hi_bf(gc[1]);
;                             if (seg < 2) {
;                                 u32x2 gn = *(const u32x2*)(gp + (seg + 1) * DM);
;                                 c0 = c0 / fmaxf(lo_bf(gn[0]), 1e-30f); c1 = c1 / fmaxf(hi_bf(gn[0]), 1e-30f);
;                                 c2 = c2 / fmaxf(lo_bf(gn[1]), 1e-30f); c3 = c3 / fmaxf(hi_bf(gn[1]), 1e-30f);
;                                 acc[ai][bj][m][n][0] *= c0; acc[ai][bj][m][n][1] *= c1; acc[ai][bj][m][n][2] *= c2; acc[ai][bj][m][n][3] *= c3;
;                             } else {
;                                 u32x2 o; o[0] = cvt_pk(acc[ai][bj][m][n][0] * c0, acc[ai][bj][m][n][1] * c1); o[1] = cvt_pk(acc[ai][bj][m][n][2] * c2, acc[ai][bj][m][n][3] * c3);
;                                 *(u32x2*)(mg + (size_t)row * DM + col) = o;
.LBB0_572:
	s_andn2_b64 vcc, exec, s[12:13]
	s_cbranch_vccnz .LBB0_574
	v_pk_mul_f32 v[26:27], v[34:35], v[146:147]
	v_pk_mul_f32 v[28:29], v[36:37], v[142:143]
	v_cvt_pk_bf16_f32 v26, v26, v27
	v_cvt_pk_bf16_f32 v27, v28, v29
	v_add_u32_e32 v140, 1824, v140
	v_xor_b32_e32 v140, v196, v140
	global_store_dwordx2 v[140:141], v[26:27], off
	v_xor_b32_e32 v140, v196, v140
	v_subrev_u32_e32 v140, 1824, v140
	v_mov_b64_e32 v[26:27], v[34:35]
	v_mov_b64_e32 v[28:29], v[36:37]

; __device__ __forceinline__ unsigned cvt_pk(float lo, float hi) { f32x2_t v = {lo, hi}; bf16x2_t b = __builtin_convertvector(v, bf16x2_t); return __builtin_bit_cast(unsigned, b); }
; __device__ __forceinline__ float lo_bf(unsigned u) { return __uint_as_float(u << 16); }
; __device__ __forceinline__ float hi_bf(unsigned u) { return __uint_as_float(u & 0xffff0000u); }
; __device__ __forceinline__ void phase_merge(const Ctx& a, LAS unsigned char* lds) {
;     ...
;                             int col = pn * 256 + bj * 128 + t.wc * 32 + n * 16 + t.fq * 4;
;                             const bf16_t* gp = g + (size_t)row * NG + col;
;                             u32x2 gc = *(const u32x2*)(gp + seg * DM);
;                             float c0 = lo_bf(gc[0]), c1 = hi_bf(gc[0]), c2 = lo_bf(gc[1]), c3 = hi_bf(gc[1]);
;                             if (seg < 2) {
;                                 u32x2 gn = *(const u32x2*)(gp + (seg + 1) * DM);
;                                 c0 = c0 / fmaxf(lo_bf(gn[0]), 1e-30f); c1 = c1 / fmaxf(hi_bf(gn[0]), 1e-30f);
;                                 c2 = c2 / fmaxf(lo_bf(gn[1]), 1e-30f); c3 = c3 / fmaxf(hi_bf(gn[1]), 1e-30f);
;                                 acc[ai][bj][m][n][0] *= c0; acc[ai][bj][m][n][1] *= c1; acc[ai][bj][m][n][2] *= c2; acc[ai][bj][m][n][3] *= c3;
;                             } else {
;                                 u32x2 o; o[0] = cvt_pk(acc[ai][bj][m][n][0] * c0, acc[ai][bj][m][n][1] * c1); o[1] = cvt_pk(acc[ai][bj][m][n][2] * c2, acc[ai][bj][m][n][3] * c3);
;                                 *(u32x2*)(mg + (size_t)row * DM + col) = o;
.LBB0_576:
	v_ashrrev_i32_e32 v141, 31, v140
	v_lshlrev_b64 v[140:141], 11, v[140:141]
	v_lshl_add_u64 v[140:141], s[72:73], 0, v[140:141]
	s_andn2_b64 vcc, exec, s[12:13]
	v_lshl_add_u64 v[140:141], v[134:135], 1, v[140:141]
	s_cbranch_vccnz .LBB0_578
	v_pk_mul_f32 v[34:35], v[42:43], v[146:147]
	v_pk_mul_f32 v[36:37], v[44:45], v[142:143]
	v_cvt_pk_bf16_f32 v34, v34, v35
	v_cvt_pk_bf16_f32 v35, v36, v37
	v_add_u32_e32 v140, 1536, v140
	v_xor_b32_e32 v140, v196, v140
	global_store_dwordx2 v[140:141], v[34:35], off
	v_xor_b32_e32 v140, v196, v140
	v_subrev_u32_e32 v140, 1536, v140
	v_mov_b64_e32 v[34:35], v[42:43]
	v_mov_b64_e32 v[36:37], v[44:45]

; __device__ __forceinline__ unsigned cvt_pk(float lo, float hi) { f32x2_t v = {lo, hi}; bf16x2_t b = __builtin_convertvector(v, bf16x2_t); return __builtin_bit_cast(unsigned, b); }
; __device__ __forceinline__ float lo_bf(unsigned u) { return __uint_as_float(u << 16); }
; __device__ __forceinline__ float hi_bf(unsigned u) { return __uint_as_float(u & 0xffff0000u); }
; __device__ __forceinline__ void phase_merge(const Ctx& a, LAS unsigned char* lds) {
;     ...
;                             int col = pn * 256 + bj * 128 + t.wc * 32 + n * 16 + t.fq * 4;
;                             const bf16_t* gp = g + (size_t)row * NG + col;
;                             u32x2 gc = *(const u32x2*)(gp + seg * DM);
;                             float c0 = lo_bf(gc[0]), c1 = hi_bf(gc[0]), c2 = lo_bf(gc[1]), c3 = hi_bf(gc[1]);
;                             if (seg < 2) {
;                                 u32x2 gn = *(const u32x2*)(gp + (seg + 1) * DM);
;                                 c0 = c0 / fmaxf(lo_bf(gn[0]), 1e-30f); c1 = c1 / fmaxf(hi_bf(gn[0]), 1e-30f);
;                                 c2 = c2 / fmaxf(lo_bf(gn[1]), 1e-30f); c3 = c3 / fmaxf(hi_bf(gn[1]), 1e-30f);
;                                 acc[ai][bj][m][n][0] *= c0; acc[ai][bj][m][n][1] *= c1; acc[ai][bj][m][n][2] *= c2; acc[ai][bj][m][n][3] *= c3;
;                             } else {
;                                 u32x2 o; o[0] = cvt_pk(acc[ai][bj][m][n][0] * c0, acc[ai][bj][m][n][1] * c1); o[1] = cvt_pk(acc[ai][bj][m][n][2] * c2, acc[ai][bj][m][n][3] * c3);
;                                 *(u32x2*)(mg + (size_t)row * DM + col) = o;
.LBB0_580:
	s_andn2_b64 vcc, exec, s[12:13]
	s_cbranch_vccnz .LBB0_582
	v_pk_mul_f32 v[42:43], v[50:51], v[146:147]
	v_pk_mul_f32 v[44:45], v[52:53], v[142:143]
	v_cvt_pk_bf16_f32 v42, v42, v43
	v_cvt_pk_bf16_f32 v43, v44, v45
	v_add_u32_e32 v140, 1568, v140
	v_xor_b32_e32 v140, v196, v140
	global_store_dwordx2 v[140:141], v[42:43], off
	v_xor_b32_e32 v140, v196, v140
	v_subrev_u32_e32 v140, 1568, v140
	v_mov_b64_e32 v[42:43], v[50:51]
	v_mov_b64_e32 v[44:45], v[52:53]

; __device__ __forceinline__ unsigned cvt_pk(float lo, float hi) { f32x2_t v = {lo, hi}; bf16x2_t b = __builtin_convertvector(v, bf16x2_t); return __builtin_bit_cast(unsigned, b); }
; __device__ __forceinline__ float lo_bf(unsigned u) { return __uint_as_float(u << 16); }
; __device__ __forceinline__ float hi_bf(unsigned u) { return __uint_as_float(u & 0xffff0000u); }
; __device__ __forceinline__ void phase_merge(const Ctx& a, LAS unsigned char* lds) {
;     ...
;                             int col = pn * 256 + bj * 128 + t.wc * 32 + n * 16 + t.fq * 4;
;                             const bf16_t* gp = g + (size_t)row * NG + col;
;                             u32x2 gc = *(const u32x2*)(gp + seg * DM);
;                             float c0 = lo_bf(gc[0]), c1 = hi_bf(gc[0]), c2 = lo_bf(gc[1]), c3 = hi_bf(gc[1]);
;                             if (seg < 2) {
;                                 u32x2 gn = *(const u32x2*)(gp + (seg + 1) * DM);
;                                 c0 = c0 / fmaxf(lo_bf(gn[0]), 1e-30f); c1 = c1 / fmaxf(hi_bf(gn[0]), 1e-30f);
;                                 c2 = c2 / fmaxf(lo_bf(gn[1]), 1e-30f); c3 = c3 / fmaxf(hi_bf(gn[1]), 1e-30f);
;                                 acc[ai][bj][m][n][0] *= c0; acc[ai][bj][m][n][1] *= c1; acc[ai][bj][m][n][2] *= c2; acc[ai][bj][m][n][3] *= c3;
;                             } else {
;                                 u32x2 o; o[0] = cvt_pk(acc[ai][bj][m][n][0] * c0, acc[ai][bj][m][n][1] * c1); o[1] = cvt_pk(acc[ai][bj][m][n][2] * c2, acc[ai][bj][m][n][3] * c3);
;                                 *(u32x2*)(mg + (size_t)row * DM + col) = o;
.LBB0_584:
	s_andn2_b64 vcc, exec, s[12:13]
	s_cbranch_vccnz .LBB0_586
	v_pk_mul_f32 v[50:51], v[58:59], v[146:147]
	v_pk_mul_f32 v[52:53], v[60:61], v[142:143]
	v_cvt_pk_bf16_f32 v50, v50, v51
	v_cvt_pk_bf16_f32 v51, v52, v53
	v_add_u32_e32 v140, 1792, v140
	v_xor_b32_e32 v140, v196, v140
	global_store_dwordx2 v[140:141], v[50:51], off
	v_xor_b32_e32 v140, v196, v140
	v_subrev_u32_e32 v140, 1792, v140
	v_mov_b64_e32 v[50:51], v[58:59]
	v_mov_b64_e32 v[52:53], v[60:61]

; __device__ __forceinline__ unsigned cvt_pk(float lo, float hi) { f32x2_t v = {lo, hi}; bf16x2_t b = __builtin_convertvector(v, bf16x2_t); return __builtin_bit_cast(unsigned, b); }
; __device__ __forceinline__ float lo_bf(unsigned u) { return __uint_as_float(u << 16); }
; __device__ __forceinline__ float hi_bf(unsigned u) { return __uint_as_float(u & 0xffff0000u); }
; __device__ __forceinline__ void phase_merge(const Ctx& a, LAS unsigned char* lds) {
;     ...
;                             int col = pn * 256 + bj * 128 + t.wc * 32 + n * 16 + t.fq * 4;
;                             const bf16_t* gp = g + (size_t)row * NG + col;
;                             u32x2 gc = *(const u32x2*)(gp + seg * DM);
;                             float c0 = lo_bf(gc[0]), c1 = hi_bf(gc[0]), c2 = lo_bf(gc[1]), c3 = hi_bf(gc[1]);
;                             if (seg < 2) {
;                                 u32x2 gn = *(const u32x2*)(gp + (seg + 1) * DM);
;                                 c0 = c0 / fmaxf(lo_bf(gn[0]), 1e-30f); c1 = c1 / fmaxf(hi_bf(gn[0]), 1e-30f);
;                                 c2 = c2 / fmaxf(lo_bf(gn[1]), 1e-30f); c3 = c3 / fmaxf(hi_bf(gn[1]), 1e-30f);
;                                 acc[ai][bj][m][n][0] *= c0; acc[ai][bj][m][n][1] *= c1; acc[ai][bj][m][n][2] *= c2; acc[ai][bj][m][n][3] *= c3;
;                             } else {
;                                 u32x2 o; o[0] = cvt_pk(acc[ai][bj][m][n][0] * c0, acc[ai][bj][m][n][1] * c1); o[1] = cvt_pk(acc[ai][bj][m][n][2] * c2, acc[ai][bj][m][n][3] * c3);
;                                 *(u32x2*)(mg + (size_t)row * DM + col) = o;
.LBB0_588:
	s_andn2_b64 vcc, exec, s[12:13]
	s_cbranch_vccnz .LBB0_590
	v_pk_mul_f32 v[58:59], v[66:67], v[146:147]
	v_pk_mul_f32 v[60:61], v[68:69], v[142:143]
	v_cvt_pk_bf16_f32 v58, v58, v59
	v_cvt_pk_bf16_f32 v59, v60, v61
	v_add_u32_e32 v140, 1824, v140
	v_xor_b32_e32 v140, v196, v140
	global_store_dwordx2 v[140:141], v[58:59], off
	v_xor_b32_e32 v140, v196, v140
	v_subrev_u32_e32 v140, 1824, v140
	v_mov_b64_e32 v[58:59], v[66:67]
	v_mov_b64_e32 v[60:61], v[68:69]

; __device__ __forceinline__ unsigned cvt_pk(float lo, float hi) { f32x2_t v = {lo, hi}; bf16x2_t b = __builtin_convertvector(v, bf16x2_t); return __builtin_bit_cast(unsigned, b); }
; __device__ __forceinline__ float lo_bf(unsigned u) { return __uint_as_float(u << 16); }
; __device__ __forceinline__ float hi_bf(unsigned u) { return __uint_as_float(u & 0xffff0000u); }
; __device__ __forceinline__ void phase_merge(const Ctx& a, LAS unsigned char* lds) {
;     ...
;                             int col = pn * 256 + bj * 128 + t.wc * 32 + n * 16 + t.fq * 4;
;                             const bf16_t* gp = g + (size_t)row * NG + col;
;                             u32x2 gc = *(const u32x2*)(gp + seg * DM);
;                             float c0 = lo_bf(gc[0]), c1 = hi_bf(gc[0]), c2 = lo_bf(gc[1]), c3 = hi_bf(gc[1]);
;                             if (seg < 2) {
;                                 u32x2 gn = *(const u32x2*)(gp + (seg + 1) * DM);
;                                 c0 = c0 / fmaxf(lo_bf(gn[0]), 1e-30f); c1 = c1 / fmaxf(hi_bf(gn[0]), 1e-30f);
;                                 c2 = c2 / fmaxf(lo_bf(gn[1]), 1e-30f); c3 = c3 / fmaxf(hi_bf(gn[1]), 1e-30f);
;                                 acc[ai][bj][m][n][0] *= c0; acc[ai][bj][m][n][1] *= c1; acc[ai][bj][m][n][2] *= c2; acc[ai][bj][m][n][3] *= c3;
;                             } else {
;                                 u32x2 o; o[0] = cvt_pk(acc[ai][bj][m][n][0] * c0, acc[ai][bj][m][n][1] * c1); o[1] = cvt_pk(acc[ai][bj][m][n][2] * c2, acc[ai][bj][m][n][3] * c3);
;                                 *(u32x2*)(mg + (size_t)row * DM + col) = o;
.LBB0_592:
	v_ashrrev_i32_e32 v141, 31, v140
	v_lshlrev_b64 v[140:141], 11, v[140:141]
	v_lshl_add_u64 v[140:141], s[72:73], 0, v[140:141]
	s_andn2_b64 vcc, exec, s[12:13]
	v_lshl_add_u64 v[140:141], v[134:135], 1, v[140:141]
	s_cbranch_vccnz .LBB0_594
	v_pk_mul_f32 v[66:67], v[74:75], v[146:147]
	v_pk_mul_f32 v[68:69], v[76:77], v[142:143]
	v_cvt_pk_bf16_f32 v66, v66, v67
	v_cvt_pk_bf16_f32 v67, v68, v69
	v_add_u32_e32 v140, 1536, v140
	v_xor_b32_e32 v140, v196, v140
	global_store_dwordx2 v[140:141], v[66:67], off
	v_xor_b32_e32 v140, v196, v140
	v_subrev_u32_e32 v140, 1536, v140
	v_mov_b64_e32 v[66:67], v[74:75]
	v_mov_b64_e32 v[68:69], v[76:77]

; __device__ __forceinline__ unsigned cvt_pk(float lo, float hi) { f32x2_t v = {lo, hi}; bf16x2_t b = __builtin_convertvector(v, bf16x2_t); return __builtin_bit_cast(unsigned, b); }
; __device__ __forceinline__ float lo_bf(unsigned u) { return __uint_as_float(u << 16); }
; __device__ __forceinline__ float hi_bf(unsigned u) { return __uint_as_float(u & 0xffff0000u); }
; __device__ __forceinline__ void phase_merge(const Ctx& a, LAS unsigned char* lds) {
;     ...
;                             int col = pn * 256 + bj * 128 + t.wc * 32 + n * 16 + t.fq * 4;
;                             const bf16_t* gp = g + (size_t)row * NG + col;
;                             u32x2 gc = *(const u32x2*)(gp + seg * DM);
;                             float c0 = lo_bf(gc[0]), c1 = hi_bf(gc[0]), c2 = lo_bf(gc[1]), c3 = hi_bf(gc[1]);
;                             if (seg < 2) {
;                                 u32x2 gn = *(const u32x2*)(gp + (seg + 1) * DM);
;                                 c0 = c0 / fmaxf(lo_bf(gn[0]), 1e-30f); c1 = c1 / fmaxf(hi_bf(gn[0]), 1e-30f);
;                                 c2 = c2 / fmaxf(lo_bf(gn[1]), 1e-30f); c3 = c3 / fmaxf(hi_bf(gn[1]), 1e-30f);
;                                 acc[ai][bj][m][n][0] *= c0; acc[ai][bj][m][n][1] *= c1; acc[ai][bj][m][n][2] *= c2; acc[ai][bj][m][n][3] *= c3;
;                             } else {
;                                 u32x2 o; o[0] = cvt_pk(acc[ai][bj][m][n][0] * c0, acc[ai][bj][m][n][1] * c1); o[1] = cvt_pk(acc[ai][bj][m][n][2] * c2, acc[ai][bj][m][n][3] * c3);
;                                 *(u32x2*)(mg + (size_t)row * DM + col) = o;
.LBB0_596:
	s_andn2_b64 vcc, exec, s[12:13]
	s_cbranch_vccnz .LBB0_598
	v_pk_mul_f32 v[74:75], v[82:83], v[146:147]
	v_pk_mul_f32 v[76:77], v[84:85], v[142:143]
	v_cvt_pk_bf16_f32 v74, v74, v75
	v_cvt_pk_bf16_f32 v75, v76, v77
	v_add_u32_e32 v140, 1568, v140
	v_xor_b32_e32 v140, v196, v140
	global_store_dwordx2 v[140:141], v[74:75], off
	v_xor_b32_e32 v140, v196, v140
	v_subrev_u32_e32 v140, 1568, v140
	v_mov_b64_e32 v[74:75], v[82:83]
	v_mov_b64_e32 v[76:77], v[84:85]

; __device__ __forceinline__ unsigned cvt_pk(float lo, float hi) { f32x2_t v = {lo, hi}; bf16x2_t b = __builtin_convertvector(v, bf16x2_t); return __builtin_bit_cast(unsigned, b); }
; __device__ __forceinline__ float lo_bf(unsigned u) { return __uint_as_float(u << 16); }
; __device__ __forceinline__ float hi_bf(unsigned u) { return __uint_as_float(u & 0xffff0000u); }
; __device__ __forceinline__ void phase_merge(const Ctx& a, LAS unsigned char* lds) {
;     ...
;                             int col = pn * 256 + bj * 128 + t.wc * 32 + n * 16 + t.fq * 4;
;                             const bf16_t* gp = g + (size_t)row * NG + col;
;                             u32x2 gc = *(const u32x2*)(gp + seg * DM);
;                             float c0 = lo_bf(gc[0]), c1 = hi_bf(gc[0]), c2 = lo_bf(gc[1]), c3 = hi_bf(gc[1]);
;                             if (seg < 2) {
;                                 u32x2 gn = *(const u32x2*)(gp + (seg + 1) * DM);
;                                 c0 = c0 / fmaxf(lo_bf(gn[0]), 1e-30f); c1 = c1 / fmaxf(hi_bf(gn[0]), 1e-30f);
;                                 c2 = c2 / fmaxf(lo_bf(gn[1]), 1e-30f); c3 = c3 / fmaxf(hi_bf(gn[1]), 1e-30f);
;                                 acc[ai][bj][m][n][0] *= c0; acc[ai][bj][m][n][1] *= c1; acc[ai][bj][m][n][2] *= c2; acc[ai][bj][m][n][3] *= c3;
;                             } else {
;                                 u32x2 o; o[0] = cvt_pk(acc[ai][bj][m][n][0] * c0, acc[ai][bj][m][n][1] * c1); o[1] = cvt_pk(acc[ai][bj][m][n][2] * c2, acc[ai][bj][m][n][3] * c3);
;                                 *(u32x2*)(mg + (size_t)row * DM + col) = o;
.LBB0_600:
	s_andn2_b64 vcc, exec, s[12:13]
	s_cbranch_vccnz .LBB0_602
	v_pk_mul_f32 v[82:83], v[90:91], v[146:147]
	v_pk_mul_f32 v[84:85], v[92:93], v[142:143]
	v_cvt_pk_bf16_f32 v82, v82, v83
	v_cvt_pk_bf16_f32 v83, v84, v85
	v_add_u32_e32 v140, 1792, v140
	v_xor_b32_e32 v140, v196, v140
	global_store_dwordx2 v[140:141], v[82:83], off
	v_xor_b32_e32 v140, v196, v140
	v_subrev_u32_e32 v140, 1792, v140
	v_mov_b64_e32 v[82:83], v[90:91]
	v_mov_b64_e32 v[84:85], v[92:93]

; __device__ __forceinline__ unsigned cvt_pk(float lo, float hi) { f32x2_t v = {lo, hi}; bf16x2_t b = __builtin_convertvector(v, bf16x2_t); return __builtin_bit_cast(unsigned, b); }
; __device__ __forceinline__ float lo_bf(unsigned u) { return __uint_as_float(u << 16); }
; __device__ __forceinline__ float hi_bf(unsigned u) { return __uint_as_float(u & 0xffff0000u); }
; __device__ __forceinline__ void phase_merge(const Ctx& a, LAS unsigned char* lds) {
;     ...
;                             int col = pn * 256 + bj * 128 + t.wc * 32 + n * 16 + t.fq * 4;
;                             const bf16_t* gp = g + (size_t)row * NG + col;
;                             u32x2 gc = *(const u32x2*)(gp + seg * DM);
;                             float c0 = lo_bf(gc[0]), c1 = hi_bf(gc[0]), c2 = lo_bf(gc[1]), c3 = hi_bf(gc[1]);
;                             if (seg < 2) {
;                                 u32x2 gn = *(const u32x2*)(gp + (seg + 1) * DM);
;                                 c0 = c0 / fmaxf(lo_bf(gn[0]), 1e-30f); c1 = c1 / fmaxf(hi_bf(gn[0]), 1e-30f);
;                                 c2 = c2 / fmaxf(lo_bf(gn[1]), 1e-30f); c3 = c3 / fmaxf(hi_bf(gn[1]), 1e-30f);
;                                 acc[ai][bj][m][n][0] *= c0; acc[ai][bj][m][n][1] *= c1; acc[ai][bj][m][n][2] *= c2; acc[ai][bj][m][n][3] *= c3;
;                             } else {
;                                 u32x2 o; o[0] = cvt_pk(acc[ai][bj][m][n][0] * c0, acc[ai][bj][m][n][1] * c1); o[1] = cvt_pk(acc[ai][bj][m][n][2] * c2, acc[ai][bj][m][n][3] * c3);
;                                 *(u32x2*)(mg + (size_t)row * DM + col) = o;
.LBB0_604:
	s_andn2_b64 vcc, exec, s[12:13]
	s_cbranch_vccnz .LBB0_606
	v_pk_mul_f32 v[90:91], v[98:99], v[146:147]
	v_pk_mul_f32 v[92:93], v[100:101], v[142:143]
	v_cvt_pk_bf16_f32 v90, v90, v91
	v_cvt_pk_bf16_f32 v91, v92, v93
	v_add_u32_e32 v140, 1824, v140
	v_xor_b32_e32 v140, v196, v140
	global_store_dwordx2 v[140:141], v[90:91], off
	v_xor_b32_e32 v140, v196, v140
	v_subrev_u32_e32 v140, 1824, v140
	v_mov_b64_e32 v[90:91], v[98:99]
	v_mov_b64_e32 v[92:93], v[100:101]

; __device__ __forceinline__ unsigned cvt_pk(float lo, float hi) { f32x2_t v = {lo, hi}; bf16x2_t b = __builtin_convertvector(v, bf16x2_t); return __builtin_bit_cast(unsigned, b); }
; __device__ __forceinline__ float lo_bf(unsigned u) { return __uint_as_float(u << 16); }
; __device__ __forceinline__ float hi_bf(unsigned u) { return __uint_as_float(u & 0xffff0000u); }
; __device__ __forceinline__ void phase_merge(const Ctx& a, LAS unsigned char* lds) {
;     ...
;                             int col = pn * 256 + bj * 128 + t.wc * 32 + n * 16 + t.fq * 4;
;                             const bf16_t* gp = g + (size_t)row * NG + col;
;                             u32x2 gc = *(const u32x2*)(gp + seg * DM);
;                             float c0 = lo_bf(gc[0]), c1 = hi_bf(gc[0]), c2 = lo_bf(gc[1]), c3 = hi_bf(gc[1]);
;                             if (seg < 2) {
;                                 u32x2 gn = *(const u32x2*)(gp + (seg + 1) * DM);
;                                 c0 = c0 / fmaxf(lo_bf(gn[0]), 1e-30f); c1 = c1 / fmaxf(hi_bf(gn[0]), 1e-30f);
;                                 c2 = c2 / fmaxf(lo_bf(gn[1]), 1e-30f); c3 = c3 / fmaxf(hi_bf(gn[1]), 1e-30f);
;                                 acc[ai][bj][m][n][0] *= c0; acc[ai][bj][m][n][1] *= c1; acc[ai][bj][m][n][2] *= c2; acc[ai][bj][m][n][3] *= c3;
;                             } else {
;                                 u32x2 o; o[0] = cvt_pk(acc[ai][bj][m][n][0] * c0, acc[ai][bj][m][n][1] * c1); o[1] = cvt_pk(acc[ai][bj][m][n][2] * c2, acc[ai][bj][m][n][3] * c3);
;                                 *(u32x2*)(mg + (size_t)row * DM + col) = o;
.LBB0_608:
	v_ashrrev_i32_e32 v141, 31, v140
	v_lshlrev_b64 v[140:141], 11, v[140:141]
	v_lshl_add_u64 v[140:141], s[72:73], 0, v[140:141]
	s_andn2_b64 vcc, exec, s[12:13]
	v_lshl_add_u64 v[140:141], v[134:135], 1, v[140:141]
	s_cbranch_vccnz .LBB0_610
	v_pk_mul_f32 v[98:99], v[106:107], v[146:147]
	v_pk_mul_f32 v[100:101], v[108:109], v[142:143]
	v_cvt_pk_bf16_f32 v98, v98, v99
	v_cvt_pk_bf16_f32 v99, v100, v101
	v_add_u32_e32 v140, 1536, v140
	v_xor_b32_e32 v140, v196, v140
	global_store_dwordx2 v[140:141], v[98:99], off
	v_xor_b32_e32 v140, v196, v140
	v_subrev_u32_e32 v140, 1536, v140
	v_mov_b64_e32 v[98:99], v[106:107]
	v_mov_b64_e32 v[100:101], v[108:109]

; __device__ __forceinline__ unsigned cvt_pk(float lo, float hi) { f32x2_t v = {lo, hi}; bf16x2_t b = __builtin_convertvector(v, bf16x2_t); return __builtin_bit_cast(unsigned, b); }
; __device__ __forceinline__ float lo_bf(unsigned u) { return __uint_as_float(u << 16); }
; __device__ __forceinline__ float hi_bf(unsigned u) { return __uint_as_float(u & 0xffff0000u); }
; __device__ __forceinline__ void phase_merge(const Ctx& a, LAS unsigned char* lds) {
;     ...
;                             int col = pn * 256 + bj * 128 + t.wc * 32 + n * 16 + t.fq * 4;
;                             const bf16_t* gp = g + (size_t)row * NG + col;
;                             u32x2 gc = *(const u32x2*)(gp + seg * DM);
;                             float c0 = lo_bf(gc[0]), c1 = hi_bf(gc[0]), c2 = lo_bf(gc[1]), c3 = hi_bf(gc[1]);
;                             if (seg < 2) {
;                                 u32x2 gn = *(const u32x2*)(gp + (seg + 1) * DM);
;                                 c0 = c0 / fmaxf(lo_bf(gn[0]), 1e-30f); c1 = c1 / fmaxf(hi_bf(gn[0]), 1e-30f);
;                                 c2 = c2 / fmaxf(lo_bf(gn[1]), 1e-30f); c3 = c3 / fmaxf(hi_bf(gn[1]), 1e-30f);
;                                 acc[ai][bj][m][n][0] *= c0; acc[ai][bj][m][n][1] *= c1; acc[ai][bj][m][n][2] *= c2; acc[ai][bj][m][n][3] *= c3;
;                             } else {
;                                 u32x2 o; o[0] = cvt_pk(acc[ai][bj][m][n][0] * c0, acc[ai][bj][m][n][1] * c1); o[1] = cvt_pk(acc[ai][bj][m][n][2] * c2, acc[ai][bj][m][n][3] * c3);
;                                 *(u32x2*)(mg + (size_t)row * DM + col) = o;
.LBB0_612:
	s_andn2_b64 vcc, exec, s[12:13]
	s_cbranch_vccnz .LBB0_614
	v_pk_mul_f32 v[106:107], v[114:115], v[146:147]
	v_pk_mul_f32 v[108:109], v[116:117], v[142:143]
	v_cvt_pk_bf16_f32 v106, v106, v107
	v_cvt_pk_bf16_f32 v107, v108, v109
	v_add_u32_e32 v140, 1568, v140
	v_xor_b32_e32 v140, v196, v140
	global_store_dwordx2 v[140:141], v[106:107], off
	v_xor_b32_e32 v140, v196, v140
	v_subrev_u32_e32 v140, 1568, v140
	v_mov_b64_e32 v[106:107], v[114:115]
	v_mov_b64_e32 v[108:109], v[116:117]

; __device__ __forceinline__ unsigned cvt_pk(float lo, float hi) { f32x2_t v = {lo, hi}; bf16x2_t b = __builtin_convertvector(v, bf16x2_t); return __builtin_bit_cast(unsigned, b); }
; __device__ __forceinline__ float lo_bf(unsigned u) { return __uint_as_float(u << 16); }
; __device__ __forceinline__ float hi_bf(unsigned u) { return __uint_as_float(u & 0xffff0000u); }
; __device__ __forceinline__ void phase_merge(const Ctx& a, LAS unsigned char* lds) {
;     ...
;                             int col = pn * 256 + bj * 128 + t.wc * 32 + n * 16 + t.fq * 4;
;                             const bf16_t* gp = g + (size_t)row * NG + col;
;                             u32x2 gc = *(const u32x2*)(gp + seg * DM);
;                             float c0 = lo_bf(gc[0]), c1 = hi_bf(gc[0]), c2 = lo_bf(gc[1]), c3 = hi_bf(gc[1]);
;                             if (seg < 2) {
;                                 u32x2 gn = *(const u32x2*)(gp + (seg + 1) * DM);
;                                 c0 = c0 / fmaxf(lo_bf(gn[0]), 1e-30f); c1 = c1 / fmaxf(hi_bf(gn[0]), 1e-30f);
;                                 c2 = c2 / fmaxf(lo_bf(gn[1]), 1e-30f); c3 = c3 / fmaxf(hi_bf(gn[1]), 1e-30f);
;                                 acc[ai][bj][m][n][0] *= c0; acc[ai][bj][m][n][1] *= c1; acc[ai][bj][m][n][2] *= c2; acc[ai][bj][m][n][3] *= c3;
;                             } else {
;                                 u32x2 o; o[0] = cvt_pk(acc[ai][bj][m][n][0] * c0, acc[ai][bj][m][n][1] * c1); o[1] = cvt_pk(acc[ai][bj][m][n][2] * c2, acc[ai][bj][m][n][3] * c3);
;                                 *(u32x2*)(mg + (size_t)row * DM + col) = o;
.LBB0_616:
	s_andn2_b64 vcc, exec, s[12:13]
	s_cbranch_vccnz .LBB0_618
	v_pk_mul_f32 v[114:115], v[122:123], v[146:147]
	v_pk_mul_f32 v[116:117], v[124:125], v[142:143]
	v_cvt_pk_bf16_f32 v114, v114, v115
	v_cvt_pk_bf16_f32 v115, v116, v117
	v_add_u32_e32 v140, 1792, v140
	v_xor_b32_e32 v140, v196, v140
	global_store_dwordx2 v[140:141], v[114:115], off
	v_xor_b32_e32 v140, v196, v140
	v_subrev_u32_e32 v140, 1792, v140
	v_mov_b64_e32 v[114:115], v[122:123]
	v_mov_b64_e32 v[116:117], v[124:125]

; __device__ __forceinline__ unsigned cvt_pk(float lo, float hi) { f32x2_t v = {lo, hi}; bf16x2_t b = __builtin_convertvector(v, bf16x2_t); return __builtin_bit_cast(unsigned, b); }
; __device__ __forceinline__ float lo_bf(unsigned u) { return __uint_as_float(u << 16); }
; __device__ __forceinline__ float hi_bf(unsigned u) { return __uint_as_float(u & 0xffff0000u); }
; __device__ __forceinline__ void phase_merge(const Ctx& a, LAS unsigned char* lds) {
;     ...
;                             int col = pn * 256 + bj * 128 + t.wc * 32 + n * 16 + t.fq * 4;
;                             const bf16_t* gp = g + (size_t)row * NG + col;
;                             u32x2 gc = *(const u32x2*)(gp + seg * DM);
;                             float c0 = lo_bf(gc[0]), c1 = hi_bf(gc[0]), c2 = lo_bf(gc[1]), c3 = hi_bf(gc[1]);
;                             if (seg < 2) {
;                                 u32x2 gn = *(const u32x2*)(gp + (seg + 1) * DM);
;                                 c0 = c0 / fmaxf(lo_bf(gn[0]), 1e-30f); c1 = c1 / fmaxf(hi_bf(gn[0]), 1e-30f);
;                                 c2 = c2 / fmaxf(lo_bf(gn[1]), 1e-30f); c3 = c3 / fmaxf(hi_bf(gn[1]), 1e-30f);
;                                 acc[ai][bj][m][n][0] *= c0; acc[ai][bj][m][n][1] *= c1; acc[ai][bj][m][n][2] *= c2; acc[ai][bj][m][n][3] *= c3;
;                             } else {
;                                 u32x2 o; o[0] = cvt_pk(acc[ai][bj][m][n][0] * c0, acc[ai][bj][m][n][1] * c1); o[1] = cvt_pk(acc[ai][bj][m][n][2] * c2, acc[ai][bj][m][n][3] * c3);
;                                 *(u32x2*)(mg + (size_t)row * DM + col) = o;
.LBB0_620:
	s_andn2_b64 vcc, exec, s[12:13]
	s_cbranch_vccnz .LBB0_622
	v_pk_mul_f32 v[122:123], v[130:131], v[146:147]
	v_pk_mul_f32 v[124:125], v[132:133], v[142:143]
	v_cvt_pk_bf16_f32 v122, v122, v123
	v_cvt_pk_bf16_f32 v123, v124, v125
	v_add_u32_e32 v140, 1824, v140
	v_xor_b32_e32 v140, v196, v140
	global_store_dwordx2 v[140:141], v[122:123], off
	v_xor_b32_e32 v140, v196, v140
	v_subrev_u32_e32 v140, 1824, v140
	v_mov_b64_e32 v[122:123], v[130:131]
	v_mov_b64_e32 v[124:125], v[132:133]

; __device__ __forceinline__ unsigned cvt_pk(float lo, float hi) { f32x2_t v = {lo, hi}; bf16x2_t b = __builtin_convertvector(v, bf16x2_t); return __builtin_bit_cast(unsigned, b); }
; __device__ __forceinline__ float lo_bf(unsigned u) { return __uint_as_float(u << 16); }
; __device__ __forceinline__ float hi_bf(unsigned u) { return __uint_as_float(u & 0xffff0000u); }
; __device__ __forceinline__ void phase_merge(const Ctx& a, LAS unsigned char* lds) {
;     ...
;                             int col = pn * 256 + bj * 128 + t.wc * 32 + n * 16 + t.fq * 4;
;                             const bf16_t* gp = g + (size_t)row * NG + col;
;                             u32x2 gc = *(const u32x2*)(gp + seg * DM);
;                             float c0 = lo_bf(gc[0]), c1 = hi_bf(gc[0]), c2 = lo_bf(gc[1]), c3 = hi_bf(gc[1]);
;                             if (seg < 2) {
;                                 u32x2 gn = *(const u32x2*)(gp + (seg + 1) * DM);
;                                 c0 = c0 / fmaxf(lo_bf(gn[0]), 1e-30f); c1 = c1 / fmaxf(hi_bf(gn[0]), 1e-30f);
;                                 c2 = c2 / fmaxf(lo_bf(gn[1]), 1e-30f); c3 = c3 / fmaxf(hi_bf(gn[1]), 1e-30f);
;                                 acc[ai][bj][m][n][0] *= c0; acc[ai][bj][m][n][1] *= c1; acc[ai][bj][m][n][2] *= c2; acc[ai][bj][m][n][3] *= c3;
;                             } else {
;                                 u32x2 o; o[0] = cvt_pk(acc[ai][bj][m][n][0] * c0, acc[ai][bj][m][n][1] * c1); o[1] = cvt_pk(acc[ai][bj][m][n][2] * c2, acc[ai][bj][m][n][3] * c3);
;                                 *(u32x2*)(mg + (size_t)row * DM + col) = o;
.LBB0_624:
	v_ashrrev_i32_e32 v141, 31, v140
	v_lshlrev_b64 v[140:141], 11, v[140:141]
	v_lshl_add_u64 v[140:141], s[72:73], 0, v[140:141]
	s_andn2_b64 vcc, exec, s[12:13]
	v_lshl_add_u64 v[140:141], v[134:135], 1, v[140:141]
	s_cbranch_vccnz .LBB0_626
	v_pk_mul_f32 v[130:131], v[126:127], v[146:147]
	v_pk_mul_f32 v[132:133], v[128:129], v[142:143]
	v_cvt_pk_bf16_f32 v130, v130, v131
	v_cvt_pk_bf16_f32 v131, v132, v133
	v_add_u32_e32 v140, 1536, v140
	v_xor_b32_e32 v140, v196, v140
	global_store_dwordx2 v[140:141], v[130:131], off
	v_xor_b32_e32 v140, v196, v140
	v_subrev_u32_e32 v140, 1536, v140
	v_mov_b64_e32 v[132:133], v[128:129]
	v_mov_b64_e32 v[130:131], v[126:127]

; __device__ __forceinline__ unsigned cvt_pk(float lo, float hi) { f32x2_t v = {lo, hi}; bf16x2_t b = __builtin_convertvector(v, bf16x2_t); return __builtin_bit_cast(unsigned, b); }
; __device__ __forceinline__ float lo_bf(unsigned u) { return __uint_as_float(u << 16); }
; __device__ __forceinline__ float hi_bf(unsigned u) { return __uint_as_float(u & 0xffff0000u); }
; __device__ __forceinline__ void phase_merge(const Ctx& a, LAS unsigned char* lds) {
;     ...
;                             int col = pn * 256 + bj * 128 + t.wc * 32 + n * 16 + t.fq * 4;
;                             const bf16_t* gp = g + (size_t)row * NG + col;
;                             u32x2 gc = *(const u32x2*)(gp + seg * DM);
;                             float c0 = lo_bf(gc[0]), c1 = hi_bf(gc[0]), c2 = lo_bf(gc[1]), c3 = hi_bf(gc[1]);
;                             if (seg < 2) {
;                                 u32x2 gn = *(const u32x2*)(gp + (seg + 1) * DM);
;                                 c0 = c0 / fmaxf(lo_bf(gn[0]), 1e-30f); c1 = c1 / fmaxf(hi_bf(gn[0]), 1e-30f);
;                                 c2 = c2 / fmaxf(lo_bf(gn[1]), 1e-30f); c3 = c3 / fmaxf(hi_bf(gn[1]), 1e-30f);
;                                 acc[ai][bj][m][n][0] *= c0; acc[ai][bj][m][n][1] *= c1; acc[ai][bj][m][n][2] *= c2; acc[ai][bj][m][n][3] *= c3;
;                             } else {
;                                 u32x2 o; o[0] = cvt_pk(acc[ai][bj][m][n][0] * c0, acc[ai][bj][m][n][1] * c1); o[1] = cvt_pk(acc[ai][bj][m][n][2] * c2, acc[ai][bj][m][n][3] * c3);
;                                 *(u32x2*)(mg + (size_t)row * DM + col) = o;
.LBB0_628:
	s_andn2_b64 vcc, exec, s[12:13]
	s_cbranch_vccnz .LBB0_630
	v_pk_mul_f32 v[126:127], v[118:119], v[146:147]
	v_pk_mul_f32 v[128:129], v[120:121], v[142:143]
	v_cvt_pk_bf16_f32 v126, v126, v127
	v_cvt_pk_bf16_f32 v127, v128, v129
	v_add_u32_e32 v140, 1568, v140
	v_xor_b32_e32 v140, v196, v140
	global_store_dwordx2 v[140:141], v[126:127], off
	v_xor_b32_e32 v140, v196, v140
	v_subrev_u32_e32 v140, 1568, v140
	v_mov_b64_e32 v[128:129], v[120:121]
	v_mov_b64_e32 v[126:127], v[118:119]

; __device__ __forceinline__ unsigned cvt_pk(float lo, float hi) { f32x2_t v = {lo, hi}; bf16x2_t b = __builtin_convertvector(v, bf16x2_t); return __builtin_bit_cast(unsigned, b); }
; __device__ __forceinline__ float lo_bf(unsigned u) { return __uint_as_float(u << 16); }
; __device__ __forceinline__ float hi_bf(unsigned u) { return __uint_as_float(u & 0xffff0000u); }
; __device__ __forceinline__ void phase_merge(const Ctx& a, LAS unsigned char* lds) {
;     ...
;                             int col = pn * 256 + bj * 128 + t.wc * 32 + n * 16 + t.fq * 4;
;                             const bf16_t* gp = g + (size_t)row * NG + col;
;                             u32x2 gc = *(const u32x2*)(gp + seg * DM);
;                             float c0 = lo_bf(gc[0]), c1 = hi_bf(gc[0]), c2 = lo_bf(gc[1]), c3 = hi_bf(gc[1]);
;                             if (seg < 2) {
;                                 u32x2 gn = *(const u32x2*)(gp + (seg + 1) * DM);
;                                 c0 = c0 / fmaxf(lo_bf(gn[0]), 1e-30f); c1 = c1 / fmaxf(hi_bf(gn[0]), 1e-30f);
;                                 c2 = c2 / fmaxf(lo_bf(gn[1]), 1e-30f); c3 = c3 / fmaxf(hi_bf(gn[1]), 1e-30f);
;                                 acc[ai][bj][m][n][0] *= c0; acc[ai][bj][m][n][1] *= c1; acc[ai][bj][m][n][2] *= c2; acc[ai][bj][m][n][3] *= c3;
;                             } else {
;                                 u32x2 o; o[0] = cvt_pk(acc[ai][bj][m][n][0] * c0, acc[ai][bj][m][n][1] * c1); o[1] = cvt_pk(acc[ai][bj][m][n][2] * c2, acc[ai][bj][m][n][3] * c3);
;                                 *(u32x2*)(mg + (size_t)row * DM + col) = o;
.LBB0_632:
	s_andn2_b64 vcc, exec, s[12:13]
	s_cbranch_vccnz .LBB0_634
	v_pk_mul_f32 v[118:119], v[110:111], v[146:147]
	v_pk_mul_f32 v[120:121], v[112:113], v[142:143]
	v_cvt_pk_bf16_f32 v118, v118, v119
	v_cvt_pk_bf16_f32 v119, v120, v121
	v_add_u32_e32 v140, 1792, v140
	v_xor_b32_e32 v140, v196, v140
	global_store_dwordx2 v[140:141], v[118:119], off
	v_xor_b32_e32 v140, v196, v140
	v_subrev_u32_e32 v140, 1792, v140
	v_mov_b64_e32 v[120:121], v[112:113]
	v_mov_b64_e32 v[118:119], v[110:111]

; __device__ __forceinline__ unsigned cvt_pk(float lo, float hi) { f32x2_t v = {lo, hi}; bf16x2_t b = __builtin_convertvector(v, bf16x2_t); return __builtin_bit_cast(unsigned, b); }
; __device__ __forceinline__ float lo_bf(unsigned u) { return __uint_as_float(u << 16); }
; __device__ __forceinline__ float hi_bf(unsigned u) { return __uint_as_float(u & 0xffff0000u); }
; __device__ __forceinline__ void phase_merge(const Ctx& a, LAS unsigned char* lds) {
;     ...
;                             int col = pn * 256 + bj * 128 + t.wc * 32 + n * 16 + t.fq * 4;
;                             const bf16_t* gp = g + (size_t)row * NG + col;
;                             u32x2 gc = *(const u32x2*)(gp + seg * DM);
;                             float c0 = lo_bf(gc[0]), c1 = hi_bf(gc[0]), c2 = lo_bf(gc[1]), c3 = hi_bf(gc[1]);
;                             if (seg < 2) {
;                                 u32x2 gn = *(const u32x2*)(gp + (seg + 1) * DM);
;                                 c0 = c0 / fmaxf(lo_bf(gn[0]), 1e-30f); c1 = c1 / fmaxf(hi_bf(gn[0]), 1e-30f);
;                                 c2 = c2 / fmaxf(lo_bf(gn[1]), 1e-30f); c3 = c3 / fmaxf(hi_bf(gn[1]), 1e-30f);
;                                 acc[ai][bj][m][n][0] *= c0; acc[ai][bj][m][n][1] *= c1; acc[ai][bj][m][n][2] *= c2; acc[ai][bj][m][n][3] *= c3;
;                             } else {
;                                 u32x2 o; o[0] = cvt_pk(acc[ai][bj][m][n][0] * c0, acc[ai][bj][m][n][1] * c1); o[1] = cvt_pk(acc[ai][bj][m][n][2] * c2, acc[ai][bj][m][n][3] * c3);
;                                 *(u32x2*)(mg + (size_t)row * DM + col) = o;
.LBB0_636:
	s_andn2_b64 vcc, exec, s[12:13]
	s_cbranch_vccnz .LBB0_638
	v_pk_mul_f32 v[110:111], v[102:103], v[146:147]
	v_pk_mul_f32 v[112:113], v[104:105], v[142:143]
	v_cvt_pk_bf16_f32 v110, v110, v111
	v_cvt_pk_bf16_f32 v111, v112, v113
	v_add_u32_e32 v140, 1824, v140
	v_xor_b32_e32 v140, v196, v140
	global_store_dwordx2 v[140:141], v[110:111], off
	v_xor_b32_e32 v140, v196, v140
	v_subrev_u32_e32 v140, 1824, v140
	v_mov_b64_e32 v[112:113], v[104:105]
	v_mov_b64_e32 v[110:111], v[102:103]

; __device__ __forceinline__ unsigned cvt_pk(float lo, float hi) { f32x2_t v = {lo, hi}; bf16x2_t b = __builtin_convertvector(v, bf16x2_t); return __builtin_bit_cast(unsigned, b); }
; __device__ __forceinline__ float lo_bf(unsigned u) { return __uint_as_float(u << 16); }
; __device__ __forceinline__ float hi_bf(unsigned u) { return __uint_as_float(u & 0xffff0000u); }
; __device__ __forceinline__ void phase_merge(const Ctx& a, LAS unsigned char* lds) {
;     ...
;                             int col = pn * 256 + bj * 128 + t.wc * 32 + n * 16 + t.fq * 4;
;                             const bf16_t* gp = g + (size_t)row * NG + col;
;                             u32x2 gc = *(const u32x2*)(gp + seg * DM);
;                             float c0 = lo_bf(gc[0]), c1 = hi_bf(gc[0]), c2 = lo_bf(gc[1]), c3 = hi_bf(gc[1]);
;                             if (seg < 2) {
;                                 u32x2 gn = *(const u32x2*)(gp + (seg + 1) * DM);
;                                 c0 = c0 / fmaxf(lo_bf(gn[0]), 1e-30f); c1 = c1 / fmaxf(hi_bf(gn[0]), 1e-30f);
;                                 c2 = c2 / fmaxf(lo_bf(gn[1]), 1e-30f); c3 = c3 / fmaxf(hi_bf(gn[1]), 1e-30f);
;                                 acc[ai][bj][m][n][0] *= c0; acc[ai][bj][m][n][1] *= c1; acc[ai][bj][m][n][2] *= c2; acc[ai][bj][m][n][3] *= c3;
;                             } else {
;                                 u32x2 o; o[0] = cvt_pk(acc[ai][bj][m][n][0] * c0, acc[ai][bj][m][n][1] * c1); o[1] = cvt_pk(acc[ai][bj][m][n][2] * c2, acc[ai][bj][m][n][3] * c3);
;                                 *(u32x2*)(mg + (size_t)row * DM + col) = o;
.LBB0_640:
	v_ashrrev_i32_e32 v141, 31, v140
	v_lshlrev_b64 v[140:141], 11, v[140:141]
	v_lshl_add_u64 v[140:141], s[72:73], 0, v[140:141]
	s_andn2_b64 vcc, exec, s[12:13]
	v_lshl_add_u64 v[140:141], v[134:135], 1, v[140:141]
	s_cbranch_vccnz .LBB0_642
	v_pk_mul_f32 v[102:103], v[94:95], v[146:147]
	v_pk_mul_f32 v[104:105], v[96:97], v[142:143]
	v_cvt_pk_bf16_f32 v102, v102, v103
	v_cvt_pk_bf16_f32 v103, v104, v105
	v_add_u32_e32 v140, 1536, v140
	v_xor_b32_e32 v140, v196, v140
	global_store_dwordx2 v[140:141], v[102:103], off
	v_xor_b32_e32 v140, v196, v140
	v_subrev_u32_e32 v140, 1536, v140
	v_mov_b64_e32 v[104:105], v[96:97]
	v_mov_b64_e32 v[102:103], v[94:95]

; __device__ __forceinline__ unsigned cvt_pk(float lo, float hi) { f32x2_t v = {lo, hi}; bf16x2_t b = __builtin_convertvector(v, bf16x2_t); return __builtin_bit_cast(unsigned, b); }
; __device__ __forceinline__ float lo_bf(unsigned u) { return __uint_as_float(u << 16); }
; __device__ __forceinline__ float hi_bf(unsigned u) { return __uint_as_float(u & 0xffff0000u); }
; __device__ __forceinline__ void phase_merge(const Ctx& a, LAS unsigned char* lds) {
;     ...
;                             int col = pn * 256 + bj * 128 + t.wc * 32 + n * 16 + t.fq * 4;
;                             const bf16_t* gp = g + (size_t)row * NG + col;
;                             u32x2 gc = *(const u32x2*)(gp + seg * DM);
;                             float c0 = lo_bf(gc[0]), c1 = hi_bf(gc[0]), c2 = lo_bf(gc[1]), c3 = hi_bf(gc[1]);
;                             if (seg < 2) {
;                                 u32x2 gn = *(const u32x2*)(gp + (seg + 1) * DM);
;                                 c0 = c0 / fmaxf(lo_bf(gn[0]), 1e-30f); c1 = c1 / fmaxf(hi_bf(gn[0]), 1e-30f);
;                                 c2 = c2 / fmaxf(lo_bf(gn[1]), 1e-30f); c3 = c3 / fmaxf(hi_bf(gn[1]), 1e-30f);
;                                 acc[ai][bj][m][n][0] *= c0; acc[ai][bj][m][n][1] *= c1; acc[ai][bj][m][n][2] *= c2; acc[ai][bj][m][n][3] *= c3;
;                             } else {
;                                 u32x2 o; o[0] = cvt_pk(acc[ai][bj][m][n][0] * c0, acc[ai][bj][m][n][1] * c1); o[1] = cvt_pk(acc[ai][bj][m][n][2] * c2, acc[ai][bj][m][n][3] * c3);
;                                 *(u32x2*)(mg + (size_t)row * DM + col) = o;
.LBB0_644:
	s_andn2_b64 vcc, exec, s[12:13]
	s_cbranch_vccnz .LBB0_646
	v_pk_mul_f32 v[94:95], v[86:87], v[146:147]
	v_pk_mul_f32 v[96:97], v[88:89], v[142:143]
	v_cvt_pk_bf16_f32 v94, v94, v95
	v_cvt_pk_bf16_f32 v95, v96, v97
	v_add_u32_e32 v140, 1568, v140
	v_xor_b32_e32 v140, v196, v140
	global_store_dwordx2 v[140:141], v[94:95], off
	v_xor_b32_e32 v140, v196, v140
	v_subrev_u32_e32 v140, 1568, v140
	v_mov_b64_e32 v[96:97], v[88:89]
	v_mov_b64_e32 v[94:95], v[86:87]

; __device__ __forceinline__ unsigned cvt_pk(float lo, float hi) { f32x2_t v = {lo, hi}; bf16x2_t b = __builtin_convertvector(v, bf16x2_t); return __builtin_bit_cast(unsigned, b); }
; __device__ __forceinline__ float lo_bf(unsigned u) { return __uint_as_float(u << 16); }
; __device__ __forceinline__ float hi_bf(unsigned u) { return __uint_as_float(u & 0xffff0000u); }
; __device__ __forceinline__ void phase_merge(const Ctx& a, LAS unsigned char* lds) {
;     ...
;                             int col = pn * 256 + bj * 128 + t.wc * 32 + n * 16 + t.fq * 4;
;                             const bf16_t* gp = g + (size_t)row * NG + col;
;                             u32x2 gc = *(const u32x2*)(gp + seg * DM);
;                             float c0 = lo_bf(gc[0]), c1 = hi_bf(gc[0]), c2 = lo_bf(gc[1]), c3 = hi_bf(gc[1]);
;                             if (seg < 2) {
;                                 u32x2 gn = *(const u32x2*)(gp + (seg + 1) * DM);
;                                 c0 = c0 / fmaxf(lo_bf(gn[0]), 1e-30f); c1 = c1 / fmaxf(hi_bf(gn[0]), 1e-30f);
;                                 c2 = c2 / fmaxf(lo_bf(gn[1]), 1e-30f); c3 = c3 / fmaxf(hi_bf(gn[1]), 1e-30f);
;                                 acc[ai][bj][m][n][0] *= c0; acc[ai][bj][m][n][1] *= c1; acc[ai][bj][m][n][2] *= c2; acc[ai][bj][m][n][3] *= c3;
;                             } else {
;                                 u32x2 o; o[0] = cvt_pk(acc[ai][bj][m][n][0] * c0, acc[ai][bj][m][n][1] * c1); o[1] = cvt_pk(acc[ai][bj][m][n][2] * c2, acc[ai][bj][m][n][3] * c3);
;                                 *(u32x2*)(mg + (size_t)row * DM + col) = o;
.LBB0_648:
	s_andn2_b64 vcc, exec, s[12:13]
	s_cbranch_vccnz .LBB0_650
	v_pk_mul_f32 v[86:87], v[78:79], v[146:147]
	v_pk_mul_f32 v[88:89], v[80:81], v[142:143]
	v_cvt_pk_bf16_f32 v86, v86, v87
	v_cvt_pk_bf16_f32 v87, v88, v89
	v_add_u32_e32 v140, 1792, v140
	v_xor_b32_e32 v140, v196, v140
	global_store_dwordx2 v[140:141], v[86:87], off
	v_xor_b32_e32 v140, v196, v140
	v_subrev_u32_e32 v140, 1792, v140
	v_mov_b64_e32 v[88:89], v[80:81]
	v_mov_b64_e32 v[86:87], v[78:79]

; __device__ __forceinline__ unsigned cvt_pk(float lo, float hi) { f32x2_t v = {lo, hi}; bf16x2_t b = __builtin_convertvector(v, bf16x2_t); return __builtin_bit_cast(unsigned, b); }
; __device__ __forceinline__ float lo_bf(unsigned u) { return __uint_as_float(u << 16); }
; __device__ __forceinline__ float hi_bf(unsigned u) { return __uint_as_float(u & 0xffff0000u); }
; __device__ __forceinline__ void phase_merge(const Ctx& a, LAS unsigned char* lds) {
;     ...
;                             int col = pn * 256 + bj * 128 + t.wc * 32 + n * 16 + t.fq * 4;
;                             const bf16_t* gp = g + (size_t)row * NG + col;
;                             u32x2 gc = *(const u32x2*)(gp + seg * DM);
;                             float c0 = lo_bf(gc[0]), c1 = hi_bf(gc[0]), c2 = lo_bf(gc[1]), c3 = hi_bf(gc[1]);
;                             if (seg < 2) {
;                                 u32x2 gn = *(const u32x2*)(gp + (seg + 1) * DM);
;                                 c0 = c0 / fmaxf(lo_bf(gn[0]), 1e-30f); c1 = c1 / fmaxf(hi_bf(gn[0]), 1e-30f);
;                                 c2 = c2 / fmaxf(lo_bf(gn[1]), 1e-30f); c3 = c3 / fmaxf(hi_bf(gn[1]), 1e-30f);
;                                 acc[ai][bj][m][n][0] *= c0; acc[ai][bj][m][n][1] *= c1; acc[ai][bj][m][n][2] *= c2; acc[ai][bj][m][n][3] *= c3;
;                             } else {
;                                 u32x2 o; o[0] = cvt_pk(acc[ai][bj][m][n][0] * c0, acc[ai][bj][m][n][1] * c1); o[1] = cvt_pk(acc[ai][bj][m][n][2] * c2, acc[ai][bj][m][n][3] * c3);
;                                 *(u32x2*)(mg + (size_t)row * DM + col) = o;
.LBB0_652:
	s_andn2_b64 vcc, exec, s[12:13]
	s_cbranch_vccnz .LBB0_654
	v_pk_mul_f32 v[78:79], v[70:71], v[146:147]
	v_pk_mul_f32 v[80:81], v[72:73], v[142:143]
	v_cvt_pk_bf16_f32 v78, v78, v79
	v_cvt_pk_bf16_f32 v79, v80, v81
	v_add_u32_e32 v140, 1824, v140
	v_xor_b32_e32 v140, v196, v140
	global_store_dwordx2 v[140:141], v[78:79], off
	v_xor_b32_e32 v140, v196, v140
	v_subrev_u32_e32 v140, 1824, v140
	v_mov_b64_e32 v[80:81], v[72:73]
	v_mov_b64_e32 v[78:79], v[70:71]

; __device__ __forceinline__ unsigned cvt_pk(float lo, float hi) { f32x2_t v = {lo, hi}; bf16x2_t b = __builtin_convertvector(v, bf16x2_t); return __builtin_bit_cast(unsigned, b); }
; __device__ __forceinline__ float lo_bf(unsigned u) { return __uint_as_float(u << 16); }
; __device__ __forceinline__ float hi_bf(unsigned u) { return __uint_as_float(u & 0xffff0000u); }
; __device__ __forceinline__ void phase_merge(const Ctx& a, LAS unsigned char* lds) {
;     ...
;                             int col = pn * 256 + bj * 128 + t.wc * 32 + n * 16 + t.fq * 4;
;                             const bf16_t* gp = g + (size_t)row * NG + col;
;                             u32x2 gc = *(const u32x2*)(gp + seg * DM);
;                             float c0 = lo_bf(gc[0]), c1 = hi_bf(gc[0]), c2 = lo_bf(gc[1]), c3 = hi_bf(gc[1]);
;                             if (seg < 2) {
;                                 u32x2 gn = *(const u32x2*)(gp + (seg + 1) * DM);
;                                 c0 = c0 / fmaxf(lo_bf(gn[0]), 1e-30f); c1 = c1 / fmaxf(hi_bf(gn[0]), 1e-30f);
;                                 c2 = c2 / fmaxf(lo_bf(gn[1]), 1e-30f); c3 = c3 / fmaxf(hi_bf(gn[1]), 1e-30f);
;                                 acc[ai][bj][m][n][0] *= c0; acc[ai][bj][m][n][1] *= c1; acc[ai][bj][m][n][2] *= c2; acc[ai][bj][m][n][3] *= c3;
;                             } else {
;                                 u32x2 o; o[0] = cvt_pk(acc[ai][bj][m][n][0] * c0, acc[ai][bj][m][n][1] * c1); o[1] = cvt_pk(acc[ai][bj][m][n][2] * c2, acc[ai][bj][m][n][3] * c3);
;                                 *(u32x2*)(mg + (size_t)row * DM + col) = o;
.LBB0_656:
	v_ashrrev_i32_e32 v141, 31, v140
	v_lshlrev_b64 v[140:141], 11, v[140:141]
	v_lshl_add_u64 v[140:141], s[72:73], 0, v[140:141]
	s_andn2_b64 vcc, exec, s[12:13]
	v_lshl_add_u64 v[140:141], v[134:135], 1, v[140:141]
	s_cbranch_vccnz .LBB0_658
	v_pk_mul_f32 v[70:71], v[62:63], v[146:147]
	v_pk_mul_f32 v[72:73], v[64:65], v[142:143]
	v_cvt_pk_bf16_f32 v70, v70, v71
	v_cvt_pk_bf16_f32 v71, v72, v73
	v_add_u32_e32 v140, 1536, v140
	v_xor_b32_e32 v140, v196, v140
	global_store_dwordx2 v[140:141], v[70:71], off
	v_xor_b32_e32 v140, v196, v140
	v_subrev_u32_e32 v140, 1536, v140
	v_mov_b64_e32 v[72:73], v[64:65]
	v_mov_b64_e32 v[70:71], v[62:63]

; __device__ __forceinline__ unsigned cvt_pk(float lo, float hi) { f32x2_t v = {lo, hi}; bf16x2_t b = __builtin_convertvector(v, bf16x2_t); return __builtin_bit_cast(unsigned, b); }
; __device__ __forceinline__ float lo_bf(unsigned u) { return __uint_as_float(u << 16); }
; __device__ __forceinline__ float hi_bf(unsigned u) { return __uint_as_float(u & 0xffff0000u); }
; __device__ __forceinline__ void phase_merge(const Ctx& a, LAS unsigned char* lds) {
;     ...
;                             int col = pn * 256 + bj * 128 + t.wc * 32 + n * 16 + t.fq * 4;
;                             const bf16_t* gp = g + (size_t)row * NG + col;
;                             u32x2 gc = *(const u32x2*)(gp + seg * DM);
;                             float c0 = lo_bf(gc[0]), c1 = hi_bf(gc[0]), c2 = lo_bf(gc[1]), c3 = hi_bf(gc[1]);
;                             if (seg < 2) {
;                                 u32x2 gn = *(const u32x2*)(gp + (seg + 1) * DM);
;                                 c0 = c0 / fmaxf(lo_bf(gn[0]), 1e-30f); c1 = c1 / fmaxf(hi_bf(gn[0]), 1e-30f);
;                                 c2 = c2 / fmaxf(lo_bf(gn[1]), 1e-30f); c3 = c3 / fmaxf(hi_bf(gn[1]), 1e-30f);
;                                 acc[ai][bj][m][n][0] *= c0; acc[ai][bj][m][n][1] *= c1; acc[ai][bj][m][n][2] *= c2; acc[ai][bj][m][n][3] *= c3;
;                             } else {
;                                 u32x2 o; o[0] = cvt_pk(acc[ai][bj][m][n][0] * c0, acc[ai][bj][m][n][1] * c1); o[1] = cvt_pk(acc[ai][bj][m][n][2] * c2, acc[ai][bj][m][n][3] * c3);
;                                 *(u32x2*)(mg + (size_t)row * DM + col) = o;
.LBB0_660:
	s_andn2_b64 vcc, exec, s[12:13]
	s_cbranch_vccnz .LBB0_662
	v_pk_mul_f32 v[62:63], v[54:55], v[146:147]
	v_pk_mul_f32 v[64:65], v[56:57], v[142:143]
	v_cvt_pk_bf16_f32 v62, v62, v63
	v_cvt_pk_bf16_f32 v63, v64, v65
	v_add_u32_e32 v140, 1568, v140
	v_xor_b32_e32 v140, v196, v140
	global_store_dwordx2 v[140:141], v[62:63], off
	v_xor_b32_e32 v140, v196, v140
	v_subrev_u32_e32 v140, 1568, v140
	v_mov_b64_e32 v[64:65], v[56:57]
	v_mov_b64_e32 v[62:63], v[54:55]

; __device__ __forceinline__ unsigned cvt_pk(float lo, float hi) { f32x2_t v = {lo, hi}; bf16x2_t b = __builtin_convertvector(v, bf16x2_t); return __builtin_bit_cast(unsigned, b); }
; __device__ __forceinline__ float lo_bf(unsigned u) { return __uint_as_float(u << 16); }
; __device__ __forceinline__ float hi_bf(unsigned u) { return __uint_as_float(u & 0xffff0000u); }
; __device__ __forceinline__ void phase_merge(const Ctx& a, LAS unsigned char* lds) {
;     ...
;                             int col = pn * 256 + bj * 128 + t.wc * 32 + n * 16 + t.fq * 4;
;                             const bf16_t* gp = g + (size_t)row * NG + col;
;                             u32x2 gc = *(const u32x2*)(gp + seg * DM);
;                             float c0 = lo_bf(gc[0]), c1 = hi_bf(gc[0]), c2 = lo_bf(gc[1]), c3 = hi_bf(gc[1]);
;                             if (seg < 2) {
;                                 u32x2 gn = *(const u32x2*)(gp + (seg + 1) * DM);
;                                 c0 = c0 / fmaxf(lo_bf(gn[0]), 1e-30f); c1 = c1 / fmaxf(hi_bf(gn[0]), 1e-30f);
;                                 c2 = c2 / fmaxf(lo_bf(gn[1]), 1e-30f); c3 = c3 / fmaxf(hi_bf(gn[1]), 1e-30f);
;                                 acc[ai][bj][m][n][0] *= c0; acc[ai][bj][m][n][1] *= c1; acc[ai][bj][m][n][2] *= c2; acc[ai][bj][m][n][3] *= c3;
;                             } else {
;                                 u32x2 o; o[0] = cvt_pk(acc[ai][bj][m][n][0] * c0, acc[ai][bj][m][n][1] * c1); o[1] = cvt_pk(acc[ai][bj][m][n][2] * c2, acc[ai][bj][m][n][3] * c3);
;                                 *(u32x2*)(mg + (size_t)row * DM + col) = o;
.LBB0_664:
	s_andn2_b64 vcc, exec, s[12:13]
	s_cbranch_vccnz .LBB0_666
	v_pk_mul_f32 v[54:55], v[46:47], v[146:147]
	v_pk_mul_f32 v[56:57], v[48:49], v[142:143]
	v_cvt_pk_bf16_f32 v54, v54, v55
	v_cvt_pk_bf16_f32 v55, v56, v57
	v_add_u32_e32 v140, 1792, v140
	v_xor_b32_e32 v140, v196, v140
	global_store_dwordx2 v[140:141], v[54:55], off
	v_xor_b32_e32 v140, v196, v140
	v_subrev_u32_e32 v140, 1792, v140
	v_mov_b64_e32 v[56:57], v[48:49]
	v_mov_b64_e32 v[54:55], v[46:47]

; __device__ __forceinline__ unsigned cvt_pk(float lo, float hi) { f32x2_t v = {lo, hi}; bf16x2_t b = __builtin_convertvector(v, bf16x2_t); return __builtin_bit_cast(unsigned, b); }
; __device__ __forceinline__ float lo_bf(unsigned u) { return __uint_as_float(u << 16); }
; __device__ __forceinline__ float hi_bf(unsigned u) { return __uint_as_float(u & 0xffff0000u); }
; __device__ __forceinline__ void phase_merge(const Ctx& a, LAS unsigned char* lds) {
;     ...
;                             int col = pn * 256 + bj * 128 + t.wc * 32 + n * 16 + t.fq * 4;
;                             const bf16_t* gp = g + (size_t)row * NG + col;
;                             u32x2 gc = *(const u32x2*)(gp + seg * DM);
;                             float c0 = lo_bf(gc[0]), c1 = hi_bf(gc[0]), c2 = lo_bf(gc[1]), c3 = hi_bf(gc[1]);
;                             if (seg < 2) {
;                                 u32x2 gn = *(const u32x2*)(gp + (seg + 1) * DM);
;                                 c0 = c0 / fmaxf(lo_bf(gn[0]), 1e-30f); c1 = c1 / fmaxf(hi_bf(gn[0]), 1e-30f);
;                                 c2 = c2 / fmaxf(lo_bf(gn[1]), 1e-30f); c3 = c3 / fmaxf(hi_bf(gn[1]), 1e-30f);
;                                 acc[ai][bj][m][n][0] *= c0; acc[ai][bj][m][n][1] *= c1; acc[ai][bj][m][n][2] *= c2; acc[ai][bj][m][n][3] *= c3;
;                             } else {
;                                 u32x2 o; o[0] = cvt_pk(acc[ai][bj][m][n][0] * c0, acc[ai][bj][m][n][1] * c1); o[1] = cvt_pk(acc[ai][bj][m][n][2] * c2, acc[ai][bj][m][n][3] * c3);
;                                 *(u32x2*)(mg + (size_t)row * DM + col) = o;
.LBB0_668:
	s_andn2_b64 vcc, exec, s[12:13]
	s_cbranch_vccnz .LBB0_670
	v_pk_mul_f32 v[46:47], v[38:39], v[146:147]
	v_pk_mul_f32 v[48:49], v[40:41], v[142:143]
	v_cvt_pk_bf16_f32 v46, v46, v47
	v_cvt_pk_bf16_f32 v47, v48, v49
	v_add_u32_e32 v140, 1824, v140
	v_xor_b32_e32 v140, v196, v140
	global_store_dwordx2 v[140:141], v[46:47], off
	v_xor_b32_e32 v140, v196, v140
	v_subrev_u32_e32 v140, 1824, v140
	v_mov_b64_e32 v[48:49], v[40:41]
	v_mov_b64_e32 v[46:47], v[38:39]

; __device__ __forceinline__ unsigned cvt_pk(float lo, float hi) { f32x2_t v = {lo, hi}; bf16x2_t b = __builtin_convertvector(v, bf16x2_t); return __builtin_bit_cast(unsigned, b); }
; __device__ __forceinline__ float lo_bf(unsigned u) { return __uint_as_float(u << 16); }
; __device__ __forceinline__ float hi_bf(unsigned u) { return __uint_as_float(u & 0xffff0000u); }
; __device__ __forceinline__ void phase_merge(const Ctx& a, LAS unsigned char* lds) {
;     ...
;                             int col = pn * 256 + bj * 128 + t.wc * 32 + n * 16 + t.fq * 4;
;                             const bf16_t* gp = g + (size_t)row * NG + col;
;                             u32x2 gc = *(const u32x2*)(gp + seg * DM);
;                             float c0 = lo_bf(gc[0]), c1 = hi_bf(gc[0]), c2 = lo_bf(gc[1]), c3 = hi_bf(gc[1]);
;                             if (seg < 2) {
;                                 u32x2 gn = *(const u32x2*)(gp + (seg + 1) * DM);
;                                 c0 = c0 / fmaxf(lo_bf(gn[0]), 1e-30f); c1 = c1 / fmaxf(hi_bf(gn[0]), 1e-30f);
;                                 c2 = c2 / fmaxf(lo_bf(gn[1]), 1e-30f); c3 = c3 / fmaxf(hi_bf(gn[1]), 1e-30f);
;                                 acc[ai][bj][m][n][0] *= c0; acc[ai][bj][m][n][1] *= c1; acc[ai][bj][m][n][2] *= c2; acc[ai][bj][m][n][3] *= c3;
;                             } else {
;                                 u32x2 o; o[0] = cvt_pk(acc[ai][bj][m][n][0] * c0, acc[ai][bj][m][n][1] * c1); o[1] = cvt_pk(acc[ai][bj][m][n][2] * c2, acc[ai][bj][m][n][3] * c3);
;                                 *(u32x2*)(mg + (size_t)row * DM + col) = o;
.LBB0_672:
	v_ashrrev_i32_e32 v139, 31, v138
	v_lshlrev_b64 v[138:139], 11, v[138:139]
	v_lshl_add_u64 v[138:139], s[72:73], 0, v[138:139]
	s_andn2_b64 vcc, exec, s[12:13]
	v_lshl_add_u64 v[134:135], v[134:135], 1, v[138:139]
	s_cbranch_vccnz .LBB0_674
	v_pk_mul_f32 v[38:39], v[30:31], v[142:143]
	v_pk_mul_f32 v[40:41], v[32:33], v[140:141]
	v_cvt_pk_bf16_f32 v38, v38, v39
	v_cvt_pk_bf16_f32 v39, v40, v41
	v_add_u32_e32 v134, 1536, v134
	v_xor_b32_e32 v134, v196, v134
	global_store_dwordx2 v[134:135], v[38:39], off
	v_xor_b32_e32 v134, v196, v134
	v_subrev_u32_e32 v134, 1536, v134
	v_mov_b64_e32 v[40:41], v[32:33]
	v_mov_b64_e32 v[38:39], v[30:31]

; __device__ __forceinline__ unsigned cvt_pk(float lo, float hi) { f32x2_t v = {lo, hi}; bf16x2_t b = __builtin_convertvector(v, bf16x2_t); return __builtin_bit_cast(unsigned, b); }
; __device__ __forceinline__ float lo_bf(unsigned u) { return __uint_as_float(u << 16); }
; __device__ __forceinline__ float hi_bf(unsigned u) { return __uint_as_float(u & 0xffff0000u); }
; __device__ __forceinline__ void phase_merge(const Ctx& a, LAS unsigned char* lds) {
;     ...
;                             int col = pn * 256 + bj * 128 + t.wc * 32 + n * 16 + t.fq * 4;
;                             const bf16_t* gp = g + (size_t)row * NG + col;
;                             u32x2 gc = *(const u32x2*)(gp + seg * DM);
;                             float c0 = lo_bf(gc[0]), c1 = hi_bf(gc[0]), c2 = lo_bf(gc[1]), c3 = hi_bf(gc[1]);
;                             if (seg < 2) {
;                                 u32x2 gn = *(const u32x2*)(gp + (seg + 1) * DM);
;                                 c0 = c0 / fmaxf(lo_bf(gn[0]), 1e-30f); c1 = c1 / fmaxf(hi_bf(gn[0]), 1e-30f);
;                                 c2 = c2 / fmaxf(lo_bf(gn[1]), 1e-30f); c3 = c3 / fmaxf(hi_bf(gn[1]), 1e-30f);
;                                 acc[ai][bj][m][n][0] *= c0; acc[ai][bj][m][n][1] *= c1; acc[ai][bj][m][n][2] *= c2; acc[ai][bj][m][n][3] *= c3;
;                             } else {
;                                 u32x2 o; o[0] = cvt_pk(acc[ai][bj][m][n][0] * c0, acc[ai][bj][m][n][1] * c1); o[1] = cvt_pk(acc[ai][bj][m][n][2] * c2, acc[ai][bj][m][n][3] * c3);
;                                 *(u32x2*)(mg + (size_t)row * DM + col) = o;
.LBB0_676:
	s_andn2_b64 vcc, exec, s[12:13]
	s_cbranch_vccnz .LBB0_678
	v_pk_mul_f32 v[30:31], v[22:23], v[140:141]
	v_pk_mul_f32 v[32:33], v[24:25], v[138:139]
	v_cvt_pk_bf16_f32 v30, v30, v31
	v_cvt_pk_bf16_f32 v31, v32, v33
	v_add_u32_e32 v134, 1568, v134
	v_xor_b32_e32 v134, v196, v134
	global_store_dwordx2 v[134:135], v[30:31], off
	v_xor_b32_e32 v134, v196, v134
	v_subrev_u32_e32 v134, 1568, v134
	v_mov_b64_e32 v[32:33], v[24:25]
	v_mov_b64_e32 v[30:31], v[22:23]

; __device__ __forceinline__ unsigned cvt_pk(float lo, float hi) { f32x2_t v = {lo, hi}; bf16x2_t b = __builtin_convertvector(v, bf16x2_t); return __builtin_bit_cast(unsigned, b); }
; __device__ __forceinline__ float lo_bf(unsigned u) { return __uint_as_float(u << 16); }
; __device__ __forceinline__ float hi_bf(unsigned u) { return __uint_as_float(u & 0xffff0000u); }
; __device__ __forceinline__ void phase_merge(const Ctx& a, LAS unsigned char* lds) {
;     ...
;                             int col = pn * 256 + bj * 128 + t.wc * 32 + n * 16 + t.fq * 4;
;                             const bf16_t* gp = g + (size_t)row * NG + col;
;                             u32x2 gc = *(const u32x2*)(gp + seg * DM);
;                             float c0 = lo_bf(gc[0]), c1 = hi_bf(gc[0]), c2 = lo_bf(gc[1]), c3 = hi_bf(gc[1]);
;                             if (seg < 2) {
;                                 u32x2 gn = *(const u32x2*)(gp + (seg + 1) * DM);
;                                 c0 = c0 / fmaxf(lo_bf(gn[0]), 1e-30f); c1 = c1 / fmaxf(hi_bf(gn[0]), 1e-30f);
;                                 c2 = c2 / fmaxf(lo_bf(gn[1]), 1e-30f); c3 = c3 / fmaxf(hi_bf(gn[1]), 1e-30f);
;                                 acc[ai][bj][m][n][0] *= c0; acc[ai][bj][m][n][1] *= c1; acc[ai][bj][m][n][2] *= c2; acc[ai][bj][m][n][3] *= c3;
;                             } else {
;                                 u32x2 o; o[0] = cvt_pk(acc[ai][bj][m][n][0] * c0, acc[ai][bj][m][n][1] * c1); o[1] = cvt_pk(acc[ai][bj][m][n][2] * c2, acc[ai][bj][m][n][3] * c3);
;                                 *(u32x2*)(mg + (size_t)row * DM + col) = o;
.LBB0_680:
	s_andn2_b64 vcc, exec, s[12:13]
	s_cbranch_vccnz .LBB0_682
	v_pk_mul_f32 v[22:23], v[14:15], v[140:141]
	v_pk_mul_f32 v[24:25], v[16:17], v[138:139]
	v_cvt_pk_bf16_f32 v22, v22, v23
	v_cvt_pk_bf16_f32 v23, v24, v25
	v_add_u32_e32 v134, 1792, v134
	v_xor_b32_e32 v134, v196, v134
	global_store_dwordx2 v[134:135], v[22:23], off
	v_xor_b32_e32 v134, v196, v134
	v_subrev_u32_e32 v134, 1792, v134
	v_mov_b64_e32 v[24:25], v[16:17]
	v_mov_b64_e32 v[22:23], v[14:15]

; __device__ __forceinline__ unsigned cvt_pk(float lo, float hi) { f32x2_t v = {lo, hi}; bf16x2_t b = __builtin_convertvector(v, bf16x2_t); return __builtin_bit_cast(unsigned, b); }
; __device__ __forceinline__ float lo_bf(unsigned u) { return __uint_as_float(u << 16); }
; __device__ __forceinline__ float hi_bf(unsigned u) { return __uint_as_float(u & 0xffff0000u); }
; __device__ __forceinline__ void phase_merge(const Ctx& a, LAS unsigned char* lds) {
;     ...
;                             int col = pn * 256 + bj * 128 + t.wc * 32 + n * 16 + t.fq * 4;
;                             const bf16_t* gp = g + (size_t)row * NG + col;
;                             u32x2 gc = *(const u32x2*)(gp + seg * DM);
;                             float c0 = lo_bf(gc[0]), c1 = hi_bf(gc[0]), c2 = lo_bf(gc[1]), c3 = hi_bf(gc[1]);
;                             if (seg < 2) {
;                                 u32x2 gn = *(const u32x2*)(gp + (seg + 1) * DM);
;                                 c0 = c0 / fmaxf(lo_bf(gn[0]), 1e-30f); c1 = c1 / fmaxf(hi_bf(gn[0]), 1e-30f);
;                                 c2 = c2 / fmaxf(lo_bf(gn[1]), 1e-30f); c3 = c3 / fmaxf(hi_bf(gn[1]), 1e-30f);
;                                 acc[ai][bj][m][n][0] *= c0; acc[ai][bj][m][n][1] *= c1; acc[ai][bj][m][n][2] *= c2; acc[ai][bj][m][n][3] *= c3;
;                             } else {
;                                 u32x2 o; o[0] = cvt_pk(acc[ai][bj][m][n][0] * c0, acc[ai][bj][m][n][1] * c1); o[1] = cvt_pk(acc[ai][bj][m][n][2] * c2, acc[ai][bj][m][n][3] * c3);
;                                 *(u32x2*)(mg + (size_t)row * DM + col) = o;
.LBB0_684:
	s_andn2_b64 vcc, exec, s[12:13]
	s_cbranch_vccnz .LBB0_551
	v_pk_mul_f32 v[14:15], v[6:7], v[140:141]
	v_pk_mul_f32 v[16:17], v[8:9], v[138:139]
	v_cvt_pk_bf16_f32 v14, v14, v15
	v_cvt_pk_bf16_f32 v15, v16, v17
	v_add_u32_e32 v134, 1824, v134
	v_xor_b32_e32 v134, v196, v134
	global_store_dwordx2 v[134:135], v[14:15], off
	v_xor_b32_e32 v134, v196, v134
	v_subrev_u32_e32 v134, 1824, v134
	v_mov_b64_e32 v[16:17], v[8:9]
	v_mov_b64_e32 v[14:15], v[6:7]
	s_branch .LBB0_551

; #define LAS __attribute__((address_space(3)))
; __device__ __forceinline__ int fresh_tid() { int t; asm volatile("v_mov_b32 %0, %1" : "=v"(t) : "v"(threadIdx.x)); return t; }
; __device__ __forceinline__ int fresh_bid() { int t; asm volatile("s_mov_b32 %0, %1" : "=s"(t) : "s"(blockIdx.x)); return t; }
; __device__ __forceinline__ void gemm_stage_first(const bf16_t* __restrict__ A, int lda, const bf16_t* __restrict__ Bt, int ldb, int brow, int bcol, LAS unsigned char* lds) {
;     const int tid = fresh_tid();
;     const int wvu = __builtin_amdgcn_readfirstlane(tid >> 6);
;     unsigned offA, offB;
;     { int _r, _c; stage_rc(tid * 16, _r, _c); offA = (unsigned)(_r * lda + _c) * 2u; offB = (unsigned)(_r * ldb + _c) * 2u; }
;     STAGE(SBo(0, 0), Bt, ldb, bcol, 0, offB); STAGE(SAo(0, 0), A, lda, brow, 0, offA);
;     STAGE(SBo(0, 1), Bt, ldb, bcol + HALF, 0, offB); STAGE(SAo(0, 1), A, lda, brow + HALF, 0, offA);
; }
; __device__ __forceinline__ void phase_gates(const Ctx& a, LAS unsigned char* lds) {
;     ...
;     const int nM = T / 256, ntile = nM * (NG / 256);
;     { const int w0 = fresh_bid(); if (w0 < ntile) { int pm0, pn0; tile_of(w0, nM, pm0, pn0); gemm_stage_first(xb, DM, W, DM, pm0 * 256, pn0 * 256, lds); } }
.LBB0_687:
	s_andn2_b64 vcc, exec, s[0:1]
	s_cbranch_vccnz .LBB0_691
	s_mov_b32 s0, s2
	s_cmpk_gt_i32 s0, 0x2ff
	s_cbranch_scc1 .LBB0_690
	s_ashr_i32 s1, s0, 31
	s_lshr_b32 s1, s1, 26
	s_add_i32 s1, s0, s1
	v_mov_b32 v1, v179
	s_and_b32 s8, s1, 0xffffc0
	s_waitcnt vmcnt(0) lgkmcnt(0)
	v_ashrrev_i32_e32 v3, 31, v1
	s_lshl_b32 s1, s1, 2
	v_lshrrev_b32_e32 v3, 26, v3
	s_and_b32 s12, s1, 0xffffff00
	v_readfirstlane_b32 s1, v1
	v_lshlrev_b32_e32 v2, 4, v1
	v_add_u32_e32 v3, v1, v3
	v_bfe_i32 v1, v1, 27, 1
	v_lshrrev_b32_e32 v1, 22, v1
	v_add_u32_e32 v1, v2, v1
	v_and_b32_e32 v1, 0xfffffc00, v1
	v_sub_u32_e32 v1, v2, v1
	v_lshrrev_b32_e32 v2, 4, v1
	v_bitop3_b32 v2, v2, v1, 32 bitop3:0x6c
	v_ashrrev_i32_e32 v1, 31, v1
	v_lshrrev_b32_e32 v1, 26, v1
	v_add_u32_e32 v1, v2, v1
	s_sub_i32 s0, s0, s8
	s_ashr_i32 s8, s1, 6
	v_ashrrev_i32_e32 v1, 6, v1
	v_ashrrev_i32_e32 v3, 6, v3
	v_mul_i32_i24_e32 v5, 64, v1
	s_mov_b32 s1, s8
	s_mov_b32 s36, s27
	v_lshlrev_b32_e32 v4, 3, v3
	v_lshlrev_b32_e32 v3, 5, v3
	v_sub_u32_e32 v2, v2, v5
	s_ashr_i32 s37, s36, 31
	s_lshl_b32 s0, s0, 8
	v_and_b32_e32 v4, 0x1ffff0, v4
	v_and_b32_e32 v3, 32, v3
	v_ashrrev_i16_sdwa v2, v194, sext(v2) dst_sel:DWORD dst_unused:UNUSED_PAD src0_sel:DWORD src1_sel:BYTE_0
	s_lshl_b64 s[36:37], s[36:37], 7
	v_add_u32_sdwa v2, v3, sext(v2) dst_sel:DWORD dst_unused:UNUSED_PAD src0_sel:DWORD src1_sel:WORD_0
	v_add_lshl_u32 v1, v1, v4, 11
	s_add_u32 s36, s82, s36
	v_lshl_add_u32 v144, v2, 1, v1
	s_addc_u32 s37, s83, s37
	s_ashr_i32 s13, s12, 31
	v_lshl_add_u64 v[2:3], s[36:37], 0, v[144:145]
	s_lshl_b64 s[36:37], s[12:13], 11
	s_lshl_b32 s1, s1, 10
	v_lshl_add_u64 v[4:5], v[2:3], 0, s[36:37]
	s_or_b32 s36, s12, 64
	s_add_i32 s1, s1, 0
	s_ashr_i32 s37, s36, 31
	s_add_i32 m0, s1, 0x10000
	s_lshl_b64 s[36:37], s[36:37], 11
	v_xor_b32_e32 v4, v197, v4
	global_load_lds_dwordx4 v[4:5], off
	v_lshl_add_u64 v[2:3], v[2:3], 0, s[36:37]
	s_add_i32 m0, s1, 0x12000
	s_mov_b32 s1, s8
	s_mov_b32 s36, s27
	v_xor_b32_e32 v2, v197, v2
	global_load_lds_dwordx4 v[2:3], off
	s_ashr_i32 s37, s36, 31
	s_lshl_b64 s[36:37], s[36:37], 7
	s_add_u32 s36, s34, s36
	s_addc_u32 s37, s35, s37
	s_lshl_b32 s1, s1, 10
	s_add_i32 s9, s1, 0
	s_ashr_i32 s1, s0, 31
	v_lshl_add_u64 v[2:3], s[36:37], 0, v[144:145]
	s_lshl_b64 s[36:37], s[0:1], 11
	v_lshl_add_u64 v[4:5], v[2:3], 0, s[36:37]
	s_or_b32 s36, s0, 64
	s_ashr_i32 s37, s36, 31
	s_mov_b32 m0, s9
	s_lshl_b64 s[36:37], s[36:37], 11
	v_xor_b32_e32 v4, v197, v4
	global_load_lds_dwordx4 v[4:5], off
	v_lshl_add_u64 v[2:3], v[2:3], 0, s[36:37]
	s_add_i32 m0, s9, 0x2000
	s_mov_b32 s1, s8
	s_mov_b32 s36, s27
	v_xor_b32_e32 v2, v197, v2
	global_load_lds_dwordx4 v[2:3], off
	s_ashr_i32 s37, s36, 31
	s_or_b32 s38, s12, 0x80
	s_lshl_b64 s[36:37], s[36:37], 7
	s_add_u32 s36, s82, s36
	s_addc_u32 s37, s83, s37
	s_lshl_b32 s1, s1, 10
	s_ashr_i32 s39, s38, 31
	s_or_b32 s12, s12, 0xc0
	v_lshl_add_u64 v[2:3], s[36:37], 0, v[144:145]
	s_add_i32 s1, s1, 0
	s_lshl_b64 s[36:37], s[38:39], 11
	s_ashr_i32 s13, s12, 31
	s_add_i32 m0, s1, 0x14000
	v_lshl_add_u64 v[4:5], v[2:3], 0, s[36:37]
	s_lshl_b64 s[12:13], s[12:13], 11
	v_xor_b32_e32 v4, v197, v4
	global_load_lds_dwordx4 v[4:5], off
	v_lshl_add_u64 v[2:3], v[2:3], 0, s[12:13]
	s_add_i32 m0, s1, 0x16000
	s_mov_b32 s12, s27
	v_xor_b32_e32 v2, v197, v2
	global_load_lds_dwordx4 v[2:3], off
	s_ashr_i32 s13, s12, 31
	s_or_b32 s36, s0, 0x80
	s_lshl_b64 s[12:13], s[12:13], 7
	s_add_u32 s12, s34, s12
	s_addc_u32 s13, s35, s13
	s_lshl_b32 s1, s8, 10
	s_ashr_i32 s37, s36, 31
	s_or_b32 s0, s0, 0xc0
	v_lshl_add_u64 v[2:3], s[12:13], 0, v[144:145]
	s_add_i32 s8, s1, 0
	s_lshl_b64 s[12:13], s[36:37], 11
	s_ashr_i32 s1, s0, 31
	s_add_i32 m0, s8, 0x4000
	v_lshl_add_u64 v[4:5], v[2:3], 0, s[12:13]
	s_lshl_b64 s[0:1], s[0:1], 11
	v_xor_b32_e32 v4, v197, v4
	global_load_lds_dwordx4 v[4:5], off
	v_lshl_add_u64 v[2:3], v[2:3], 0, s[0:1]
	s_add_i32 m0, s8, 0x6000
	s_nop 0
	v_xor_b32_e32 v2, v197, v2
	global_load_lds_dwordx4 v[2:3], off

; __device__ __forceinline__ unsigned cvt_pk(float lo, float hi) { f32x2_t v = {lo, hi}; bf16x2_t b = __builtin_convertvector(v, bf16x2_t); return __builtin_bit_cast(unsigned, b); }
; __device__ __forceinline__ int fresh_bid() { int t; asm volatile("s_mov_b32 %0, %1" : "=s"(t) : "s"(blockIdx.x)); return t; }
; __device__ __forceinline__ void phase_convert(const Ctx& a, int l, LAS unsigned char* lds) {
;     ...
;         const int nkt = c.K / 64, nnt = c.Ntot / 64, ntile = nkt * nnt;
;         int first = (int)((fresh_bid() + gridDim.x - (base % gridDim.x)) % gridDim.x);
;         float pv[8];
;     ...
;         if (first < ntile) CV_LOAD(first);
;         for (int i = first; i < ntile; i += gridDim.x) {
;             const int kt = i / nnt, ntl = i % nnt, k0 = kt * 64, n0 = ntl * 64;
; #pragma unroll
;             for (int it = 0; it < 8; ++it) tile[((tid >> 6) + it * 8) * 65 + (tid & 63)] = pv[it];
;             __syncthreads();
;             if (i + (int)gridDim.x < ntile) CV_LOAD(i + gridDim.x);
;             {
;                 int nn = tid >> 3, kc = (tid & 7) * 8, n = n0 + nn, row = n;
;                 if (c.perm) { if (n < FF) row = (n / 128) * 256 + (n % 128); else { int jn = n - FF; row = (jn / 128) * 256 + 128 + (jn % 128); } }
;                 u32x4 w;
;                 w[0] = cvt_pk(tile[(kc + 0) * 65 + nn], tile[(kc + 1) * 65 + nn]);
;                 w[1] = cvt_pk(tile[(kc + 2) * 65 + nn], tile[(kc + 3) * 65 + nn]);
;                 w[2] = cvt_pk(tile[(kc + 4) * 65 + nn], tile[(kc + 5) * 65 + nn]);
;                 w[3] = cvt_pk(tile[(kc + 6) * 65 + nn], tile[(kc + 7) * 65 + nn]);
;                 *(u32x4*)(c.dst + (size_t)row * c.lddst + c.koff + k0 + kc) = w;
.LBB0_692:
	s_waitcnt vmcnt(0)
	v_mov_b32 v10, v179
	s_movk_i32 s0, 0x104
	s_waitcnt lgkmcnt(0)
	v_lshlrev_b32_e32 v4, 3, v10
	v_ashrrev_i32_e32 v11, 3, v10
	v_and_b32_e32 v6, 56, v4
	v_and_b32_e32 v1, 63, v10
	v_ashrrev_i32_e32 v2, 6, v10
	v_mul_u32_u24_e32 v4, 0x104, v6
	v_lshlrev_b32_e32 v7, 2, v11
	v_lshl_add_u32 v5, v1, 2, 0
	v_add3_u32 v18, 0, v4, v7
	v_mul_lo_u32 v7, v2, s0
	v_mov_b32_e32 v4, 0
	v_ashrrev_i32_e32 v3, 31, v2
	v_lshlrev_b32_e32 v19, 1, v11
	v_add_u32_e32 v19, 0x7fffea00, v19
	s_mov_b32 s48, 0
	v_add_u32_e32 v20, v5, v7
	v_lshlrev_b32_e32 v144, 1, v6
	s_mov_b32 s49, 0
	v_mov_b32_e32 v5, v4
	v_mov_b32_e32 v6, v4
	v_mov_b32_e32 v7, v4
	v_mov_b32_e32 v12, v4
	v_mov_b32_e32 v13, v4
	v_mov_b32_e32 v8, v4
	v_mov_b32_e32 v9, v4
	s_branch .LBB0_694

; __device__ __forceinline__ unsigned cvt_pk(float lo, float hi) { f32x2_t v = {lo, hi}; bf16x2_t b = __builtin_convertvector(v, bf16x2_t); return __builtin_bit_cast(unsigned, b); }
; __device__ __forceinline__ void phase_convert(const Ctx& a, int l, LAS unsigned char* lds) {
;     ...
;             {
;                 int nn = tid >> 3, kc = (tid & 7) * 8, n = n0 + nn, row = n;
;                 if (c.perm) { if (n < FF) row = (n / 128) * 256 + (n % 128); else { int jn = n - FF; row = (jn / 128) * 256 + 128 + (jn % 128); } }
;                 u32x4 w;
;                 w[0] = cvt_pk(tile[(kc + 0) * 65 + nn], tile[(kc + 1) * 65 + nn]);
;                 w[1] = cvt_pk(tile[(kc + 2) * 65 + nn], tile[(kc + 3) * 65 + nn]);
;                 w[2] = cvt_pk(tile[(kc + 4) * 65 + nn], tile[(kc + 5) * 65 + nn]);
;                 w[3] = cvt_pk(tile[(kc + 6) * 65 + nn], tile[(kc + 7) * 65 + nn]);
;                 *(u32x4*)(c.dst + (size_t)row * c.lddst + c.koff + k0 + kc) = w;
;             }
;             __syncthreads();
.LBB0_737:
	ds_read2_b32 v[24:25], v18 offset1:65
	ds_read2_b32 v[26:27], v18 offset0:130 offset1:195
	v_add_u32_e32 v30, 0x400, v18
	ds_read2_b32 v[28:29], v30 offset0:4 offset1:69
	ds_read2_b32 v[30:31], v30 offset0:134 offset1:199
	s_lshl_b32 s46, s26, 6
	s_waitcnt lgkmcnt(0)
	v_cvt_pk_bf16_f32 v24, v24, v25
	v_cvt_pk_bf16_f32 v25, v26, v27
	v_cvt_pk_bf16_f32 v26, v28, v29
	v_ashrrev_i32_e32 v28, 31, v23
	v_cvt_pk_bf16_f32 v27, v30, v31
	v_mul_lo_u32 v30, s13, v23
	v_mul_lo_u32 v31, s12, v28
	v_mad_u64_u32 v[28:29], s[62:63], s12, v23, 0
	v_add3_u32 v29, v29, v31, v30
	v_lshl_add_u64 v[28:29], v[28:29], 1, s[38:39]
	s_ashr_i32 s47, s46, 31
	v_lshl_add_u64 v[28:29], s[46:47], 1, v[28:29]
	v_lshl_add_u64 v[28:29], v[28:29], 0, v[144:145]
	s_add_i32 s56, s56, s57
	v_add_u32_e32 v21, s59, v21
	s_add_i32 s60, s60, s9
	s_and_b64 vcc, exec, s[44:45]
	v_and_b32_e32 v34, 15, v23
	v_lshlrev_b32_e32 v34, 7, v34
	s_cmp_eq_u32 s12, 0x400
	s_cselect_b32 s8, -1, 0
	v_and_b32_e32 v34, s8, v34
	v_xor_b32_e32 v28, v34, v28
	global_store_dwordx4 v[28:29], v[24:27], off
	s_barrier
	s_cbranch_vccnz .LBB0_693
	s_mov_b32 s53, s61
	s_branch .LBB0_725

; __device__ __forceinline__ int fresh_tid() { int t; asm volatile("v_mov_b32 %0, %1" : "=v"(t) : "v"(threadIdx.x)); return t; }
; #define WAIT_V(n) asm volatile("s_waitcnt vmcnt(" #n ")" ::: "memory")
; #define BAR __builtin_amdgcn_s_barrier()
; template <bool PRE = false>
; __device__ __forceinline__ void gemm_kloop(Acc& acc, const bf16_t* __restrict__ A, int lda, const bf16_t* __restrict__ Bt, int ldb,
;                                            int brow, int bcol, int nt, LAS unsigned char* lds) {
;     const int tid = fresh_tid();
;     const int wid = tid >> 6, lane = tid & 63, wr = wid >> 2, wc = wid & 3, fr = lane & 15, fq = lane >> 4;
;     const int wvu = __builtin_amdgcn_readfirstlane(tid >> 6);
;     unsigned offA, offB;
;     { int _r, _c; stage_rc(tid * 16, _r, _c); offA = (unsigned)(_r * lda + _c) * 2u; offB = (unsigned)(_r * ldb + _c) * 2u; }
;     ...
;     bf16x8 At[4][2], B0[2][2], B1[2][2];
;     if (!PRE) {
;     STAGE(SBo(0, 0), Bt, ldb, bcol, 0, offB); STAGE(SAo(0, 0), A, lda, brow, 0, offA);
;     STAGE(SBo(0, 1), Bt, ldb, bcol + HALF, 0, offB); STAGE(SAo(0, 1), A, lda, brow + HALF, 0, offA);
;     }
;     if (wr == 1) BAR;
;     WAIT_V(4); BAR;
;     STAGE(SBo(1, 0), Bt, ldb, bcol, 1, offB); STAGE(SAo(1, 0), A, lda, brow, 1, offA); STAGE(SBo(1, 1), Bt, ldb, bcol + HALF, 1, offB);
;     WAIT_V(6); BAR;
.LBB0_747:
	s_or_b64 exec, exec, s[0:1]
	v_bfe_i32 v6, v1, 27, 1
	v_lshlrev_b32_e32 v4, 4, v1
	v_lshrrev_b32_e32 v6, 22, v6
	v_add_u32_e32 v6, v4, v6
	v_and_b32_e32 v6, 0xfffffc00, v6
	v_sub_u32_e32 v4, v4, v6
	v_lshrrev_b32_e32 v6, 4, v4
	s_ashr_i32 s0, s9, 31
	v_bitop3_b32 v6, v6, v4, 32 bitop3:0x6c
	v_ashrrev_i32_e32 v4, 31, v4
	s_lshr_b32 s0, s0, 26
	v_ashrrev_i32_e32 v5, 31, v1
	v_lshrrev_b32_e32 v4, 26, v4
	s_add_i32 s1, s9, s0
	v_lshrrev_b32_e32 v5, 26, v5
	v_add_u32_e32 v4, v6, v4
	s_and_b32 s0, s1, 0xffffc0
	s_lshl_b32 s1, s1, 2
	v_add_u32_e32 v5, v1, v5
	v_ashrrev_i32_e32 v4, 6, v4
	s_and_b32 s36, s1, 0xffffff00
	v_ashrrev_i32_e32 v5, 6, v5
	v_mul_i32_i24_e32 v10, 64, v4
	s_mov_b32 s1, s26
	s_mov_b32 s12, 1
	s_sub_i32 s0, s9, s0
	v_lshlrev_b32_e32 v7, 3, v5
	v_lshlrev_b32_e32 v5, 5, v5
	v_sub_u32_e32 v6, v6, v10
	s_waitcnt vmcnt(4)
	s_barrier
	s_ashr_i32 s13, s12, 31
	s_lshl_b32 s0, s0, 8
	v_and_b32_e32 v7, 0x1ffff0, v7
	v_and_b32_e32 v5, 32, v5
	v_ashrrev_i16_sdwa v6, v194, sext(v6) dst_sel:DWORD dst_unused:UNUSED_PAD src0_sel:DWORD src1_sel:BYTE_0
	s_lshl_b64 s[12:13], s[12:13], 7
	v_add_u32_sdwa v5, v5, sext(v6) dst_sel:DWORD dst_unused:UNUSED_PAD src0_sel:DWORD src1_sel:WORD_0
	v_add_lshl_u32 v4, v4, v7, 11
	s_add_u32 s12, s82, s12
	v_lshl_add_u32 v144, v5, 1, v4
	s_addc_u32 s13, s83, s13
	s_lshl_b32 s1, s1, 10
	s_ashr_i32 s37, s36, 31
	s_or_b32 s38, s36, 64
	v_lshl_add_u64 v[4:5], s[12:13], 0, v[144:145]
	s_add_i32 s1, s31, s1
	s_lshl_b64 s[12:13], s[36:37], 11
	s_ashr_i32 s39, s38, 31
	v_lshl_add_u64 v[6:7], v[4:5], 0, s[12:13]
	s_mov_b32 m0, s1
	s_lshl_b64 s[38:39], s[38:39], 11
	v_xor_b32_e32 v6, v197, v6
	global_load_lds_dwordx4 v[6:7], off
	v_lshl_add_u64 v[4:5], v[4:5], 0, s[38:39]
	s_add_i32 m0, s1, 0x2000
	s_mov_b32 s1, s26
	s_mov_b32 s40, 1
	v_xor_b32_e32 v4, v197, v4
	global_load_lds_dwordx4 v[4:5], off
	s_ashr_i32 s41, s40, 31
	s_lshl_b64 s[40:41], s[40:41], 7
	s_add_u32 s40, s34, s40
	s_addc_u32 s41, s35, s41
	s_lshl_b32 s1, s1, 10
	s_add_i32 s8, s1, 0
	s_ashr_i32 s1, s0, 31
	s_or_b32 s42, s0, 64
	v_lshl_add_u64 v[4:5], s[40:41], 0, v[144:145]
	s_lshl_b64 s[40:41], s[0:1], 11
	s_ashr_i32 s43, s42, 31
	s_add_i32 m0, s8, 0x8000
	v_lshl_add_u64 v[6:7], v[4:5], 0, s[40:41]
	s_lshl_b64 s[42:43], s[42:43], 11
	v_xor_b32_e32 v6, v197, v6
	global_load_lds_dwordx4 v[6:7], off
	v_lshl_add_u64 v[4:5], v[4:5], 0, s[42:43]
	s_add_i32 m0, s8, 0xa000
	s_mov_b32 s1, s26
	s_mov_b32 s44, 1
	v_xor_b32_e32 v4, v197, v4
	global_load_lds_dwordx4 v[4:5], off
	s_ashr_i32 s45, s44, 31
	s_or_b32 s46, s36, 0x80
	s_lshl_b64 s[44:45], s[44:45], 7
	s_add_u32 s44, s82, s44
	s_addc_u32 s45, s83, s45
	s_ashr_i32 s47, s46, 31
	v_lshl_add_u64 v[4:5], s[44:45], 0, v[144:145]
	s_lshl_b32 s1, s1, 10
	s_lshl_b64 s[44:45], s[46:47], 11
	s_or_b32 s46, s36, 0xc0
	s_add_i32 s1, s24, s1
	s_ashr_i32 s47, s46, 31
	v_lshl_add_u64 v[6:7], v[4:5], 0, s[44:45]
	s_mov_b32 m0, s1
	s_lshl_b64 s[46:47], s[46:47], 11
	v_xor_b32_e32 v6, v197, v6
	global_load_lds_dwordx4 v[6:7], off
	v_lshl_add_u64 v[4:5], v[4:5], 0, s[46:47]
	s_add_i32 m0, s1, 0x2000
	v_and_b32_e32 v8, 15, v1
	v_xor_b32_e32 v4, v197, v4
	global_load_lds_dwordx4 v[4:5], off
	v_lshlrev_b32_e32 v5, 2, v1
	v_and_b32_e32 v9, 48, v1
	v_lshlrev_b32_e32 v4, 6, v8
	v_and_b32_e32 v5, 32, v5
	v_bitop3_b32 v4, v4, v5, v9 bitop3:0x36
	s_add_i32 s1, 0, 0x10000
	v_lshlrev_b32_e32 v11, 13, v2
	v_lshlrev_b32_e32 v2, 6, v1
	s_waitcnt vmcnt(6)
	v_lshlrev_b32_e32 v3, 12, v3
	v_add_u32_e32 v6, s1, v4
	s_or_b32 s48, s0, 0x80
	s_add_i32 s1, 0, 0x14000
	v_and_or_b32 v2, v2, s25, v9
	s_or_b32 s50, s0, 0xc0
	v_and_b32_e32 v3, 0x3000, v3
	v_add_u32_e32 v7, s1, v4
	v_add_u32_e32 v8, s31, v4
	v_add_u32_e32 v10, s24, v4
	v_add_u32_e32 v4, 0, v4
	v_xad_u32 v5, v2, v5, 0
	v_or_b32_e32 v9, 0x800, v11
	v_or_b32_e32 v12, 0x1000, v11
	v_or_b32_e32 v13, 0x1800, v11
	s_ashr_i32 s49, s48, 31
	s_ashr_i32 s51, s50, 31
	v_mov_b32_e32 v2, 0
	v_lshl_add_u64 v[130:131], s[34:35], 0, v[144:145]
	v_lshl_add_u64 v[132:133], s[82:83], 0, v[144:145]
	s_lshl_b64 s[48:49], s[48:49], 11
	s_lshl_b64 s[50:51], s[50:51], 11
	s_mov_b32 s1, -2
	v_add_u32_e32 v141, v6, v3
	v_add_u32_e32 v137, v4, v11
	v_add_u32_e32 v136, v5, v9
	v_add_u32_e32 v135, v5, v12
	v_add_u32_e32 v134, v5, v13
	v_add_u32_e32 v140, v7, v3
	v_add_u32_e32 v139, v8, v3
	v_add_u32_e32 v138, v10, v3
	v_mov_b32_e32 v3, v2
	v_mov_b32_e32 v4, v2
	v_mov_b32_e32 v5, v2
	v_mov_b32_e32 v6, v2
	v_mov_b32_e32 v7, v2
	v_mov_b32_e32 v8, v2
	v_mov_b32_e32 v9, v2
	v_mov_b32_e32 v10, v2
	v_mov_b32_e32 v11, v2
	v_mov_b32_e32 v12, v2
	v_mov_b32_e32 v13, v2
	v_mov_b32_e32 v14, v2
	v_mov_b32_e32 v15, v2
	v_mov_b32_e32 v16, v2
	v_mov_b32_e32 v17, v2
	v_mov_b32_e32 v18, v2
	v_mov_b32_e32 v19, v2
	v_mov_b32_e32 v20, v2
	v_mov_b32_e32 v21, v2
	v_mov_b32_e32 v22, v2
	v_mov_b32_e32 v23, v2
	v_mov_b32_e32 v24, v2
	v_mov_b32_e32 v25, v2
	v_mov_b32_e32 v26, v2
	v_mov_b32_e32 v27, v2
	v_mov_b32_e32 v28, v2
	v_mov_b32_e32 v29, v2
	v_mov_b32_e32 v30, v2
	v_mov_b32_e32 v31, v2
	v_mov_b32_e32 v32, v2
	v_mov_b32_e32 v33, v2
	v_mov_b32_e32 v34, v2
	v_mov_b32_e32 v35, v2
	v_mov_b32_e32 v36, v2
	v_mov_b32_e32 v37, v2
	v_mov_b32_e32 v38, v2
	v_mov_b32_e32 v39, v2
	v_mov_b32_e32 v40, v2
	v_mov_b32_e32 v41, v2
	v_mov_b32_e32 v42, v2
	v_mov_b32_e32 v43, v2
	v_mov_b32_e32 v44, v2
	v_mov_b32_e32 v45, v2
	v_mov_b32_e32 v46, v2
	v_mov_b32_e32 v47, v2
	v_mov_b32_e32 v48, v2
	v_mov_b32_e32 v49, v2
	v_mov_b32_e32 v50, v2
	v_mov_b32_e32 v51, v2
	v_mov_b32_e32 v52, v2
	v_mov_b32_e32 v53, v2
	v_mov_b32_e32 v54, v2
	v_mov_b32_e32 v55, v2
	v_mov_b32_e32 v56, v2
	v_mov_b32_e32 v57, v2
	v_mov_b32_e32 v58, v2
	v_mov_b32_e32 v59, v2
; #define LDA(dst, b, h) _Pragma("unroll") for (int m = 0; m < 4; ++m) _Pragma("unroll") for (int k = 0; k < 2; ++k) \
;     dst[m][k] = *reinterpret_cast<const LAS bf16x8*>(lds + SAo(b, h) + lds_byte(wr * 64 + m * 16 + fr, k * 32 + fq * 8))
; #define LDB(dst, b, h) _Pragma("unroll") for (int n = 0; n < 2; ++n) _Pragma("unroll") for (int k = 0; k < 2; ++k) \
;     dst[n][k] = *reinterpret_cast<const LAS bf16x8*>(lds + SBo(b, h) + lds_byte(wc * 32 + n * 16 + fr, k * 32 + fq * 8))
; #define MMA(ai, bj, At_, Bt_) do { __builtin_amdgcn_s_setprio(1); \
;     _Pragma("unroll") for (int m = 0; m < 4; ++m) _Pragma("unroll") for (int n = 0; n < 2; ++n) _Pragma("unroll") for (int k = 0; k < 2; ++k) \
;       acc[ai][bj][m][n] = __builtin_amdgcn_mfma_f32_16x16x32_bf16(Bt_[n][k], At_[m][k], acc[ai][bj][m][n], 0, 0, 0); \
;     __builtin_amdgcn_s_setprio(0); } while (0)
; #define WAIT_V(n) asm volatile("s_waitcnt vmcnt(" #n ")" ::: "memory")
; #define WAIT_L(n) asm volatile("s_waitcnt lgkmcnt(" #n ")" ::: "memory")
; template <bool PRE = false>
; __device__ __forceinline__ void gemm_kloop(Acc& acc, const bf16_t* __restrict__ A, int lda, const bf16_t* __restrict__ Bt, int ldb,
;                                            int brow, int bcol, int nt, LAS unsigned char* lds) {
;     ...
;     for (int t = 0; t < nt - 2; t += 2) {
;         LDB(B0, 0, 0); SCHED; LDA(At, 0, 0); STAGE(SAo(1, 1), A, lda, brow + HALF, t + 1, offA);
;         WAIT_L(8); BAR; WAIT_L(0); MMA(0, 0, At, B0); BAR; SCHED;
;         LDB(B1, 0, 1); STAGE(SBo(0, 0), Bt, ldb, bcol, t + 2, offB);
;         BAR; WAIT_L(0); MMA(0, 1, At, B1); BAR;
;         LDA(At, 0, 1); STAGE(SAo(0, 0), A, lda, brow, t + 2, offA);
;         BAR; WAIT_L(0); MMA(1, 0, At, B0); BAR; SCHED;
;         STAGE(SBo(0, 1), Bt, ldb, bcol + HALF, t + 2, offB);
;         WAIT_V(6); BAR; MMA(1, 1, At, B1); BAR;
;         LDB(B0, 1, 0); SCHED; LDA(At, 1, 0); STAGE(SAo(0, 1), A, lda, brow + HALF, t + 2, offA);
;         WAIT_L(8); BAR; WAIT_L(0); MMA(0, 0, At, B0); BAR; SCHED;
;         LDB(B1, 1, 1); STAGE(SBo(1, 0), Bt, ldb, bcol, t + 3, offB);
;         BAR; WAIT_L(0); MMA(0, 1, At, B1); BAR;
;         LDA(At, 1, 1); STAGE(SAo(1, 0), A, lda, brow, t + 3, offA);
;         BAR; WAIT_L(0); MMA(1, 0, At, B0); BAR; SCHED;
;         STAGE(SBo(1, 1), Bt, ldb, bcol + HALF, t + 3, offB);
;         WAIT_V(6); BAR; MMA(1, 1, At, B1); BAR;
;     }
	v_mov_b32_e32 v60, v2
	v_mov_b32_e32 v61, v2
	v_mov_b32_e32 v62, v2
	v_mov_b32_e32 v63, v2
	v_mov_b32_e32 v64, v2
	v_mov_b32_e32 v65, v2
	v_mov_b32_e32 v66, v2
	v_mov_b32_e32 v67, v2
	v_mov_b32_e32 v68, v2
	v_mov_b32_e32 v69, v2
	v_mov_b32_e32 v70, v2
	v_mov_b32_e32 v71, v2
	v_mov_b32_e32 v72, v2
	v_mov_b32_e32 v73, v2
	v_mov_b32_e32 v74, v2
	v_mov_b32_e32 v75, v2
	v_mov_b32_e32 v76, v2
	v_mov_b32_e32 v77, v2
	v_mov_b32_e32 v78, v2
	v_mov_b32_e32 v79, v2
	v_mov_b32_e32 v80, v2
	v_mov_b32_e32 v81, v2
	v_mov_b32_e32 v82, v2
	v_mov_b32_e32 v83, v2
	v_mov_b32_e32 v84, v2
	v_mov_b32_e32 v85, v2
	v_mov_b32_e32 v86, v2
	v_mov_b32_e32 v87, v2
	v_mov_b32_e32 v88, v2
	v_mov_b32_e32 v89, v2
	v_mov_b32_e32 v90, v2
	v_mov_b32_e32 v91, v2
	v_mov_b32_e32 v92, v2
	v_mov_b32_e32 v93, v2
	v_mov_b32_e32 v94, v2
	v_mov_b32_e32 v95, v2
	v_mov_b32_e32 v96, v2
	v_mov_b32_e32 v97, v2
	v_mov_b32_e32 v98, v2
	v_mov_b32_e32 v99, v2
	v_mov_b32_e32 v100, v2
	v_mov_b32_e32 v101, v2
	v_mov_b32_e32 v102, v2
	v_mov_b32_e32 v103, v2
	v_mov_b32_e32 v104, v2
	v_mov_b32_e32 v105, v2
	v_mov_b32_e32 v106, v2
	v_mov_b32_e32 v107, v2
	v_mov_b32_e32 v108, v2
	v_mov_b32_e32 v109, v2
	v_mov_b32_e32 v110, v2
	v_mov_b32_e32 v111, v2
	v_mov_b32_e32 v112, v2
	v_mov_b32_e32 v113, v2
	v_mov_b32_e32 v114, v2
	v_mov_b32_e32 v115, v2
	v_mov_b32_e32 v116, v2
	v_mov_b32_e32 v117, v2
	v_mov_b32_e32 v118, v2
	v_mov_b32_e32 v119, v2
	v_mov_b32_e32 v120, v2
	v_mov_b32_e32 v121, v2
	v_mov_b32_e32 v122, v2
	v_mov_b32_e32 v123, v2
	v_mov_b32_e32 v124, v2
	v_mov_b32_e32 v125, v2
	v_mov_b32_e32 v126, v2
	v_mov_b32_e32 v127, v2
	v_mov_b32_e32 v128, v2
	v_mov_b32_e32 v129, v2
	s_barrier
.LBB0_748:
	ds_read_b128 v[146:149], v141
	ds_read_b128 v[150:153], v141 offset:1024
	ds_read_b128 v[154:157], v141 offset:2048
	ds_read_b128 v[158:161], v141 offset:3072
	s_add_i32 s52, s1, 3
	s_mov_b32 s8, s26
	ds_read_b128 v[162:165], v137
	ds_read_b128 v[166:169], v137 offset:1024
	ds_read_b128 v[170:173], v136
	ds_read_b128 v[174:177], v136 offset:1024
	ds_read_b128 v[184:187], v135
	ds_read_b128 v[188:191], v135 offset:1024
	ds_read_b128 v[200:203], v134
	ds_read_b128 v[204:207], v134 offset:1024
	s_ashr_i32 s53, s52, 31
	s_lshl_b64 s[52:53], s[52:53], 7
	s_lshl_b32 s8, s8, 10
	v_lshl_add_u64 v[142:143], v[130:131], 0, s[52:53]
	s_add_i32 s8, s8, 0
	s_add_i32 m0, s8, 0xc000
	v_lshl_add_u64 v[192:193], v[142:143], 0, s[48:49]
	v_xor_b32_e32 v192, v197, v192
	global_load_lds_dwordx4 v[192:193], off
	v_lshl_add_u64 v[142:143], v[142:143], 0, s[50:51]
	s_add_i32 m0, s8, 0xe000
	s_nop 0
	v_xor_b32_e32 v142, v197, v142
	global_load_lds_dwordx4 v[142:143], off
	s_waitcnt lgkmcnt(8)
	s_barrier
	s_waitcnt lgkmcnt(0)
	s_setprio 1
	s_waitcnt lgkmcnt(0)
	v_mfma_f32_16x16x32_bf16 v[126:129], v[146:149], v[162:165], v[126:129]
	v_mfma_f32_16x16x32_bf16 v[122:125], v[154:157], v[162:165], v[122:125]
	v_mfma_f32_16x16x32_bf16 v[118:121], v[146:149], v[170:173], v[118:121]
	v_mfma_f32_16x16x32_bf16 v[114:117], v[154:157], v[170:173], v[114:117]
	v_mfma_f32_16x16x32_bf16 v[110:113], v[146:149], v[184:187], v[110:113]
	v_mfma_f32_16x16x32_bf16 v[106:109], v[154:157], v[184:187], v[106:109]
	v_mfma_f32_16x16x32_bf16 v[102:105], v[146:149], v[200:203], v[102:105]
	v_mfma_f32_16x16x32_bf16 v[98:101], v[154:157], v[200:203], v[98:101]
	v_mfma_f32_16x16x32_bf16 v[126:129], v[150:153], v[166:169], v[126:129]
	v_mfma_f32_16x16x32_bf16 v[122:125], v[158:161], v[166:169], v[122:125]
	v_mfma_f32_16x16x32_bf16 v[118:121], v[150:153], v[174:177], v[118:121]
	v_mfma_f32_16x16x32_bf16 v[114:117], v[158:161], v[174:177], v[114:117]
	v_mfma_f32_16x16x32_bf16 v[110:113], v[150:153], v[188:191], v[110:113]
	v_mfma_f32_16x16x32_bf16 v[106:109], v[158:161], v[188:191], v[106:109]
	v_mfma_f32_16x16x32_bf16 v[102:105], v[150:153], v[204:207], v[102:105]
	v_mfma_f32_16x16x32_bf16 v[98:101], v[158:161], v[204:207], v[98:101]
	s_setprio 0
	s_barrier
	s_add_i32 s52, s1, 4
	s_mov_b32 s8, s26
	s_mov_b32 s54, s52
	ds_read_b128 v[208:211], v140
	ds_read_b128 v[212:215], v140 offset:1024
	ds_read_b128 v[216:219], v140 offset:2048
	ds_read_b128 v[220:223], v140 offset:3072
	s_ashr_i32 s55, s54, 31
	s_lshl_b64 s[54:55], s[54:55], 7
	s_lshl_b32 s8, s8, 10
	v_lshl_add_u64 v[142:143], v[132:133], 0, s[54:55]
	s_add_i32 s8, s8, 0
	s_add_i32 m0, s8, 0x10000
	v_lshl_add_u64 v[192:193], v[142:143], 0, s[12:13]
	v_xor_b32_e32 v192, v197, v192
	global_load_lds_dwordx4 v[192:193], off
	v_lshl_add_u64 v[142:143], v[142:143], 0, s[38:39]
	s_add_i32 m0, s8, 0x12000
	s_nop 0
	v_xor_b32_e32 v142, v197, v142
	global_load_lds_dwordx4 v[142:143], off
	s_barrier
	s_waitcnt lgkmcnt(0)
	s_setprio 1
	s_waitcnt lgkmcnt(0)
	v_mfma_f32_16x16x32_bf16 v[94:97], v[208:211], v[162:165], v[94:97]
	v_mfma_f32_16x16x32_bf16 v[90:93], v[216:219], v[162:165], v[90:93]
	v_mfma_f32_16x16x32_bf16 v[86:89], v[208:211], v[170:173], v[86:89]
	v_mfma_f32_16x16x32_bf16 v[82:85], v[216:219], v[170:173], v[82:85]
	v_mfma_f32_16x16x32_bf16 v[78:81], v[208:211], v[184:187], v[78:81]
	v_mfma_f32_16x16x32_bf16 v[74:77], v[216:219], v[184:187], v[74:77]
	v_mfma_f32_16x16x32_bf16 v[70:73], v[208:211], v[200:203], v[70:73]
	v_mfma_f32_16x16x32_bf16 v[66:69], v[216:219], v[200:203], v[66:69]
	v_mfma_f32_16x16x32_bf16 v[94:97], v[212:215], v[166:169], v[94:97]
	v_mfma_f32_16x16x32_bf16 v[90:93], v[220:223], v[166:169], v[90:93]
	v_mfma_f32_16x16x32_bf16 v[86:89], v[212:215], v[174:177], v[86:89]
	v_mfma_f32_16x16x32_bf16 v[82:85], v[220:223], v[174:177], v[82:85]
	v_mfma_f32_16x16x32_bf16 v[78:81], v[212:215], v[188:191], v[78:81]
	v_mfma_f32_16x16x32_bf16 v[74:77], v[220:223], v[188:191], v[74:77]
	v_mfma_f32_16x16x32_bf16 v[70:73], v[212:215], v[204:207], v[70:73]
	v_mfma_f32_16x16x32_bf16 v[66:69], v[220:223], v[204:207], v[66:69]
	s_setprio 0
	s_mov_b32 s8, s26
	s_mov_b32 s54, s52
	s_barrier
; #define LDA(dst, b, h) _Pragma("unroll") for (int m = 0; m < 4; ++m) _Pragma("unroll") for (int k = 0; k < 2; ++k) \
;     dst[m][k] = *reinterpret_cast<const LAS bf16x8*>(lds + SAo(b, h) + lds_byte(wr * 64 + m * 16 + fr, k * 32 + fq * 8))
; #define LDB(dst, b, h) _Pragma("unroll") for (int n = 0; n < 2; ++n) _Pragma("unroll") for (int k = 0; k < 2; ++k) \
;     dst[n][k] = *reinterpret_cast<const LAS bf16x8*>(lds + SBo(b, h) + lds_byte(wc * 32 + n * 16 + fr, k * 32 + fq * 8))
; #define MMA(ai, bj, At_, Bt_) do { __builtin_amdgcn_s_setprio(1); \
;     _Pragma("unroll") for (int m = 0; m < 4; ++m) _Pragma("unroll") for (int n = 0; n < 2; ++n) _Pragma("unroll") for (int k = 0; k < 2; ++k) \
;       acc[ai][bj][m][n] = __builtin_amdgcn_mfma_f32_16x16x32_bf16(Bt_[n][k], At_[m][k], acc[ai][bj][m][n], 0, 0, 0); \
;     __builtin_amdgcn_s_setprio(0); } while (0)
; #define WAIT_V(n) asm volatile("s_waitcnt vmcnt(" #n ")" ::: "memory")
; #define WAIT_L(n) asm volatile("s_waitcnt lgkmcnt(" #n ")" ::: "memory")
; template <bool PRE = false>
; __device__ __forceinline__ void gemm_kloop(Acc& acc, const bf16_t* __restrict__ A, int lda, const bf16_t* __restrict__ Bt, int ldb,
;                                            int brow, int bcol, int nt, LAS unsigned char* lds) {
;     ...
;     for (int t = 0; t < nt - 2; t += 2) {
;         LDB(B0, 0, 0); SCHED; LDA(At, 0, 0); STAGE(SAo(1, 1), A, lda, brow + HALF, t + 1, offA);
;         WAIT_L(8); BAR; WAIT_L(0); MMA(0, 0, At, B0); BAR; SCHED;
;         LDB(B1, 0, 1); STAGE(SBo(0, 0), Bt, ldb, bcol, t + 2, offB);
;         BAR; WAIT_L(0); MMA(0, 1, At, B1); BAR;
;         LDA(At, 0, 1); STAGE(SAo(0, 0), A, lda, brow, t + 2, offA);
;         BAR; WAIT_L(0); MMA(1, 0, At, B0); BAR; SCHED;
;         STAGE(SBo(0, 1), Bt, ldb, bcol + HALF, t + 2, offB);
;         WAIT_V(6); BAR; MMA(1, 1, At, B1); BAR;
;         LDB(B0, 1, 0); SCHED; LDA(At, 1, 0); STAGE(SAo(0, 1), A, lda, brow + HALF, t + 2, offA);
;         WAIT_L(8); BAR; WAIT_L(0); MMA(0, 0, At, B0); BAR; SCHED;
;         LDB(B1, 1, 1); STAGE(SBo(1, 0), Bt, ldb, bcol, t + 3, offB);
;         BAR; WAIT_L(0); MMA(0, 1, At, B1); BAR;
;         LDA(At, 1, 1); STAGE(SAo(1, 0), A, lda, brow, t + 3, offA);
;         BAR; WAIT_L(0); MMA(1, 0, At, B0); BAR; SCHED;
;         STAGE(SBo(1, 1), Bt, ldb, bcol + HALF, t + 3, offB);
;         WAIT_V(6); BAR; MMA(1, 1, At, B1); BAR;
;     }
	ds_read_b128 v[162:165], v137 offset:16384
	ds_read_b128 v[166:169], v137 offset:17408
	ds_read_b128 v[170:173], v136 offset:16384
	ds_read_b128 v[174:177], v136 offset:17408
	ds_read_b128 v[184:187], v135 offset:16384
	ds_read_b128 v[188:191], v135 offset:17408
	ds_read_b128 v[200:203], v134 offset:16384
	ds_read_b128 v[204:207], v134 offset:17408
	s_ashr_i32 s55, s54, 31
	s_lshl_b64 s[54:55], s[54:55], 7
	s_lshl_b32 s8, s8, 10
	v_lshl_add_u64 v[142:143], v[130:131], 0, s[54:55]
	s_add_i32 s8, s8, 0
	v_lshl_add_u64 v[192:193], v[142:143], 0, s[40:41]
	s_mov_b32 m0, s8
	v_lshl_add_u64 v[142:143], v[142:143], 0, s[42:43]
	v_xor_b32_e32 v192, v197, v192
	global_load_lds_dwordx4 v[192:193], off
	s_add_i32 m0, s8, 0x2000
	s_nop 0
	v_xor_b32_e32 v142, v197, v142
	global_load_lds_dwordx4 v[142:143], off
	s_barrier
	s_waitcnt lgkmcnt(0)
	s_setprio 1
	s_waitcnt lgkmcnt(0)
	v_mfma_f32_16x16x32_bf16 v[62:65], v[146:149], v[162:165], v[62:65]
	v_mfma_f32_16x16x32_bf16 v[58:61], v[154:157], v[162:165], v[58:61]
	v_mfma_f32_16x16x32_bf16 v[54:57], v[146:149], v[170:173], v[54:57]
	v_mfma_f32_16x16x32_bf16 v[50:53], v[154:157], v[170:173], v[50:53]
	v_mfma_f32_16x16x32_bf16 v[46:49], v[146:149], v[184:187], v[46:49]
	v_mfma_f32_16x16x32_bf16 v[42:45], v[154:157], v[184:187], v[42:45]
	v_mfma_f32_16x16x32_bf16 v[38:41], v[146:149], v[200:203], v[38:41]
	v_mfma_f32_16x16x32_bf16 v[34:37], v[154:157], v[200:203], v[34:37]
	v_mfma_f32_16x16x32_bf16 v[62:65], v[150:153], v[166:169], v[62:65]
	v_mfma_f32_16x16x32_bf16 v[58:61], v[158:161], v[166:169], v[58:61]
	v_mfma_f32_16x16x32_bf16 v[54:57], v[150:153], v[174:177], v[54:57]
	v_mfma_f32_16x16x32_bf16 v[50:53], v[158:161], v[174:177], v[50:53]
	v_mfma_f32_16x16x32_bf16 v[46:49], v[150:153], v[188:191], v[46:49]
	v_mfma_f32_16x16x32_bf16 v[42:45], v[158:161], v[188:191], v[42:45]
	v_mfma_f32_16x16x32_bf16 v[38:41], v[150:153], v[204:207], v[38:41]
	v_mfma_f32_16x16x32_bf16 v[34:37], v[158:161], v[204:207], v[34:37]
	s_setprio 0
	s_barrier
	s_mov_b32 s8, s26
	s_mov_b32 s54, s52
	s_ashr_i32 s55, s54, 31
	s_lshl_b64 s[54:55], s[54:55], 7
	s_lshl_b32 s8, s8, 10
	v_lshl_add_u64 v[142:143], v[132:133], 0, s[54:55]
	s_add_i32 s8, s8, 0
	s_add_i32 m0, s8, 0x14000
	v_lshl_add_u64 v[146:147], v[142:143], 0, s[44:45]
	v_xor_b32_e32 v146, v197, v146
	global_load_lds_dwordx4 v[146:147], off
	v_lshl_add_u64 v[142:143], v[142:143], 0, s[46:47]
	s_add_i32 m0, s8, 0x16000
	s_nop 0
	v_xor_b32_e32 v142, v197, v142
	global_load_lds_dwordx4 v[142:143], off
	s_waitcnt vmcnt(6)
	s_barrier
	s_setprio 1
	v_mfma_f32_16x16x32_bf16 v[30:33], v[208:211], v[162:165], v[30:33]
	v_mfma_f32_16x16x32_bf16 v[26:29], v[216:219], v[162:165], v[26:29]
	v_mfma_f32_16x16x32_bf16 v[22:25], v[208:211], v[170:173], v[22:25]
	v_mfma_f32_16x16x32_bf16 v[18:21], v[216:219], v[170:173], v[18:21]
	v_mfma_f32_16x16x32_bf16 v[14:17], v[208:211], v[184:187], v[14:17]
	v_mfma_f32_16x16x32_bf16 v[10:13], v[216:219], v[184:187], v[10:13]
	v_mfma_f32_16x16x32_bf16 v[6:9], v[208:211], v[200:203], v[6:9]
	v_mfma_f32_16x16x32_bf16 v[2:5], v[216:219], v[200:203], v[2:5]
	v_mfma_f32_16x16x32_bf16 v[30:33], v[212:215], v[166:169], v[30:33]
	v_mfma_f32_16x16x32_bf16 v[26:29], v[220:223], v[166:169], v[26:29]
	v_mfma_f32_16x16x32_bf16 v[22:25], v[212:215], v[174:177], v[22:25]
	v_mfma_f32_16x16x32_bf16 v[18:21], v[220:223], v[174:177], v[18:21]
	v_mfma_f32_16x16x32_bf16 v[14:17], v[212:215], v[188:191], v[14:17]
	v_mfma_f32_16x16x32_bf16 v[10:13], v[220:223], v[188:191], v[10:13]
	v_mfma_f32_16x16x32_bf16 v[6:9], v[212:215], v[204:207], v[6:9]
	v_mfma_f32_16x16x32_bf16 v[2:5], v[220:223], v[204:207], v[2:5]
	s_setprio 0
	s_barrier
	ds_read_b128 v[146:149], v139
	ds_read_b128 v[150:153], v139 offset:1024
	ds_read_b128 v[154:157], v139 offset:2048
	ds_read_b128 v[158:161], v139 offset:3072
	s_mov_b32 s8, s26
	ds_read_b128 v[162:165], v137 offset:32768
	ds_read_b128 v[166:169], v137 offset:33792
	ds_read_b128 v[170:173], v136 offset:32768
	ds_read_b128 v[174:177], v136 offset:33792
	ds_read_b128 v[184:187], v135 offset:32768
	ds_read_b128 v[188:191], v135 offset:33792
	ds_read_b128 v[200:203], v134 offset:32768
	ds_read_b128 v[204:207], v134 offset:33792
	s_ashr_i32 s53, s52, 31
	s_lshl_b64 s[52:53], s[52:53], 7
	s_lshl_b32 s8, s8, 10
	v_lshl_add_u64 v[142:143], v[130:131], 0, s[52:53]
	s_add_i32 s8, s8, 0
	s_add_i32 m0, s8, 0x4000
	v_lshl_add_u64 v[192:193], v[142:143], 0, s[48:49]
	v_xor_b32_e32 v192, v197, v192
	global_load_lds_dwordx4 v[192:193], off
	v_lshl_add_u64 v[142:143], v[142:143], 0, s[50:51]
	s_add_i32 m0, s8, 0x6000
	s_nop 0
	v_xor_b32_e32 v142, v197, v142
	global_load_lds_dwordx4 v[142:143], off
	s_waitcnt lgkmcnt(8)
	s_barrier
	s_waitcnt lgkmcnt(0)
	s_setprio 1
	s_waitcnt lgkmcnt(0)
	v_mfma_f32_16x16x32_bf16 v[126:129], v[146:149], v[162:165], v[126:129]
	v_mfma_f32_16x16x32_bf16 v[122:125], v[154:157], v[162:165], v[122:125]
	v_mfma_f32_16x16x32_bf16 v[118:121], v[146:149], v[170:173], v[118:121]
	v_mfma_f32_16x16x32_bf16 v[114:117], v[154:157], v[170:173], v[114:117]
	v_mfma_f32_16x16x32_bf16 v[110:113], v[146:149], v[184:187], v[110:113]
	v_mfma_f32_16x16x32_bf16 v[106:109], v[154:157], v[184:187], v[106:109]
	v_mfma_f32_16x16x32_bf16 v[102:105], v[146:149], v[200:203], v[102:105]
	v_mfma_f32_16x16x32_bf16 v[98:101], v[154:157], v[200:203], v[98:101]
	v_mfma_f32_16x16x32_bf16 v[126:129], v[150:153], v[166:169], v[126:129]
	v_mfma_f32_16x16x32_bf16 v[122:125], v[158:161], v[166:169], v[122:125]
	v_mfma_f32_16x16x32_bf16 v[118:121], v[150:153], v[174:177], v[118:121]
	v_mfma_f32_16x16x32_bf16 v[114:117], v[158:161], v[174:177], v[114:117]
	v_mfma_f32_16x16x32_bf16 v[110:113], v[150:153], v[188:191], v[110:113]
	v_mfma_f32_16x16x32_bf16 v[106:109], v[158:161], v[188:191], v[106:109]
	v_mfma_f32_16x16x32_bf16 v[102:105], v[150:153], v[204:207], v[102:105]
	v_mfma_f32_16x16x32_bf16 v[98:101], v[158:161], v[204:207], v[98:101]
	s_setprio 0
	s_barrier
; #define LDA(dst, b, h) _Pragma("unroll") for (int m = 0; m < 4; ++m) _Pragma("unroll") for (int k = 0; k < 2; ++k) \
;     dst[m][k] = *reinterpret_cast<const LAS bf16x8*>(lds + SAo(b, h) + lds_byte(wr * 64 + m * 16 + fr, k * 32 + fq * 8))
; #define LDB(dst, b, h) _Pragma("unroll") for (int n = 0; n < 2; ++n) _Pragma("unroll") for (int k = 0; k < 2; ++k) \
;     dst[n][k] = *reinterpret_cast<const LAS bf16x8*>(lds + SBo(b, h) + lds_byte(wc * 32 + n * 16 + fr, k * 32 + fq * 8))
; #define MMA(ai, bj, At_, Bt_) do { __builtin_amdgcn_s_setprio(1); \
;     _Pragma("unroll") for (int m = 0; m < 4; ++m) _Pragma("unroll") for (int n = 0; n < 2; ++n) _Pragma("unroll") for (int k = 0; k < 2; ++k) \
;       acc[ai][bj][m][n] = __builtin_amdgcn_mfma_f32_16x16x32_bf16(Bt_[n][k], At_[m][k], acc[ai][bj][m][n], 0, 0, 0); \
;     __builtin_amdgcn_s_setprio(0); } while (0)
; #define WAIT_V(n) asm volatile("s_waitcnt vmcnt(" #n ")" ::: "memory")
; #define WAIT_L(n) asm volatile("s_waitcnt lgkmcnt(" #n ")" ::: "memory")
; template <bool PRE = false>
; __device__ __forceinline__ void gemm_kloop(Acc& acc, const bf16_t* __restrict__ A, int lda, const bf16_t* __restrict__ Bt, int ldb,
;                                            int brow, int bcol, int nt, LAS unsigned char* lds) {
;     ...
;     for (int t = 0; t < nt - 2; t += 2) {
;         LDB(B0, 0, 0); SCHED; LDA(At, 0, 0); STAGE(SAo(1, 1), A, lda, brow + HALF, t + 1, offA);
;         WAIT_L(8); BAR; WAIT_L(0); MMA(0, 0, At, B0); BAR; SCHED;
;         LDB(B1, 0, 1); STAGE(SBo(0, 0), Bt, ldb, bcol, t + 2, offB);
;         BAR; WAIT_L(0); MMA(0, 1, At, B1); BAR;
;         LDA(At, 0, 1); STAGE(SAo(0, 0), A, lda, brow, t + 2, offA);
;         BAR; WAIT_L(0); MMA(1, 0, At, B0); BAR; SCHED;
;         STAGE(SBo(0, 1), Bt, ldb, bcol + HALF, t + 2, offB);
;         WAIT_V(6); BAR; MMA(1, 1, At, B1); BAR;
;         LDB(B0, 1, 0); SCHED; LDA(At, 1, 0); STAGE(SAo(0, 1), A, lda, brow + HALF, t + 2, offA);
;         WAIT_L(8); BAR; WAIT_L(0); MMA(0, 0, At, B0); BAR; SCHED;
;         LDB(B1, 1, 1); STAGE(SBo(1, 0), Bt, ldb, bcol, t + 3, offB);
;         BAR; WAIT_L(0); MMA(0, 1, At, B1); BAR;
;         LDA(At, 1, 1); STAGE(SAo(1, 0), A, lda, brow, t + 3, offA);
;         BAR; WAIT_L(0); MMA(1, 0, At, B0); BAR; SCHED;
;         STAGE(SBo(1, 1), Bt, ldb, bcol + HALF, t + 3, offB);
;         WAIT_V(6); BAR; MMA(1, 1, At, B1); BAR;
;     }
	s_add_i32 s52, s1, 5
	s_mov_b32 s8, s26
	s_mov_b32 s54, s52
	ds_read_b128 v[208:211], v138
	ds_read_b128 v[212:215], v138 offset:1024
	ds_read_b128 v[216:219], v138 offset:2048
	ds_read_b128 v[220:223], v138 offset:3072
	s_ashr_i32 s55, s54, 31
	s_lshl_b64 s[54:55], s[54:55], 7
	s_lshl_b32 s8, s8, 10
	v_lshl_add_u64 v[142:143], v[132:133], 0, s[54:55]
	s_add_i32 s8, s8, 0
	s_add_i32 m0, s8, 0x18000
	v_lshl_add_u64 v[192:193], v[142:143], 0, s[12:13]
	v_xor_b32_e32 v192, v197, v192
	global_load_lds_dwordx4 v[192:193], off
	v_lshl_add_u64 v[142:143], v[142:143], 0, s[38:39]
	s_add_i32 m0, s8, 0x1a000
	s_nop 0
	v_xor_b32_e32 v142, v197, v142
	global_load_lds_dwordx4 v[142:143], off
	s_barrier
	s_waitcnt lgkmcnt(0)
	s_setprio 1
	s_waitcnt lgkmcnt(0)
	v_mfma_f32_16x16x32_bf16 v[94:97], v[208:211], v[162:165], v[94:97]
	v_mfma_f32_16x16x32_bf16 v[90:93], v[216:219], v[162:165], v[90:93]
	v_mfma_f32_16x16x32_bf16 v[86:89], v[208:211], v[170:173], v[86:89]
	v_mfma_f32_16x16x32_bf16 v[82:85], v[216:219], v[170:173], v[82:85]
	v_mfma_f32_16x16x32_bf16 v[78:81], v[208:211], v[184:187], v[78:81]
	v_mfma_f32_16x16x32_bf16 v[74:77], v[216:219], v[184:187], v[74:77]
	v_mfma_f32_16x16x32_bf16 v[70:73], v[208:211], v[200:203], v[70:73]
	v_mfma_f32_16x16x32_bf16 v[66:69], v[216:219], v[200:203], v[66:69]
	v_mfma_f32_16x16x32_bf16 v[94:97], v[212:215], v[166:169], v[94:97]
	v_mfma_f32_16x16x32_bf16 v[90:93], v[220:223], v[166:169], v[90:93]
	v_mfma_f32_16x16x32_bf16 v[86:89], v[212:215], v[174:177], v[86:89]
	v_mfma_f32_16x16x32_bf16 v[82:85], v[220:223], v[174:177], v[82:85]
	v_mfma_f32_16x16x32_bf16 v[78:81], v[212:215], v[188:191], v[78:81]
	v_mfma_f32_16x16x32_bf16 v[74:77], v[220:223], v[188:191], v[74:77]
	v_mfma_f32_16x16x32_bf16 v[70:73], v[212:215], v[204:207], v[70:73]
	v_mfma_f32_16x16x32_bf16 v[66:69], v[220:223], v[204:207], v[66:69]
	s_setprio 0
	s_mov_b32 s8, s26
	s_mov_b32 s54, s52
	s_barrier
	ds_read_b128 v[162:165], v137 offset:49152
	ds_read_b128 v[166:169], v137 offset:50176
	ds_read_b128 v[170:173], v136 offset:49152
	ds_read_b128 v[174:177], v136 offset:50176
	ds_read_b128 v[184:187], v135 offset:49152
	ds_read_b128 v[188:191], v135 offset:50176
	ds_read_b128 v[200:203], v134 offset:49152
	ds_read_b128 v[204:207], v134 offset:50176
	s_ashr_i32 s55, s54, 31
	s_lshl_b64 s[54:55], s[54:55], 7
	s_lshl_b32 s8, s8, 10
	v_lshl_add_u64 v[142:143], v[130:131], 0, s[54:55]
	s_add_i32 s8, s8, 0
	s_add_i32 m0, s8, 0x8000
	v_lshl_add_u64 v[192:193], v[142:143], 0, s[40:41]
	v_xor_b32_e32 v192, v197, v192
	global_load_lds_dwordx4 v[192:193], off
	v_lshl_add_u64 v[142:143], v[142:143], 0, s[42:43]
	s_add_i32 m0, s8, 0xa000
	s_nop 0
	v_xor_b32_e32 v142, v197, v142
	global_load_lds_dwordx4 v[142:143], off
	s_barrier
	s_waitcnt lgkmcnt(0)
	s_setprio 1
	s_waitcnt lgkmcnt(0)
	v_mfma_f32_16x16x32_bf16 v[62:65], v[146:149], v[162:165], v[62:65]
	v_mfma_f32_16x16x32_bf16 v[58:61], v[154:157], v[162:165], v[58:61]
	v_mfma_f32_16x16x32_bf16 v[54:57], v[146:149], v[170:173], v[54:57]
	v_mfma_f32_16x16x32_bf16 v[50:53], v[154:157], v[170:173], v[50:53]
	v_mfma_f32_16x16x32_bf16 v[46:49], v[146:149], v[184:187], v[46:49]
	v_mfma_f32_16x16x32_bf16 v[42:45], v[154:157], v[184:187], v[42:45]
	v_mfma_f32_16x16x32_bf16 v[38:41], v[146:149], v[200:203], v[38:41]
	v_mfma_f32_16x16x32_bf16 v[34:37], v[154:157], v[200:203], v[34:37]
	v_mfma_f32_16x16x32_bf16 v[62:65], v[150:153], v[166:169], v[62:65]
	v_mfma_f32_16x16x32_bf16 v[58:61], v[158:161], v[166:169], v[58:61]
	v_mfma_f32_16x16x32_bf16 v[54:57], v[150:153], v[174:177], v[54:57]
	v_mfma_f32_16x16x32_bf16 v[50:53], v[158:161], v[174:177], v[50:53]
	v_mfma_f32_16x16x32_bf16 v[46:49], v[150:153], v[188:191], v[46:49]
	v_mfma_f32_16x16x32_bf16 v[42:45], v[158:161], v[188:191], v[42:45]
	v_mfma_f32_16x16x32_bf16 v[38:41], v[150:153], v[204:207], v[38:41]
	v_mfma_f32_16x16x32_bf16 v[34:37], v[158:161], v[204:207], v[34:37]
	s_setprio 0
	s_barrier
	s_mov_b32 s8, s26
	s_ashr_i32 s53, s52, 31
	s_lshl_b64 s[52:53], s[52:53], 7
	s_lshl_b32 s8, s8, 10
	v_lshl_add_u64 v[142:143], v[132:133], 0, s[52:53]
	s_add_i32 s8, s8, 0
	s_add_i32 m0, s8, 0x1c000
	v_lshl_add_u64 v[146:147], v[142:143], 0, s[44:45]
	v_xor_b32_e32 v146, v197, v146
	global_load_lds_dwordx4 v[146:147], off
	v_lshl_add_u64 v[142:143], v[142:143], 0, s[46:47]
	s_add_i32 m0, s8, 0x1e000
	s_nop 0
	v_xor_b32_e32 v142, v197, v142
	global_load_lds_dwordx4 v[142:143], off
	s_waitcnt vmcnt(6)
	s_barrier
	s_setprio 1
	v_mfma_f32_16x16x32_bf16 v[30:33], v[208:211], v[162:165], v[30:33]
	v_mfma_f32_16x16x32_bf16 v[26:29], v[216:219], v[162:165], v[26:29]
	v_mfma_f32_16x16x32_bf16 v[22:25], v[208:211], v[170:173], v[22:25]
	v_mfma_f32_16x16x32_bf16 v[18:21], v[216:219], v[170:173], v[18:21]
	v_mfma_f32_16x16x32_bf16 v[14:17], v[208:211], v[184:187], v[14:17]
	v_mfma_f32_16x16x32_bf16 v[10:13], v[216:219], v[184:187], v[10:13]
	v_mfma_f32_16x16x32_bf16 v[6:9], v[208:211], v[200:203], v[6:9]
	v_mfma_f32_16x16x32_bf16 v[2:5], v[216:219], v[200:203], v[2:5]
	v_mfma_f32_16x16x32_bf16 v[30:33], v[212:215], v[166:169], v[30:33]
	v_mfma_f32_16x16x32_bf16 v[26:29], v[220:223], v[166:169], v[26:29]
	v_mfma_f32_16x16x32_bf16 v[22:25], v[212:215], v[174:177], v[22:25]
	v_mfma_f32_16x16x32_bf16 v[18:21], v[220:223], v[174:177], v[18:21]
	v_mfma_f32_16x16x32_bf16 v[14:17], v[212:215], v[188:191], v[14:17]
	v_mfma_f32_16x16x32_bf16 v[10:13], v[220:223], v[188:191], v[10:13]
	v_mfma_f32_16x16x32_bf16 v[6:9], v[212:215], v[204:207], v[6:9]
	v_mfma_f32_16x16x32_bf16 v[2:5], v[220:223], v[204:207], v[2:5]
	s_setprio 0
	s_add_i32 s1, s1, 2
	s_cmp_lt_u32 s1, 12
	s_barrier
	s_cbranch_scc1 .LBB0_748
; #define LDA(dst, b, h) _Pragma("unroll") for (int m = 0; m < 4; ++m) _Pragma("unroll") for (int k = 0; k < 2; ++k) \
;     dst[m][k] = *reinterpret_cast<const LAS bf16x8*>(lds + SAo(b, h) + lds_byte(wr * 64 + m * 16 + fr, k * 32 + fq * 8))
; #define LDB(dst, b, h) _Pragma("unroll") for (int n = 0; n < 2; ++n) _Pragma("unroll") for (int k = 0; k < 2; ++k) \
;     dst[n][k] = *reinterpret_cast<const LAS bf16x8*>(lds + SBo(b, h) + lds_byte(wc * 32 + n * 16 + fr, k * 32 + fq * 8))
; #define MMA(ai, bj, At_, Bt_) do { __builtin_amdgcn_s_setprio(1); \
;     _Pragma("unroll") for (int m = 0; m < 4; ++m) _Pragma("unroll") for (int n = 0; n < 2; ++n) _Pragma("unroll") for (int k = 0; k < 2; ++k) \
;       acc[ai][bj][m][n] = __builtin_amdgcn_mfma_f32_16x16x32_bf16(Bt_[n][k], At_[m][k], acc[ai][bj][m][n], 0, 0, 0); \
;     __builtin_amdgcn_s_setprio(0); } while (0)
; #define WAIT_V(n) asm volatile("s_waitcnt vmcnt(" #n ")" ::: "memory")
; #define WAIT_L(n) asm volatile("s_waitcnt lgkmcnt(" #n ")" ::: "memory")
; #define BAR __builtin_amdgcn_s_barrier()
; template <bool PRE = false>
; __device__ __forceinline__ void gemm_kloop(Acc& acc, const bf16_t* __restrict__ A, int lda, const bf16_t* __restrict__ Bt, int ldb,
;                                            int brow, int bcol, int nt, LAS unsigned char* lds) {
;     ...
;     { LDB(B0, 0, 0); LDA(At, 0, 0); STAGE(SAo(1, 1), A, lda, brow + HALF, nt - 1, offA);
;       BAR; WAIT_L(0); MMA(0, 0, At, B0); BAR;
;       LDB(B1, 0, 1); BAR; WAIT_L(0); MMA(0, 1, At, B1); BAR;
;       LDA(At, 0, 1); WAIT_V(4); BAR; WAIT_L(0); MMA(1, 0, At, B0); MMA(1, 1, At, B1); BAR; }
	s_mov_b32 s12, 15
	ds_read_b128 v[130:133], v141
	ds_read_b128 v[146:149], v141 offset:1024
	ds_read_b128 v[150:153], v141 offset:2048
	ds_read_b128 v[154:157], v141 offset:3072
	ds_read_b128 v[158:161], v137
	ds_read_b128 v[162:165], v137 offset:1024
	ds_read_b128 v[166:169], v136
	ds_read_b128 v[170:173], v136 offset:1024
	ds_read_b128 v[174:177], v135
	ds_read_b128 v[184:187], v135 offset:1024
	ds_read_b128 v[188:191], v134
	ds_read_b128 v[200:203], v134 offset:1024
	s_ashr_i32 s13, s12, 31
	s_lshl_b64 s[12:13], s[12:13], 7
	s_add_u32 s12, s34, s12
	s_addc_u32 s13, s35, s13
	s_lshl_b32 s1, s26, 10
	v_lshl_add_u64 v[142:143], s[12:13], 0, v[144:145]
	s_add_i32 s1, s1, 0
	s_add_i32 m0, s1, 0xc000
	v_lshl_add_u64 v[192:193], v[142:143], 0, s[48:49]
	v_xor_b32_e32 v192, v197, v192
	global_load_lds_dwordx4 v[192:193], off
	v_lshl_add_u64 v[142:143], v[142:143], 0, s[50:51]
	s_add_i32 m0, s1, 0xe000
	s_nop 0
	v_xor_b32_e32 v142, v197, v142
	global_load_lds_dwordx4 v[142:143], off
	s_barrier
	s_waitcnt lgkmcnt(0)
	s_setprio 1
	s_waitcnt lgkmcnt(0)
	v_mfma_f32_16x16x32_bf16 v[126:129], v[130:133], v[158:161], v[126:129]
	v_mfma_f32_16x16x32_bf16 v[122:125], v[150:153], v[158:161], v[122:125]
	v_mfma_f32_16x16x32_bf16 v[118:121], v[130:133], v[166:169], v[118:121]
	v_mfma_f32_16x16x32_bf16 v[114:117], v[150:153], v[166:169], v[114:117]
	v_mfma_f32_16x16x32_bf16 v[102:105], v[130:133], v[188:191], v[102:105]
	v_mfma_f32_16x16x32_bf16 v[98:101], v[150:153], v[188:191], v[98:101]
	v_mfma_f32_16x16x32_bf16 v[126:129], v[146:149], v[162:165], v[126:129]
	v_mfma_f32_16x16x32_bf16 v[122:125], v[154:157], v[162:165], v[122:125]
	v_mfma_f32_16x16x32_bf16 v[118:121], v[146:149], v[170:173], v[118:121]
	v_mfma_f32_16x16x32_bf16 v[114:117], v[154:157], v[170:173], v[114:117]
	v_mfma_f32_16x16x32_bf16 v[110:113], v[130:133], v[174:177], v[110:113]
	v_mfma_f32_16x16x32_bf16 v[106:109], v[150:153], v[174:177], v[106:109]
	v_mfma_f32_16x16x32_bf16 v[102:105], v[146:149], v[200:203], v[102:105]
	v_mfma_f32_16x16x32_bf16 v[98:101], v[154:157], v[200:203], v[98:101]
	v_mfma_f32_16x16x32_bf16 v[204:207], v[146:149], v[184:187], v[110:113]
	v_mfma_f32_16x16x32_bf16 v[208:211], v[154:157], v[184:187], v[106:109]
	s_setprio 0
	s_barrier
	s_nop 1
	ds_read_b128 v[106:109], v140
	ds_read_b128 v[110:113], v140 offset:1024
	ds_read_b128 v[212:215], v140 offset:2048
	ds_read_b128 v[140:143], v140 offset:3072
	s_barrier
	s_waitcnt lgkmcnt(0)
	s_setprio 1
	s_waitcnt lgkmcnt(0)
	v_mfma_f32_16x16x32_bf16 v[86:89], v[106:109], v[166:169], v[86:89]
	v_mfma_f32_16x16x32_bf16 v[82:85], v[212:215], v[166:169], v[82:85]
	v_mfma_f32_16x16x32_bf16 v[70:73], v[106:109], v[188:191], v[70:73]
	v_mfma_f32_16x16x32_bf16 v[66:69], v[212:215], v[188:191], v[66:69]
	v_mfma_f32_16x16x32_bf16 v[94:97], v[106:109], v[158:161], v[94:97]
	v_mfma_f32_16x16x32_bf16 v[90:93], v[212:215], v[158:161], v[90:93]
	v_mfma_f32_16x16x32_bf16 v[86:89], v[110:113], v[170:173], v[86:89]
	v_mfma_f32_16x16x32_bf16 v[82:85], v[140:143], v[170:173], v[82:85]
	v_mfma_f32_16x16x32_bf16 v[78:81], v[106:109], v[174:177], v[78:81]
	v_mfma_f32_16x16x32_bf16 v[74:77], v[212:215], v[174:177], v[74:77]
	v_mfma_f32_16x16x32_bf16 v[70:73], v[110:113], v[200:203], v[70:73]
	v_mfma_f32_16x16x32_bf16 v[66:69], v[140:143], v[200:203], v[66:69]
	v_mfma_f32_16x16x32_bf16 v[216:219], v[110:113], v[162:165], v[94:97]
	v_mfma_f32_16x16x32_bf16 v[158:161], v[140:143], v[162:165], v[90:93]
	v_mfma_f32_16x16x32_bf16 v[162:165], v[110:113], v[184:187], v[78:81]
	v_mfma_f32_16x16x32_bf16 v[166:169], v[140:143], v[184:187], v[74:77]
	s_setprio 0
	s_barrier
	s_nop 0
	ds_read_b128 v[74:77], v137 offset:16384
	ds_read_b128 v[78:81], v137 offset:17408
	ds_read_b128 v[90:93], v136 offset:16384
	ds_read_b128 v[94:97], v136 offset:17408
	ds_read_b128 v[170:173], v135 offset:16384
	ds_read_b128 v[174:177], v135 offset:17408
	ds_read_b128 v[184:187], v134 offset:16384
	ds_read_b128 v[188:191], v134 offset:17408
	s_waitcnt vmcnt(4)
	s_barrier
	s_waitcnt lgkmcnt(0)
	s_setprio 1
	s_waitcnt lgkmcnt(0)
	v_mfma_f32_16x16x32_bf16 v[62:65], v[130:133], v[74:77], v[62:65]
	v_mfma_f32_16x16x32_bf16 v[58:61], v[150:153], v[74:77], v[58:61]
	v_mfma_f32_16x16x32_bf16 v[54:57], v[130:133], v[90:93], v[54:57]
	v_mfma_f32_16x16x32_bf16 v[50:53], v[150:153], v[90:93], v[50:53]
	v_mfma_f32_16x16x32_bf16 v[38:41], v[130:133], v[184:187], v[38:41]
	v_mfma_f32_16x16x32_bf16 v[34:37], v[150:153], v[184:187], v[34:37]
	v_mfma_f32_16x16x32_bf16 v[62:65], v[146:149], v[78:81], v[62:65]
	v_mfma_f32_16x16x32_bf16 v[58:61], v[154:157], v[78:81], v[58:61]
	v_mfma_f32_16x16x32_bf16 v[54:57], v[146:149], v[94:97], v[54:57]
	v_mfma_f32_16x16x32_bf16 v[50:53], v[154:157], v[94:97], v[50:53]
	v_mfma_f32_16x16x32_bf16 v[46:49], v[130:133], v[170:173], v[46:49]
	v_mfma_f32_16x16x32_bf16 v[42:45], v[150:153], v[170:173], v[42:45]
	v_mfma_f32_16x16x32_bf16 v[38:41], v[146:149], v[188:191], v[38:41]
	v_mfma_f32_16x16x32_bf16 v[34:37], v[154:157], v[188:191], v[34:37]
	v_mfma_f32_16x16x32_bf16 v[200:203], v[146:149], v[174:177], v[46:49]
	v_mfma_f32_16x16x32_bf16 v[220:223], v[154:157], v[174:177], v[42:45]
	s_setprio 0
	s_setprio 1
	v_mfma_f32_16x16x32_bf16 v[22:25], v[106:109], v[90:93], v[22:25]
	v_mfma_f32_16x16x32_bf16 v[18:21], v[212:215], v[90:93], v[18:21]
	v_mfma_f32_16x16x32_bf16 v[6:9], v[106:109], v[184:187], v[6:9]
	v_mfma_f32_16x16x32_bf16 v[2:5], v[212:215], v[184:187], v[2:5]
	v_mfma_f32_16x16x32_bf16 v[30:33], v[106:109], v[74:77], v[30:33]
	v_mfma_f32_16x16x32_bf16 v[26:29], v[212:215], v[74:77], v[26:29]
	v_mfma_f32_16x16x32_bf16 v[22:25], v[110:113], v[94:97], v[22:25]
	v_mfma_f32_16x16x32_bf16 v[18:21], v[140:143], v[94:97], v[18:21]
	v_mfma_f32_16x16x32_bf16 v[14:17], v[106:109], v[170:173], v[14:17]
	v_mfma_f32_16x16x32_bf16 v[10:13], v[212:215], v[170:173], v[10:13]
	v_mfma_f32_16x16x32_bf16 v[6:9], v[110:113], v[188:191], v[6:9]
	v_mfma_f32_16x16x32_bf16 v[2:5], v[140:143], v[188:191], v[2:5]
	v_mfma_f32_16x16x32_bf16 v[130:133], v[110:113], v[78:81], v[30:33]
	v_mfma_f32_16x16x32_bf16 v[146:149], v[140:143], v[78:81], v[26:29]
	v_mfma_f32_16x16x32_bf16 v[150:153], v[110:113], v[174:177], v[14:17]
	v_mfma_f32_16x16x32_bf16 v[154:157], v[140:143], v[174:177], v[10:13]
	s_setprio 0
	s_barrier
; #define LDA(dst, b, h) _Pragma("unroll") for (int m = 0; m < 4; ++m) _Pragma("unroll") for (int k = 0; k < 2; ++k) \
;     dst[m][k] = *reinterpret_cast<const LAS bf16x8*>(lds + SAo(b, h) + lds_byte(wr * 64 + m * 16 + fr, k * 32 + fq * 8))
; #define LDB(dst, b, h) _Pragma("unroll") for (int n = 0; n < 2; ++n) _Pragma("unroll") for (int k = 0; k < 2; ++k) \
;     dst[n][k] = *reinterpret_cast<const LAS bf16x8*>(lds + SBo(b, h) + lds_byte(wc * 32 + n * 16 + fr, k * 32 + fq * 8))
; #define MMA(ai, bj, At_, Bt_) do { __builtin_amdgcn_s_setprio(1); \
;     _Pragma("unroll") for (int m = 0; m < 4; ++m) _Pragma("unroll") for (int n = 0; n < 2; ++n) _Pragma("unroll") for (int k = 0; k < 2; ++k) \
;       acc[ai][bj][m][n] = __builtin_amdgcn_mfma_f32_16x16x32_bf16(Bt_[n][k], At_[m][k], acc[ai][bj][m][n], 0, 0, 0); \
;     __builtin_amdgcn_s_setprio(0); } while (0)
; #define WAIT_V(n) asm volatile("s_waitcnt vmcnt(" #n ")" ::: "memory")
; #define WAIT_L(n) asm volatile("s_waitcnt lgkmcnt(" #n ")" ::: "memory")
; #define BAR __builtin_amdgcn_s_barrier()
; template <bool PRE = false>
; __device__ __forceinline__ void gemm_kloop(Acc& acc, const bf16_t* __restrict__ A, int lda, const bf16_t* __restrict__ Bt, int ldb,
;                                            int brow, int bcol, int nt, LAS unsigned char* lds) {
;     ...
;       LDA(At, 0, 1); WAIT_V(4); BAR; WAIT_L(0); MMA(1, 0, At, B0); MMA(1, 1, At, B1); BAR; }
;     { LDB(B0, 1, 0); LDA(At, 1, 0); WAIT_V(2); BAR; WAIT_L(0); MMA(0, 0, At, B0); BAR;
;       LDB(B1, 1, 1); WAIT_V(0); BAR; WAIT_L(0); MMA(0, 1, At, B1); BAR;
;       LDA(At, 1, 1); BAR; WAIT_L(0); MMA(1, 0, At, B0); MMA(1, 1, At, B1); BAR; }
;     if (wr == 0) BAR;
	s_nop 0
	ds_read_b128 v[10:13], v139
	ds_read_b128 v[14:17], v139 offset:1024
	ds_read_b128 v[140:143], v139 offset:2048
	ds_read_b128 v[170:173], v139 offset:3072
	ds_read_b128 v[26:29], v137 offset:32768
	ds_read_b128 v[30:33], v137 offset:33792
	ds_read_b128 v[42:45], v136 offset:32768
	ds_read_b128 v[46:49], v136 offset:33792
	ds_read_b128 v[174:177], v135 offset:32768
	ds_read_b128 v[184:187], v135 offset:33792
	ds_read_b128 v[188:191], v134 offset:32768
	ds_read_b128 v[212:215], v134 offset:33792
	s_waitcnt vmcnt(2)
	s_barrier
	s_waitcnt lgkmcnt(0)
	s_setprio 1
	s_waitcnt lgkmcnt(0)
	v_mfma_f32_16x16x32_bf16 v[74:77], v[10:13], v[26:29], v[126:129]
	v_mfma_f32_16x16x32_bf16 v[126:129], v[14:17], v[30:33], v[74:77]
	v_mfma_f32_16x16x32_bf16 v[74:77], v[140:143], v[26:29], v[122:125]
	v_mfma_f32_16x16x32_bf16 v[122:125], v[170:173], v[30:33], v[74:77]
	v_mfma_f32_16x16x32_bf16 v[74:77], v[10:13], v[42:45], v[118:121]
	v_mfma_f32_16x16x32_bf16 v[110:113], v[14:17], v[46:49], v[74:77]
	v_mfma_f32_16x16x32_bf16 v[74:77], v[140:143], v[42:45], v[114:117]
	v_mfma_f32_16x16x32_bf16 v[106:109], v[170:173], v[46:49], v[74:77]
	v_mfma_f32_16x16x32_bf16 v[74:77], v[10:13], v[174:177], v[204:207]
	v_mfma_f32_16x16x32_bf16 v[94:97], v[14:17], v[184:187], v[74:77]
	v_mfma_f32_16x16x32_bf16 v[74:77], v[140:143], v[174:177], v[208:211]
	v_mfma_f32_16x16x32_bf16 v[90:93], v[170:173], v[184:187], v[74:77]
	v_mfma_f32_16x16x32_bf16 v[74:77], v[10:13], v[188:191], v[102:105]
	v_mfma_f32_16x16x32_bf16 v[78:81], v[14:17], v[212:215], v[74:77]
	v_mfma_f32_16x16x32_bf16 v[74:77], v[140:143], v[188:191], v[98:101]
	v_mfma_f32_16x16x32_bf16 v[74:77], v[170:173], v[212:215], v[74:77]
	s_setprio 0
	s_barrier
	ds_read_b128 v[204:207], v138
	ds_read_b128 v[208:211], v138 offset:1024
	ds_read_b128 v[224:227], v138 offset:2048
	ds_read_b128 v[228:231], v138 offset:3072
	s_waitcnt vmcnt(0)
	s_barrier
	s_waitcnt lgkmcnt(0)
	s_setprio 1
	s_waitcnt lgkmcnt(0)
	v_mfma_f32_16x16x32_bf16 v[98:101], v[204:207], v[26:29], v[216:219]
	v_mfma_f32_16x16x32_bf16 v[26:29], v[224:227], v[26:29], v[158:161]
	v_mfma_f32_16x16x32_bf16 v[114:117], v[228:231], v[30:33], v[26:29]
	v_mfma_f32_16x16x32_bf16 v[26:29], v[204:207], v[42:45], v[86:89]
	v_mfma_f32_16x16x32_bf16 v[102:105], v[208:211], v[46:49], v[26:29]
	v_mfma_f32_16x16x32_bf16 v[26:29], v[224:227], v[42:45], v[82:85]
	v_mfma_f32_16x16x32_bf16 v[118:121], v[208:211], v[30:33], v[98:101]
	v_mfma_f32_16x16x32_bf16 v[98:101], v[228:231], v[46:49], v[26:29]
	v_mfma_f32_16x16x32_bf16 v[26:29], v[204:207], v[174:177], v[162:165]
	v_mfma_f32_16x16x32_bf16 v[86:89], v[208:211], v[184:187], v[26:29]
	v_mfma_f32_16x16x32_bf16 v[26:29], v[224:227], v[174:177], v[166:169]
	v_mfma_f32_16x16x32_bf16 v[82:85], v[228:231], v[184:187], v[26:29]
	v_mfma_f32_16x16x32_bf16 v[26:29], v[204:207], v[188:191], v[70:73]
	v_mfma_f32_16x16x32_bf16 v[70:73], v[208:211], v[212:215], v[26:29]
	v_mfma_f32_16x16x32_bf16 v[26:29], v[224:227], v[188:191], v[66:69]
	v_mfma_f32_16x16x32_bf16 v[66:69], v[228:231], v[212:215], v[26:29]
	s_setprio 0
	s_barrier
	ds_read_b128 v[158:161], v137 offset:49152
	ds_read_b128 v[162:165], v137 offset:50176
	ds_read_b128 v[166:169], v136 offset:49152
	ds_read_b128 v[136:139], v136 offset:50176
	ds_read_b128 v[174:177], v135 offset:49152
	ds_read_b128 v[184:187], v135 offset:50176
	ds_read_b128 v[188:191], v134 offset:49152
	ds_read_b128 v[212:215], v134 offset:50176
	s_barrier
	s_waitcnt lgkmcnt(0)
	s_setprio 1
	s_waitcnt lgkmcnt(0)
	v_mfma_f32_16x16x32_bf16 v[26:29], v[10:13], v[158:161], v[62:65]
	v_mfma_f32_16x16x32_bf16 v[62:65], v[14:17], v[162:165], v[26:29]
	v_mfma_f32_16x16x32_bf16 v[26:29], v[140:143], v[158:161], v[58:61]
	v_mfma_f32_16x16x32_bf16 v[58:61], v[170:173], v[162:165], v[26:29]
	v_mfma_f32_16x16x32_bf16 v[26:29], v[10:13], v[166:169], v[54:57]
	v_mfma_f32_16x16x32_bf16 v[46:49], v[14:17], v[136:139], v[26:29]
	v_mfma_f32_16x16x32_bf16 v[26:29], v[140:143], v[166:169], v[50:53]
	v_mfma_f32_16x16x32_bf16 v[42:45], v[170:173], v[136:139], v[26:29]
	v_mfma_f32_16x16x32_bf16 v[26:29], v[10:13], v[174:177], v[200:203]
	v_mfma_f32_16x16x32_bf16 v[10:13], v[10:13], v[188:191], v[38:41]
	v_mfma_f32_16x16x32_bf16 v[30:33], v[14:17], v[184:187], v[26:29]
	v_mfma_f32_16x16x32_bf16 v[26:29], v[140:143], v[174:177], v[220:223]
	v_mfma_f32_16x16x32_bf16 v[14:17], v[14:17], v[212:215], v[10:13]
	v_mfma_f32_16x16x32_bf16 v[10:13], v[140:143], v[188:191], v[34:37]
	v_mfma_f32_16x16x32_bf16 v[26:29], v[170:173], v[184:187], v[26:29]
	v_mfma_f32_16x16x32_bf16 v[10:13], v[170:173], v[212:215], v[10:13]
	s_setprio 0
	s_setprio 1
	v_mfma_f32_16x16x32_bf16 v[34:37], v[204:207], v[158:161], v[130:133]
	v_mfma_f32_16x16x32_bf16 v[54:57], v[208:211], v[162:165], v[34:37]
	v_mfma_f32_16x16x32_bf16 v[34:37], v[224:227], v[158:161], v[146:149]
	v_mfma_f32_16x16x32_bf16 v[18:21], v[224:227], v[166:169], v[18:21]
	v_mfma_f32_16x16x32_bf16 v[50:53], v[228:231], v[162:165], v[34:37]
	v_mfma_f32_16x16x32_bf16 v[22:25], v[204:207], v[166:169], v[22:25]
	v_mfma_f32_16x16x32_bf16 v[34:37], v[228:231], v[136:139], v[18:21]
	v_mfma_f32_16x16x32_bf16 v[18:21], v[204:207], v[174:177], v[150:153]
	v_mfma_f32_16x16x32_bf16 v[38:41], v[208:211], v[136:139], v[22:25]
	v_mfma_f32_16x16x32_bf16 v[22:25], v[208:211], v[184:187], v[18:21]
	v_mfma_f32_16x16x32_bf16 v[18:21], v[224:227], v[174:177], v[154:157]
	v_mfma_f32_16x16x32_bf16 v[6:9], v[204:207], v[188:191], v[6:9]
	v_mfma_f32_16x16x32_bf16 v[2:5], v[224:227], v[188:191], v[2:5]
	v_mfma_f32_16x16x32_bf16 v[18:21], v[228:231], v[184:187], v[18:21]
	v_mfma_f32_16x16x32_bf16 v[6:9], v[208:211], v[212:215], v[6:9]
	v_mfma_f32_16x16x32_bf16 v[2:5], v[228:231], v[212:215], v[2:5]
	s_setprio 0
	v_cmp_gt_u32_e32 vcc, s85, v1
	s_barrier
	s_and_saveexec_b64 s[12:13], vcc
	s_cbranch_execz .LBB0_751
	s_barrier
; #define LAS __attribute__((address_space(3)))
; __device__ __forceinline__ int fresh_tid() { int t; asm volatile("v_mov_b32 %0, %1" : "=v"(t) : "v"(threadIdx.x)); return t; }
; __device__ __forceinline__ int fresh_bid() { int t; asm volatile("s_mov_b32 %0, %1" : "=s"(t) : "s"(blockIdx.x)); return t; }
; #define ACC_ZERO(acc) _Pragma("unroll") for (int _a = 0; _a < 2; ++_a) _Pragma("unroll") for (int _b = 0; _b < 2; ++_b) _Pragma("unroll") for (int _m = 0; _m < 4; ++_m) \
;     _Pragma("unroll") for (int _n = 0; _n < 2; ++_n) acc[_a][_b][_m][_n] = (f32x4){0.f, 0.f, 0.f, 0.f}
; __device__ __forceinline__ void gemm_stage_first(const bf16_t* __restrict__ A, int lda, const bf16_t* __restrict__ Bt, int ldb, int brow, int bcol, LAS unsigned char* lds) {
;     const int tid = fresh_tid();
;     const int wvu = __builtin_amdgcn_readfirstlane(tid >> 6);
;     unsigned offA, offB;
;     { int _r, _c; stage_rc(tid * 16, _r, _c); offA = (unsigned)(_r * lda + _c) * 2u; offB = (unsigned)(_r * ldb + _c) * 2u; }
;     STAGE(SBo(0, 0), Bt, ldb, bcol, 0, offB); STAGE(SAo(0, 0), A, lda, brow, 0, offA);
;     STAGE(SBo(0, 1), Bt, ldb, bcol + HALF, 0, offB); STAGE(SAo(0, 1), A, lda, brow + HALF, 0, offA);
; }
; __device__ __forceinline__ void phase_gates(const Ctx& a, LAS unsigned char* lds) {
;     ...
;     for (int w = fresh_bid(); w < ntile; w += gridDim.x) {
;         int pm, pn; tile_of(w, nM, pm, pn);
;         Acc acc; ACC_ZERO(acc);
;         gemm_kloop<true>(acc, xb, DM, W, DM, pm * 256, pn * 256, DM / 64, lds);
;         { const int wn = w + (int)gridDim.x; if (wn < ntile) { int pm2, pn2; tile_of(wn, nM, pm2, pn2); gemm_stage_first(xb, DM, W, DM, pm2 * 256, pn2 * 256, lds); } }
.LBB0_751:
	s_or_b64 exec, exec, s[12:13]
	s_load_dword s1, s[74:75], 0x0
	s_waitcnt lgkmcnt(0)
	s_add_i32 s9, s1, s9
	s_cmpk_gt_i32 s9, 0x2ff
	s_cselect_b64 s[12:13], -1, 0
	s_and_b64 vcc, exec, s[12:13]
	s_cbranch_vccnz .LBB0_744
	s_ashr_i32 s1, s9, 31
	s_lshr_b32 s1, s1, 26
	s_add_i32 s1, s9, s1
	v_mov_b32 v1, v179
	s_and_b32 s8, s1, 0xffffc0
	v_ashrrev_i32_e32 v131, 31, v1
	s_lshl_b32 s1, s1, 2
	v_lshrrev_b32_e32 v131, 26, v131
	s_and_b32 s40, s1, 0xffffff00
	v_readfirstlane_b32 s1, v1
	v_lshlrev_b32_e32 v130, 4, v1
	v_add_u32_e32 v131, v1, v131
	v_bfe_i32 v1, v1, 27, 1
	v_lshrrev_b32_e32 v1, 22, v1
	v_add_u32_e32 v1, v130, v1
	v_and_b32_e32 v1, 0xfffffc00, v1
	v_sub_u32_e32 v1, v130, v1
	v_lshrrev_b32_e32 v130, 4, v1
	v_bitop3_b32 v130, v130, v1, 32 bitop3:0x6c
	v_ashrrev_i32_e32 v1, 31, v1
	v_lshrrev_b32_e32 v1, 26, v1
	v_add_u32_e32 v1, v130, v1
	s_sub_i32 s8, s9, s8
	s_ashr_i32 s1, s1, 6
	v_ashrrev_i32_e32 v1, 6, v1
	s_lshl_b32 s38, s8, 8
	v_ashrrev_i32_e32 v131, 6, v131
	v_mul_i32_i24_e32 v133, 64, v1
	s_mov_b32 s42, s27
	s_mov_b32 s8, s1
	v_lshlrev_b32_e32 v132, 3, v131
	v_lshlrev_b32_e32 v131, 5, v131
	v_sub_u32_e32 v130, v130, v133
	s_ashr_i32 s43, s42, 31
	v_and_b32_e32 v132, 0x1ffff0, v132
	v_and_b32_e32 v131, 32, v131
	v_ashrrev_i16_sdwa v130, v194, sext(v130) dst_sel:DWORD dst_unused:UNUSED_PAD src0_sel:DWORD src1_sel:BYTE_0
	s_lshl_b64 s[42:43], s[42:43], 7
	v_add_u32_sdwa v130, v131, sext(v130) dst_sel:DWORD dst_unused:UNUSED_PAD src0_sel:DWORD src1_sel:WORD_0
	v_add_lshl_u32 v1, v1, v132, 11
	s_add_u32 s42, s82, s42
	v_lshl_add_u32 v144, v130, 1, v1
	s_addc_u32 s43, s83, s43
	s_ashr_i32 s41, s40, 31
	v_lshl_add_u64 v[130:131], s[42:43], 0, v[144:145]
	s_lshl_b64 s[42:43], s[40:41], 11
	s_lshl_b32 s8, s8, 10
	v_lshl_add_u64 v[132:133], v[130:131], 0, s[42:43]
	s_or_b32 s42, s40, 64
	s_add_i32 s8, s8, 0
	s_ashr_i32 s43, s42, 31
	s_add_i32 m0, s8, 0x10000
	s_lshl_b64 s[42:43], s[42:43], 11
	v_xor_b32_e32 v132, v197, v132
	global_load_lds_dwordx4 v[132:133], off
	v_lshl_add_u64 v[130:131], v[130:131], 0, s[42:43]
	s_add_i32 m0, s8, 0x12000
	s_mov_b32 s42, s27
	s_mov_b32 s8, s1
	v_xor_b32_e32 v130, v197, v130
	global_load_lds_dwordx4 v[130:131], off
	s_ashr_i32 s43, s42, 31
	s_lshl_b64 s[42:43], s[42:43], 7
	s_add_u32 s42, s34, s42
	s_addc_u32 s43, s35, s43
	s_ashr_i32 s39, s38, 31
	v_lshl_add_u64 v[130:131], s[42:43], 0, v[144:145]
	s_lshl_b64 s[42:43], s[38:39], 11
	s_lshl_b32 s8, s8, 10
	v_lshl_add_u64 v[132:133], v[130:131], 0, s[42:43]
	s_or_b32 s42, s38, 64
	s_add_i32 s8, s8, 0
	s_ashr_i32 s43, s42, 31
	s_mov_b32 m0, s8
	s_lshl_b64 s[42:43], s[42:43], 11
	v_xor_b32_e32 v132, v197, v132
	global_load_lds_dwordx4 v[132:133], off
	v_lshl_add_u64 v[130:131], v[130:131], 0, s[42:43]
	s_add_i32 m0, s8, 0x2000
	s_mov_b32 s42, s27
	s_mov_b32 s8, s1
	v_xor_b32_e32 v130, v197, v130
	global_load_lds_dwordx4 v[130:131], off
	s_ashr_i32 s43, s42, 31
	s_or_b32 s44, s40, 0x80
	s_lshl_b64 s[42:43], s[42:43], 7
	s_add_u32 s42, s82, s42
	s_addc_u32 s43, s83, s43
	s_lshl_b32 s8, s8, 10
	s_ashr_i32 s45, s44, 31
	s_or_b32 s40, s40, 0xc0
	v_lshl_add_u64 v[130:131], s[42:43], 0, v[144:145]
	s_add_i32 s8, s8, 0
	s_lshl_b64 s[42:43], s[44:45], 11
	s_ashr_i32 s41, s40, 31
	s_add_i32 m0, s8, 0x14000
	v_lshl_add_u64 v[132:133], v[130:131], 0, s[42:43]
	s_lshl_b64 s[40:41], s[40:41], 11
	v_xor_b32_e32 v132, v197, v132
	global_load_lds_dwordx4 v[132:133], off
	v_lshl_add_u64 v[130:131], v[130:131], 0, s[40:41]
	s_add_i32 m0, s8, 0x16000
	s_mov_b32 s40, s27
	v_xor_b32_e32 v130, v197, v130
	global_load_lds_dwordx4 v[130:131], off
	s_ashr_i32 s41, s40, 31
	s_or_b32 s42, s38, 0x80
	s_lshl_b64 s[40:41], s[40:41], 7
	s_add_u32 s40, s34, s40
	s_addc_u32 s41, s35, s41
	s_lshl_b32 s1, s1, 10
	s_ashr_i32 s43, s42, 31
	s_or_b32 s38, s38, 0xc0
	v_lshl_add_u64 v[130:131], s[40:41], 0, v[144:145]
	s_add_i32 s1, s1, 0
	s_lshl_b64 s[40:41], s[42:43], 11
	s_ashr_i32 s39, s38, 31
	s_add_i32 m0, s1, 0x4000
	v_lshl_add_u64 v[132:133], v[130:131], 0, s[40:41]
	s_lshl_b64 s[38:39], s[38:39], 11
	v_xor_b32_e32 v132, v197, v132
	global_load_lds_dwordx4 v[132:133], off
	v_lshl_add_u64 v[130:131], v[130:131], 0, s[38:39]
	s_add_i32 m0, s1, 0x6000
	s_nop 0
	v_xor_b32_e32 v130, v197, v130
	global_load_lds_dwordx4 v[130:131], off
	s_branch .LBB0_744

; __device__ __forceinline__ int fresh_bid() { int t; asm volatile("s_mov_b32 %0, %1" : "=s"(t) : "s"(blockIdx.x)); return t; }
; __device__ __forceinline__ void phase_convert(const Ctx& a, int l, LAS unsigned char* lds) {
;     ...
;         for (int e = fresh_bid() * NT + tid; e < SEQ * 48; e += gridDim.x * NT) {
;             int s = e / 48, i = e % 48;
;             float invf; float2* dst;
;             if (i < 32) { invf = exp2f(-(float)(2 * i) / 64.f * 13.287712379549449f); dst = t64 + s * 32 + i; }
;             else { int ii = i - 32; invf = exp2f(-(float)(2 * ii) / 32.f * 13.287712379549449f); dst = t32 + s * 16 + ii; }
;             float ang = (float)s * invf;
;             double rev = (double)ang * 0.15915494309189535; rev -= floor(rev);
;             float fr = (float)rev;
;             *dst = make_float2(__builtin_amdgcn_cosf(fr), __builtin_amdgcn_sinf(fr));
.LBB0_792:
	s_mov_b32 s8, 0x2aaaaaab
	v_mul_hi_i32 v3, v2, s8
	v_lshrrev_b32_e32 v5, 31, v3
	v_ashrrev_i32_e32 v3, 3, v3
	v_add_u32_e32 v3, v3, v5
	s_movk_i32 s36, 0xffd0
	v_mad_u64_u32 v[6:7], s[36:37], v3, s36, v[2:3]
	v_cmp_lt_i32_e32 vcc, 31, v6
	s_and_saveexec_b64 s[36:37], vcc
	s_xor_b64 s[36:37], exec, s[36:37]
	s_cbranch_execz .LBB0_794
	s_movk_i32 s8, 0xffa0
	v_mul_lo_u32 v5, v3, s8
	s_movk_i32 s38, 0xffc0
	v_add3_u32 v5, v4, v5, s38
	v_cvt_f32_u32_e32 v5, v5
	s_mov_b32 s8, 0xc2fc0000
	v_subrev_u32_e32 v144, 32, v6
	v_lshlrev_b32_e32 v6, 4, v3
	v_mul_f32_e32 v5, 0xbd000000, v5
	v_mul_f32_e32 v7, 0x41549a78, v5
	v_cmp_gt_f32_e32 vcc, s8, v7
	v_readlane_b32 s6, v254, 1
	v_readlane_b32 s7, v254, 2
	v_cndmask_b32_e32 v7, 0, v199, vcc
	v_fmac_f32_e32 v7, 0x41549a78, v5
	v_exp_f32_e32 v5, v7
	v_ashrrev_i32_e32 v7, 31, v6
	v_lshl_add_u64 v[6:7], v[6:7], 3, s[6:7]
	v_mov_b32_e32 v8, 0xffffffc0
	v_cndmask_b32_e32 v8, 0, v8, vcc
	v_ldexp_f32 v5, v5, v8
	v_lshl_add_u64 v[8:9], v[144:145], 3, v[6:7]
.LBB0_794:
	s_andn2_saveexec_b64 s[36:37], s[36:37]
	s_cbranch_execz .LBB0_791
	s_movk_i32 s8, 0xffa0
	v_mad_u64_u32 v[8:9], s[38:39], v3, s8, v[4:5]
	v_cvt_f32_i32_e32 v5, v8
	s_mov_b32 s8, 0xc2fc0000
	v_lshlrev_b32_e32 v8, 5, v3
	v_readlane_b32 s6, v253, 63
	v_mul_f32_e32 v5, 0xbc800000, v5
	v_mul_f32_e32 v9, 0x41549a78, v5
	v_cmp_gt_f32_e32 vcc, s8, v9
	v_readlane_b32 s7, v254, 0
	v_ashrrev_i32_e32 v7, 31, v6
	v_cndmask_b32_e32 v9, 0, v199, vcc
	v_fmac_f32_e32 v9, 0x41549a78, v5
	v_exp_f32_e32 v5, v9
	v_ashrrev_i32_e32 v9, 31, v8
	v_lshl_add_u64 v[8:9], v[8:9], 3, s[6:7]
	v_mov_b32_e32 v11, 0xffffffc0
	v_cndmask_b32_e32 v11, 0, v11, vcc
	v_ldexp_f32 v5, v5, v11
	v_lshl_add_u64 v[8:9], v[6:7], 3, v[8:9]
	s_branch .LBB0_791

; __device__ __forceinline__ unsigned cvt_pk(float lo, float hi) { f32x2_t v = {lo, hi}; bf16x2_t b = __builtin_convertvector(v, bf16x2_t); return __builtin_bit_cast(unsigned, b); }
; __device__ __forceinline__ int fresh_bid() { int t; asm volatile("s_mov_b32 %0, %1" : "=s"(t) : "s"(blockIdx.x)); return t; }
; __device__ __forceinline__ void phase_convert(const Ctx& a, int l, LAS unsigned char* lds) {
;     ...
;         for (int r2 = fresh_bid(); r2 < T / 2; r2 += gridDim.x) {
;             int row = r2 * 2 + (tid >> 8), tt = tid & 255;
;             f32x4 v = *(const f32x4*)(x + (size_t)row * DM + tt * 4);
;             u32x2 w; w[0] = cvt_pk(v[0], v[1]); w[1] = cvt_pk(v[2], v[3]);
;             *(u32x2*)(xb + (size_t)row * DM + tt * 4) = w;
;             float ss = wave_sum(v[0] * v[0] + v[1] * v[1] + v[2] * v[2] + v[3] * v[3]);
;             if ((tid & 63) == 0) ssq[(size_t)row * 4 + (tt >> 6)] = ss;
;         }
.LBB0_799:
	v_ashrrev_i32_e32 v9, 31, v8
	v_lshlrev_b64 v[18:19], 12, v[8:9]
	v_lshl_add_u64 v[18:19], v[2:3], 0, v[18:19]
	flat_load_dwordx4 v[18:21], v[18:19]
	s_waitcnt vmcnt(0) lgkmcnt(0)
	v_mul_f32_e32 v1, v19, v19
	v_fmac_f32_e32 v1, v18, v18
	v_fmac_f32_e32 v1, v20, v20
	v_fmac_f32_e32 v1, v21, v21
	ds_bpermute_b32 v17, v11, v1
	v_cvt_pk_bf16_f32 v18, v18, v19
	v_cvt_pk_bf16_f32 v19, v20, v21
	v_lshlrev_b64 v[20:21], 11, v[8:9]
	v_lshl_add_u64 v[20:21], v[4:5], 0, v[20:21]
	s_waitcnt lgkmcnt(0)
	v_add_f32_e32 v1, v1, v17
	ds_bpermute_b32 v17, v12, v1
	v_and_b32_e32 v22, 15, v8
	v_lshlrev_b32_e32 v22, 7, v22
	v_xor_b32_e32 v20, v22, v20
	global_store_dwordx2 v[20:21], v[18:19], off
	s_waitcnt lgkmcnt(0)
	v_add_f32_e32 v1, v1, v17
	ds_bpermute_b32 v17, v13, v1
	s_waitcnt lgkmcnt(0)
	v_add_f32_e32 v1, v1, v17
	ds_bpermute_b32 v17, v14, v1
	s_waitcnt lgkmcnt(0)
	v_add_f32_e32 v1, v1, v17
	ds_bpermute_b32 v17, v15, v1
	s_waitcnt lgkmcnt(0)
	v_add_f32_e32 v1, v1, v17
	ds_bpermute_b32 v17, v16, v1
	s_and_saveexec_b64 s[0:1], vcc
	s_cbranch_execz .LBB0_798
	s_waitcnt lgkmcnt(0)
	v_add_f32_e32 v1, v1, v17
	v_lshl_add_u64 v[18:19], v[8:9], 4, v[6:7]
	global_store_dword v[18:19], v1, off
	s_branch .LBB0_798
